# projection GEMM logit-tile epilogue: dt_bias/A_log scalars loaded once instead of 80 dependent load+wait round trips
# speedup vs baseline: 1.0036x; 1.0036x over previous
;     __device__ __forceinline__ void operator()(f32x4 (&acc)[2][2][4][2], const Unit& u, int row0t, int wr, int wc, int fr, int fq) const {
;     ...
;                         for (int n = 0; n < 2; ++n) { const f32x4 v = acc[ai][0][m][n]; f32x4 o;
;                             if (fq == 0) {
; #pragma unroll
;                                 for (int e = 0; e < 4; ++e) o[e] = 1.0f / (1.0f + __expf(-v[e])); }
;                             else {
; #pragma unroll
;                                 for (int e = 0; e < 4; ++e) { const int h = 4 * n + e; const float xx = v[e] + dt_bias[h]; const float sp = xx > 20.f ? xx : log1pf(__expf(xx)); o[e] = -__expf(A_log[h]) * sp; } }
;                             *(f32x4*)(bg + (size_t)r * 16 + 8 * fq + 4 * n) = o; } }
.LBB0_177:
	s_and_b64 vcc, exec, s[24:25]
	s_cbranch_vccz .LBB0_378
	s_and_saveexec_b64 s[86:87], s[80:81]
	s_cbranch_execz .LBB0_372
	global_load_dword v150, v2, s[76:77]
	global_load_dword v151, v2, s[76:77] offset:4
	global_load_dword v152, v2, s[76:77] offset:8
	global_load_dword v153, v2, s[76:77] offset:12
	global_load_dword v154, v2, s[76:77] offset:16
	global_load_dword v155, v2, s[76:77] offset:20
	global_load_dword v156, v2, s[76:77] offset:24
	global_load_dword v157, v2, s[76:77] offset:28
	global_load_dword v158, v2, s[74:75]
	global_load_dword v159, v2, s[74:75] offset:4
	global_load_dword v160, v2, s[74:75] offset:8
	global_load_dword v161, v2, s[74:75] offset:12
	global_load_dword v162, v2, s[74:75] offset:16
	global_load_dword v163, v2, s[74:75] offset:20
	global_load_dword v164, v2, s[74:75] offset:24
	global_load_dword v165, v2, s[74:75] offset:28
	s_waitcnt vmcnt(0)
	s_and_saveexec_b64 s[24:25], s[4:5]
	s_xor_b64 s[24:25], exec, s[24:25]
	s_cbranch_execz .LBB0_189
	v_mov_b32_e32 v3, v150
	v_add_f32_e32 v3, v66, v3
	v_cmp_nlt_f32_e32 vcc, s53, v3
	s_and_saveexec_b64 s[36:37], vcc
	s_cbranch_execz .LBB0_182
	v_mul_f32_e32 v3, 0x3fb8aa3b, v3
	v_exp_f32_e32 v3, v3
	s_nop 0
	v_add_f32_e32 v66, 1.0, v3
	v_frexp_mant_f32_e32 v71, v66
	v_cvt_f64_f32_e32 v[4:5], v66
	v_frexp_exp_i32_f64_e32 v4, v[4:5]
	v_cmp_gt_f32_e32 vcc, s55, v71
	v_add_f32_e32 v70, -1.0, v66
	v_sub_f32_e32 v72, v70, v66
	v_subbrev_co_u32_e32 v76, vcc, 0, v4, vcc
	v_sub_u32_e32 v4, 0, v76
	v_sub_f32_e32 v70, v3, v70
	v_add_f32_e32 v72, 1.0, v72
	v_ldexp_f32 v5, v66, v4
	v_add_f32_e32 v70, v70, v72
	v_add_f32_e32 v66, -1.0, v5
	v_add_f32_e32 v71, 1.0, v5
	v_ldexp_f32 v4, v70, v4
	v_add_f32_e32 v70, 1.0, v66
	v_add_f32_e32 v72, -1.0, v71
	v_sub_f32_e32 v70, v5, v70
	v_sub_f32_e32 v5, v5, v72
	v_add_f32_e32 v70, v4, v70
	v_add_f32_e32 v4, v4, v5
	v_add_f32_e32 v77, v71, v4
	v_rcp_f32_e32 v79, v77
	v_sub_f32_e32 v5, v77, v71
	v_sub_f32_e32 v78, v4, v5
	v_add_f32_e32 v5, v66, v70
	v_sub_f32_e32 v4, v5, v66
	v_mul_f32_e32 v80, v5, v79
	v_sub_f32_e32 v66, v70, v4
	v_mul_f32_e32 v70, v77, v80
	v_fma_f32 v72, v80, v77, -v70
	v_fmac_f32_e32 v72, v80, v78
	v_add_f32_e32 v4, v70, v72
	v_sub_f32_e32 v71, v5, v4
	v_pk_add_f32 v[74:75], v[4:5], v[70:71] neg_lo:[0,1] neg_hi:[0,1]
	v_mov_b32_e32 v73, v4
	v_pk_add_f32 v[4:5], v[74:75], v[72:73] neg_lo:[0,1] neg_hi:[0,1]
	v_cmp_neq_f32_e32 vcc, s57, v3
	v_add_f32_e32 v5, v66, v5
	v_add_f32_e32 v4, v4, v5
	v_add_f32_e32 v5, v71, v4
	v_mul_f32_e32 v66, v79, v5
	v_mul_f32_e32 v70, v77, v66
	v_fma_f32 v72, v66, v77, -v70
	v_fmac_f32_e32 v72, v66, v78
	v_sub_f32_e32 v71, v71, v5
	v_add_f32_e32 v77, v4, v71
	v_add_f32_e32 v4, v70, v72
	v_sub_f32_e32 v71, v5, v4
	v_pk_add_f32 v[74:75], v[4:5], v[70:71] neg_lo:[0,1] neg_hi:[0,1]
	v_mov_b32_e32 v73, v4
	v_pk_add_f32 v[4:5], v[74:75], v[72:73] neg_lo:[0,1] neg_hi:[0,1]
	s_nop 0
	v_add_f32_e32 v5, v77, v5
	v_add_f32_e32 v4, v4, v5
	v_add_f32_e32 v5, v80, v66
	v_add_f32_e32 v4, v71, v4
	v_sub_f32_e32 v70, v5, v80
	v_mul_f32_e32 v4, v79, v4
	v_sub_f32_e32 v66, v66, v70
	v_add_f32_e32 v66, v66, v4
	v_add_f32_e32 v70, v5, v66
	v_mul_f32_e32 v72, v70, v70
	v_fmamk_f32 v4, v72, 0x3e9b6dac, v235
	v_fmaak_f32 v227, v72, v4, 0x3f2aaada
	v_cvt_f32_i32_e32 v4, v76
	v_sub_f32_e32 v5, v70, v5
	v_sub_f32_e32 v5, v66, v5
	v_ldexp_f32 v66, v5, 1
	v_mul_f32_e32 v5, v70, v72
	v_pk_mul_f32 v[72:73], v[4:5], v[226:227]
	v_ldexp_f32 v71, v70, 1
	v_fma_f32 v70, v4, s56, -v72
	v_fmac_f32_e32 v70, 0xb102e308, v4
	v_pk_add_f32 v[4:5], v[72:73], v[70:71]
	v_mov_b32_e32 v74, v72
	v_sub_f32_e32 v71, v5, v71
	v_sub_f32_e32 v71, v73, v71
	v_add_f32_e32 v75, v66, v71
	v_pk_add_f32 v[72:73], v[4:5], v[72:73] neg_lo:[0,1] neg_hi:[0,1]
	v_pk_add_f32 v[76:77], v[4:5], v[74:75]
	v_mov_b32_e32 v71, v4
	v_mov_b32_e32 v73, v77
	v_pk_add_f32 v[78:79], v[70:71], v[72:73] neg_lo:[0,1] neg_hi:[0,1]
	v_pk_add_f32 v[70:71], v[70:71], v[72:73]
	v_mov_b32_e32 v74, v75
	v_pk_add_f32 v[72:73], v[70:71], v[4:5] op_sel:[1,0] op_sel_hi:[0,1] neg_lo:[0,1] neg_hi:[0,1]
	v_pk_add_f32 v[80:81], v[76:77], v[72:73] op_sel_hi:[1,0] neg_lo:[0,1] neg_hi:[0,1]
	v_mov_b32_e32 v76, v77
	v_mov_b32_e32 v77, v71
	v_pk_mov_b32 v[72:73], v[4:5], v[72:73] op_sel:[1,0]
	v_mov_b32_e32 v75, v4
	v_pk_add_f32 v[72:73], v[76:77], v[72:73] neg_lo:[0,1] neg_hi:[0,1]
	v_mov_b32_e32 v80, v78
	v_pk_add_f32 v[4:5], v[74:75], v[72:73] neg_lo:[0,1] neg_hi:[0,1]
	v_mov_b32_e32 v79, v71
	v_pk_add_f32 v[72:73], v[80:81], v[4:5]
	s_nop 0
	v_pk_add_f32 v[74:75], v[72:73], v[72:73] op_sel:[0,1] op_sel_hi:[1,0]
	s_nop 0
	v_pk_add_f32 v[70:71], v[70:71], v[74:75] op_sel:[1,0] op_sel_hi:[0,1]
	v_mov_b32_e32 v73, v70
	v_pk_add_f32 v[76:77], v[72:73], v[78:79] neg_lo:[0,1] neg_hi:[0,1]
	v_mov_b32_e32 v5, v74
	v_sub_f32_e32 v66, v72, v76
	v_pk_add_f32 v[4:5], v[4:5], v[76:77] neg_lo:[0,1] neg_hi:[0,1]
	v_sub_f32_e32 v66, v78, v66
	v_add_f32_e32 v4, v4, v66
	v_add_f32_e32 v4, v4, v5
	v_add_f32_e32 v4, v70, v4
	v_cndmask_b32_e32 v4, v236, v4, vcc
	v_cmp_ngt_f32_e32 vcc, -1.0, v3
	s_nop 1
	v_cndmask_b32_e32 v4, v237, v4, vcc
	v_cmp_neq_f32_e32 vcc, -1.0, v3
	s_nop 1
	v_cndmask_b32_e32 v4, v238, v4, vcc
	v_cmp_lt_f32_e64 vcc, |v3|, s58
	s_nop 1
	v_cndmask_b32_e32 v3, v4, v3, vcc
;     __device__ __forceinline__ void operator()(f32x4 (&acc)[2][2][4][2], const Unit& u, int row0t, int wr, int wc, int fr, int fq) const {
;     ...
;                                 for (int e = 0; e < 4; ++e) { const int h = 4 * n + e; const float xx = v[e] + dt_bias[h]; const float sp = xx > 20.f ? xx : log1pf(__expf(xx)); o[e] = -__expf(A_log[h]) * sp; } }
.LBB0_182:
	s_or_b64 exec, exec, s[36:37]
	v_mov_b32_e32 v5, v151
	v_mov_b32_e32 v4, v158
	v_add_f32_e32 v5, v67, v5
	v_cmp_nlt_f32_e32 vcc, s53, v5
	s_and_saveexec_b64 s[36:37], vcc
	s_cbranch_execz .LBB0_184
	v_mul_f32_e32 v5, 0x3fb8aa3b, v5
	v_exp_f32_e32 v5, v5
	s_nop 0
	v_add_f32_e32 v70, 1.0, v5
	v_frexp_mant_f32_e32 v72, v70
	v_cvt_f64_f32_e32 v[66:67], v70
	v_frexp_exp_i32_f64_e32 v66, v[66:67]
	v_cmp_gt_f32_e32 vcc, s55, v72
	v_add_f32_e32 v71, -1.0, v70
	v_sub_f32_e32 v73, v71, v70
	v_subbrev_co_u32_e32 v76, vcc, 0, v66, vcc
	v_sub_u32_e32 v66, 0, v76
	v_sub_f32_e32 v71, v5, v71
	v_add_f32_e32 v73, 1.0, v73
	v_ldexp_f32 v67, v70, v66
	v_add_f32_e32 v71, v71, v73
	v_add_f32_e32 v70, -1.0, v67
	v_add_f32_e32 v72, 1.0, v67
	v_ldexp_f32 v66, v71, v66
	v_add_f32_e32 v71, 1.0, v70
	v_add_f32_e32 v73, -1.0, v72
	v_sub_f32_e32 v71, v67, v71
	v_sub_f32_e32 v67, v67, v73
	v_add_f32_e32 v71, v66, v71
	v_add_f32_e32 v66, v66, v67
	v_add_f32_e32 v77, v72, v66
	v_rcp_f32_e32 v79, v77
	v_sub_f32_e32 v67, v77, v72
	v_sub_f32_e32 v78, v66, v67
	v_add_f32_e32 v67, v70, v71
	v_mul_f32_e32 v81, v67, v79
	v_sub_f32_e32 v66, v67, v70
	v_mul_f32_e32 v70, v77, v81
	v_fma_f32 v72, v81, v77, -v70
	v_fmac_f32_e32 v72, v81, v78
	v_sub_f32_e32 v80, v71, v66
	v_add_f32_e32 v66, v70, v72
	v_sub_f32_e32 v71, v67, v66
	v_pk_add_f32 v[74:75], v[66:67], v[70:71] neg_lo:[0,1] neg_hi:[0,1]
	v_mov_b32_e32 v73, v66
	v_pk_add_f32 v[66:67], v[74:75], v[72:73] neg_lo:[0,1] neg_hi:[0,1]
	v_cmp_neq_f32_e32 vcc, s57, v5
	v_add_f32_e32 v67, v80, v67
	v_add_f32_e32 v66, v66, v67
	v_add_f32_e32 v67, v71, v66
	v_mul_f32_e32 v80, v79, v67
	v_mul_f32_e32 v70, v77, v80
	v_fma_f32 v72, v80, v77, -v70
	v_fmac_f32_e32 v72, v80, v78
	v_sub_f32_e32 v71, v71, v67
	v_add_f32_e32 v77, v66, v71
	v_add_f32_e32 v66, v70, v72
	v_sub_f32_e32 v71, v67, v66
	v_pk_add_f32 v[74:75], v[66:67], v[70:71] neg_lo:[0,1] neg_hi:[0,1]
	v_mov_b32_e32 v73, v66
	v_pk_add_f32 v[66:67], v[74:75], v[72:73] neg_lo:[0,1] neg_hi:[0,1]
	s_nop 0
	v_add_f32_e32 v67, v77, v67
	v_add_f32_e32 v66, v66, v67
	v_add_f32_e32 v67, v81, v80
	v_add_f32_e32 v66, v71, v66
	v_sub_f32_e32 v70, v67, v81
	v_mul_f32_e32 v66, v79, v66
	v_sub_f32_e32 v70, v80, v70
	v_add_f32_e32 v70, v70, v66
	v_add_f32_e32 v72, v67, v70
	v_mul_f32_e32 v73, v72, v72
	v_fmamk_f32 v66, v73, 0x3e9b6dac, v235
	v_fmaak_f32 v227, v73, v66, 0x3f2aaada
	v_cvt_f32_i32_e32 v66, v76
	v_sub_f32_e32 v67, v72, v67
	v_sub_f32_e32 v67, v70, v67
	v_ldexp_f32 v74, v67, 1
	v_mul_f32_e32 v67, v72, v73
	v_ldexp_f32 v71, v72, 1
	v_pk_mul_f32 v[72:73], v[66:67], v[226:227]
	s_nop 0
	v_fma_f32 v70, v66, s56, -v72
	v_fmac_f32_e32 v70, 0xb102e308, v66
	v_pk_add_f32 v[66:67], v[72:73], v[70:71]
	s_nop 0
	v_sub_f32_e32 v71, v67, v71
	v_sub_f32_e32 v71, v73, v71
	v_add_f32_e32 v75, v74, v71
	v_mov_b32_e32 v74, v72
	v_pk_add_f32 v[72:73], v[66:67], v[72:73] neg_lo:[0,1] neg_hi:[0,1]
	v_pk_add_f32 v[76:77], v[66:67], v[74:75]
	v_mov_b32_e32 v71, v66
	v_mov_b32_e32 v73, v77
	v_pk_add_f32 v[78:79], v[70:71], v[72:73] neg_lo:[0,1] neg_hi:[0,1]
	v_pk_add_f32 v[70:71], v[70:71], v[72:73]
	v_mov_b32_e32 v74, v75
	v_pk_add_f32 v[72:73], v[70:71], v[66:67] op_sel:[1,0] op_sel_hi:[0,1] neg_lo:[0,1] neg_hi:[0,1]
	v_pk_add_f32 v[80:81], v[76:77], v[72:73] op_sel_hi:[1,0] neg_lo:[0,1] neg_hi:[0,1]
	v_mov_b32_e32 v76, v77
	v_mov_b32_e32 v77, v71
	v_pk_mov_b32 v[72:73], v[66:67], v[72:73] op_sel:[1,0]
	v_mov_b32_e32 v75, v66
	v_pk_add_f32 v[72:73], v[76:77], v[72:73] neg_lo:[0,1] neg_hi:[0,1]
	v_mov_b32_e32 v80, v78
	v_pk_add_f32 v[66:67], v[74:75], v[72:73] neg_lo:[0,1] neg_hi:[0,1]
	v_mov_b32_e32 v79, v71
	v_pk_add_f32 v[72:73], v[80:81], v[66:67]
	s_nop 0
	v_pk_add_f32 v[74:75], v[72:73], v[72:73] op_sel:[0,1] op_sel_hi:[1,0]
	s_nop 0
	v_pk_add_f32 v[70:71], v[70:71], v[74:75] op_sel:[1,0] op_sel_hi:[0,1]
	v_mov_b32_e32 v73, v70
	v_pk_add_f32 v[76:77], v[72:73], v[78:79] neg_lo:[0,1] neg_hi:[0,1]
	v_mov_b32_e32 v67, v74
	v_sub_f32_e32 v71, v72, v76
	v_pk_add_f32 v[66:67], v[66:67], v[76:77] neg_lo:[0,1] neg_hi:[0,1]
	v_sub_f32_e32 v71, v78, v71
	v_add_f32_e32 v66, v66, v71
	v_add_f32_e32 v66, v66, v67
	v_add_f32_e32 v66, v70, v66
	v_cndmask_b32_e32 v66, v236, v66, vcc
	v_cmp_ngt_f32_e32 vcc, -1.0, v5
	s_nop 1
	v_cndmask_b32_e32 v66, v237, v66, vcc
	v_cmp_neq_f32_e32 vcc, -1.0, v5
	s_nop 1
	v_cndmask_b32_e32 v66, v238, v66, vcc
	v_cmp_lt_f32_e64 vcc, |v5|, s58
	s_nop 1
	v_cndmask_b32_e32 v5, v66, v5, vcc
;     __device__ __forceinline__ void operator()(f32x4 (&acc)[2][2][4][2], const Unit& u, int row0t, int wr, int wc, int fr, int fq) const {
;     ...
;                                 for (int e = 0; e < 4; ++e) { const int h = 4 * n + e; const float xx = v[e] + dt_bias[h]; const float sp = xx > 20.f ? xx : log1pf(__expf(xx)); o[e] = -__expf(A_log[h]) * sp; } }
.LBB0_184:
	s_or_b64 exec, exec, s[36:37]
	v_mov_b32_e32 v67, v152
	v_mov_b32_e32 v66, v159
	v_add_f32_e32 v67, v68, v67
	v_cmp_nlt_f32_e32 vcc, s53, v67
	s_and_saveexec_b64 s[36:37], vcc
	s_cbranch_execz .LBB0_186
	v_mul_f32_e32 v67, 0x3fb8aa3b, v67
	v_exp_f32_e32 v67, v67
	s_nop 0
	v_add_f32_e32 v68, 1.0, v67
	v_frexp_mant_f32_e32 v73, v68
	v_cvt_f64_f32_e32 v[70:71], v68
	v_add_f32_e32 v72, -1.0, v68
	v_frexp_exp_i32_f64_e32 v70, v[70:71]
	v_cmp_gt_f32_e32 vcc, s55, v73
	v_sub_f32_e32 v74, v72, v68
	v_sub_f32_e32 v72, v67, v72
	v_subbrev_co_u32_e32 v78, vcc, 0, v70, vcc
	v_add_f32_e32 v74, 1.0, v74
	v_sub_u32_e32 v70, 0, v78
	v_add_f32_e32 v72, v72, v74
	v_ldexp_f32 v68, v68, v70
	v_ldexp_f32 v70, v72, v70
	v_add_f32_e32 v72, -1.0, v68
	v_add_f32_e32 v71, 1.0, v72
	v_sub_f32_e32 v71, v68, v71
	v_add_f32_e32 v73, v70, v71
	v_add_f32_e32 v71, 1.0, v68
	v_add_f32_e32 v74, -1.0, v71
	v_sub_f32_e32 v68, v68, v74
	v_add_f32_e32 v68, v70, v68
	v_add_f32_e32 v79, v71, v68
	v_rcp_f32_e32 v80, v79
	v_sub_f32_e32 v70, v79, v71
	v_add_f32_e32 v71, v72, v73
	v_sub_f32_e32 v68, v68, v70
	v_mul_f32_e32 v82, v71, v80
	v_sub_f32_e32 v70, v71, v72
	v_mul_f32_e32 v72, v79, v82
	v_fma_f32 v74, v82, v79, -v72
	v_fmac_f32_e32 v74, v82, v68
	v_sub_f32_e32 v81, v73, v70
	v_add_f32_e32 v70, v72, v74
	v_sub_f32_e32 v73, v71, v70
	v_pk_add_f32 v[76:77], v[70:71], v[72:73] neg_lo:[0,1] neg_hi:[0,1]
	v_mov_b32_e32 v75, v70
	v_pk_add_f32 v[70:71], v[76:77], v[74:75] neg_lo:[0,1] neg_hi:[0,1]
	v_cmp_neq_f32_e32 vcc, s57, v67
	v_add_f32_e32 v71, v81, v71
	v_add_f32_e32 v70, v70, v71
	v_add_f32_e32 v71, v73, v70
	v_mul_f32_e32 v81, v80, v71
	v_mul_f32_e32 v72, v79, v81
	v_fma_f32 v74, v81, v79, -v72
	v_fmac_f32_e32 v74, v81, v68
	v_sub_f32_e32 v68, v73, v71
	v_add_f32_e32 v68, v70, v68
	v_add_f32_e32 v70, v72, v74
	v_sub_f32_e32 v73, v71, v70
	v_pk_add_f32 v[76:77], v[70:71], v[72:73] neg_lo:[0,1] neg_hi:[0,1]
	v_mov_b32_e32 v75, v70
	v_pk_add_f32 v[70:71], v[76:77], v[74:75] neg_lo:[0,1] neg_hi:[0,1]
	s_nop 0
	v_add_f32_e32 v68, v68, v71
	v_add_f32_e32 v68, v70, v68
	v_add_f32_e32 v71, v82, v81
	v_add_f32_e32 v68, v73, v68
	v_sub_f32_e32 v70, v71, v82
	v_mul_f32_e32 v68, v80, v68
	v_sub_f32_e32 v70, v81, v70
	v_add_f32_e32 v68, v70, v68
	v_add_f32_e32 v72, v71, v68
	v_mul_f32_e32 v74, v72, v72
	v_fmamk_f32 v70, v74, 0x3e9b6dac, v235
	v_fmaak_f32 v227, v74, v70, 0x3f2aaada
	v_cvt_f32_i32_e32 v70, v78
	v_sub_f32_e32 v71, v72, v71
	v_sub_f32_e32 v68, v68, v71
	v_mul_f32_e32 v71, v72, v74
	v_pk_mul_f32 v[74:75], v[70:71], v[226:227]
	v_ldexp_f32 v73, v72, 1
	v_fma_f32 v72, v70, s56, -v74
	v_fmac_f32_e32 v72, 0xb102e308, v70
	v_pk_add_f32 v[70:71], v[74:75], v[72:73]
	v_ldexp_f32 v68, v68, 1
	v_sub_f32_e32 v73, v71, v73
	v_sub_f32_e32 v73, v75, v73
	v_add_f32_e32 v77, v68, v73
	v_mov_b32_e32 v76, v74
	v_pk_add_f32 v[74:75], v[70:71], v[74:75] neg_lo:[0,1] neg_hi:[0,1]
	v_pk_add_f32 v[78:79], v[70:71], v[76:77]
	v_mov_b32_e32 v73, v70
	v_mov_b32_e32 v75, v79
	v_pk_add_f32 v[80:81], v[72:73], v[74:75] neg_lo:[0,1] neg_hi:[0,1]
	v_pk_add_f32 v[72:73], v[72:73], v[74:75]
	v_mov_b32_e32 v76, v77
	v_pk_add_f32 v[74:75], v[72:73], v[70:71] op_sel:[1,0] op_sel_hi:[0,1] neg_lo:[0,1] neg_hi:[0,1]
	v_pk_add_f32 v[82:83], v[78:79], v[74:75] op_sel_hi:[1,0] neg_lo:[0,1] neg_hi:[0,1]
	v_mov_b32_e32 v78, v79
	v_mov_b32_e32 v79, v73
	v_pk_mov_b32 v[74:75], v[70:71], v[74:75] op_sel:[1,0]
	v_mov_b32_e32 v77, v70
	v_pk_add_f32 v[74:75], v[78:79], v[74:75] neg_lo:[0,1] neg_hi:[0,1]
	v_mov_b32_e32 v82, v80
	v_pk_add_f32 v[70:71], v[76:77], v[74:75] neg_lo:[0,1] neg_hi:[0,1]
	v_mov_b32_e32 v81, v73
	v_pk_add_f32 v[74:75], v[82:83], v[70:71]
	s_nop 0
	v_pk_add_f32 v[76:77], v[74:75], v[74:75] op_sel:[0,1] op_sel_hi:[1,0]
	s_nop 0
	v_pk_add_f32 v[72:73], v[72:73], v[76:77] op_sel:[1,0] op_sel_hi:[0,1]
	v_mov_b32_e32 v75, v72
	v_pk_add_f32 v[78:79], v[74:75], v[80:81] neg_lo:[0,1] neg_hi:[0,1]
	v_mov_b32_e32 v71, v76
	v_sub_f32_e32 v68, v74, v78
	v_pk_add_f32 v[70:71], v[70:71], v[78:79] neg_lo:[0,1] neg_hi:[0,1]
	v_sub_f32_e32 v68, v80, v68
	v_add_f32_e32 v68, v70, v68
	v_add_f32_e32 v68, v68, v71
	v_add_f32_e32 v68, v72, v68
	v_cndmask_b32_e32 v68, v236, v68, vcc
	v_cmp_ngt_f32_e32 vcc, -1.0, v67
	s_nop 1
	v_cndmask_b32_e32 v68, v237, v68, vcc
	v_cmp_neq_f32_e32 vcc, -1.0, v67
	s_nop 1
	v_cndmask_b32_e32 v68, v238, v68, vcc
	v_cmp_lt_f32_e64 vcc, |v67|, s58
	s_nop 1
	v_cndmask_b32_e32 v67, v68, v67, vcc
;     __device__ __forceinline__ void operator()(f32x4 (&acc)[2][2][4][2], const Unit& u, int row0t, int wr, int wc, int fr, int fq) const {
;     ...
;                                 for (int e = 0; e < 4; ++e) { const int h = 4 * n + e; const float xx = v[e] + dt_bias[h]; const float sp = xx > 20.f ? xx : log1pf(__expf(xx)); o[e] = -__expf(A_log[h]) * sp; } }
.LBB0_186:
	s_or_b64 exec, exec, s[36:37]
	v_mov_b32_e32 v70, v153
	v_mov_b32_e32 v68, v160
	v_add_f32_e32 v69, v69, v70
	v_cmp_nlt_f32_e32 vcc, s53, v69
	s_and_saveexec_b64 s[36:37], vcc
	s_cbranch_execz .LBB0_188
	v_mul_f32_e32 v69, 0x3fb8aa3b, v69
	v_exp_f32_e32 v69, v69
	s_nop 0
	v_add_f32_e32 v72, 1.0, v69
	v_frexp_mant_f32_e32 v74, v72
	v_cvt_f64_f32_e32 v[70:71], v72
	v_frexp_exp_i32_f64_e32 v70, v[70:71]
	v_cmp_gt_f32_e32 vcc, s55, v74
	v_add_f32_e32 v73, -1.0, v72
	v_sub_f32_e32 v75, v73, v72
	v_subbrev_co_u32_e32 v78, vcc, 0, v70, vcc
	v_sub_u32_e32 v70, 0, v78
	v_sub_f32_e32 v73, v69, v73
	v_add_f32_e32 v75, 1.0, v75
	v_ldexp_f32 v71, v72, v70
	v_add_f32_e32 v73, v73, v75
	v_add_f32_e32 v72, -1.0, v71
	v_add_f32_e32 v74, 1.0, v71
	v_ldexp_f32 v70, v73, v70
	v_add_f32_e32 v73, 1.0, v72
	v_add_f32_e32 v75, -1.0, v74
	v_sub_f32_e32 v73, v71, v73
	v_sub_f32_e32 v71, v71, v75
	v_add_f32_e32 v73, v70, v73
	v_add_f32_e32 v70, v70, v71
	v_add_f32_e32 v79, v74, v70
	v_rcp_f32_e32 v81, v79
	v_sub_f32_e32 v71, v79, v74
	v_sub_f32_e32 v80, v70, v71
	v_add_f32_e32 v71, v72, v73
	v_mul_f32_e32 v83, v71, v81
	v_sub_f32_e32 v70, v71, v72
	v_mul_f32_e32 v72, v79, v83
	v_fma_f32 v74, v83, v79, -v72
	v_fmac_f32_e32 v74, v83, v80
	v_sub_f32_e32 v82, v73, v70
	v_add_f32_e32 v70, v72, v74
	v_sub_f32_e32 v73, v71, v70
	v_pk_add_f32 v[76:77], v[70:71], v[72:73] neg_lo:[0,1] neg_hi:[0,1]
	v_mov_b32_e32 v75, v70
	v_pk_add_f32 v[70:71], v[76:77], v[74:75] neg_lo:[0,1] neg_hi:[0,1]
	v_cmp_neq_f32_e32 vcc, s57, v69
	v_add_f32_e32 v71, v82, v71
	v_add_f32_e32 v70, v70, v71
	v_add_f32_e32 v71, v73, v70
	v_mul_f32_e32 v82, v81, v71
	v_mul_f32_e32 v72, v79, v82
	v_fma_f32 v74, v82, v79, -v72
	v_fmac_f32_e32 v74, v82, v80
	v_sub_f32_e32 v73, v73, v71
	v_add_f32_e32 v79, v70, v73
	v_add_f32_e32 v70, v72, v74
	v_sub_f32_e32 v73, v71, v70
	v_pk_add_f32 v[76:77], v[70:71], v[72:73] neg_lo:[0,1] neg_hi:[0,1]
	v_mov_b32_e32 v75, v70
	v_pk_add_f32 v[70:71], v[76:77], v[74:75] neg_lo:[0,1] neg_hi:[0,1]
	s_nop 0
	v_add_f32_e32 v71, v79, v71
	v_add_f32_e32 v70, v70, v71
	v_add_f32_e32 v71, v83, v82
	v_add_f32_e32 v70, v73, v70
	v_sub_f32_e32 v72, v71, v83
	v_mul_f32_e32 v70, v81, v70
	v_sub_f32_e32 v72, v82, v72
	v_add_f32_e32 v72, v72, v70
	v_add_f32_e32 v74, v71, v72
	v_mul_f32_e32 v75, v74, v74
	v_fmamk_f32 v70, v75, 0x3e9b6dac, v235
	v_fmaak_f32 v227, v75, v70, 0x3f2aaada
	v_cvt_f32_i32_e32 v70, v78
	v_sub_f32_e32 v71, v74, v71
	v_sub_f32_e32 v71, v72, v71
	v_ldexp_f32 v76, v71, 1
	v_mul_f32_e32 v71, v74, v75
	v_ldexp_f32 v73, v74, 1
	v_pk_mul_f32 v[74:75], v[70:71], v[226:227]
	s_nop 0
	v_fma_f32 v72, v70, s56, -v74
	v_fmac_f32_e32 v72, 0xb102e308, v70
	v_pk_add_f32 v[70:71], v[74:75], v[72:73]
	s_nop 0
	v_sub_f32_e32 v73, v71, v73
	v_sub_f32_e32 v73, v75, v73
	v_add_f32_e32 v77, v76, v73
	v_mov_b32_e32 v76, v74
	v_pk_add_f32 v[74:75], v[70:71], v[74:75] neg_lo:[0,1] neg_hi:[0,1]
	v_pk_add_f32 v[78:79], v[70:71], v[76:77]
	v_mov_b32_e32 v73, v70
	v_mov_b32_e32 v75, v79
	v_pk_add_f32 v[80:81], v[72:73], v[74:75] neg_lo:[0,1] neg_hi:[0,1]
	v_pk_add_f32 v[72:73], v[72:73], v[74:75]
	v_mov_b32_e32 v76, v77
	v_pk_add_f32 v[74:75], v[72:73], v[70:71] op_sel:[1,0] op_sel_hi:[0,1] neg_lo:[0,1] neg_hi:[0,1]
	v_pk_add_f32 v[82:83], v[78:79], v[74:75] op_sel_hi:[1,0] neg_lo:[0,1] neg_hi:[0,1]
	v_mov_b32_e32 v78, v79
	v_mov_b32_e32 v79, v73
	v_pk_mov_b32 v[74:75], v[70:71], v[74:75] op_sel:[1,0]
	v_mov_b32_e32 v77, v70
	v_pk_add_f32 v[74:75], v[78:79], v[74:75] neg_lo:[0,1] neg_hi:[0,1]
	v_mov_b32_e32 v82, v80
	v_pk_add_f32 v[70:71], v[76:77], v[74:75] neg_lo:[0,1] neg_hi:[0,1]
	v_mov_b32_e32 v81, v73
	v_pk_add_f32 v[74:75], v[82:83], v[70:71]
	s_nop 0
	v_pk_add_f32 v[76:77], v[74:75], v[74:75] op_sel:[0,1] op_sel_hi:[1,0]
	s_nop 0
	v_pk_add_f32 v[72:73], v[72:73], v[76:77] op_sel:[1,0] op_sel_hi:[0,1]
	v_mov_b32_e32 v75, v72
	v_pk_add_f32 v[78:79], v[74:75], v[80:81] neg_lo:[0,1] neg_hi:[0,1]
	v_mov_b32_e32 v71, v76
	v_sub_f32_e32 v73, v74, v78
	v_pk_add_f32 v[70:71], v[70:71], v[78:79] neg_lo:[0,1] neg_hi:[0,1]
	v_sub_f32_e32 v73, v80, v73
	v_add_f32_e32 v70, v70, v73
	v_add_f32_e32 v70, v70, v71
	v_add_f32_e32 v70, v72, v70
	v_cndmask_b32_e32 v70, v236, v70, vcc
	v_cmp_ngt_f32_e32 vcc, -1.0, v69
	s_nop 1
	v_cndmask_b32_e32 v70, v237, v70, vcc
	v_cmp_neq_f32_e32 vcc, -1.0, v69
	s_nop 1
	v_cndmask_b32_e32 v70, v238, v70, vcc
	v_cmp_lt_f32_e64 vcc, |v69|, s58
	s_nop 1
	v_cndmask_b32_e32 v69, v70, v69, vcc
.LBB0_188:
	s_or_b64 exec, exec, s[36:37]
	v_mul_f32_e32 v4, 0x3fb8aa3b, v4
	v_exp_f32_e32 v4, v4
	s_nop 0
	v_mul_f32_e64 v70, v3, -v4
	v_mul_f32_e32 v3, 0x3fb8aa3b, v66
	v_exp_f32_e32 v3, v3
	s_nop 0
	v_mul_f32_e64 v71, v5, -v3
	v_mul_f32_e32 v3, 0x3fb8aa3b, v68
	v_exp_f32_e32 v3, v3
	s_nop 0
	v_mul_f32_e64 v72, v67, -v3
	v_mov_b32_e32 v3, v161
	v_mul_f32_e32 v3, 0x3fb8aa3b, v3
	v_exp_f32_e32 v3, v3
	s_nop 0
	v_mul_f32_e64 v73, v69, -v3

;     __device__ __forceinline__ void operator()(f32x4 (&acc)[2][2][4][2], const Unit& u, int row0t, int wr, int wc, int fr, int fq) const {
;     ...
;                                 for (int e = 0; e < 4; ++e) { const int h = 4 * n + e; const float xx = v[e] + dt_bias[h]; const float sp = xx > 20.f ? xx : log1pf(__expf(xx)); o[e] = -__expf(A_log[h]) * sp; } }
;                             *(f32x4*)(bg + (size_t)r * 16 + 8 * fq + 4 * n) = o; } }
.LBB0_191:
	s_or_b64 exec, exec, s[24:25]
	v_add_u32_e32 v4, s3, v1
	v_ashrrev_i32_e32 v5, 31, v4
	v_lshlrev_b64 v[66:67], 6, v[4:5]
	v_lshl_add_u64 v[74:75], v[214:215], 0, v[66:67]
	global_store_dwordx4 v[74:75], v[70:73], off
	s_and_saveexec_b64 s[2:3], s[4:5]
	s_xor_b64 s[24:25], exec, s[2:3]
	s_cbranch_execz .LBB0_201
	v_mov_b32_e32 v3, v154
	v_add_f32_e32 v3, v62, v3
	v_cmp_nlt_f32_e32 vcc, s53, v3
	s_and_saveexec_b64 s[36:37], vcc
	s_cbranch_execz .LBB0_194
	v_mul_f32_e32 v3, 0x3fb8aa3b, v3
	v_exp_f32_e32 v3, v3
	s_nop 0
	v_add_f32_e32 v62, 1.0, v3
	v_frexp_mant_f32_e32 v69, v62
	v_cvt_f64_f32_e32 v[66:67], v62
	v_add_f32_e32 v68, -1.0, v62
	v_frexp_exp_i32_f64_e32 v66, v[66:67]
	v_cmp_gt_f32_e32 vcc, s55, v69
	v_sub_f32_e32 v70, v68, v62
	v_sub_f32_e32 v68, v3, v68
	v_subbrev_co_u32_e32 v76, vcc, 0, v66, vcc
	v_add_f32_e32 v70, 1.0, v70
	v_sub_u32_e32 v66, 0, v76
	v_add_f32_e32 v68, v68, v70
	v_ldexp_f32 v62, v62, v66
	v_ldexp_f32 v66, v68, v66
	v_add_f32_e32 v68, -1.0, v62
	v_add_f32_e32 v67, 1.0, v68
	v_sub_f32_e32 v67, v62, v67
	v_add_f32_e32 v69, v66, v67
	v_add_f32_e32 v67, 1.0, v62
	v_add_f32_e32 v70, -1.0, v67
	v_sub_f32_e32 v62, v62, v70
	v_add_f32_e32 v62, v66, v62
	v_add_f32_e32 v77, v67, v62
	v_rcp_f32_e32 v78, v77
	v_sub_f32_e32 v66, v77, v67
	v_add_f32_e32 v67, v68, v69
	v_sub_f32_e32 v62, v62, v66
	v_mul_f32_e32 v80, v67, v78
	v_sub_f32_e32 v66, v67, v68
	v_mul_f32_e32 v68, v77, v80
	v_fma_f32 v70, v80, v77, -v68
	v_fmac_f32_e32 v70, v80, v62
	v_sub_f32_e32 v79, v69, v66
	v_add_f32_e32 v66, v68, v70
	v_sub_f32_e32 v69, v67, v66
	v_pk_add_f32 v[72:73], v[66:67], v[68:69] neg_lo:[0,1] neg_hi:[0,1]
	v_mov_b32_e32 v71, v66
	v_pk_add_f32 v[66:67], v[72:73], v[70:71] neg_lo:[0,1] neg_hi:[0,1]
	v_cmp_neq_f32_e32 vcc, s57, v3
	v_add_f32_e32 v67, v79, v67
	v_add_f32_e32 v66, v66, v67
	v_add_f32_e32 v67, v69, v66
	v_mul_f32_e32 v79, v78, v67
	v_mul_f32_e32 v68, v77, v79
	v_fma_f32 v70, v79, v77, -v68
	v_fmac_f32_e32 v70, v79, v62
	v_sub_f32_e32 v62, v69, v67
	v_add_f32_e32 v62, v66, v62
	v_add_f32_e32 v66, v68, v70
	v_sub_f32_e32 v69, v67, v66
	v_pk_add_f32 v[72:73], v[66:67], v[68:69] neg_lo:[0,1] neg_hi:[0,1]
	v_mov_b32_e32 v71, v66
	v_pk_add_f32 v[66:67], v[72:73], v[70:71] neg_lo:[0,1] neg_hi:[0,1]
	s_nop 0
	v_add_f32_e32 v62, v62, v67
	v_add_f32_e32 v62, v66, v62
	v_add_f32_e32 v67, v80, v79
	v_add_f32_e32 v62, v69, v62
	v_sub_f32_e32 v66, v67, v80
	v_mul_f32_e32 v62, v78, v62
	v_sub_f32_e32 v66, v79, v66
	v_add_f32_e32 v62, v66, v62
	v_add_f32_e32 v68, v67, v62
	v_mul_f32_e32 v70, v68, v68
	v_fmamk_f32 v66, v70, 0x3e9b6dac, v235
	v_fmaak_f32 v227, v70, v66, 0x3f2aaada
	v_cvt_f32_i32_e32 v66, v76
	v_sub_f32_e32 v67, v68, v67
	v_sub_f32_e32 v62, v62, v67
	v_mul_f32_e32 v67, v68, v70
	v_pk_mul_f32 v[70:71], v[66:67], v[226:227]
	v_ldexp_f32 v69, v68, 1
	v_fma_f32 v68, v66, s56, -v70
	v_fmac_f32_e32 v68, 0xb102e308, v66
	v_pk_add_f32 v[66:67], v[70:71], v[68:69]
	v_ldexp_f32 v62, v62, 1
	v_sub_f32_e32 v69, v67, v69
	v_sub_f32_e32 v69, v71, v69
	v_add_f32_e32 v73, v62, v69
	v_mov_b32_e32 v72, v70
	v_pk_add_f32 v[70:71], v[66:67], v[70:71] neg_lo:[0,1] neg_hi:[0,1]
	v_pk_add_f32 v[76:77], v[66:67], v[72:73]
	v_mov_b32_e32 v69, v66
	v_mov_b32_e32 v71, v77
	v_pk_add_f32 v[78:79], v[68:69], v[70:71] neg_lo:[0,1] neg_hi:[0,1]
	v_pk_add_f32 v[68:69], v[68:69], v[70:71]
	v_mov_b32_e32 v72, v73
	v_pk_add_f32 v[70:71], v[68:69], v[66:67] op_sel:[1,0] op_sel_hi:[0,1] neg_lo:[0,1] neg_hi:[0,1]
	v_pk_add_f32 v[80:81], v[76:77], v[70:71] op_sel_hi:[1,0] neg_lo:[0,1] neg_hi:[0,1]
	v_mov_b32_e32 v76, v77
	v_mov_b32_e32 v77, v69
	v_pk_mov_b32 v[70:71], v[66:67], v[70:71] op_sel:[1,0]
	v_mov_b32_e32 v73, v66
	v_pk_add_f32 v[70:71], v[76:77], v[70:71] neg_lo:[0,1] neg_hi:[0,1]
	v_mov_b32_e32 v80, v78
	v_pk_add_f32 v[66:67], v[72:73], v[70:71] neg_lo:[0,1] neg_hi:[0,1]
	v_mov_b32_e32 v79, v69
	v_pk_add_f32 v[70:71], v[80:81], v[66:67]
	s_nop 0
	v_pk_add_f32 v[72:73], v[70:71], v[70:71] op_sel:[0,1] op_sel_hi:[1,0]
	s_nop 0
	v_pk_add_f32 v[68:69], v[68:69], v[72:73] op_sel:[1,0] op_sel_hi:[0,1]
	v_mov_b32_e32 v71, v68
	v_pk_add_f32 v[76:77], v[70:71], v[78:79] neg_lo:[0,1] neg_hi:[0,1]
	v_mov_b32_e32 v67, v72
	v_sub_f32_e32 v62, v70, v76
	v_pk_add_f32 v[66:67], v[66:67], v[76:77] neg_lo:[0,1] neg_hi:[0,1]
	v_sub_f32_e32 v62, v78, v62
	v_add_f32_e32 v62, v66, v62
	v_add_f32_e32 v62, v62, v67
	v_add_f32_e32 v62, v68, v62
	v_cndmask_b32_e32 v62, v236, v62, vcc
	v_cmp_ngt_f32_e32 vcc, -1.0, v3
	s_nop 1
	v_cndmask_b32_e32 v62, v237, v62, vcc
	v_cmp_neq_f32_e32 vcc, -1.0, v3
	s_nop 1
	v_cndmask_b32_e32 v62, v238, v62, vcc
	v_cmp_lt_f32_e64 vcc, |v3|, s58
	s_nop 1
	v_cndmask_b32_e32 v3, v62, v3, vcc
;     __device__ __forceinline__ void operator()(f32x4 (&acc)[2][2][4][2], const Unit& u, int row0t, int wr, int wc, int fr, int fq) const {
;     ...
;                                 for (int e = 0; e < 4; ++e) { const int h = 4 * n + e; const float xx = v[e] + dt_bias[h]; const float sp = xx > 20.f ? xx : log1pf(__expf(xx)); o[e] = -__expf(A_log[h]) * sp; } }
.LBB0_194:
	s_or_b64 exec, exec, s[36:37]
	v_mov_b32_e32 v66, v155
	v_mov_b32_e32 v62, v162
	v_add_f32_e32 v63, v63, v66
	v_cmp_nlt_f32_e32 vcc, s53, v63
	s_and_saveexec_b64 s[36:37], vcc
	s_cbranch_execz .LBB0_196
	v_mul_f32_e32 v63, 0x3fb8aa3b, v63
	v_exp_f32_e32 v63, v63
	s_nop 0
	v_add_f32_e32 v68, 1.0, v63
	v_frexp_mant_f32_e32 v70, v68
	v_cvt_f64_f32_e32 v[66:67], v68
	v_frexp_exp_i32_f64_e32 v66, v[66:67]
	v_cmp_gt_f32_e32 vcc, s55, v70
	v_add_f32_e32 v69, -1.0, v68
	v_sub_f32_e32 v71, v69, v68
	v_subbrev_co_u32_e32 v76, vcc, 0, v66, vcc
	v_sub_u32_e32 v66, 0, v76
	v_sub_f32_e32 v69, v63, v69
	v_add_f32_e32 v71, 1.0, v71
	v_ldexp_f32 v67, v68, v66
	v_add_f32_e32 v69, v69, v71
	v_add_f32_e32 v68, -1.0, v67
	v_add_f32_e32 v70, 1.0, v67
	v_ldexp_f32 v66, v69, v66
	v_add_f32_e32 v69, 1.0, v68
	v_add_f32_e32 v71, -1.0, v70
	v_sub_f32_e32 v69, v67, v69
	v_sub_f32_e32 v67, v67, v71
	v_add_f32_e32 v69, v66, v69
	v_add_f32_e32 v66, v66, v67
	v_add_f32_e32 v77, v70, v66
	v_rcp_f32_e32 v79, v77
	v_sub_f32_e32 v67, v77, v70
	v_sub_f32_e32 v78, v66, v67
	v_add_f32_e32 v67, v68, v69
	v_mul_f32_e32 v81, v67, v79
	v_sub_f32_e32 v66, v67, v68
	v_mul_f32_e32 v68, v77, v81
	v_fma_f32 v70, v81, v77, -v68
	v_fmac_f32_e32 v70, v81, v78
	v_sub_f32_e32 v80, v69, v66
	v_add_f32_e32 v66, v68, v70
	v_sub_f32_e32 v69, v67, v66
	v_pk_add_f32 v[72:73], v[66:67], v[68:69] neg_lo:[0,1] neg_hi:[0,1]
	v_mov_b32_e32 v71, v66
	v_pk_add_f32 v[66:67], v[72:73], v[70:71] neg_lo:[0,1] neg_hi:[0,1]
	v_cmp_neq_f32_e32 vcc, s57, v63
	v_add_f32_e32 v67, v80, v67
	v_add_f32_e32 v66, v66, v67
	v_add_f32_e32 v67, v69, v66
	v_mul_f32_e32 v80, v79, v67
	v_mul_f32_e32 v68, v77, v80
	v_fma_f32 v70, v80, v77, -v68
	v_fmac_f32_e32 v70, v80, v78
	v_sub_f32_e32 v69, v69, v67
	v_add_f32_e32 v77, v66, v69
	v_add_f32_e32 v66, v68, v70
	v_sub_f32_e32 v69, v67, v66
	v_pk_add_f32 v[72:73], v[66:67], v[68:69] neg_lo:[0,1] neg_hi:[0,1]
	v_mov_b32_e32 v71, v66
	v_pk_add_f32 v[66:67], v[72:73], v[70:71] neg_lo:[0,1] neg_hi:[0,1]
	s_nop 0
	v_add_f32_e32 v67, v77, v67
	v_add_f32_e32 v66, v66, v67
	v_add_f32_e32 v67, v81, v80
	v_add_f32_e32 v66, v69, v66
	v_sub_f32_e32 v68, v67, v81
	v_mul_f32_e32 v66, v79, v66
	v_sub_f32_e32 v68, v80, v68
	v_add_f32_e32 v68, v68, v66
	v_add_f32_e32 v70, v67, v68
	v_mul_f32_e32 v71, v70, v70
	v_fmamk_f32 v66, v71, 0x3e9b6dac, v235
	v_fmaak_f32 v227, v71, v66, 0x3f2aaada
	v_cvt_f32_i32_e32 v66, v76
	v_sub_f32_e32 v67, v70, v67
	v_sub_f32_e32 v67, v68, v67
	v_ldexp_f32 v72, v67, 1
	v_mul_f32_e32 v67, v70, v71
	v_ldexp_f32 v69, v70, 1
	v_pk_mul_f32 v[70:71], v[66:67], v[226:227]
	s_nop 0
	v_fma_f32 v68, v66, s56, -v70
	v_fmac_f32_e32 v68, 0xb102e308, v66
	v_pk_add_f32 v[66:67], v[70:71], v[68:69]
	s_nop 0
	v_sub_f32_e32 v69, v67, v69
	v_sub_f32_e32 v69, v71, v69
	v_add_f32_e32 v73, v72, v69
	v_mov_b32_e32 v72, v70
	v_pk_add_f32 v[70:71], v[66:67], v[70:71] neg_lo:[0,1] neg_hi:[0,1]
	v_pk_add_f32 v[76:77], v[66:67], v[72:73]
	v_mov_b32_e32 v69, v66
	v_mov_b32_e32 v71, v77
	v_pk_add_f32 v[78:79], v[68:69], v[70:71] neg_lo:[0,1] neg_hi:[0,1]
	v_pk_add_f32 v[68:69], v[68:69], v[70:71]
	v_mov_b32_e32 v72, v73
	v_pk_add_f32 v[70:71], v[68:69], v[66:67] op_sel:[1,0] op_sel_hi:[0,1] neg_lo:[0,1] neg_hi:[0,1]
	v_pk_add_f32 v[80:81], v[76:77], v[70:71] op_sel_hi:[1,0] neg_lo:[0,1] neg_hi:[0,1]
	v_mov_b32_e32 v76, v77
	v_mov_b32_e32 v77, v69
	v_pk_mov_b32 v[70:71], v[66:67], v[70:71] op_sel:[1,0]
	v_mov_b32_e32 v73, v66
	v_pk_add_f32 v[70:71], v[76:77], v[70:71] neg_lo:[0,1] neg_hi:[0,1]
	v_mov_b32_e32 v80, v78
	v_pk_add_f32 v[66:67], v[72:73], v[70:71] neg_lo:[0,1] neg_hi:[0,1]
	v_mov_b32_e32 v79, v69
	v_pk_add_f32 v[70:71], v[80:81], v[66:67]
	s_nop 0
	v_pk_add_f32 v[72:73], v[70:71], v[70:71] op_sel:[0,1] op_sel_hi:[1,0]
	s_nop 0
	v_pk_add_f32 v[68:69], v[68:69], v[72:73] op_sel:[1,0] op_sel_hi:[0,1]
	v_mov_b32_e32 v71, v68
	v_pk_add_f32 v[76:77], v[70:71], v[78:79] neg_lo:[0,1] neg_hi:[0,1]
	v_mov_b32_e32 v67, v72
	v_sub_f32_e32 v69, v70, v76
	v_pk_add_f32 v[66:67], v[66:67], v[76:77] neg_lo:[0,1] neg_hi:[0,1]
	v_sub_f32_e32 v69, v78, v69
	v_add_f32_e32 v66, v66, v69
	v_add_f32_e32 v66, v66, v67
	v_add_f32_e32 v66, v68, v66
	v_cndmask_b32_e32 v66, v236, v66, vcc
	v_cmp_ngt_f32_e32 vcc, -1.0, v63
	s_nop 1
	v_cndmask_b32_e32 v66, v237, v66, vcc
	v_cmp_neq_f32_e32 vcc, -1.0, v63
	s_nop 1
	v_cndmask_b32_e32 v66, v238, v66, vcc
	v_cmp_lt_f32_e64 vcc, |v63|, s58
	s_nop 1
	v_cndmask_b32_e32 v63, v66, v63, vcc
;     __device__ __forceinline__ void operator()(f32x4 (&acc)[2][2][4][2], const Unit& u, int row0t, int wr, int wc, int fr, int fq) const {
;     ...
;                                 for (int e = 0; e < 4; ++e) { const int h = 4 * n + e; const float xx = v[e] + dt_bias[h]; const float sp = xx > 20.f ? xx : log1pf(__expf(xx)); o[e] = -__expf(A_log[h]) * sp; } }
.LBB0_196:
	s_or_b64 exec, exec, s[36:37]
	v_mov_b32_e32 v66, v156
	v_mov_b32_e32 v67, v163
	v_add_f32_e32 v64, v64, v66
	v_cmp_nlt_f32_e32 vcc, s53, v64
	s_and_saveexec_b64 s[36:37], vcc
	s_cbranch_execz .LBB0_198
	v_mul_f32_e32 v64, 0x3fb8aa3b, v64
	v_exp_f32_e32 v64, v64
	s_nop 0
	v_add_f32_e32 v66, 1.0, v64
	v_frexp_mant_f32_e32 v71, v66
	v_cvt_f64_f32_e32 v[68:69], v66
	v_add_f32_e32 v70, -1.0, v66
	v_frexp_exp_i32_f64_e32 v68, v[68:69]
	v_cmp_gt_f32_e32 vcc, s55, v71
	v_sub_f32_e32 v72, v70, v66
	v_sub_f32_e32 v70, v64, v70
	v_subbrev_co_u32_e32 v78, vcc, 0, v68, vcc
	v_add_f32_e32 v72, 1.0, v72
	v_sub_u32_e32 v68, 0, v78
	v_add_f32_e32 v70, v70, v72
	v_ldexp_f32 v66, v66, v68
	v_ldexp_f32 v68, v70, v68
	v_add_f32_e32 v70, -1.0, v66
	v_add_f32_e32 v69, 1.0, v70
	v_sub_f32_e32 v69, v66, v69
	v_add_f32_e32 v71, v68, v69
	v_add_f32_e32 v69, 1.0, v66
	v_add_f32_e32 v72, -1.0, v69
	v_sub_f32_e32 v66, v66, v72
	v_add_f32_e32 v66, v68, v66
	v_add_f32_e32 v79, v69, v66
	v_rcp_f32_e32 v80, v79
	v_sub_f32_e32 v68, v79, v69
	v_add_f32_e32 v69, v70, v71
	v_sub_f32_e32 v66, v66, v68
	v_mul_f32_e32 v82, v69, v80
	v_sub_f32_e32 v68, v69, v70
	v_mul_f32_e32 v70, v79, v82
	v_fma_f32 v72, v82, v79, -v70
	v_fmac_f32_e32 v72, v82, v66
	v_sub_f32_e32 v81, v71, v68
	v_add_f32_e32 v68, v70, v72
	v_sub_f32_e32 v71, v69, v68
	v_pk_add_f32 v[76:77], v[68:69], v[70:71] neg_lo:[0,1] neg_hi:[0,1]
	v_mov_b32_e32 v73, v68
	v_pk_add_f32 v[68:69], v[76:77], v[72:73] neg_lo:[0,1] neg_hi:[0,1]
	v_cmp_neq_f32_e32 vcc, s57, v64
	v_add_f32_e32 v69, v81, v69
	v_add_f32_e32 v68, v68, v69
	v_add_f32_e32 v69, v71, v68
	v_mul_f32_e32 v81, v80, v69
	v_mul_f32_e32 v70, v79, v81
	v_fma_f32 v72, v81, v79, -v70
	v_fmac_f32_e32 v72, v81, v66
	v_sub_f32_e32 v66, v71, v69
	v_add_f32_e32 v66, v68, v66
	v_add_f32_e32 v68, v70, v72
	v_sub_f32_e32 v71, v69, v68
	v_pk_add_f32 v[76:77], v[68:69], v[70:71] neg_lo:[0,1] neg_hi:[0,1]
	v_mov_b32_e32 v73, v68
	v_pk_add_f32 v[68:69], v[76:77], v[72:73] neg_lo:[0,1] neg_hi:[0,1]
	s_nop 0
	v_add_f32_e32 v66, v66, v69
	v_add_f32_e32 v66, v68, v66
	v_add_f32_e32 v69, v82, v81
	v_add_f32_e32 v66, v71, v66
	v_sub_f32_e32 v68, v69, v82
	v_mul_f32_e32 v66, v80, v66
	v_sub_f32_e32 v68, v81, v68
	v_add_f32_e32 v66, v68, v66
	v_add_f32_e32 v70, v69, v66
	v_mul_f32_e32 v72, v70, v70
	v_fmamk_f32 v68, v72, 0x3e9b6dac, v235
	v_fmaak_f32 v227, v72, v68, 0x3f2aaada
	v_cvt_f32_i32_e32 v68, v78
	v_sub_f32_e32 v69, v70, v69
	v_sub_f32_e32 v66, v66, v69
	v_mul_f32_e32 v69, v70, v72
	v_pk_mul_f32 v[72:73], v[68:69], v[226:227]
	v_ldexp_f32 v71, v70, 1
	v_fma_f32 v70, v68, s56, -v72
	v_fmac_f32_e32 v70, 0xb102e308, v68
	v_pk_add_f32 v[68:69], v[72:73], v[70:71]
	v_ldexp_f32 v66, v66, 1
	v_sub_f32_e32 v71, v69, v71
	v_sub_f32_e32 v71, v73, v71
	v_add_f32_e32 v77, v66, v71
	v_mov_b32_e32 v76, v72
	v_pk_add_f32 v[72:73], v[68:69], v[72:73] neg_lo:[0,1] neg_hi:[0,1]
	v_pk_add_f32 v[78:79], v[68:69], v[76:77]
	v_mov_b32_e32 v71, v68
	v_mov_b32_e32 v73, v79
	v_pk_add_f32 v[80:81], v[70:71], v[72:73] neg_lo:[0,1] neg_hi:[0,1]
	v_pk_add_f32 v[70:71], v[70:71], v[72:73]
	v_mov_b32_e32 v76, v77
	v_pk_add_f32 v[72:73], v[70:71], v[68:69] op_sel:[1,0] op_sel_hi:[0,1] neg_lo:[0,1] neg_hi:[0,1]
	v_pk_add_f32 v[82:83], v[78:79], v[72:73] op_sel_hi:[1,0] neg_lo:[0,1] neg_hi:[0,1]
	v_mov_b32_e32 v78, v79
	v_mov_b32_e32 v79, v71
	v_pk_mov_b32 v[72:73], v[68:69], v[72:73] op_sel:[1,0]
	v_mov_b32_e32 v77, v68
	v_pk_add_f32 v[72:73], v[78:79], v[72:73] neg_lo:[0,1] neg_hi:[0,1]
	v_mov_b32_e32 v82, v80
	v_pk_add_f32 v[68:69], v[76:77], v[72:73] neg_lo:[0,1] neg_hi:[0,1]
	v_mov_b32_e32 v81, v71
	v_pk_add_f32 v[72:73], v[82:83], v[68:69]
	s_nop 0
	v_pk_add_f32 v[76:77], v[72:73], v[72:73] op_sel:[0,1] op_sel_hi:[1,0]
	s_nop 0
	v_pk_add_f32 v[70:71], v[70:71], v[76:77] op_sel:[1,0] op_sel_hi:[0,1]
	v_mov_b32_e32 v73, v70
	v_pk_add_f32 v[78:79], v[72:73], v[80:81] neg_lo:[0,1] neg_hi:[0,1]
	v_mov_b32_e32 v69, v76
	v_sub_f32_e32 v66, v72, v78
	v_pk_add_f32 v[68:69], v[68:69], v[78:79] neg_lo:[0,1] neg_hi:[0,1]
	v_sub_f32_e32 v66, v80, v66
	v_add_f32_e32 v66, v68, v66
	v_add_f32_e32 v66, v66, v69
	v_add_f32_e32 v66, v70, v66
	v_cndmask_b32_e32 v66, v236, v66, vcc
	v_cmp_ngt_f32_e32 vcc, -1.0, v64
	s_nop 1
	v_cndmask_b32_e32 v66, v237, v66, vcc
	v_cmp_neq_f32_e32 vcc, -1.0, v64
	s_nop 1
	v_cndmask_b32_e32 v66, v238, v66, vcc
	v_cmp_lt_f32_e64 vcc, |v64|, s58
	s_nop 1
	v_cndmask_b32_e32 v64, v66, v64, vcc
;     __device__ __forceinline__ void operator()(f32x4 (&acc)[2][2][4][2], const Unit& u, int row0t, int wr, int wc, int fr, int fq) const {
;     ...
;                                 for (int e = 0; e < 4; ++e) { const int h = 4 * n + e; const float xx = v[e] + dt_bias[h]; const float sp = xx > 20.f ? xx : log1pf(__expf(xx)); o[e] = -__expf(A_log[h]) * sp; } }
.LBB0_198:
	s_or_b64 exec, exec, s[36:37]
	v_mov_b32_e32 v66, v157
	v_mov_b32_e32 v68, v164
	v_add_f32_e32 v65, v65, v66
	v_cmp_nlt_f32_e32 vcc, s53, v65
	s_and_saveexec_b64 s[36:37], vcc
	s_cbranch_execz .LBB0_200
	v_mul_f32_e32 v65, 0x3fb8aa3b, v65
	v_exp_f32_e32 v65, v65
	s_nop 0
	v_add_f32_e32 v66, 1.0, v65
	v_frexp_mant_f32_e32 v72, v66
	v_cvt_f64_f32_e32 v[70:71], v66
	v_add_f32_e32 v69, -1.0, v66
	v_frexp_exp_i32_f64_e32 v70, v[70:71]
	v_cmp_gt_f32_e32 vcc, s55, v72
	v_sub_f32_e32 v73, v69, v66
	v_sub_f32_e32 v69, v65, v69
	v_subbrev_co_u32_e32 v80, vcc, 0, v70, vcc
	v_add_f32_e32 v73, 1.0, v73
	v_sub_u32_e32 v70, 0, v80
	v_add_f32_e32 v69, v69, v73
	v_ldexp_f32 v66, v66, v70
	v_ldexp_f32 v69, v69, v70
	v_add_f32_e32 v70, -1.0, v66
	v_add_f32_e32 v71, 1.0, v70
	v_sub_f32_e32 v71, v66, v71
	v_add_f32_e32 v72, v69, v71
	v_add_f32_e32 v71, 1.0, v66
	v_add_f32_e32 v73, -1.0, v71
	v_sub_f32_e32 v66, v66, v73
	v_add_f32_e32 v66, v69, v66
	v_add_f32_e32 v69, v71, v66
	v_rcp_f32_e32 v81, v69
	v_sub_f32_e32 v71, v69, v71
	v_sub_f32_e32 v66, v66, v71
	v_add_f32_e32 v71, v70, v72
	v_sub_f32_e32 v70, v71, v70
	v_mul_f32_e32 v83, v71, v81
	v_sub_f32_e32 v82, v72, v70
	v_mul_f32_e32 v72, v69, v83
	v_fma_f32 v76, v83, v69, -v72
	v_fmac_f32_e32 v76, v83, v66
	v_add_f32_e32 v70, v72, v76
	v_sub_f32_e32 v73, v71, v70
	v_pk_add_f32 v[78:79], v[70:71], v[72:73] neg_lo:[0,1] neg_hi:[0,1]
	v_mov_b32_e32 v77, v70
	v_pk_add_f32 v[70:71], v[78:79], v[76:77] neg_lo:[0,1] neg_hi:[0,1]
	v_cmp_neq_f32_e32 vcc, s57, v65
	v_add_f32_e32 v71, v82, v71
	v_add_f32_e32 v70, v70, v71
	v_add_f32_e32 v71, v73, v70
	v_mul_f32_e32 v82, v81, v71
	v_mul_f32_e32 v72, v69, v82
	v_fma_f32 v76, v82, v69, -v72
	v_fmac_f32_e32 v76, v82, v66
	v_sub_f32_e32 v66, v73, v71
	v_add_f32_e32 v66, v70, v66
	v_add_f32_e32 v70, v72, v76
	v_sub_f32_e32 v73, v71, v70
	v_pk_add_f32 v[78:79], v[70:71], v[72:73] neg_lo:[0,1] neg_hi:[0,1]
	v_mov_b32_e32 v77, v70
	v_pk_add_f32 v[70:71], v[78:79], v[76:77] neg_lo:[0,1] neg_hi:[0,1]
	v_add_f32_e32 v69, v83, v82
	v_add_f32_e32 v66, v66, v71
	v_add_f32_e32 v66, v70, v66
	v_add_f32_e32 v66, v73, v66
	v_sub_f32_e32 v70, v69, v83
	v_mul_f32_e32 v66, v81, v66
	v_sub_f32_e32 v70, v82, v70
	v_add_f32_e32 v66, v70, v66
	v_add_f32_e32 v71, v69, v66
	v_mul_f32_e32 v72, v71, v71
	v_fmamk_f32 v70, v72, 0x3e9b6dac, v235
	v_fmaak_f32 v227, v72, v70, 0x3f2aaada
	v_cvt_f32_i32_e32 v70, v80
	v_sub_f32_e32 v69, v71, v69
	v_ldexp_f32 v73, v71, 1
	v_mul_f32_e32 v71, v71, v72
	v_pk_mul_f32 v[76:77], v[70:71], v[226:227]
	v_sub_f32_e32 v66, v66, v69
	v_fma_f32 v72, v70, s56, -v76
	v_fmac_f32_e32 v72, 0xb102e308, v70
	v_pk_add_f32 v[70:71], v[76:77], v[72:73]
	v_ldexp_f32 v66, v66, 1
	v_sub_f32_e32 v69, v71, v73
	v_sub_f32_e32 v69, v77, v69
	v_add_f32_e32 v79, v66, v69
	v_mov_b32_e32 v78, v76
	v_pk_add_f32 v[76:77], v[70:71], v[76:77] neg_lo:[0,1] neg_hi:[0,1]
	v_pk_add_f32 v[80:81], v[70:71], v[78:79]
	v_mov_b32_e32 v73, v70
	v_mov_b32_e32 v77, v81
	v_pk_add_f32 v[82:83], v[72:73], v[76:77] neg_lo:[0,1] neg_hi:[0,1]
	v_pk_add_f32 v[72:73], v[72:73], v[76:77]
	v_mov_b32_e32 v78, v79
	v_pk_add_f32 v[76:77], v[72:73], v[70:71] op_sel:[1,0] op_sel_hi:[0,1] neg_lo:[0,1] neg_hi:[0,1]
	v_pk_add_f32 v[84:85], v[80:81], v[76:77] op_sel_hi:[1,0] neg_lo:[0,1] neg_hi:[0,1]
	v_mov_b32_e32 v80, v81
	v_mov_b32_e32 v81, v73
	v_pk_mov_b32 v[76:77], v[70:71], v[76:77] op_sel:[1,0]
	v_mov_b32_e32 v79, v70
	v_pk_add_f32 v[76:77], v[80:81], v[76:77] neg_lo:[0,1] neg_hi:[0,1]
	v_mov_b32_e32 v84, v82
	v_pk_add_f32 v[70:71], v[78:79], v[76:77] neg_lo:[0,1] neg_hi:[0,1]
	v_mov_b32_e32 v83, v73
	v_pk_add_f32 v[76:77], v[84:85], v[70:71]
	s_nop 0
	v_pk_add_f32 v[78:79], v[76:77], v[76:77] op_sel:[0,1] op_sel_hi:[1,0]
	s_nop 0
	v_pk_add_f32 v[72:73], v[72:73], v[78:79] op_sel:[1,0] op_sel_hi:[0,1]
	v_mov_b32_e32 v77, v72
	v_pk_add_f32 v[80:81], v[76:77], v[82:83] neg_lo:[0,1] neg_hi:[0,1]
	v_mov_b32_e32 v71, v78
	v_sub_f32_e32 v66, v76, v80
	v_pk_add_f32 v[70:71], v[70:71], v[80:81] neg_lo:[0,1] neg_hi:[0,1]
	v_sub_f32_e32 v66, v82, v66
	v_add_f32_e32 v66, v70, v66
	v_add_f32_e32 v66, v66, v71
	v_add_f32_e32 v66, v72, v66
	v_cndmask_b32_e32 v66, v236, v66, vcc
	v_cmp_ngt_f32_e32 vcc, -1.0, v65
	s_nop 1
	v_cndmask_b32_e32 v66, v237, v66, vcc
	v_cmp_neq_f32_e32 vcc, -1.0, v65
	s_nop 1
	v_cndmask_b32_e32 v66, v238, v66, vcc
	v_cmp_lt_f32_e64 vcc, |v65|, s58
	s_nop 1
	v_cndmask_b32_e32 v65, v66, v65, vcc
.LBB0_200:
	s_or_b64 exec, exec, s[36:37]
	v_mul_f32_e32 v62, 0x3fb8aa3b, v62
	v_exp_f32_e32 v62, v62
	s_nop 0
	v_mul_f32_e64 v66, v3, -v62
	v_mul_f32_e32 v3, 0x3fb8aa3b, v67
	v_exp_f32_e32 v3, v3
	s_nop 0
	v_mul_f32_e64 v67, v63, -v3
	v_mul_f32_e32 v3, 0x3fb8aa3b, v68
	v_exp_f32_e32 v3, v3
	s_nop 0
	v_mul_f32_e64 v68, v64, -v3
	v_mov_b32_e32 v3, v165
	v_mul_f32_e32 v3, 0x3fb8aa3b, v3
	v_exp_f32_e32 v3, v3
	s_nop 0
	v_mul_f32_e64 v69, v65, -v3

;     __device__ __forceinline__ void operator()(f32x4 (&acc)[2][2][4][2], const Unit& u, int row0t, int wr, int wc, int fr, int fq) const {
;     ...
;                                 for (int e = 0; e < 4; ++e) { const int h = 4 * n + e; const float xx = v[e] + dt_bias[h]; const float sp = xx > 20.f ? xx : log1pf(__expf(xx)); o[e] = -__expf(A_log[h]) * sp; } }
;                             *(f32x4*)(bg + (size_t)r * 16 + 8 * fq + 4 * n) = o; } }
.LBB0_203:
	s_or_b64 exec, exec, s[24:25]
	global_store_dwordx4 v[74:75], v[66:69], off offset:16
	s_and_saveexec_b64 s[2:3], s[4:5]
	s_xor_b64 s[24:25], exec, s[2:3]
	s_cbranch_execz .LBB0_213
	v_mov_b32_e32 v3, v150
	v_add_f32_e32 v3, v58, v3
	v_cmp_nlt_f32_e32 vcc, s53, v3
	s_and_saveexec_b64 s[36:37], vcc
	s_cbranch_execz .LBB0_206
	v_mul_f32_e32 v3, 0x3fb8aa3b, v3
	v_exp_f32_e32 v3, v3
	s_nop 0
	v_add_f32_e32 v58, 1.0, v3
	v_frexp_mant_f32_e32 v65, v58
	v_cvt_f64_f32_e32 v[62:63], v58
	v_add_f32_e32 v64, -1.0, v58
	v_frexp_exp_i32_f64_e32 v62, v[62:63]
	v_cmp_gt_f32_e32 vcc, s55, v65
	v_sub_f32_e32 v66, v64, v58
	v_sub_f32_e32 v64, v3, v64
	v_subbrev_co_u32_e32 v70, vcc, 0, v62, vcc
	v_add_f32_e32 v66, 1.0, v66
	v_sub_u32_e32 v62, 0, v70
	v_add_f32_e32 v64, v64, v66
	v_ldexp_f32 v58, v58, v62
	v_ldexp_f32 v62, v64, v62
	v_add_f32_e32 v64, -1.0, v58
	v_add_f32_e32 v63, 1.0, v64
	v_sub_f32_e32 v63, v58, v63
	v_add_f32_e32 v65, v62, v63
	v_add_f32_e32 v63, 1.0, v58
	v_add_f32_e32 v66, -1.0, v63
	v_sub_f32_e32 v58, v58, v66
	v_add_f32_e32 v58, v62, v58
	v_add_f32_e32 v71, v63, v58
	v_rcp_f32_e32 v72, v71
	v_sub_f32_e32 v62, v71, v63
	v_add_f32_e32 v63, v64, v65
	v_sub_f32_e32 v58, v58, v62
	v_mul_f32_e32 v74, v63, v72
	v_sub_f32_e32 v62, v63, v64
	v_mul_f32_e32 v64, v71, v74
	v_fma_f32 v66, v74, v71, -v64
	v_fmac_f32_e32 v66, v74, v58
	v_sub_f32_e32 v73, v65, v62
	v_add_f32_e32 v62, v64, v66
	v_sub_f32_e32 v65, v63, v62
	v_pk_add_f32 v[68:69], v[62:63], v[64:65] neg_lo:[0,1] neg_hi:[0,1]
	v_mov_b32_e32 v67, v62
	v_pk_add_f32 v[62:63], v[68:69], v[66:67] neg_lo:[0,1] neg_hi:[0,1]
	v_cmp_neq_f32_e32 vcc, s57, v3
	v_add_f32_e32 v63, v73, v63
	v_add_f32_e32 v62, v62, v63
	v_add_f32_e32 v63, v65, v62
	v_mul_f32_e32 v73, v72, v63
	v_mul_f32_e32 v64, v71, v73
	v_fma_f32 v66, v73, v71, -v64
	v_fmac_f32_e32 v66, v73, v58
	v_sub_f32_e32 v58, v65, v63
	v_add_f32_e32 v58, v62, v58
	v_add_f32_e32 v62, v64, v66
	v_sub_f32_e32 v65, v63, v62
	v_pk_add_f32 v[68:69], v[62:63], v[64:65] neg_lo:[0,1] neg_hi:[0,1]
	v_mov_b32_e32 v67, v62
	v_pk_add_f32 v[62:63], v[68:69], v[66:67] neg_lo:[0,1] neg_hi:[0,1]
	s_nop 0
	v_add_f32_e32 v58, v58, v63
	v_add_f32_e32 v58, v62, v58
	v_add_f32_e32 v63, v74, v73
	v_add_f32_e32 v58, v65, v58
	v_sub_f32_e32 v62, v63, v74
	v_mul_f32_e32 v58, v72, v58
	v_sub_f32_e32 v62, v73, v62
	v_add_f32_e32 v58, v62, v58
	v_add_f32_e32 v64, v63, v58
	v_mul_f32_e32 v66, v64, v64
	v_fmamk_f32 v62, v66, 0x3e9b6dac, v235
	v_fmaak_f32 v227, v66, v62, 0x3f2aaada
	v_cvt_f32_i32_e32 v62, v70
	v_sub_f32_e32 v63, v64, v63
	v_sub_f32_e32 v58, v58, v63
	v_mul_f32_e32 v63, v64, v66
	v_pk_mul_f32 v[66:67], v[62:63], v[226:227]
	v_ldexp_f32 v65, v64, 1
	v_fma_f32 v64, v62, s56, -v66
	v_fmac_f32_e32 v64, 0xb102e308, v62
	v_pk_add_f32 v[62:63], v[66:67], v[64:65]
	v_ldexp_f32 v58, v58, 1
	v_sub_f32_e32 v65, v63, v65
	v_sub_f32_e32 v65, v67, v65
	v_add_f32_e32 v69, v58, v65
	v_mov_b32_e32 v68, v66
	v_pk_add_f32 v[66:67], v[62:63], v[66:67] neg_lo:[0,1] neg_hi:[0,1]
	v_pk_add_f32 v[70:71], v[62:63], v[68:69]
	v_mov_b32_e32 v65, v62
	v_mov_b32_e32 v67, v71
	v_pk_add_f32 v[72:73], v[64:65], v[66:67] neg_lo:[0,1] neg_hi:[0,1]
	v_pk_add_f32 v[64:65], v[64:65], v[66:67]
	v_mov_b32_e32 v68, v69
	v_pk_add_f32 v[66:67], v[64:65], v[62:63] op_sel:[1,0] op_sel_hi:[0,1] neg_lo:[0,1] neg_hi:[0,1]
	v_pk_add_f32 v[74:75], v[70:71], v[66:67] op_sel_hi:[1,0] neg_lo:[0,1] neg_hi:[0,1]
	v_mov_b32_e32 v70, v71
	v_mov_b32_e32 v71, v65
	v_pk_mov_b32 v[66:67], v[62:63], v[66:67] op_sel:[1,0]
	v_mov_b32_e32 v69, v62
	v_pk_add_f32 v[66:67], v[70:71], v[66:67] neg_lo:[0,1] neg_hi:[0,1]
	v_mov_b32_e32 v74, v72
	v_pk_add_f32 v[62:63], v[68:69], v[66:67] neg_lo:[0,1] neg_hi:[0,1]
	v_mov_b32_e32 v73, v65
	v_pk_add_f32 v[66:67], v[74:75], v[62:63]
	s_nop 0
	v_pk_add_f32 v[68:69], v[66:67], v[66:67] op_sel:[0,1] op_sel_hi:[1,0]
	s_nop 0
	v_pk_add_f32 v[64:65], v[64:65], v[68:69] op_sel:[1,0] op_sel_hi:[0,1]
	v_mov_b32_e32 v67, v64
	v_pk_add_f32 v[70:71], v[66:67], v[72:73] neg_lo:[0,1] neg_hi:[0,1]
	v_mov_b32_e32 v63, v68
	v_sub_f32_e32 v58, v66, v70
	v_pk_add_f32 v[62:63], v[62:63], v[70:71] neg_lo:[0,1] neg_hi:[0,1]
	v_sub_f32_e32 v58, v72, v58
	v_add_f32_e32 v58, v62, v58
	v_add_f32_e32 v58, v58, v63
	v_add_f32_e32 v58, v64, v58
	v_cndmask_b32_e32 v58, v236, v58, vcc
	v_cmp_ngt_f32_e32 vcc, -1.0, v3
	s_nop 1
	v_cndmask_b32_e32 v58, v237, v58, vcc
	v_cmp_neq_f32_e32 vcc, -1.0, v3
	s_nop 1
	v_cndmask_b32_e32 v58, v238, v58, vcc
	v_cmp_lt_f32_e64 vcc, |v3|, s58
	s_nop 1
	v_cndmask_b32_e32 v3, v58, v3, vcc
;     __device__ __forceinline__ void operator()(f32x4 (&acc)[2][2][4][2], const Unit& u, int row0t, int wr, int wc, int fr, int fq) const {
;     ...
;                                 for (int e = 0; e < 4; ++e) { const int h = 4 * n + e; const float xx = v[e] + dt_bias[h]; const float sp = xx > 20.f ? xx : log1pf(__expf(xx)); o[e] = -__expf(A_log[h]) * sp; } }
.LBB0_206:
	s_or_b64 exec, exec, s[36:37]
	v_mov_b32_e32 v62, v151
	v_mov_b32_e32 v58, v158
	v_add_f32_e32 v59, v59, v62
	v_cmp_nlt_f32_e32 vcc, s53, v59
	s_and_saveexec_b64 s[36:37], vcc
	s_cbranch_execz .LBB0_208
	v_mul_f32_e32 v59, 0x3fb8aa3b, v59
	v_exp_f32_e32 v59, v59
	s_nop 0
	v_add_f32_e32 v64, 1.0, v59
	v_frexp_mant_f32_e32 v66, v64
	v_cvt_f64_f32_e32 v[62:63], v64
	v_frexp_exp_i32_f64_e32 v62, v[62:63]
	v_cmp_gt_f32_e32 vcc, s55, v66
	v_add_f32_e32 v65, -1.0, v64
	v_sub_f32_e32 v67, v65, v64
	v_subbrev_co_u32_e32 v70, vcc, 0, v62, vcc
	v_sub_u32_e32 v62, 0, v70
	v_sub_f32_e32 v65, v59, v65
	v_add_f32_e32 v67, 1.0, v67
	v_ldexp_f32 v63, v64, v62
	v_add_f32_e32 v65, v65, v67
	v_add_f32_e32 v64, -1.0, v63
	v_add_f32_e32 v66, 1.0, v63
	v_ldexp_f32 v62, v65, v62
	v_add_f32_e32 v65, 1.0, v64
	v_add_f32_e32 v67, -1.0, v66
	v_sub_f32_e32 v65, v63, v65
	v_sub_f32_e32 v63, v63, v67
	v_add_f32_e32 v65, v62, v65
	v_add_f32_e32 v62, v62, v63
	v_add_f32_e32 v71, v66, v62
	v_rcp_f32_e32 v73, v71
	v_sub_f32_e32 v63, v71, v66
	v_sub_f32_e32 v72, v62, v63
	v_add_f32_e32 v63, v64, v65
	v_mul_f32_e32 v75, v63, v73
	v_sub_f32_e32 v62, v63, v64
	v_mul_f32_e32 v64, v71, v75
	v_fma_f32 v66, v75, v71, -v64
	v_fmac_f32_e32 v66, v75, v72
	v_sub_f32_e32 v74, v65, v62
	v_add_f32_e32 v62, v64, v66
	v_sub_f32_e32 v65, v63, v62
	v_pk_add_f32 v[68:69], v[62:63], v[64:65] neg_lo:[0,1] neg_hi:[0,1]
	v_mov_b32_e32 v67, v62
	v_pk_add_f32 v[62:63], v[68:69], v[66:67] neg_lo:[0,1] neg_hi:[0,1]
	v_cmp_neq_f32_e32 vcc, s57, v59
	v_add_f32_e32 v63, v74, v63
	v_add_f32_e32 v62, v62, v63
	v_add_f32_e32 v63, v65, v62
	v_mul_f32_e32 v74, v73, v63
	v_mul_f32_e32 v64, v71, v74
	v_fma_f32 v66, v74, v71, -v64
	v_fmac_f32_e32 v66, v74, v72
	v_sub_f32_e32 v65, v65, v63
	v_add_f32_e32 v71, v62, v65
	v_add_f32_e32 v62, v64, v66
	v_sub_f32_e32 v65, v63, v62
	v_pk_add_f32 v[68:69], v[62:63], v[64:65] neg_lo:[0,1] neg_hi:[0,1]
	v_mov_b32_e32 v67, v62
	v_pk_add_f32 v[62:63], v[68:69], v[66:67] neg_lo:[0,1] neg_hi:[0,1]
	s_nop 0
	v_add_f32_e32 v63, v71, v63
	v_add_f32_e32 v62, v62, v63
	v_add_f32_e32 v63, v75, v74
	v_add_f32_e32 v62, v65, v62
	v_sub_f32_e32 v64, v63, v75
	v_mul_f32_e32 v62, v73, v62
	v_sub_f32_e32 v64, v74, v64
	v_add_f32_e32 v64, v64, v62
	v_add_f32_e32 v66, v63, v64
	v_mul_f32_e32 v67, v66, v66
	v_fmamk_f32 v62, v67, 0x3e9b6dac, v235
	v_fmaak_f32 v227, v67, v62, 0x3f2aaada
	v_cvt_f32_i32_e32 v62, v70
	v_sub_f32_e32 v63, v66, v63
	v_sub_f32_e32 v63, v64, v63
	v_ldexp_f32 v68, v63, 1
	v_mul_f32_e32 v63, v66, v67
	v_ldexp_f32 v65, v66, 1
	v_pk_mul_f32 v[66:67], v[62:63], v[226:227]
	s_nop 0
	v_fma_f32 v64, v62, s56, -v66
	v_fmac_f32_e32 v64, 0xb102e308, v62
	v_pk_add_f32 v[62:63], v[66:67], v[64:65]
	s_nop 0
	v_sub_f32_e32 v65, v63, v65
	v_sub_f32_e32 v65, v67, v65
	v_add_f32_e32 v69, v68, v65
	v_mov_b32_e32 v68, v66
	v_pk_add_f32 v[66:67], v[62:63], v[66:67] neg_lo:[0,1] neg_hi:[0,1]
	v_pk_add_f32 v[70:71], v[62:63], v[68:69]
	v_mov_b32_e32 v65, v62
	v_mov_b32_e32 v67, v71
	v_pk_add_f32 v[72:73], v[64:65], v[66:67] neg_lo:[0,1] neg_hi:[0,1]
	v_pk_add_f32 v[64:65], v[64:65], v[66:67]
	v_mov_b32_e32 v68, v69
	v_pk_add_f32 v[66:67], v[64:65], v[62:63] op_sel:[1,0] op_sel_hi:[0,1] neg_lo:[0,1] neg_hi:[0,1]
	v_pk_add_f32 v[74:75], v[70:71], v[66:67] op_sel_hi:[1,0] neg_lo:[0,1] neg_hi:[0,1]
	v_mov_b32_e32 v70, v71
	v_mov_b32_e32 v71, v65
	v_pk_mov_b32 v[66:67], v[62:63], v[66:67] op_sel:[1,0]
	v_mov_b32_e32 v69, v62
	v_pk_add_f32 v[66:67], v[70:71], v[66:67] neg_lo:[0,1] neg_hi:[0,1]
	v_mov_b32_e32 v74, v72
	v_pk_add_f32 v[62:63], v[68:69], v[66:67] neg_lo:[0,1] neg_hi:[0,1]
	v_mov_b32_e32 v73, v65
	v_pk_add_f32 v[66:67], v[74:75], v[62:63]
	s_nop 0
	v_pk_add_f32 v[68:69], v[66:67], v[66:67] op_sel:[0,1] op_sel_hi:[1,0]
	s_nop 0
	v_pk_add_f32 v[64:65], v[64:65], v[68:69] op_sel:[1,0] op_sel_hi:[0,1]
	v_mov_b32_e32 v67, v64
	v_pk_add_f32 v[70:71], v[66:67], v[72:73] neg_lo:[0,1] neg_hi:[0,1]
	v_mov_b32_e32 v63, v68
	v_sub_f32_e32 v65, v66, v70
	v_pk_add_f32 v[62:63], v[62:63], v[70:71] neg_lo:[0,1] neg_hi:[0,1]
	v_sub_f32_e32 v65, v72, v65
	v_add_f32_e32 v62, v62, v65
	v_add_f32_e32 v62, v62, v63
	v_add_f32_e32 v62, v64, v62
	v_cndmask_b32_e32 v62, v236, v62, vcc
	v_cmp_ngt_f32_e32 vcc, -1.0, v59
	s_nop 1
	v_cndmask_b32_e32 v62, v237, v62, vcc
	v_cmp_neq_f32_e32 vcc, -1.0, v59
	s_nop 1
	v_cndmask_b32_e32 v62, v238, v62, vcc
	v_cmp_lt_f32_e64 vcc, |v59|, s58
	s_nop 1
	v_cndmask_b32_e32 v59, v62, v59, vcc
;     __device__ __forceinline__ void operator()(f32x4 (&acc)[2][2][4][2], const Unit& u, int row0t, int wr, int wc, int fr, int fq) const {
;     ...
;                                 for (int e = 0; e < 4; ++e) { const int h = 4 * n + e; const float xx = v[e] + dt_bias[h]; const float sp = xx > 20.f ? xx : log1pf(__expf(xx)); o[e] = -__expf(A_log[h]) * sp; } }
.LBB0_208:
	s_or_b64 exec, exec, s[36:37]
	v_mov_b32_e32 v62, v152
	v_mov_b32_e32 v63, v159
	v_add_f32_e32 v60, v60, v62
	v_cmp_nlt_f32_e32 vcc, s53, v60
	s_and_saveexec_b64 s[36:37], vcc
	s_cbranch_execz .LBB0_210
	v_mul_f32_e32 v60, 0x3fb8aa3b, v60
	v_exp_f32_e32 v60, v60
	s_nop 0
	v_add_f32_e32 v62, 1.0, v60
	v_frexp_mant_f32_e32 v67, v62
	v_cvt_f64_f32_e32 v[64:65], v62
	v_add_f32_e32 v66, -1.0, v62
	v_frexp_exp_i32_f64_e32 v64, v[64:65]
	v_cmp_gt_f32_e32 vcc, s55, v67
	v_sub_f32_e32 v68, v66, v62
	v_sub_f32_e32 v66, v60, v66
	v_subbrev_co_u32_e32 v72, vcc, 0, v64, vcc
	v_add_f32_e32 v68, 1.0, v68
	v_sub_u32_e32 v64, 0, v72
	v_add_f32_e32 v66, v66, v68
	v_ldexp_f32 v62, v62, v64
	v_ldexp_f32 v64, v66, v64
	v_add_f32_e32 v66, -1.0, v62
	v_add_f32_e32 v65, 1.0, v66
	v_sub_f32_e32 v65, v62, v65
	v_add_f32_e32 v67, v64, v65
	v_add_f32_e32 v65, 1.0, v62
	v_add_f32_e32 v68, -1.0, v65
	v_sub_f32_e32 v62, v62, v68
	v_add_f32_e32 v62, v64, v62
	v_add_f32_e32 v73, v65, v62
	v_rcp_f32_e32 v74, v73
	v_sub_f32_e32 v64, v73, v65
	v_add_f32_e32 v65, v66, v67
	v_sub_f32_e32 v62, v62, v64
	v_mul_f32_e32 v76, v65, v74
	v_sub_f32_e32 v64, v65, v66
	v_mul_f32_e32 v66, v73, v76
	v_fma_f32 v68, v76, v73, -v66
	v_fmac_f32_e32 v68, v76, v62
	v_sub_f32_e32 v75, v67, v64
	v_add_f32_e32 v64, v66, v68
	v_sub_f32_e32 v67, v65, v64
	v_pk_add_f32 v[70:71], v[64:65], v[66:67] neg_lo:[0,1] neg_hi:[0,1]
	v_mov_b32_e32 v69, v64
	v_pk_add_f32 v[64:65], v[70:71], v[68:69] neg_lo:[0,1] neg_hi:[0,1]
	v_cmp_neq_f32_e32 vcc, s57, v60
	v_add_f32_e32 v65, v75, v65
	v_add_f32_e32 v64, v64, v65
	v_add_f32_e32 v65, v67, v64
	v_mul_f32_e32 v75, v74, v65
	v_mul_f32_e32 v66, v73, v75
	v_fma_f32 v68, v75, v73, -v66
	v_fmac_f32_e32 v68, v75, v62
	v_sub_f32_e32 v62, v67, v65
	v_add_f32_e32 v62, v64, v62
	v_add_f32_e32 v64, v66, v68
	v_sub_f32_e32 v67, v65, v64
	v_pk_add_f32 v[70:71], v[64:65], v[66:67] neg_lo:[0,1] neg_hi:[0,1]
	v_mov_b32_e32 v69, v64
	v_pk_add_f32 v[64:65], v[70:71], v[68:69] neg_lo:[0,1] neg_hi:[0,1]
	s_nop 0
	v_add_f32_e32 v62, v62, v65
	v_add_f32_e32 v62, v64, v62
	v_add_f32_e32 v65, v76, v75
	v_add_f32_e32 v62, v67, v62
	v_sub_f32_e32 v64, v65, v76
	v_mul_f32_e32 v62, v74, v62
	v_sub_f32_e32 v64, v75, v64
	v_add_f32_e32 v62, v64, v62
	v_add_f32_e32 v66, v65, v62
	v_mul_f32_e32 v68, v66, v66
	v_fmamk_f32 v64, v68, 0x3e9b6dac, v235
	v_fmaak_f32 v227, v68, v64, 0x3f2aaada
	v_cvt_f32_i32_e32 v64, v72
	v_sub_f32_e32 v65, v66, v65
	v_sub_f32_e32 v62, v62, v65
	v_mul_f32_e32 v65, v66, v68
	v_pk_mul_f32 v[68:69], v[64:65], v[226:227]
	v_ldexp_f32 v67, v66, 1
	v_fma_f32 v66, v64, s56, -v68
	v_fmac_f32_e32 v66, 0xb102e308, v64
	v_pk_add_f32 v[64:65], v[68:69], v[66:67]
	v_ldexp_f32 v62, v62, 1
	v_sub_f32_e32 v67, v65, v67
	v_sub_f32_e32 v67, v69, v67
	v_add_f32_e32 v71, v62, v67
	v_mov_b32_e32 v70, v68
	v_pk_add_f32 v[68:69], v[64:65], v[68:69] neg_lo:[0,1] neg_hi:[0,1]
	v_pk_add_f32 v[72:73], v[64:65], v[70:71]
	v_mov_b32_e32 v67, v64
	v_mov_b32_e32 v69, v73
	v_pk_add_f32 v[74:75], v[66:67], v[68:69] neg_lo:[0,1] neg_hi:[0,1]
	v_pk_add_f32 v[66:67], v[66:67], v[68:69]
	v_mov_b32_e32 v70, v71
	v_pk_add_f32 v[68:69], v[66:67], v[64:65] op_sel:[1,0] op_sel_hi:[0,1] neg_lo:[0,1] neg_hi:[0,1]
	v_pk_add_f32 v[76:77], v[72:73], v[68:69] op_sel_hi:[1,0] neg_lo:[0,1] neg_hi:[0,1]
	v_mov_b32_e32 v72, v73
	v_mov_b32_e32 v73, v67
	v_pk_mov_b32 v[68:69], v[64:65], v[68:69] op_sel:[1,0]
	v_mov_b32_e32 v71, v64
	v_pk_add_f32 v[68:69], v[72:73], v[68:69] neg_lo:[0,1] neg_hi:[0,1]
	v_mov_b32_e32 v76, v74
	v_pk_add_f32 v[64:65], v[70:71], v[68:69] neg_lo:[0,1] neg_hi:[0,1]
	v_mov_b32_e32 v75, v67
	v_pk_add_f32 v[68:69], v[76:77], v[64:65]
	s_nop 0
	v_pk_add_f32 v[70:71], v[68:69], v[68:69] op_sel:[0,1] op_sel_hi:[1,0]
	s_nop 0
	v_pk_add_f32 v[66:67], v[66:67], v[70:71] op_sel:[1,0] op_sel_hi:[0,1]
	v_mov_b32_e32 v69, v66
	v_pk_add_f32 v[72:73], v[68:69], v[74:75] neg_lo:[0,1] neg_hi:[0,1]
	v_mov_b32_e32 v65, v70
	v_sub_f32_e32 v62, v68, v72
	v_pk_add_f32 v[64:65], v[64:65], v[72:73] neg_lo:[0,1] neg_hi:[0,1]
	v_sub_f32_e32 v62, v74, v62
	v_add_f32_e32 v62, v64, v62
	v_add_f32_e32 v62, v62, v65
	v_add_f32_e32 v62, v66, v62
	v_cndmask_b32_e32 v62, v236, v62, vcc
	v_cmp_ngt_f32_e32 vcc, -1.0, v60
	s_nop 1
	v_cndmask_b32_e32 v62, v237, v62, vcc
	v_cmp_neq_f32_e32 vcc, -1.0, v60
	s_nop 1
	v_cndmask_b32_e32 v62, v238, v62, vcc
	v_cmp_lt_f32_e64 vcc, |v60|, s58
	s_nop 1
	v_cndmask_b32_e32 v60, v62, v60, vcc
;     __device__ __forceinline__ void operator()(f32x4 (&acc)[2][2][4][2], const Unit& u, int row0t, int wr, int wc, int fr, int fq) const {
;     ...
;                                 for (int e = 0; e < 4; ++e) { const int h = 4 * n + e; const float xx = v[e] + dt_bias[h]; const float sp = xx > 20.f ? xx : log1pf(__expf(xx)); o[e] = -__expf(A_log[h]) * sp; } }
.LBB0_210:
	s_or_b64 exec, exec, s[36:37]
	v_mov_b32_e32 v62, v153
	v_mov_b32_e32 v64, v160
	v_add_f32_e32 v61, v61, v62
	v_cmp_nlt_f32_e32 vcc, s53, v61
	s_and_saveexec_b64 s[36:37], vcc
	s_cbranch_execz .LBB0_212
	v_mul_f32_e32 v61, 0x3fb8aa3b, v61
	v_exp_f32_e32 v61, v61
	s_nop 0
	v_add_f32_e32 v62, 1.0, v61
	v_frexp_mant_f32_e32 v68, v62
	v_cvt_f64_f32_e32 v[66:67], v62
	v_add_f32_e32 v65, -1.0, v62
	v_frexp_exp_i32_f64_e32 v66, v[66:67]
	v_cmp_gt_f32_e32 vcc, s55, v68
	v_sub_f32_e32 v69, v65, v62
	v_sub_f32_e32 v65, v61, v65
	v_subbrev_co_u32_e32 v74, vcc, 0, v66, vcc
	v_add_f32_e32 v69, 1.0, v69
	v_sub_u32_e32 v66, 0, v74
	v_add_f32_e32 v65, v65, v69
	v_ldexp_f32 v62, v62, v66
	v_ldexp_f32 v65, v65, v66
	v_add_f32_e32 v66, -1.0, v62
	v_add_f32_e32 v67, 1.0, v66
	v_sub_f32_e32 v67, v62, v67
	v_add_f32_e32 v68, v65, v67
	v_add_f32_e32 v67, 1.0, v62
	v_add_f32_e32 v69, -1.0, v67
	v_sub_f32_e32 v62, v62, v69
	v_add_f32_e32 v62, v65, v62
	v_add_f32_e32 v65, v67, v62
	v_rcp_f32_e32 v75, v65
	v_sub_f32_e32 v67, v65, v67
	v_sub_f32_e32 v62, v62, v67
	v_add_f32_e32 v67, v66, v68
	v_sub_f32_e32 v66, v67, v66
	v_mul_f32_e32 v77, v67, v75
	v_sub_f32_e32 v76, v68, v66
	v_mul_f32_e32 v68, v65, v77
	v_fma_f32 v70, v77, v65, -v68
	v_fmac_f32_e32 v70, v77, v62
	v_add_f32_e32 v66, v68, v70
	v_sub_f32_e32 v69, v67, v66
	v_pk_add_f32 v[72:73], v[66:67], v[68:69] neg_lo:[0,1] neg_hi:[0,1]
	v_mov_b32_e32 v71, v66
	v_pk_add_f32 v[66:67], v[72:73], v[70:71] neg_lo:[0,1] neg_hi:[0,1]
	v_cmp_neq_f32_e32 vcc, s57, v61
	v_add_f32_e32 v67, v76, v67
	v_add_f32_e32 v66, v66, v67
	v_add_f32_e32 v67, v69, v66
	v_mul_f32_e32 v76, v75, v67
	v_mul_f32_e32 v68, v65, v76
	v_fma_f32 v70, v76, v65, -v68
	v_fmac_f32_e32 v70, v76, v62
	v_sub_f32_e32 v62, v69, v67
	v_add_f32_e32 v62, v66, v62
	v_add_f32_e32 v66, v68, v70
	v_sub_f32_e32 v69, v67, v66
	v_pk_add_f32 v[72:73], v[66:67], v[68:69] neg_lo:[0,1] neg_hi:[0,1]
	v_mov_b32_e32 v71, v66
	v_pk_add_f32 v[66:67], v[72:73], v[70:71] neg_lo:[0,1] neg_hi:[0,1]
	v_add_f32_e32 v65, v77, v76
	v_add_f32_e32 v62, v62, v67
	v_add_f32_e32 v62, v66, v62
	v_add_f32_e32 v62, v69, v62
	v_sub_f32_e32 v66, v65, v77
	v_mul_f32_e32 v62, v75, v62
	v_sub_f32_e32 v66, v76, v66
	v_add_f32_e32 v62, v66, v62
	v_add_f32_e32 v67, v65, v62
	v_mul_f32_e32 v68, v67, v67
	v_fmamk_f32 v66, v68, 0x3e9b6dac, v235
	v_fmaak_f32 v227, v68, v66, 0x3f2aaada
	v_cvt_f32_i32_e32 v66, v74
	v_sub_f32_e32 v65, v67, v65
	v_ldexp_f32 v69, v67, 1
	v_mul_f32_e32 v67, v67, v68
	v_pk_mul_f32 v[70:71], v[66:67], v[226:227]
	v_sub_f32_e32 v62, v62, v65
	v_fma_f32 v68, v66, s56, -v70
	v_fmac_f32_e32 v68, 0xb102e308, v66
	v_pk_add_f32 v[66:67], v[70:71], v[68:69]
	v_ldexp_f32 v62, v62, 1
	v_sub_f32_e32 v65, v67, v69
	v_sub_f32_e32 v65, v71, v65
	v_add_f32_e32 v73, v62, v65
	v_mov_b32_e32 v72, v70
	v_pk_add_f32 v[70:71], v[66:67], v[70:71] neg_lo:[0,1] neg_hi:[0,1]
	v_pk_add_f32 v[74:75], v[66:67], v[72:73]
	v_mov_b32_e32 v69, v66
	v_mov_b32_e32 v71, v75
	v_pk_add_f32 v[76:77], v[68:69], v[70:71] neg_lo:[0,1] neg_hi:[0,1]
	v_pk_add_f32 v[68:69], v[68:69], v[70:71]
	v_mov_b32_e32 v72, v73
	v_pk_add_f32 v[70:71], v[68:69], v[66:67] op_sel:[1,0] op_sel_hi:[0,1] neg_lo:[0,1] neg_hi:[0,1]
	v_pk_add_f32 v[78:79], v[74:75], v[70:71] op_sel_hi:[1,0] neg_lo:[0,1] neg_hi:[0,1]
	v_mov_b32_e32 v74, v75
	v_mov_b32_e32 v75, v69
	v_pk_mov_b32 v[70:71], v[66:67], v[70:71] op_sel:[1,0]
	v_mov_b32_e32 v73, v66
	v_pk_add_f32 v[70:71], v[74:75], v[70:71] neg_lo:[0,1] neg_hi:[0,1]
	v_mov_b32_e32 v78, v76
	v_pk_add_f32 v[66:67], v[72:73], v[70:71] neg_lo:[0,1] neg_hi:[0,1]
	v_mov_b32_e32 v77, v69
	v_pk_add_f32 v[70:71], v[78:79], v[66:67]
	s_nop 0
	v_pk_add_f32 v[72:73], v[70:71], v[70:71] op_sel:[0,1] op_sel_hi:[1,0]
	s_nop 0
	v_pk_add_f32 v[68:69], v[68:69], v[72:73] op_sel:[1,0] op_sel_hi:[0,1]
	v_mov_b32_e32 v71, v68
	v_pk_add_f32 v[74:75], v[70:71], v[76:77] neg_lo:[0,1] neg_hi:[0,1]
	v_mov_b32_e32 v67, v72
	v_sub_f32_e32 v62, v70, v74
	v_pk_add_f32 v[66:67], v[66:67], v[74:75] neg_lo:[0,1] neg_hi:[0,1]
	v_sub_f32_e32 v62, v76, v62
	v_add_f32_e32 v62, v66, v62
	v_add_f32_e32 v62, v62, v67
	v_add_f32_e32 v62, v68, v62
	v_cndmask_b32_e32 v62, v236, v62, vcc
	v_cmp_ngt_f32_e32 vcc, -1.0, v61
	s_nop 1
	v_cndmask_b32_e32 v62, v237, v62, vcc
	v_cmp_neq_f32_e32 vcc, -1.0, v61
	s_nop 1
	v_cndmask_b32_e32 v62, v238, v62, vcc
	v_cmp_lt_f32_e64 vcc, |v61|, s58
	s_nop 1
	v_cndmask_b32_e32 v61, v62, v61, vcc
.LBB0_212:
	s_or_b64 exec, exec, s[36:37]
	v_mul_f32_e32 v58, 0x3fb8aa3b, v58
	v_exp_f32_e32 v58, v58
	s_nop 0
	v_mul_f32_e64 v62, v3, -v58
	v_mul_f32_e32 v3, 0x3fb8aa3b, v63
	v_exp_f32_e32 v3, v3
	s_nop 0
	v_mul_f32_e64 v63, v59, -v3
	v_mul_f32_e32 v3, 0x3fb8aa3b, v64
	v_exp_f32_e32 v3, v3
	s_nop 0
	v_mul_f32_e64 v64, v60, -v3
	v_mov_b32_e32 v3, v161
	v_mul_f32_e32 v3, 0x3fb8aa3b, v3
	v_exp_f32_e32 v3, v3
	s_nop 0
	v_mul_f32_e64 v65, v61, -v3

;     __device__ __forceinline__ void operator()(f32x4 (&acc)[2][2][4][2], const Unit& u, int row0t, int wr, int wc, int fr, int fq) const {
;     ...
;                                 for (int e = 0; e < 4; ++e) { const int h = 4 * n + e; const float xx = v[e] + dt_bias[h]; const float sp = xx > 20.f ? xx : log1pf(__expf(xx)); o[e] = -__expf(A_log[h]) * sp; } }
;                             *(f32x4*)(bg + (size_t)r * 16 + 8 * fq + 4 * n) = o; } }
.LBB0_215:
	s_or_b64 exec, exec, s[24:25]
	v_or_b32_e32 v58, 16, v4
	v_ashrrev_i32_e32 v59, 31, v58
	v_lshlrev_b64 v[58:59], 6, v[58:59]
	v_lshl_add_u64 v[66:67], v[214:215], 0, v[58:59]
	global_store_dwordx4 v[66:67], v[62:65], off
	s_and_saveexec_b64 s[2:3], s[4:5]
	s_xor_b64 s[24:25], exec, s[2:3]
	s_cbranch_execz .LBB0_225
	v_mov_b32_e32 v3, v154
	v_add_f32_e32 v3, v54, v3
	v_cmp_nlt_f32_e32 vcc, s53, v3
	s_and_saveexec_b64 s[36:37], vcc
	s_cbranch_execz .LBB0_218
	v_mul_f32_e32 v3, 0x3fb8aa3b, v3
	v_exp_f32_e32 v3, v3
	s_nop 0
	v_add_f32_e32 v54, 1.0, v3
	v_frexp_mant_f32_e32 v61, v54
	v_cvt_f64_f32_e32 v[58:59], v54
	v_add_f32_e32 v60, -1.0, v54
	v_frexp_exp_i32_f64_e32 v58, v[58:59]
	v_cmp_gt_f32_e32 vcc, s55, v61
	v_sub_f32_e32 v62, v60, v54
	v_sub_f32_e32 v60, v3, v60
	v_subbrev_co_u32_e32 v68, vcc, 0, v58, vcc
	v_add_f32_e32 v62, 1.0, v62
	v_sub_u32_e32 v58, 0, v68
	v_add_f32_e32 v60, v60, v62
	v_ldexp_f32 v54, v54, v58
	v_ldexp_f32 v58, v60, v58
	v_add_f32_e32 v60, -1.0, v54
	v_add_f32_e32 v59, 1.0, v60
	v_sub_f32_e32 v59, v54, v59
	v_add_f32_e32 v61, v58, v59
	v_add_f32_e32 v59, 1.0, v54
	v_add_f32_e32 v62, -1.0, v59
	v_sub_f32_e32 v54, v54, v62
	v_add_f32_e32 v54, v58, v54
	v_add_f32_e32 v69, v59, v54
	v_rcp_f32_e32 v70, v69
	v_sub_f32_e32 v58, v69, v59
	v_add_f32_e32 v59, v60, v61
	v_sub_f32_e32 v54, v54, v58
	v_mul_f32_e32 v72, v59, v70
	v_sub_f32_e32 v58, v59, v60
	v_mul_f32_e32 v60, v69, v72
	v_fma_f32 v62, v72, v69, -v60
	v_fmac_f32_e32 v62, v72, v54
	v_sub_f32_e32 v71, v61, v58
	v_add_f32_e32 v58, v60, v62
	v_sub_f32_e32 v61, v59, v58
	v_pk_add_f32 v[64:65], v[58:59], v[60:61] neg_lo:[0,1] neg_hi:[0,1]
	v_mov_b32_e32 v63, v58
	v_pk_add_f32 v[58:59], v[64:65], v[62:63] neg_lo:[0,1] neg_hi:[0,1]
	v_cmp_neq_f32_e32 vcc, s57, v3
	v_add_f32_e32 v59, v71, v59
	v_add_f32_e32 v58, v58, v59
	v_add_f32_e32 v59, v61, v58
	v_mul_f32_e32 v71, v70, v59
	v_mul_f32_e32 v60, v69, v71
	v_fma_f32 v62, v71, v69, -v60
	v_fmac_f32_e32 v62, v71, v54
	v_sub_f32_e32 v54, v61, v59
	v_add_f32_e32 v54, v58, v54
	v_add_f32_e32 v58, v60, v62
	v_sub_f32_e32 v61, v59, v58
	v_pk_add_f32 v[64:65], v[58:59], v[60:61] neg_lo:[0,1] neg_hi:[0,1]
	v_mov_b32_e32 v63, v58
	v_pk_add_f32 v[58:59], v[64:65], v[62:63] neg_lo:[0,1] neg_hi:[0,1]
	s_nop 0
	v_add_f32_e32 v54, v54, v59
	v_add_f32_e32 v54, v58, v54
	v_add_f32_e32 v59, v72, v71
	v_add_f32_e32 v54, v61, v54
	v_sub_f32_e32 v58, v59, v72
	v_mul_f32_e32 v54, v70, v54
	v_sub_f32_e32 v58, v71, v58
	v_add_f32_e32 v54, v58, v54
	v_add_f32_e32 v60, v59, v54
	v_mul_f32_e32 v62, v60, v60
	v_fmamk_f32 v58, v62, 0x3e9b6dac, v235
	v_fmaak_f32 v227, v62, v58, 0x3f2aaada
	v_cvt_f32_i32_e32 v58, v68
	v_sub_f32_e32 v59, v60, v59
	v_sub_f32_e32 v54, v54, v59
	v_mul_f32_e32 v59, v60, v62
	v_pk_mul_f32 v[62:63], v[58:59], v[226:227]
	v_ldexp_f32 v61, v60, 1
	v_fma_f32 v60, v58, s56, -v62
	v_fmac_f32_e32 v60, 0xb102e308, v58
	v_pk_add_f32 v[58:59], v[62:63], v[60:61]
	v_ldexp_f32 v54, v54, 1
	v_sub_f32_e32 v61, v59, v61
	v_sub_f32_e32 v61, v63, v61
	v_add_f32_e32 v65, v54, v61
	v_mov_b32_e32 v64, v62
	v_pk_add_f32 v[62:63], v[58:59], v[62:63] neg_lo:[0,1] neg_hi:[0,1]
	v_pk_add_f32 v[68:69], v[58:59], v[64:65]
	v_mov_b32_e32 v61, v58
	v_mov_b32_e32 v63, v69
	v_pk_add_f32 v[70:71], v[60:61], v[62:63] neg_lo:[0,1] neg_hi:[0,1]
	v_pk_add_f32 v[60:61], v[60:61], v[62:63]
	v_mov_b32_e32 v64, v65
	v_pk_add_f32 v[62:63], v[60:61], v[58:59] op_sel:[1,0] op_sel_hi:[0,1] neg_lo:[0,1] neg_hi:[0,1]
	v_pk_add_f32 v[72:73], v[68:69], v[62:63] op_sel_hi:[1,0] neg_lo:[0,1] neg_hi:[0,1]
	v_mov_b32_e32 v68, v69
	v_mov_b32_e32 v69, v61
	v_pk_mov_b32 v[62:63], v[58:59], v[62:63] op_sel:[1,0]
	v_mov_b32_e32 v65, v58
	v_pk_add_f32 v[62:63], v[68:69], v[62:63] neg_lo:[0,1] neg_hi:[0,1]
	v_mov_b32_e32 v72, v70
	v_pk_add_f32 v[58:59], v[64:65], v[62:63] neg_lo:[0,1] neg_hi:[0,1]
	v_mov_b32_e32 v71, v61
	v_pk_add_f32 v[62:63], v[72:73], v[58:59]
	s_nop 0
	v_pk_add_f32 v[64:65], v[62:63], v[62:63] op_sel:[0,1] op_sel_hi:[1,0]
	s_nop 0
	v_pk_add_f32 v[60:61], v[60:61], v[64:65] op_sel:[1,0] op_sel_hi:[0,1]
	v_mov_b32_e32 v63, v60
	v_pk_add_f32 v[68:69], v[62:63], v[70:71] neg_lo:[0,1] neg_hi:[0,1]
	v_mov_b32_e32 v59, v64
	v_sub_f32_e32 v54, v62, v68
	v_pk_add_f32 v[58:59], v[58:59], v[68:69] neg_lo:[0,1] neg_hi:[0,1]
	v_sub_f32_e32 v54, v70, v54
	v_add_f32_e32 v54, v58, v54
	v_add_f32_e32 v54, v54, v59
	v_add_f32_e32 v54, v60, v54
	v_cndmask_b32_e32 v54, v236, v54, vcc
	v_cmp_ngt_f32_e32 vcc, -1.0, v3
	s_nop 1
	v_cndmask_b32_e32 v54, v237, v54, vcc
	v_cmp_neq_f32_e32 vcc, -1.0, v3
	s_nop 1
	v_cndmask_b32_e32 v54, v238, v54, vcc
	v_cmp_lt_f32_e64 vcc, |v3|, s58
	s_nop 1
	v_cndmask_b32_e32 v3, v54, v3, vcc
;     __device__ __forceinline__ void operator()(f32x4 (&acc)[2][2][4][2], const Unit& u, int row0t, int wr, int wc, int fr, int fq) const {
;     ...
;                                 for (int e = 0; e < 4; ++e) { const int h = 4 * n + e; const float xx = v[e] + dt_bias[h]; const float sp = xx > 20.f ? xx : log1pf(__expf(xx)); o[e] = -__expf(A_log[h]) * sp; } }
.LBB0_218:
	s_or_b64 exec, exec, s[36:37]
	v_mov_b32_e32 v58, v155
	v_mov_b32_e32 v54, v162
	v_add_f32_e32 v55, v55, v58
	v_cmp_nlt_f32_e32 vcc, s53, v55
	s_and_saveexec_b64 s[36:37], vcc
	s_cbranch_execz .LBB0_220
	v_mul_f32_e32 v55, 0x3fb8aa3b, v55
	v_exp_f32_e32 v55, v55
	s_nop 0
	v_add_f32_e32 v60, 1.0, v55
	v_frexp_mant_f32_e32 v62, v60
	v_cvt_f64_f32_e32 v[58:59], v60
	v_frexp_exp_i32_f64_e32 v58, v[58:59]
	v_cmp_gt_f32_e32 vcc, s55, v62
	v_add_f32_e32 v61, -1.0, v60
	v_sub_f32_e32 v63, v61, v60
	v_subbrev_co_u32_e32 v68, vcc, 0, v58, vcc
	v_sub_u32_e32 v58, 0, v68
	v_sub_f32_e32 v61, v55, v61
	v_add_f32_e32 v63, 1.0, v63
	v_ldexp_f32 v59, v60, v58
	v_add_f32_e32 v61, v61, v63
	v_add_f32_e32 v60, -1.0, v59
	v_add_f32_e32 v62, 1.0, v59
	v_ldexp_f32 v58, v61, v58
	v_add_f32_e32 v61, 1.0, v60
	v_add_f32_e32 v63, -1.0, v62
	v_sub_f32_e32 v61, v59, v61
	v_sub_f32_e32 v59, v59, v63
	v_add_f32_e32 v61, v58, v61
	v_add_f32_e32 v58, v58, v59
	v_add_f32_e32 v69, v62, v58
	v_rcp_f32_e32 v71, v69
	v_sub_f32_e32 v59, v69, v62
	v_sub_f32_e32 v70, v58, v59
	v_add_f32_e32 v59, v60, v61
	v_mul_f32_e32 v73, v59, v71
	v_sub_f32_e32 v58, v59, v60
	v_mul_f32_e32 v60, v69, v73
	v_fma_f32 v62, v73, v69, -v60
	v_fmac_f32_e32 v62, v73, v70
	v_sub_f32_e32 v72, v61, v58
	v_add_f32_e32 v58, v60, v62
	v_sub_f32_e32 v61, v59, v58
	v_pk_add_f32 v[64:65], v[58:59], v[60:61] neg_lo:[0,1] neg_hi:[0,1]
	v_mov_b32_e32 v63, v58
	v_pk_add_f32 v[58:59], v[64:65], v[62:63] neg_lo:[0,1] neg_hi:[0,1]
	v_cmp_neq_f32_e32 vcc, s57, v55
	v_add_f32_e32 v59, v72, v59
	v_add_f32_e32 v58, v58, v59
	v_add_f32_e32 v59, v61, v58
	v_mul_f32_e32 v72, v71, v59
	v_mul_f32_e32 v60, v69, v72
	v_fma_f32 v62, v72, v69, -v60
	v_fmac_f32_e32 v62, v72, v70
	v_sub_f32_e32 v61, v61, v59
	v_add_f32_e32 v69, v58, v61
	v_add_f32_e32 v58, v60, v62
	v_sub_f32_e32 v61, v59, v58
	v_pk_add_f32 v[64:65], v[58:59], v[60:61] neg_lo:[0,1] neg_hi:[0,1]
	v_mov_b32_e32 v63, v58
	v_pk_add_f32 v[58:59], v[64:65], v[62:63] neg_lo:[0,1] neg_hi:[0,1]
	s_nop 0
	v_add_f32_e32 v59, v69, v59
	v_add_f32_e32 v58, v58, v59
	v_add_f32_e32 v59, v73, v72
	v_add_f32_e32 v58, v61, v58
	v_sub_f32_e32 v60, v59, v73
	v_mul_f32_e32 v58, v71, v58
	v_sub_f32_e32 v60, v72, v60
	v_add_f32_e32 v60, v60, v58
	v_add_f32_e32 v62, v59, v60
	v_mul_f32_e32 v63, v62, v62
	v_fmamk_f32 v58, v63, 0x3e9b6dac, v235
	v_fmaak_f32 v227, v63, v58, 0x3f2aaada
	v_cvt_f32_i32_e32 v58, v68
	v_sub_f32_e32 v59, v62, v59
	v_sub_f32_e32 v59, v60, v59
	v_ldexp_f32 v64, v59, 1
	v_mul_f32_e32 v59, v62, v63
	v_ldexp_f32 v61, v62, 1
	v_pk_mul_f32 v[62:63], v[58:59], v[226:227]
	s_nop 0
	v_fma_f32 v60, v58, s56, -v62
	v_fmac_f32_e32 v60, 0xb102e308, v58
	v_pk_add_f32 v[58:59], v[62:63], v[60:61]
	s_nop 0
	v_sub_f32_e32 v61, v59, v61
	v_sub_f32_e32 v61, v63, v61
	v_add_f32_e32 v65, v64, v61
	v_mov_b32_e32 v64, v62
	v_pk_add_f32 v[62:63], v[58:59], v[62:63] neg_lo:[0,1] neg_hi:[0,1]
	v_pk_add_f32 v[68:69], v[58:59], v[64:65]
	v_mov_b32_e32 v61, v58
	v_mov_b32_e32 v63, v69
	v_pk_add_f32 v[70:71], v[60:61], v[62:63] neg_lo:[0,1] neg_hi:[0,1]
	v_pk_add_f32 v[60:61], v[60:61], v[62:63]
	v_mov_b32_e32 v64, v65
	v_pk_add_f32 v[62:63], v[60:61], v[58:59] op_sel:[1,0] op_sel_hi:[0,1] neg_lo:[0,1] neg_hi:[0,1]
	v_pk_add_f32 v[72:73], v[68:69], v[62:63] op_sel_hi:[1,0] neg_lo:[0,1] neg_hi:[0,1]
	v_mov_b32_e32 v68, v69
	v_mov_b32_e32 v69, v61
	v_pk_mov_b32 v[62:63], v[58:59], v[62:63] op_sel:[1,0]
	v_mov_b32_e32 v65, v58
	v_pk_add_f32 v[62:63], v[68:69], v[62:63] neg_lo:[0,1] neg_hi:[0,1]
	v_mov_b32_e32 v72, v70
	v_pk_add_f32 v[58:59], v[64:65], v[62:63] neg_lo:[0,1] neg_hi:[0,1]
	v_mov_b32_e32 v71, v61
	v_pk_add_f32 v[62:63], v[72:73], v[58:59]
	s_nop 0
	v_pk_add_f32 v[64:65], v[62:63], v[62:63] op_sel:[0,1] op_sel_hi:[1,0]
	s_nop 0
	v_pk_add_f32 v[60:61], v[60:61], v[64:65] op_sel:[1,0] op_sel_hi:[0,1]
	v_mov_b32_e32 v63, v60
	v_pk_add_f32 v[68:69], v[62:63], v[70:71] neg_lo:[0,1] neg_hi:[0,1]
	v_mov_b32_e32 v59, v64
	v_sub_f32_e32 v61, v62, v68
	v_pk_add_f32 v[58:59], v[58:59], v[68:69] neg_lo:[0,1] neg_hi:[0,1]
	v_sub_f32_e32 v61, v70, v61
	v_add_f32_e32 v58, v58, v61
	v_add_f32_e32 v58, v58, v59
	v_add_f32_e32 v58, v60, v58
	v_cndmask_b32_e32 v58, v236, v58, vcc
	v_cmp_ngt_f32_e32 vcc, -1.0, v55
	s_nop 1
	v_cndmask_b32_e32 v58, v237, v58, vcc
	v_cmp_neq_f32_e32 vcc, -1.0, v55
	s_nop 1
	v_cndmask_b32_e32 v58, v238, v58, vcc
	v_cmp_lt_f32_e64 vcc, |v55|, s58
	s_nop 1
	v_cndmask_b32_e32 v55, v58, v55, vcc
;     __device__ __forceinline__ void operator()(f32x4 (&acc)[2][2][4][2], const Unit& u, int row0t, int wr, int wc, int fr, int fq) const {
;     ...
;                                 for (int e = 0; e < 4; ++e) { const int h = 4 * n + e; const float xx = v[e] + dt_bias[h]; const float sp = xx > 20.f ? xx : log1pf(__expf(xx)); o[e] = -__expf(A_log[h]) * sp; } }
.LBB0_220:
	s_or_b64 exec, exec, s[36:37]
	v_mov_b32_e32 v58, v156
	v_mov_b32_e32 v59, v163
	v_add_f32_e32 v56, v56, v58
	v_cmp_nlt_f32_e32 vcc, s53, v56
	s_and_saveexec_b64 s[36:37], vcc
	s_cbranch_execz .LBB0_222
	v_mul_f32_e32 v56, 0x3fb8aa3b, v56
	v_exp_f32_e32 v56, v56
	s_nop 0
	v_add_f32_e32 v58, 1.0, v56
	v_frexp_mant_f32_e32 v63, v58
	v_cvt_f64_f32_e32 v[60:61], v58
	v_add_f32_e32 v62, -1.0, v58
	v_frexp_exp_i32_f64_e32 v60, v[60:61]
	v_cmp_gt_f32_e32 vcc, s55, v63
	v_sub_f32_e32 v64, v62, v58
	v_sub_f32_e32 v62, v56, v62
	v_subbrev_co_u32_e32 v70, vcc, 0, v60, vcc
	v_add_f32_e32 v64, 1.0, v64
	v_sub_u32_e32 v60, 0, v70
	v_add_f32_e32 v62, v62, v64
	v_ldexp_f32 v58, v58, v60
	v_ldexp_f32 v60, v62, v60
	v_add_f32_e32 v62, -1.0, v58
	v_add_f32_e32 v61, 1.0, v62
	v_sub_f32_e32 v61, v58, v61
	v_add_f32_e32 v63, v60, v61
	v_add_f32_e32 v61, 1.0, v58
	v_add_f32_e32 v64, -1.0, v61
	v_sub_f32_e32 v58, v58, v64
	v_add_f32_e32 v58, v60, v58
	v_add_f32_e32 v71, v61, v58
	v_rcp_f32_e32 v72, v71
	v_sub_f32_e32 v60, v71, v61
	v_add_f32_e32 v61, v62, v63
	v_sub_f32_e32 v58, v58, v60
	v_mul_f32_e32 v74, v61, v72
	v_sub_f32_e32 v60, v61, v62
	v_mul_f32_e32 v62, v71, v74
	v_fma_f32 v64, v74, v71, -v62
	v_fmac_f32_e32 v64, v74, v58
	v_sub_f32_e32 v73, v63, v60
	v_add_f32_e32 v60, v62, v64
	v_sub_f32_e32 v63, v61, v60
	v_pk_add_f32 v[68:69], v[60:61], v[62:63] neg_lo:[0,1] neg_hi:[0,1]
	v_mov_b32_e32 v65, v60
	v_pk_add_f32 v[60:61], v[68:69], v[64:65] neg_lo:[0,1] neg_hi:[0,1]
	v_cmp_neq_f32_e32 vcc, s57, v56
	v_add_f32_e32 v61, v73, v61
	v_add_f32_e32 v60, v60, v61
	v_add_f32_e32 v61, v63, v60
	v_mul_f32_e32 v73, v72, v61
	v_mul_f32_e32 v62, v71, v73
	v_fma_f32 v64, v73, v71, -v62
	v_fmac_f32_e32 v64, v73, v58
	v_sub_f32_e32 v58, v63, v61
	v_add_f32_e32 v58, v60, v58
	v_add_f32_e32 v60, v62, v64
	v_sub_f32_e32 v63, v61, v60
	v_pk_add_f32 v[68:69], v[60:61], v[62:63] neg_lo:[0,1] neg_hi:[0,1]
	v_mov_b32_e32 v65, v60
	v_pk_add_f32 v[60:61], v[68:69], v[64:65] neg_lo:[0,1] neg_hi:[0,1]
	s_nop 0
	v_add_f32_e32 v58, v58, v61
	v_add_f32_e32 v58, v60, v58
	v_add_f32_e32 v61, v74, v73
	v_add_f32_e32 v58, v63, v58
	v_sub_f32_e32 v60, v61, v74
	v_mul_f32_e32 v58, v72, v58
	v_sub_f32_e32 v60, v73, v60
	v_add_f32_e32 v58, v60, v58
	v_add_f32_e32 v62, v61, v58
	v_mul_f32_e32 v64, v62, v62
	v_fmamk_f32 v60, v64, 0x3e9b6dac, v235
	v_fmaak_f32 v227, v64, v60, 0x3f2aaada
	v_cvt_f32_i32_e32 v60, v70
	v_sub_f32_e32 v61, v62, v61
	v_sub_f32_e32 v58, v58, v61
	v_mul_f32_e32 v61, v62, v64
	v_pk_mul_f32 v[64:65], v[60:61], v[226:227]
	v_ldexp_f32 v63, v62, 1
	v_fma_f32 v62, v60, s56, -v64
	v_fmac_f32_e32 v62, 0xb102e308, v60
	v_pk_add_f32 v[60:61], v[64:65], v[62:63]
	v_ldexp_f32 v58, v58, 1
	v_sub_f32_e32 v63, v61, v63
	v_sub_f32_e32 v63, v65, v63
	v_add_f32_e32 v69, v58, v63
	v_mov_b32_e32 v68, v64
	v_pk_add_f32 v[64:65], v[60:61], v[64:65] neg_lo:[0,1] neg_hi:[0,1]
	v_pk_add_f32 v[70:71], v[60:61], v[68:69]
	v_mov_b32_e32 v63, v60
	v_mov_b32_e32 v65, v71
	v_pk_add_f32 v[72:73], v[62:63], v[64:65] neg_lo:[0,1] neg_hi:[0,1]
	v_pk_add_f32 v[62:63], v[62:63], v[64:65]
	v_mov_b32_e32 v68, v69
	v_pk_add_f32 v[64:65], v[62:63], v[60:61] op_sel:[1,0] op_sel_hi:[0,1] neg_lo:[0,1] neg_hi:[0,1]
	v_pk_add_f32 v[74:75], v[70:71], v[64:65] op_sel_hi:[1,0] neg_lo:[0,1] neg_hi:[0,1]
	v_mov_b32_e32 v70, v71
	v_mov_b32_e32 v71, v63
	v_pk_mov_b32 v[64:65], v[60:61], v[64:65] op_sel:[1,0]
	v_mov_b32_e32 v69, v60
	v_pk_add_f32 v[64:65], v[70:71], v[64:65] neg_lo:[0,1] neg_hi:[0,1]
	v_mov_b32_e32 v74, v72
	v_pk_add_f32 v[60:61], v[68:69], v[64:65] neg_lo:[0,1] neg_hi:[0,1]
	v_mov_b32_e32 v73, v63
	v_pk_add_f32 v[64:65], v[74:75], v[60:61]
	s_nop 0
	v_pk_add_f32 v[68:69], v[64:65], v[64:65] op_sel:[0,1] op_sel_hi:[1,0]
	s_nop 0
	v_pk_add_f32 v[62:63], v[62:63], v[68:69] op_sel:[1,0] op_sel_hi:[0,1]
	v_mov_b32_e32 v65, v62
	v_pk_add_f32 v[70:71], v[64:65], v[72:73] neg_lo:[0,1] neg_hi:[0,1]
	v_mov_b32_e32 v61, v68
	v_sub_f32_e32 v58, v64, v70
	v_pk_add_f32 v[60:61], v[60:61], v[70:71] neg_lo:[0,1] neg_hi:[0,1]
	v_sub_f32_e32 v58, v72, v58
	v_add_f32_e32 v58, v60, v58
	v_add_f32_e32 v58, v58, v61
	v_add_f32_e32 v58, v62, v58
	v_cndmask_b32_e32 v58, v236, v58, vcc
	v_cmp_ngt_f32_e32 vcc, -1.0, v56
	s_nop 1
	v_cndmask_b32_e32 v58, v237, v58, vcc
	v_cmp_neq_f32_e32 vcc, -1.0, v56
	s_nop 1
	v_cndmask_b32_e32 v58, v238, v58, vcc
	v_cmp_lt_f32_e64 vcc, |v56|, s58
	s_nop 1
	v_cndmask_b32_e32 v56, v58, v56, vcc
;     __device__ __forceinline__ void operator()(f32x4 (&acc)[2][2][4][2], const Unit& u, int row0t, int wr, int wc, int fr, int fq) const {
;     ...
;                                 for (int e = 0; e < 4; ++e) { const int h = 4 * n + e; const float xx = v[e] + dt_bias[h]; const float sp = xx > 20.f ? xx : log1pf(__expf(xx)); o[e] = -__expf(A_log[h]) * sp; } }
.LBB0_222:
	s_or_b64 exec, exec, s[36:37]
	v_mov_b32_e32 v58, v157
	v_mov_b32_e32 v60, v164
	v_add_f32_e32 v57, v57, v58
	v_cmp_nlt_f32_e32 vcc, s53, v57
	s_and_saveexec_b64 s[36:37], vcc
	s_cbranch_execz .LBB0_224
	v_mul_f32_e32 v57, 0x3fb8aa3b, v57
	v_exp_f32_e32 v57, v57
	s_nop 0
	v_add_f32_e32 v58, 1.0, v57
	v_frexp_mant_f32_e32 v64, v58
	v_cvt_f64_f32_e32 v[62:63], v58
	v_add_f32_e32 v61, -1.0, v58
	v_frexp_exp_i32_f64_e32 v62, v[62:63]
	v_cmp_gt_f32_e32 vcc, s55, v64
	v_sub_f32_e32 v65, v61, v58
	v_sub_f32_e32 v61, v57, v61
	v_subbrev_co_u32_e32 v72, vcc, 0, v62, vcc
	v_add_f32_e32 v65, 1.0, v65
	v_sub_u32_e32 v62, 0, v72
	v_add_f32_e32 v61, v61, v65
	v_ldexp_f32 v58, v58, v62
	v_ldexp_f32 v61, v61, v62
	v_add_f32_e32 v62, -1.0, v58
	v_add_f32_e32 v63, 1.0, v62
	v_sub_f32_e32 v63, v58, v63
	v_add_f32_e32 v64, v61, v63
	v_add_f32_e32 v63, 1.0, v58
	v_add_f32_e32 v65, -1.0, v63
	v_sub_f32_e32 v58, v58, v65
	v_add_f32_e32 v58, v61, v58
	v_add_f32_e32 v61, v63, v58
	v_rcp_f32_e32 v73, v61
	v_sub_f32_e32 v63, v61, v63
	v_sub_f32_e32 v58, v58, v63
	v_add_f32_e32 v63, v62, v64
	v_sub_f32_e32 v62, v63, v62
	v_mul_f32_e32 v75, v63, v73
	v_sub_f32_e32 v74, v64, v62
	v_mul_f32_e32 v64, v61, v75
	v_fma_f32 v68, v75, v61, -v64
	v_fmac_f32_e32 v68, v75, v58
	v_add_f32_e32 v62, v64, v68
	v_sub_f32_e32 v65, v63, v62
	v_pk_add_f32 v[70:71], v[62:63], v[64:65] neg_lo:[0,1] neg_hi:[0,1]
	v_mov_b32_e32 v69, v62
	v_pk_add_f32 v[62:63], v[70:71], v[68:69] neg_lo:[0,1] neg_hi:[0,1]
	v_cmp_neq_f32_e32 vcc, s57, v57
	v_add_f32_e32 v63, v74, v63
	v_add_f32_e32 v62, v62, v63
	v_add_f32_e32 v63, v65, v62
	v_mul_f32_e32 v74, v73, v63
	v_mul_f32_e32 v64, v61, v74
	v_fma_f32 v68, v74, v61, -v64
	v_fmac_f32_e32 v68, v74, v58
	v_sub_f32_e32 v58, v65, v63
	v_add_f32_e32 v58, v62, v58
	v_add_f32_e32 v62, v64, v68
	v_sub_f32_e32 v65, v63, v62
	v_pk_add_f32 v[70:71], v[62:63], v[64:65] neg_lo:[0,1] neg_hi:[0,1]
	v_mov_b32_e32 v69, v62
	v_pk_add_f32 v[62:63], v[70:71], v[68:69] neg_lo:[0,1] neg_hi:[0,1]
	v_add_f32_e32 v61, v75, v74
	v_add_f32_e32 v58, v58, v63
	v_add_f32_e32 v58, v62, v58
	v_add_f32_e32 v58, v65, v58
	v_sub_f32_e32 v62, v61, v75
	v_mul_f32_e32 v58, v73, v58
	v_sub_f32_e32 v62, v74, v62
	v_add_f32_e32 v58, v62, v58
	v_add_f32_e32 v63, v61, v58
	v_mul_f32_e32 v64, v63, v63
	v_fmamk_f32 v62, v64, 0x3e9b6dac, v235
	v_fmaak_f32 v227, v64, v62, 0x3f2aaada
	v_cvt_f32_i32_e32 v62, v72
	v_sub_f32_e32 v61, v63, v61
	v_ldexp_f32 v65, v63, 1
	v_mul_f32_e32 v63, v63, v64
	v_pk_mul_f32 v[68:69], v[62:63], v[226:227]
	v_sub_f32_e32 v58, v58, v61
	v_fma_f32 v64, v62, s56, -v68
	v_fmac_f32_e32 v64, 0xb102e308, v62
	v_pk_add_f32 v[62:63], v[68:69], v[64:65]
	v_ldexp_f32 v58, v58, 1
	v_sub_f32_e32 v61, v63, v65
	v_sub_f32_e32 v61, v69, v61
	v_add_f32_e32 v71, v58, v61
	v_mov_b32_e32 v70, v68
	v_pk_add_f32 v[68:69], v[62:63], v[68:69] neg_lo:[0,1] neg_hi:[0,1]
	v_pk_add_f32 v[72:73], v[62:63], v[70:71]
	v_mov_b32_e32 v65, v62
	v_mov_b32_e32 v69, v73
	v_pk_add_f32 v[74:75], v[64:65], v[68:69] neg_lo:[0,1] neg_hi:[0,1]
	v_pk_add_f32 v[64:65], v[64:65], v[68:69]
	v_mov_b32_e32 v70, v71
	v_pk_add_f32 v[68:69], v[64:65], v[62:63] op_sel:[1,0] op_sel_hi:[0,1] neg_lo:[0,1] neg_hi:[0,1]
	v_pk_add_f32 v[76:77], v[72:73], v[68:69] op_sel_hi:[1,0] neg_lo:[0,1] neg_hi:[0,1]
	v_mov_b32_e32 v72, v73
	v_mov_b32_e32 v73, v65
	v_pk_mov_b32 v[68:69], v[62:63], v[68:69] op_sel:[1,0]
	v_mov_b32_e32 v71, v62
	v_pk_add_f32 v[68:69], v[72:73], v[68:69] neg_lo:[0,1] neg_hi:[0,1]
	v_mov_b32_e32 v76, v74
	v_pk_add_f32 v[62:63], v[70:71], v[68:69] neg_lo:[0,1] neg_hi:[0,1]
	v_mov_b32_e32 v75, v65
	v_pk_add_f32 v[68:69], v[76:77], v[62:63]
	s_nop 0
	v_pk_add_f32 v[70:71], v[68:69], v[68:69] op_sel:[0,1] op_sel_hi:[1,0]
	s_nop 0
	v_pk_add_f32 v[64:65], v[64:65], v[70:71] op_sel:[1,0] op_sel_hi:[0,1]
	v_mov_b32_e32 v69, v64
	v_pk_add_f32 v[72:73], v[68:69], v[74:75] neg_lo:[0,1] neg_hi:[0,1]
	v_mov_b32_e32 v63, v70
	v_sub_f32_e32 v58, v68, v72
	v_pk_add_f32 v[62:63], v[62:63], v[72:73] neg_lo:[0,1] neg_hi:[0,1]
	v_sub_f32_e32 v58, v74, v58
	v_add_f32_e32 v58, v62, v58
	v_add_f32_e32 v58, v58, v63
	v_add_f32_e32 v58, v64, v58
	v_cndmask_b32_e32 v58, v236, v58, vcc
	v_cmp_ngt_f32_e32 vcc, -1.0, v57
	s_nop 1
	v_cndmask_b32_e32 v58, v237, v58, vcc
	v_cmp_neq_f32_e32 vcc, -1.0, v57
	s_nop 1
	v_cndmask_b32_e32 v58, v238, v58, vcc
	v_cmp_lt_f32_e64 vcc, |v57|, s58
	s_nop 1
	v_cndmask_b32_e32 v57, v58, v57, vcc
.LBB0_224:
	s_or_b64 exec, exec, s[36:37]
	v_mul_f32_e32 v54, 0x3fb8aa3b, v54
	v_exp_f32_e32 v54, v54
	s_nop 0
	v_mul_f32_e64 v58, v3, -v54
	v_mul_f32_e32 v3, 0x3fb8aa3b, v59
	v_exp_f32_e32 v3, v3
	s_nop 0
	v_mul_f32_e64 v59, v55, -v3
	v_mul_f32_e32 v3, 0x3fb8aa3b, v60
	v_exp_f32_e32 v3, v3
	s_nop 0
	v_mul_f32_e64 v60, v56, -v3
	v_mov_b32_e32 v3, v165
	v_mul_f32_e32 v3, 0x3fb8aa3b, v3
	v_exp_f32_e32 v3, v3
	s_nop 0
	v_mul_f32_e64 v61, v57, -v3

;     __device__ __forceinline__ void operator()(f32x4 (&acc)[2][2][4][2], const Unit& u, int row0t, int wr, int wc, int fr, int fq) const {
;     ...
;                                 for (int e = 0; e < 4; ++e) { const int h = 4 * n + e; const float xx = v[e] + dt_bias[h]; const float sp = xx > 20.f ? xx : log1pf(__expf(xx)); o[e] = -__expf(A_log[h]) * sp; } }
;                             *(f32x4*)(bg + (size_t)r * 16 + 8 * fq + 4 * n) = o; } }
.LBB0_227:
	s_or_b64 exec, exec, s[24:25]
	global_store_dwordx4 v[66:67], v[58:61], off offset:16
	s_and_saveexec_b64 s[2:3], s[4:5]
	s_xor_b64 s[24:25], exec, s[2:3]
	s_cbranch_execz .LBB0_237
	v_mov_b32_e32 v3, v150
	v_add_f32_e32 v3, v50, v3
	v_cmp_nlt_f32_e32 vcc, s53, v3
	s_and_saveexec_b64 s[36:37], vcc
	s_cbranch_execz .LBB0_230
	v_mul_f32_e32 v3, 0x3fb8aa3b, v3
	v_exp_f32_e32 v3, v3
	s_nop 0
	v_add_f32_e32 v50, 1.0, v3
	v_frexp_mant_f32_e32 v57, v50
	v_cvt_f64_f32_e32 v[54:55], v50
	v_add_f32_e32 v56, -1.0, v50
	v_frexp_exp_i32_f64_e32 v54, v[54:55]
	v_cmp_gt_f32_e32 vcc, s55, v57
	v_sub_f32_e32 v58, v56, v50
	v_sub_f32_e32 v56, v3, v56
	v_subbrev_co_u32_e32 v62, vcc, 0, v54, vcc
	v_add_f32_e32 v58, 1.0, v58
	v_sub_u32_e32 v54, 0, v62
	v_add_f32_e32 v56, v56, v58
	v_ldexp_f32 v50, v50, v54
	v_ldexp_f32 v54, v56, v54
	v_add_f32_e32 v56, -1.0, v50
	v_add_f32_e32 v55, 1.0, v56
	v_sub_f32_e32 v55, v50, v55
	v_add_f32_e32 v57, v54, v55
	v_add_f32_e32 v55, 1.0, v50
	v_add_f32_e32 v58, -1.0, v55
	v_sub_f32_e32 v50, v50, v58
	v_add_f32_e32 v50, v54, v50
	v_add_f32_e32 v63, v55, v50
	v_rcp_f32_e32 v64, v63
	v_sub_f32_e32 v54, v63, v55
	v_add_f32_e32 v55, v56, v57
	v_sub_f32_e32 v50, v50, v54
	v_mul_f32_e32 v66, v55, v64
	v_sub_f32_e32 v54, v55, v56
	v_mul_f32_e32 v56, v63, v66
	v_fma_f32 v58, v66, v63, -v56
	v_fmac_f32_e32 v58, v66, v50
	v_sub_f32_e32 v65, v57, v54
	v_add_f32_e32 v54, v56, v58
	v_sub_f32_e32 v57, v55, v54
	v_pk_add_f32 v[60:61], v[54:55], v[56:57] neg_lo:[0,1] neg_hi:[0,1]
	v_mov_b32_e32 v59, v54
	v_pk_add_f32 v[54:55], v[60:61], v[58:59] neg_lo:[0,1] neg_hi:[0,1]
	v_cmp_neq_f32_e32 vcc, s57, v3
	v_add_f32_e32 v55, v65, v55
	v_add_f32_e32 v54, v54, v55
	v_add_f32_e32 v55, v57, v54
	v_mul_f32_e32 v65, v64, v55
	v_mul_f32_e32 v56, v63, v65
	v_fma_f32 v58, v65, v63, -v56
	v_fmac_f32_e32 v58, v65, v50
	v_sub_f32_e32 v50, v57, v55
	v_add_f32_e32 v50, v54, v50
	v_add_f32_e32 v54, v56, v58
	v_sub_f32_e32 v57, v55, v54
	v_pk_add_f32 v[60:61], v[54:55], v[56:57] neg_lo:[0,1] neg_hi:[0,1]
	v_mov_b32_e32 v59, v54
	v_pk_add_f32 v[54:55], v[60:61], v[58:59] neg_lo:[0,1] neg_hi:[0,1]
	s_nop 0
	v_add_f32_e32 v50, v50, v55
	v_add_f32_e32 v50, v54, v50
	v_add_f32_e32 v55, v66, v65
	v_add_f32_e32 v50, v57, v50
	v_sub_f32_e32 v54, v55, v66
	v_mul_f32_e32 v50, v64, v50
	v_sub_f32_e32 v54, v65, v54
	v_add_f32_e32 v50, v54, v50
	v_add_f32_e32 v56, v55, v50
	v_mul_f32_e32 v58, v56, v56
	v_fmamk_f32 v54, v58, 0x3e9b6dac, v235
	v_fmaak_f32 v227, v58, v54, 0x3f2aaada
	v_cvt_f32_i32_e32 v54, v62
	v_sub_f32_e32 v55, v56, v55
	v_sub_f32_e32 v50, v50, v55
	v_mul_f32_e32 v55, v56, v58
	v_pk_mul_f32 v[58:59], v[54:55], v[226:227]
	v_ldexp_f32 v57, v56, 1
	v_fma_f32 v56, v54, s56, -v58
	v_fmac_f32_e32 v56, 0xb102e308, v54
	v_pk_add_f32 v[54:55], v[58:59], v[56:57]
	v_ldexp_f32 v50, v50, 1
	v_sub_f32_e32 v57, v55, v57
	v_sub_f32_e32 v57, v59, v57
	v_add_f32_e32 v61, v50, v57
	v_mov_b32_e32 v60, v58
	v_pk_add_f32 v[58:59], v[54:55], v[58:59] neg_lo:[0,1] neg_hi:[0,1]
	v_pk_add_f32 v[62:63], v[54:55], v[60:61]
	v_mov_b32_e32 v57, v54
	v_mov_b32_e32 v59, v63
	v_pk_add_f32 v[64:65], v[56:57], v[58:59] neg_lo:[0,1] neg_hi:[0,1]
	v_pk_add_f32 v[56:57], v[56:57], v[58:59]
	v_mov_b32_e32 v60, v61
	v_pk_add_f32 v[58:59], v[56:57], v[54:55] op_sel:[1,0] op_sel_hi:[0,1] neg_lo:[0,1] neg_hi:[0,1]
	v_pk_add_f32 v[66:67], v[62:63], v[58:59] op_sel_hi:[1,0] neg_lo:[0,1] neg_hi:[0,1]
	v_mov_b32_e32 v62, v63
	v_mov_b32_e32 v63, v57
	v_pk_mov_b32 v[58:59], v[54:55], v[58:59] op_sel:[1,0]
	v_mov_b32_e32 v61, v54
	v_pk_add_f32 v[58:59], v[62:63], v[58:59] neg_lo:[0,1] neg_hi:[0,1]
	v_mov_b32_e32 v66, v64
	v_pk_add_f32 v[54:55], v[60:61], v[58:59] neg_lo:[0,1] neg_hi:[0,1]
	v_mov_b32_e32 v65, v57
	v_pk_add_f32 v[58:59], v[66:67], v[54:55]
	s_nop 0
	v_pk_add_f32 v[60:61], v[58:59], v[58:59] op_sel:[0,1] op_sel_hi:[1,0]
	s_nop 0
	v_pk_add_f32 v[56:57], v[56:57], v[60:61] op_sel:[1,0] op_sel_hi:[0,1]
	v_mov_b32_e32 v59, v56
	v_pk_add_f32 v[62:63], v[58:59], v[64:65] neg_lo:[0,1] neg_hi:[0,1]
	v_mov_b32_e32 v55, v60
	v_sub_f32_e32 v50, v58, v62
	v_pk_add_f32 v[54:55], v[54:55], v[62:63] neg_lo:[0,1] neg_hi:[0,1]
	v_sub_f32_e32 v50, v64, v50
	v_add_f32_e32 v50, v54, v50
	v_add_f32_e32 v50, v50, v55
	v_add_f32_e32 v50, v56, v50
	v_cndmask_b32_e32 v50, v236, v50, vcc
	v_cmp_ngt_f32_e32 vcc, -1.0, v3
	s_nop 1
	v_cndmask_b32_e32 v50, v237, v50, vcc
	v_cmp_neq_f32_e32 vcc, -1.0, v3
	s_nop 1
	v_cndmask_b32_e32 v50, v238, v50, vcc
	v_cmp_lt_f32_e64 vcc, |v3|, s58
	s_nop 1
	v_cndmask_b32_e32 v3, v50, v3, vcc
;     __device__ __forceinline__ void operator()(f32x4 (&acc)[2][2][4][2], const Unit& u, int row0t, int wr, int wc, int fr, int fq) const {
;     ...
;                                 for (int e = 0; e < 4; ++e) { const int h = 4 * n + e; const float xx = v[e] + dt_bias[h]; const float sp = xx > 20.f ? xx : log1pf(__expf(xx)); o[e] = -__expf(A_log[h]) * sp; } }
.LBB0_230:
	s_or_b64 exec, exec, s[36:37]
	v_mov_b32_e32 v54, v151
	v_mov_b32_e32 v50, v158
	v_add_f32_e32 v51, v51, v54
	v_cmp_nlt_f32_e32 vcc, s53, v51
	s_and_saveexec_b64 s[36:37], vcc
	s_cbranch_execz .LBB0_232
	v_mul_f32_e32 v51, 0x3fb8aa3b, v51
	v_exp_f32_e32 v51, v51
	s_nop 0
	v_add_f32_e32 v56, 1.0, v51
	v_frexp_mant_f32_e32 v58, v56
	v_cvt_f64_f32_e32 v[54:55], v56
	v_frexp_exp_i32_f64_e32 v54, v[54:55]
	v_cmp_gt_f32_e32 vcc, s55, v58
	v_add_f32_e32 v57, -1.0, v56
	v_sub_f32_e32 v59, v57, v56
	v_subbrev_co_u32_e32 v62, vcc, 0, v54, vcc
	v_sub_u32_e32 v54, 0, v62
	v_sub_f32_e32 v57, v51, v57
	v_add_f32_e32 v59, 1.0, v59
	v_ldexp_f32 v55, v56, v54
	v_add_f32_e32 v57, v57, v59
	v_add_f32_e32 v56, -1.0, v55
	v_add_f32_e32 v58, 1.0, v55
	v_ldexp_f32 v54, v57, v54
	v_add_f32_e32 v57, 1.0, v56
	v_add_f32_e32 v59, -1.0, v58
	v_sub_f32_e32 v57, v55, v57
	v_sub_f32_e32 v55, v55, v59
	v_add_f32_e32 v57, v54, v57
	v_add_f32_e32 v54, v54, v55
	v_add_f32_e32 v63, v58, v54
	v_rcp_f32_e32 v65, v63
	v_sub_f32_e32 v55, v63, v58
	v_sub_f32_e32 v64, v54, v55
	v_add_f32_e32 v55, v56, v57
	v_mul_f32_e32 v67, v55, v65
	v_sub_f32_e32 v54, v55, v56
	v_mul_f32_e32 v56, v63, v67
	v_fma_f32 v58, v67, v63, -v56
	v_fmac_f32_e32 v58, v67, v64
	v_sub_f32_e32 v66, v57, v54
	v_add_f32_e32 v54, v56, v58
	v_sub_f32_e32 v57, v55, v54
	v_pk_add_f32 v[60:61], v[54:55], v[56:57] neg_lo:[0,1] neg_hi:[0,1]
	v_mov_b32_e32 v59, v54
	v_pk_add_f32 v[54:55], v[60:61], v[58:59] neg_lo:[0,1] neg_hi:[0,1]
	v_cmp_neq_f32_e32 vcc, s57, v51
	v_add_f32_e32 v55, v66, v55
	v_add_f32_e32 v54, v54, v55
	v_add_f32_e32 v55, v57, v54
	v_mul_f32_e32 v66, v65, v55
	v_mul_f32_e32 v56, v63, v66
	v_fma_f32 v58, v66, v63, -v56
	v_fmac_f32_e32 v58, v66, v64
	v_sub_f32_e32 v57, v57, v55
	v_add_f32_e32 v63, v54, v57
	v_add_f32_e32 v54, v56, v58
	v_sub_f32_e32 v57, v55, v54
	v_pk_add_f32 v[60:61], v[54:55], v[56:57] neg_lo:[0,1] neg_hi:[0,1]
	v_mov_b32_e32 v59, v54
	v_pk_add_f32 v[54:55], v[60:61], v[58:59] neg_lo:[0,1] neg_hi:[0,1]
	s_nop 0
	v_add_f32_e32 v55, v63, v55
	v_add_f32_e32 v54, v54, v55
	v_add_f32_e32 v55, v67, v66
	v_add_f32_e32 v54, v57, v54
	v_sub_f32_e32 v56, v55, v67
	v_mul_f32_e32 v54, v65, v54
	v_sub_f32_e32 v56, v66, v56
	v_add_f32_e32 v56, v56, v54
	v_add_f32_e32 v58, v55, v56
	v_mul_f32_e32 v59, v58, v58
	v_fmamk_f32 v54, v59, 0x3e9b6dac, v235
	v_fmaak_f32 v227, v59, v54, 0x3f2aaada
	v_cvt_f32_i32_e32 v54, v62
	v_sub_f32_e32 v55, v58, v55
	v_sub_f32_e32 v55, v56, v55
	v_ldexp_f32 v60, v55, 1
	v_mul_f32_e32 v55, v58, v59
	v_ldexp_f32 v57, v58, 1
	v_pk_mul_f32 v[58:59], v[54:55], v[226:227]
	s_nop 0
	v_fma_f32 v56, v54, s56, -v58
	v_fmac_f32_e32 v56, 0xb102e308, v54
	v_pk_add_f32 v[54:55], v[58:59], v[56:57]
	s_nop 0
	v_sub_f32_e32 v57, v55, v57
	v_sub_f32_e32 v57, v59, v57
	v_add_f32_e32 v61, v60, v57
	v_mov_b32_e32 v60, v58
	v_pk_add_f32 v[58:59], v[54:55], v[58:59] neg_lo:[0,1] neg_hi:[0,1]
	v_pk_add_f32 v[62:63], v[54:55], v[60:61]
	v_mov_b32_e32 v57, v54
	v_mov_b32_e32 v59, v63
	v_pk_add_f32 v[64:65], v[56:57], v[58:59] neg_lo:[0,1] neg_hi:[0,1]
	v_pk_add_f32 v[56:57], v[56:57], v[58:59]
	v_mov_b32_e32 v60, v61
	v_pk_add_f32 v[58:59], v[56:57], v[54:55] op_sel:[1,0] op_sel_hi:[0,1] neg_lo:[0,1] neg_hi:[0,1]
	v_pk_add_f32 v[66:67], v[62:63], v[58:59] op_sel_hi:[1,0] neg_lo:[0,1] neg_hi:[0,1]
	v_mov_b32_e32 v62, v63
	v_mov_b32_e32 v63, v57
	v_pk_mov_b32 v[58:59], v[54:55], v[58:59] op_sel:[1,0]
	v_mov_b32_e32 v61, v54
	v_pk_add_f32 v[58:59], v[62:63], v[58:59] neg_lo:[0,1] neg_hi:[0,1]
	v_mov_b32_e32 v66, v64
	v_pk_add_f32 v[54:55], v[60:61], v[58:59] neg_lo:[0,1] neg_hi:[0,1]
	v_mov_b32_e32 v65, v57
	v_pk_add_f32 v[58:59], v[66:67], v[54:55]
	s_nop 0
	v_pk_add_f32 v[60:61], v[58:59], v[58:59] op_sel:[0,1] op_sel_hi:[1,0]
	s_nop 0
	v_pk_add_f32 v[56:57], v[56:57], v[60:61] op_sel:[1,0] op_sel_hi:[0,1]
	v_mov_b32_e32 v59, v56
	v_pk_add_f32 v[62:63], v[58:59], v[64:65] neg_lo:[0,1] neg_hi:[0,1]
	v_mov_b32_e32 v55, v60
	v_sub_f32_e32 v57, v58, v62
	v_pk_add_f32 v[54:55], v[54:55], v[62:63] neg_lo:[0,1] neg_hi:[0,1]
	v_sub_f32_e32 v57, v64, v57
	v_add_f32_e32 v54, v54, v57
	v_add_f32_e32 v54, v54, v55
	v_add_f32_e32 v54, v56, v54
	v_cndmask_b32_e32 v54, v236, v54, vcc
	v_cmp_ngt_f32_e32 vcc, -1.0, v51
	s_nop 1
	v_cndmask_b32_e32 v54, v237, v54, vcc
	v_cmp_neq_f32_e32 vcc, -1.0, v51
	s_nop 1
	v_cndmask_b32_e32 v54, v238, v54, vcc
	v_cmp_lt_f32_e64 vcc, |v51|, s58
	s_nop 1
	v_cndmask_b32_e32 v51, v54, v51, vcc
;     __device__ __forceinline__ void operator()(f32x4 (&acc)[2][2][4][2], const Unit& u, int row0t, int wr, int wc, int fr, int fq) const {
;     ...
;                                 for (int e = 0; e < 4; ++e) { const int h = 4 * n + e; const float xx = v[e] + dt_bias[h]; const float sp = xx > 20.f ? xx : log1pf(__expf(xx)); o[e] = -__expf(A_log[h]) * sp; } }
.LBB0_232:
	s_or_b64 exec, exec, s[36:37]
	v_mov_b32_e32 v54, v152
	v_mov_b32_e32 v55, v159
	v_add_f32_e32 v52, v52, v54
	v_cmp_nlt_f32_e32 vcc, s53, v52
	s_and_saveexec_b64 s[36:37], vcc
	s_cbranch_execz .LBB0_234
	v_mul_f32_e32 v52, 0x3fb8aa3b, v52
	v_exp_f32_e32 v52, v52
	s_nop 0
	v_add_f32_e32 v54, 1.0, v52
	v_frexp_mant_f32_e32 v59, v54
	v_cvt_f64_f32_e32 v[56:57], v54
	v_add_f32_e32 v58, -1.0, v54
	v_frexp_exp_i32_f64_e32 v56, v[56:57]
	v_cmp_gt_f32_e32 vcc, s55, v59
	v_sub_f32_e32 v60, v58, v54
	v_sub_f32_e32 v58, v52, v58
	v_subbrev_co_u32_e32 v64, vcc, 0, v56, vcc
	v_add_f32_e32 v60, 1.0, v60
	v_sub_u32_e32 v56, 0, v64
	v_add_f32_e32 v58, v58, v60
	v_ldexp_f32 v54, v54, v56
	v_ldexp_f32 v56, v58, v56
	v_add_f32_e32 v58, -1.0, v54
	v_add_f32_e32 v57, 1.0, v58
	v_sub_f32_e32 v57, v54, v57
	v_add_f32_e32 v59, v56, v57
	v_add_f32_e32 v57, 1.0, v54
	v_add_f32_e32 v60, -1.0, v57
	v_sub_f32_e32 v54, v54, v60
	v_add_f32_e32 v54, v56, v54
	v_add_f32_e32 v65, v57, v54
	v_rcp_f32_e32 v66, v65
	v_sub_f32_e32 v56, v65, v57
	v_add_f32_e32 v57, v58, v59
	v_sub_f32_e32 v54, v54, v56
	v_mul_f32_e32 v68, v57, v66
	v_sub_f32_e32 v56, v57, v58
	v_mul_f32_e32 v58, v65, v68
	v_fma_f32 v60, v68, v65, -v58
	v_fmac_f32_e32 v60, v68, v54
	v_sub_f32_e32 v67, v59, v56
	v_add_f32_e32 v56, v58, v60
	v_sub_f32_e32 v59, v57, v56
	v_pk_add_f32 v[62:63], v[56:57], v[58:59] neg_lo:[0,1] neg_hi:[0,1]
	v_mov_b32_e32 v61, v56
	v_pk_add_f32 v[56:57], v[62:63], v[60:61] neg_lo:[0,1] neg_hi:[0,1]
	v_cmp_neq_f32_e32 vcc, s57, v52
	v_add_f32_e32 v57, v67, v57
	v_add_f32_e32 v56, v56, v57
	v_add_f32_e32 v57, v59, v56
	v_mul_f32_e32 v67, v66, v57
	v_mul_f32_e32 v58, v65, v67
	v_fma_f32 v60, v67, v65, -v58
	v_fmac_f32_e32 v60, v67, v54
	v_sub_f32_e32 v54, v59, v57
	v_add_f32_e32 v54, v56, v54
	v_add_f32_e32 v56, v58, v60
	v_sub_f32_e32 v59, v57, v56
	v_pk_add_f32 v[62:63], v[56:57], v[58:59] neg_lo:[0,1] neg_hi:[0,1]
	v_mov_b32_e32 v61, v56
	v_pk_add_f32 v[56:57], v[62:63], v[60:61] neg_lo:[0,1] neg_hi:[0,1]
	s_nop 0
	v_add_f32_e32 v54, v54, v57
	v_add_f32_e32 v54, v56, v54
	v_add_f32_e32 v57, v68, v67
	v_add_f32_e32 v54, v59, v54
	v_sub_f32_e32 v56, v57, v68
	v_mul_f32_e32 v54, v66, v54
	v_sub_f32_e32 v56, v67, v56
	v_add_f32_e32 v54, v56, v54
	v_add_f32_e32 v58, v57, v54
	v_mul_f32_e32 v60, v58, v58
	v_fmamk_f32 v56, v60, 0x3e9b6dac, v235
	v_fmaak_f32 v227, v60, v56, 0x3f2aaada
	v_cvt_f32_i32_e32 v56, v64
	v_sub_f32_e32 v57, v58, v57
	v_sub_f32_e32 v54, v54, v57
	v_mul_f32_e32 v57, v58, v60
	v_pk_mul_f32 v[60:61], v[56:57], v[226:227]
	v_ldexp_f32 v59, v58, 1
	v_fma_f32 v58, v56, s56, -v60
	v_fmac_f32_e32 v58, 0xb102e308, v56
	v_pk_add_f32 v[56:57], v[60:61], v[58:59]
	v_ldexp_f32 v54, v54, 1
	v_sub_f32_e32 v59, v57, v59
	v_sub_f32_e32 v59, v61, v59
	v_add_f32_e32 v63, v54, v59
	v_mov_b32_e32 v62, v60
	v_pk_add_f32 v[60:61], v[56:57], v[60:61] neg_lo:[0,1] neg_hi:[0,1]
	v_pk_add_f32 v[64:65], v[56:57], v[62:63]
	v_mov_b32_e32 v59, v56
	v_mov_b32_e32 v61, v65
	v_pk_add_f32 v[66:67], v[58:59], v[60:61] neg_lo:[0,1] neg_hi:[0,1]
	v_pk_add_f32 v[58:59], v[58:59], v[60:61]
	v_mov_b32_e32 v62, v63
	v_pk_add_f32 v[60:61], v[58:59], v[56:57] op_sel:[1,0] op_sel_hi:[0,1] neg_lo:[0,1] neg_hi:[0,1]
	v_pk_add_f32 v[68:69], v[64:65], v[60:61] op_sel_hi:[1,0] neg_lo:[0,1] neg_hi:[0,1]
	v_mov_b32_e32 v64, v65
	v_mov_b32_e32 v65, v59
	v_pk_mov_b32 v[60:61], v[56:57], v[60:61] op_sel:[1,0]
	v_mov_b32_e32 v63, v56
	v_pk_add_f32 v[60:61], v[64:65], v[60:61] neg_lo:[0,1] neg_hi:[0,1]
	v_mov_b32_e32 v68, v66
	v_pk_add_f32 v[56:57], v[62:63], v[60:61] neg_lo:[0,1] neg_hi:[0,1]
	v_mov_b32_e32 v67, v59
	v_pk_add_f32 v[60:61], v[68:69], v[56:57]
	s_nop 0
	v_pk_add_f32 v[62:63], v[60:61], v[60:61] op_sel:[0,1] op_sel_hi:[1,0]
	s_nop 0
	v_pk_add_f32 v[58:59], v[58:59], v[62:63] op_sel:[1,0] op_sel_hi:[0,1]
	v_mov_b32_e32 v61, v58
	v_pk_add_f32 v[64:65], v[60:61], v[66:67] neg_lo:[0,1] neg_hi:[0,1]
	v_mov_b32_e32 v57, v62
	v_sub_f32_e32 v54, v60, v64
	v_pk_add_f32 v[56:57], v[56:57], v[64:65] neg_lo:[0,1] neg_hi:[0,1]
	v_sub_f32_e32 v54, v66, v54
	v_add_f32_e32 v54, v56, v54
	v_add_f32_e32 v54, v54, v57
	v_add_f32_e32 v54, v58, v54
	v_cndmask_b32_e32 v54, v236, v54, vcc
	v_cmp_ngt_f32_e32 vcc, -1.0, v52
	s_nop 1
	v_cndmask_b32_e32 v54, v237, v54, vcc
	v_cmp_neq_f32_e32 vcc, -1.0, v52
	s_nop 1
	v_cndmask_b32_e32 v54, v238, v54, vcc
	v_cmp_lt_f32_e64 vcc, |v52|, s58
	s_nop 1
	v_cndmask_b32_e32 v52, v54, v52, vcc
;     __device__ __forceinline__ void operator()(f32x4 (&acc)[2][2][4][2], const Unit& u, int row0t, int wr, int wc, int fr, int fq) const {
;     ...
;                                 for (int e = 0; e < 4; ++e) { const int h = 4 * n + e; const float xx = v[e] + dt_bias[h]; const float sp = xx > 20.f ? xx : log1pf(__expf(xx)); o[e] = -__expf(A_log[h]) * sp; } }
.LBB0_234:
	s_or_b64 exec, exec, s[36:37]
	v_mov_b32_e32 v54, v153
	v_mov_b32_e32 v56, v160
	v_add_f32_e32 v53, v53, v54
	v_cmp_nlt_f32_e32 vcc, s53, v53
	s_and_saveexec_b64 s[36:37], vcc
	s_cbranch_execz .LBB0_236
	v_mul_f32_e32 v53, 0x3fb8aa3b, v53
	v_exp_f32_e32 v53, v53
	s_nop 0
	v_add_f32_e32 v54, 1.0, v53
	v_frexp_mant_f32_e32 v60, v54
	v_cvt_f64_f32_e32 v[58:59], v54
	v_add_f32_e32 v57, -1.0, v54
	v_frexp_exp_i32_f64_e32 v58, v[58:59]
	v_cmp_gt_f32_e32 vcc, s55, v60
	v_sub_f32_e32 v61, v57, v54
	v_sub_f32_e32 v57, v53, v57
	v_subbrev_co_u32_e32 v66, vcc, 0, v58, vcc
	v_add_f32_e32 v61, 1.0, v61
	v_sub_u32_e32 v58, 0, v66
	v_add_f32_e32 v57, v57, v61
	v_ldexp_f32 v54, v54, v58
	v_ldexp_f32 v57, v57, v58
	v_add_f32_e32 v58, -1.0, v54
	v_add_f32_e32 v59, 1.0, v58
	v_sub_f32_e32 v59, v54, v59
	v_add_f32_e32 v60, v57, v59
	v_add_f32_e32 v59, 1.0, v54
	v_add_f32_e32 v61, -1.0, v59
	v_sub_f32_e32 v54, v54, v61
	v_add_f32_e32 v54, v57, v54
	v_add_f32_e32 v57, v59, v54
	v_rcp_f32_e32 v67, v57
	v_sub_f32_e32 v59, v57, v59
	v_sub_f32_e32 v54, v54, v59
	v_add_f32_e32 v59, v58, v60
	v_sub_f32_e32 v58, v59, v58
	v_mul_f32_e32 v69, v59, v67
	v_sub_f32_e32 v68, v60, v58
	v_mul_f32_e32 v60, v57, v69
	v_fma_f32 v62, v69, v57, -v60
	v_fmac_f32_e32 v62, v69, v54
	v_add_f32_e32 v58, v60, v62
	v_sub_f32_e32 v61, v59, v58
	v_pk_add_f32 v[64:65], v[58:59], v[60:61] neg_lo:[0,1] neg_hi:[0,1]
	v_mov_b32_e32 v63, v58
	v_pk_add_f32 v[58:59], v[64:65], v[62:63] neg_lo:[0,1] neg_hi:[0,1]
	v_cmp_neq_f32_e32 vcc, s57, v53
	v_add_f32_e32 v59, v68, v59
	v_add_f32_e32 v58, v58, v59
	v_add_f32_e32 v59, v61, v58
	v_mul_f32_e32 v68, v67, v59
	v_mul_f32_e32 v60, v57, v68
	v_fma_f32 v62, v68, v57, -v60
	v_fmac_f32_e32 v62, v68, v54
	v_sub_f32_e32 v54, v61, v59
	v_add_f32_e32 v54, v58, v54
	v_add_f32_e32 v58, v60, v62
	v_sub_f32_e32 v61, v59, v58
	v_pk_add_f32 v[64:65], v[58:59], v[60:61] neg_lo:[0,1] neg_hi:[0,1]
	v_mov_b32_e32 v63, v58
	v_pk_add_f32 v[58:59], v[64:65], v[62:63] neg_lo:[0,1] neg_hi:[0,1]
	v_add_f32_e32 v57, v69, v68
	v_add_f32_e32 v54, v54, v59
	v_add_f32_e32 v54, v58, v54
	v_add_f32_e32 v54, v61, v54
	v_sub_f32_e32 v58, v57, v69
	v_mul_f32_e32 v54, v67, v54
	v_sub_f32_e32 v58, v68, v58
	v_add_f32_e32 v54, v58, v54
	v_add_f32_e32 v59, v57, v54
	v_mul_f32_e32 v60, v59, v59
	v_fmamk_f32 v58, v60, 0x3e9b6dac, v235
	v_fmaak_f32 v227, v60, v58, 0x3f2aaada
	v_cvt_f32_i32_e32 v58, v66
	v_sub_f32_e32 v57, v59, v57
	v_ldexp_f32 v61, v59, 1
	v_mul_f32_e32 v59, v59, v60
	v_pk_mul_f32 v[62:63], v[58:59], v[226:227]
	v_sub_f32_e32 v54, v54, v57
	v_fma_f32 v60, v58, s56, -v62
	v_fmac_f32_e32 v60, 0xb102e308, v58
	v_pk_add_f32 v[58:59], v[62:63], v[60:61]
	v_ldexp_f32 v54, v54, 1
	v_sub_f32_e32 v57, v59, v61
	v_sub_f32_e32 v57, v63, v57
	v_add_f32_e32 v65, v54, v57
	v_mov_b32_e32 v64, v62
	v_pk_add_f32 v[62:63], v[58:59], v[62:63] neg_lo:[0,1] neg_hi:[0,1]
	v_pk_add_f32 v[66:67], v[58:59], v[64:65]
	v_mov_b32_e32 v61, v58
	v_mov_b32_e32 v63, v67
	v_pk_add_f32 v[68:69], v[60:61], v[62:63] neg_lo:[0,1] neg_hi:[0,1]
	v_pk_add_f32 v[60:61], v[60:61], v[62:63]
	v_mov_b32_e32 v64, v65
	v_pk_add_f32 v[62:63], v[60:61], v[58:59] op_sel:[1,0] op_sel_hi:[0,1] neg_lo:[0,1] neg_hi:[0,1]
	v_pk_add_f32 v[70:71], v[66:67], v[62:63] op_sel_hi:[1,0] neg_lo:[0,1] neg_hi:[0,1]
	v_mov_b32_e32 v66, v67
	v_mov_b32_e32 v67, v61
	v_pk_mov_b32 v[62:63], v[58:59], v[62:63] op_sel:[1,0]
	v_mov_b32_e32 v65, v58
	v_pk_add_f32 v[62:63], v[66:67], v[62:63] neg_lo:[0,1] neg_hi:[0,1]
	v_mov_b32_e32 v70, v68
	v_pk_add_f32 v[58:59], v[64:65], v[62:63] neg_lo:[0,1] neg_hi:[0,1]
	v_mov_b32_e32 v69, v61
	v_pk_add_f32 v[62:63], v[70:71], v[58:59]
	s_nop 0
	v_pk_add_f32 v[64:65], v[62:63], v[62:63] op_sel:[0,1] op_sel_hi:[1,0]
	s_nop 0
	v_pk_add_f32 v[60:61], v[60:61], v[64:65] op_sel:[1,0] op_sel_hi:[0,1]
	v_mov_b32_e32 v63, v60
	v_pk_add_f32 v[66:67], v[62:63], v[68:69] neg_lo:[0,1] neg_hi:[0,1]
	v_mov_b32_e32 v59, v64
	v_sub_f32_e32 v54, v62, v66
	v_pk_add_f32 v[58:59], v[58:59], v[66:67] neg_lo:[0,1] neg_hi:[0,1]
	v_sub_f32_e32 v54, v68, v54
	v_add_f32_e32 v54, v58, v54
	v_add_f32_e32 v54, v54, v59
	v_add_f32_e32 v54, v60, v54
	v_cndmask_b32_e32 v54, v236, v54, vcc
	v_cmp_ngt_f32_e32 vcc, -1.0, v53
	s_nop 1
	v_cndmask_b32_e32 v54, v237, v54, vcc
	v_cmp_neq_f32_e32 vcc, -1.0, v53
	s_nop 1
	v_cndmask_b32_e32 v54, v238, v54, vcc
	v_cmp_lt_f32_e64 vcc, |v53|, s58
	s_nop 1
	v_cndmask_b32_e32 v53, v54, v53, vcc
.LBB0_236:
	s_or_b64 exec, exec, s[36:37]
	v_mul_f32_e32 v50, 0x3fb8aa3b, v50
	v_exp_f32_e32 v50, v50
	s_nop 0
	v_mul_f32_e64 v54, v3, -v50
	v_mul_f32_e32 v3, 0x3fb8aa3b, v55
	v_exp_f32_e32 v3, v3
	s_nop 0
	v_mul_f32_e64 v55, v51, -v3
	v_mul_f32_e32 v3, 0x3fb8aa3b, v56
	v_exp_f32_e32 v3, v3
	s_nop 0
	v_mul_f32_e64 v56, v52, -v3
	v_mov_b32_e32 v3, v161
	v_mul_f32_e32 v3, 0x3fb8aa3b, v3
	v_exp_f32_e32 v3, v3
	s_nop 0
	v_mul_f32_e64 v57, v53, -v3

;     __device__ __forceinline__ void operator()(f32x4 (&acc)[2][2][4][2], const Unit& u, int row0t, int wr, int wc, int fr, int fq) const {
;     ...
;                                 for (int e = 0; e < 4; ++e) { const int h = 4 * n + e; const float xx = v[e] + dt_bias[h]; const float sp = xx > 20.f ? xx : log1pf(__expf(xx)); o[e] = -__expf(A_log[h]) * sp; } }
;                             *(f32x4*)(bg + (size_t)r * 16 + 8 * fq + 4 * n) = o; } }
.LBB0_239:
	s_or_b64 exec, exec, s[24:25]
	v_or_b32_e32 v50, 32, v4
	v_ashrrev_i32_e32 v51, 31, v50
	v_lshlrev_b64 v[50:51], 6, v[50:51]
	v_lshl_add_u64 v[58:59], v[214:215], 0, v[50:51]
	global_store_dwordx4 v[58:59], v[54:57], off
	s_and_saveexec_b64 s[2:3], s[4:5]
	s_xor_b64 s[24:25], exec, s[2:3]
	s_cbranch_execz .LBB0_249
	v_mov_b32_e32 v3, v154
	v_add_f32_e32 v3, v46, v3
	v_cmp_nlt_f32_e32 vcc, s53, v3
	s_and_saveexec_b64 s[36:37], vcc
	s_cbranch_execz .LBB0_242
	v_mul_f32_e32 v3, 0x3fb8aa3b, v3
	v_exp_f32_e32 v3, v3
	s_nop 0
	v_add_f32_e32 v46, 1.0, v3
	v_frexp_mant_f32_e32 v53, v46
	v_cvt_f64_f32_e32 v[50:51], v46
	v_add_f32_e32 v52, -1.0, v46
	v_frexp_exp_i32_f64_e32 v50, v[50:51]
	v_cmp_gt_f32_e32 vcc, s55, v53
	v_sub_f32_e32 v54, v52, v46
	v_sub_f32_e32 v52, v3, v52
	v_subbrev_co_u32_e32 v60, vcc, 0, v50, vcc
	v_add_f32_e32 v54, 1.0, v54
	v_sub_u32_e32 v50, 0, v60
	v_add_f32_e32 v52, v52, v54
	v_ldexp_f32 v46, v46, v50
	v_ldexp_f32 v50, v52, v50
	v_add_f32_e32 v52, -1.0, v46
	v_add_f32_e32 v51, 1.0, v52
	v_sub_f32_e32 v51, v46, v51
	v_add_f32_e32 v53, v50, v51
	v_add_f32_e32 v51, 1.0, v46
	v_add_f32_e32 v54, -1.0, v51
	v_sub_f32_e32 v46, v46, v54
	v_add_f32_e32 v46, v50, v46
	v_add_f32_e32 v61, v51, v46
	v_rcp_f32_e32 v62, v61
	v_sub_f32_e32 v50, v61, v51
	v_add_f32_e32 v51, v52, v53
	v_sub_f32_e32 v46, v46, v50
	v_mul_f32_e32 v64, v51, v62
	v_sub_f32_e32 v50, v51, v52
	v_mul_f32_e32 v52, v61, v64
	v_fma_f32 v54, v64, v61, -v52
	v_fmac_f32_e32 v54, v64, v46
	v_sub_f32_e32 v63, v53, v50
	v_add_f32_e32 v50, v52, v54
	v_sub_f32_e32 v53, v51, v50
	v_pk_add_f32 v[56:57], v[50:51], v[52:53] neg_lo:[0,1] neg_hi:[0,1]
	v_mov_b32_e32 v55, v50
	v_pk_add_f32 v[50:51], v[56:57], v[54:55] neg_lo:[0,1] neg_hi:[0,1]
	v_cmp_neq_f32_e32 vcc, s57, v3
	v_add_f32_e32 v51, v63, v51
	v_add_f32_e32 v50, v50, v51
	v_add_f32_e32 v51, v53, v50
	v_mul_f32_e32 v63, v62, v51
	v_mul_f32_e32 v52, v61, v63
	v_fma_f32 v54, v63, v61, -v52
	v_fmac_f32_e32 v54, v63, v46
	v_sub_f32_e32 v46, v53, v51
	v_add_f32_e32 v46, v50, v46
	v_add_f32_e32 v50, v52, v54
	v_sub_f32_e32 v53, v51, v50
	v_pk_add_f32 v[56:57], v[50:51], v[52:53] neg_lo:[0,1] neg_hi:[0,1]
	v_mov_b32_e32 v55, v50
	v_pk_add_f32 v[50:51], v[56:57], v[54:55] neg_lo:[0,1] neg_hi:[0,1]
	s_nop 0
	v_add_f32_e32 v46, v46, v51
	v_add_f32_e32 v46, v50, v46
	v_add_f32_e32 v51, v64, v63
	v_add_f32_e32 v46, v53, v46
	v_sub_f32_e32 v50, v51, v64
	v_mul_f32_e32 v46, v62, v46
	v_sub_f32_e32 v50, v63, v50
	v_add_f32_e32 v46, v50, v46
	v_add_f32_e32 v52, v51, v46
	v_mul_f32_e32 v54, v52, v52
	v_fmamk_f32 v50, v54, 0x3e9b6dac, v235
	v_fmaak_f32 v227, v54, v50, 0x3f2aaada
	v_cvt_f32_i32_e32 v50, v60
	v_sub_f32_e32 v51, v52, v51
	v_sub_f32_e32 v46, v46, v51
	v_mul_f32_e32 v51, v52, v54
	v_pk_mul_f32 v[54:55], v[50:51], v[226:227]
	v_ldexp_f32 v53, v52, 1
	v_fma_f32 v52, v50, s56, -v54
	v_fmac_f32_e32 v52, 0xb102e308, v50
	v_pk_add_f32 v[50:51], v[54:55], v[52:53]
	v_ldexp_f32 v46, v46, 1
	v_sub_f32_e32 v53, v51, v53
	v_sub_f32_e32 v53, v55, v53
	v_add_f32_e32 v57, v46, v53
	v_mov_b32_e32 v56, v54
	v_pk_add_f32 v[54:55], v[50:51], v[54:55] neg_lo:[0,1] neg_hi:[0,1]
	v_pk_add_f32 v[60:61], v[50:51], v[56:57]
	v_mov_b32_e32 v53, v50
	v_mov_b32_e32 v55, v61
	v_pk_add_f32 v[62:63], v[52:53], v[54:55] neg_lo:[0,1] neg_hi:[0,1]
	v_pk_add_f32 v[52:53], v[52:53], v[54:55]
	v_mov_b32_e32 v56, v57
	v_pk_add_f32 v[54:55], v[52:53], v[50:51] op_sel:[1,0] op_sel_hi:[0,1] neg_lo:[0,1] neg_hi:[0,1]
	v_pk_add_f32 v[64:65], v[60:61], v[54:55] op_sel_hi:[1,0] neg_lo:[0,1] neg_hi:[0,1]
	v_mov_b32_e32 v60, v61
	v_mov_b32_e32 v61, v53
	v_pk_mov_b32 v[54:55], v[50:51], v[54:55] op_sel:[1,0]
	v_mov_b32_e32 v57, v50
	v_pk_add_f32 v[54:55], v[60:61], v[54:55] neg_lo:[0,1] neg_hi:[0,1]
	v_mov_b32_e32 v64, v62
	v_pk_add_f32 v[50:51], v[56:57], v[54:55] neg_lo:[0,1] neg_hi:[0,1]
	v_mov_b32_e32 v63, v53
	v_pk_add_f32 v[54:55], v[64:65], v[50:51]
	s_nop 0
	v_pk_add_f32 v[56:57], v[54:55], v[54:55] op_sel:[0,1] op_sel_hi:[1,0]
	s_nop 0
	v_pk_add_f32 v[52:53], v[52:53], v[56:57] op_sel:[1,0] op_sel_hi:[0,1]
	v_mov_b32_e32 v55, v52
	v_pk_add_f32 v[60:61], v[54:55], v[62:63] neg_lo:[0,1] neg_hi:[0,1]
	v_mov_b32_e32 v51, v56
	v_sub_f32_e32 v46, v54, v60
	v_pk_add_f32 v[50:51], v[50:51], v[60:61] neg_lo:[0,1] neg_hi:[0,1]
	v_sub_f32_e32 v46, v62, v46
	v_add_f32_e32 v46, v50, v46
	v_add_f32_e32 v46, v46, v51
	v_add_f32_e32 v46, v52, v46
	v_cndmask_b32_e32 v46, v236, v46, vcc
	v_cmp_ngt_f32_e32 vcc, -1.0, v3
	s_nop 1
	v_cndmask_b32_e32 v46, v237, v46, vcc
	v_cmp_neq_f32_e32 vcc, -1.0, v3
	s_nop 1
	v_cndmask_b32_e32 v46, v238, v46, vcc
	v_cmp_lt_f32_e64 vcc, |v3|, s58
	s_nop 1
	v_cndmask_b32_e32 v3, v46, v3, vcc
;     __device__ __forceinline__ void operator()(f32x4 (&acc)[2][2][4][2], const Unit& u, int row0t, int wr, int wc, int fr, int fq) const {
;     ...
;                                 for (int e = 0; e < 4; ++e) { const int h = 4 * n + e; const float xx = v[e] + dt_bias[h]; const float sp = xx > 20.f ? xx : log1pf(__expf(xx)); o[e] = -__expf(A_log[h]) * sp; } }
.LBB0_242:
	s_or_b64 exec, exec, s[36:37]
	v_mov_b32_e32 v50, v155
	v_mov_b32_e32 v46, v162
	v_add_f32_e32 v47, v47, v50
	v_cmp_nlt_f32_e32 vcc, s53, v47
	s_and_saveexec_b64 s[36:37], vcc
	s_cbranch_execz .LBB0_244
	v_mul_f32_e32 v47, 0x3fb8aa3b, v47
	v_exp_f32_e32 v47, v47
	s_nop 0
	v_add_f32_e32 v52, 1.0, v47
	v_frexp_mant_f32_e32 v54, v52
	v_cvt_f64_f32_e32 v[50:51], v52
	v_frexp_exp_i32_f64_e32 v50, v[50:51]
	v_cmp_gt_f32_e32 vcc, s55, v54
	v_add_f32_e32 v53, -1.0, v52
	v_sub_f32_e32 v55, v53, v52
	v_subbrev_co_u32_e32 v60, vcc, 0, v50, vcc
	v_sub_u32_e32 v50, 0, v60
	v_sub_f32_e32 v53, v47, v53
	v_add_f32_e32 v55, 1.0, v55
	v_ldexp_f32 v51, v52, v50
	v_add_f32_e32 v53, v53, v55
	v_add_f32_e32 v52, -1.0, v51
	v_add_f32_e32 v54, 1.0, v51
	v_ldexp_f32 v50, v53, v50
	v_add_f32_e32 v53, 1.0, v52
	v_add_f32_e32 v55, -1.0, v54
	v_sub_f32_e32 v53, v51, v53
	v_sub_f32_e32 v51, v51, v55
	v_add_f32_e32 v53, v50, v53
	v_add_f32_e32 v50, v50, v51
	v_add_f32_e32 v61, v54, v50
	v_rcp_f32_e32 v63, v61
	v_sub_f32_e32 v51, v61, v54
	v_sub_f32_e32 v62, v50, v51
	v_add_f32_e32 v51, v52, v53
	v_mul_f32_e32 v65, v51, v63
	v_sub_f32_e32 v50, v51, v52
	v_mul_f32_e32 v52, v61, v65
	v_fma_f32 v54, v65, v61, -v52
	v_fmac_f32_e32 v54, v65, v62
	v_sub_f32_e32 v64, v53, v50
	v_add_f32_e32 v50, v52, v54
	v_sub_f32_e32 v53, v51, v50
	v_pk_add_f32 v[56:57], v[50:51], v[52:53] neg_lo:[0,1] neg_hi:[0,1]
	v_mov_b32_e32 v55, v50
	v_pk_add_f32 v[50:51], v[56:57], v[54:55] neg_lo:[0,1] neg_hi:[0,1]
	v_cmp_neq_f32_e32 vcc, s57, v47
	v_add_f32_e32 v51, v64, v51
	v_add_f32_e32 v50, v50, v51
	v_add_f32_e32 v51, v53, v50
	v_mul_f32_e32 v64, v63, v51
	v_mul_f32_e32 v52, v61, v64
	v_fma_f32 v54, v64, v61, -v52
	v_fmac_f32_e32 v54, v64, v62
	v_sub_f32_e32 v53, v53, v51
	v_add_f32_e32 v61, v50, v53
	v_add_f32_e32 v50, v52, v54
	v_sub_f32_e32 v53, v51, v50
	v_pk_add_f32 v[56:57], v[50:51], v[52:53] neg_lo:[0,1] neg_hi:[0,1]
	v_mov_b32_e32 v55, v50
	v_pk_add_f32 v[50:51], v[56:57], v[54:55] neg_lo:[0,1] neg_hi:[0,1]
	s_nop 0
	v_add_f32_e32 v51, v61, v51
	v_add_f32_e32 v50, v50, v51
	v_add_f32_e32 v51, v65, v64
	v_add_f32_e32 v50, v53, v50
	v_sub_f32_e32 v52, v51, v65
	v_mul_f32_e32 v50, v63, v50
	v_sub_f32_e32 v52, v64, v52
	v_add_f32_e32 v52, v52, v50
	v_add_f32_e32 v54, v51, v52
	v_mul_f32_e32 v55, v54, v54
	v_fmamk_f32 v50, v55, 0x3e9b6dac, v235
	v_fmaak_f32 v227, v55, v50, 0x3f2aaada
	v_cvt_f32_i32_e32 v50, v60
	v_sub_f32_e32 v51, v54, v51
	v_sub_f32_e32 v51, v52, v51
	v_ldexp_f32 v56, v51, 1
	v_mul_f32_e32 v51, v54, v55
	v_ldexp_f32 v53, v54, 1
	v_pk_mul_f32 v[54:55], v[50:51], v[226:227]
	s_nop 0
	v_fma_f32 v52, v50, s56, -v54
	v_fmac_f32_e32 v52, 0xb102e308, v50
	v_pk_add_f32 v[50:51], v[54:55], v[52:53]
	s_nop 0
	v_sub_f32_e32 v53, v51, v53
	v_sub_f32_e32 v53, v55, v53
	v_add_f32_e32 v57, v56, v53
	v_mov_b32_e32 v56, v54
	v_pk_add_f32 v[54:55], v[50:51], v[54:55] neg_lo:[0,1] neg_hi:[0,1]
	v_pk_add_f32 v[60:61], v[50:51], v[56:57]
	v_mov_b32_e32 v53, v50
	v_mov_b32_e32 v55, v61
	v_pk_add_f32 v[62:63], v[52:53], v[54:55] neg_lo:[0,1] neg_hi:[0,1]
	v_pk_add_f32 v[52:53], v[52:53], v[54:55]
	v_mov_b32_e32 v56, v57
	v_pk_add_f32 v[54:55], v[52:53], v[50:51] op_sel:[1,0] op_sel_hi:[0,1] neg_lo:[0,1] neg_hi:[0,1]
	v_pk_add_f32 v[64:65], v[60:61], v[54:55] op_sel_hi:[1,0] neg_lo:[0,1] neg_hi:[0,1]
	v_mov_b32_e32 v60, v61
	v_mov_b32_e32 v61, v53
	v_pk_mov_b32 v[54:55], v[50:51], v[54:55] op_sel:[1,0]
	v_mov_b32_e32 v57, v50
	v_pk_add_f32 v[54:55], v[60:61], v[54:55] neg_lo:[0,1] neg_hi:[0,1]
	v_mov_b32_e32 v64, v62
	v_pk_add_f32 v[50:51], v[56:57], v[54:55] neg_lo:[0,1] neg_hi:[0,1]
	v_mov_b32_e32 v63, v53
	v_pk_add_f32 v[54:55], v[64:65], v[50:51]
	s_nop 0
	v_pk_add_f32 v[56:57], v[54:55], v[54:55] op_sel:[0,1] op_sel_hi:[1,0]
	s_nop 0
	v_pk_add_f32 v[52:53], v[52:53], v[56:57] op_sel:[1,0] op_sel_hi:[0,1]
	v_mov_b32_e32 v55, v52
	v_pk_add_f32 v[60:61], v[54:55], v[62:63] neg_lo:[0,1] neg_hi:[0,1]
	v_mov_b32_e32 v51, v56
	v_sub_f32_e32 v53, v54, v60
	v_pk_add_f32 v[50:51], v[50:51], v[60:61] neg_lo:[0,1] neg_hi:[0,1]
	v_sub_f32_e32 v53, v62, v53
	v_add_f32_e32 v50, v50, v53
	v_add_f32_e32 v50, v50, v51
	v_add_f32_e32 v50, v52, v50
	v_cndmask_b32_e32 v50, v236, v50, vcc
	v_cmp_ngt_f32_e32 vcc, -1.0, v47
	s_nop 1
	v_cndmask_b32_e32 v50, v237, v50, vcc
	v_cmp_neq_f32_e32 vcc, -1.0, v47
	s_nop 1
	v_cndmask_b32_e32 v50, v238, v50, vcc
	v_cmp_lt_f32_e64 vcc, |v47|, s58
	s_nop 1
	v_cndmask_b32_e32 v47, v50, v47, vcc
;     __device__ __forceinline__ void operator()(f32x4 (&acc)[2][2][4][2], const Unit& u, int row0t, int wr, int wc, int fr, int fq) const {
;     ...
;                                 for (int e = 0; e < 4; ++e) { const int h = 4 * n + e; const float xx = v[e] + dt_bias[h]; const float sp = xx > 20.f ? xx : log1pf(__expf(xx)); o[e] = -__expf(A_log[h]) * sp; } }
.LBB0_244:
	s_or_b64 exec, exec, s[36:37]
	v_mov_b32_e32 v50, v156
	v_mov_b32_e32 v51, v163
	v_add_f32_e32 v48, v48, v50
	v_cmp_nlt_f32_e32 vcc, s53, v48
	s_and_saveexec_b64 s[36:37], vcc
	s_cbranch_execz .LBB0_246
	v_mul_f32_e32 v48, 0x3fb8aa3b, v48
	v_exp_f32_e32 v48, v48
	s_nop 0
	v_add_f32_e32 v50, 1.0, v48
	v_frexp_mant_f32_e32 v55, v50
	v_cvt_f64_f32_e32 v[52:53], v50
	v_add_f32_e32 v54, -1.0, v50
	v_frexp_exp_i32_f64_e32 v52, v[52:53]
	v_cmp_gt_f32_e32 vcc, s55, v55
	v_sub_f32_e32 v56, v54, v50
	v_sub_f32_e32 v54, v48, v54
	v_subbrev_co_u32_e32 v62, vcc, 0, v52, vcc
	v_add_f32_e32 v56, 1.0, v56
	v_sub_u32_e32 v52, 0, v62
	v_add_f32_e32 v54, v54, v56
	v_ldexp_f32 v50, v50, v52
	v_ldexp_f32 v52, v54, v52
	v_add_f32_e32 v54, -1.0, v50
	v_add_f32_e32 v53, 1.0, v54
	v_sub_f32_e32 v53, v50, v53
	v_add_f32_e32 v55, v52, v53
	v_add_f32_e32 v53, 1.0, v50
	v_add_f32_e32 v56, -1.0, v53
	v_sub_f32_e32 v50, v50, v56
	v_add_f32_e32 v50, v52, v50
	v_add_f32_e32 v63, v53, v50
	v_rcp_f32_e32 v64, v63
	v_sub_f32_e32 v52, v63, v53
	v_add_f32_e32 v53, v54, v55
	v_sub_f32_e32 v50, v50, v52
	v_mul_f32_e32 v66, v53, v64
	v_sub_f32_e32 v52, v53, v54
	v_mul_f32_e32 v54, v63, v66
	v_fma_f32 v56, v66, v63, -v54
	v_fmac_f32_e32 v56, v66, v50
	v_sub_f32_e32 v65, v55, v52
	v_add_f32_e32 v52, v54, v56
	v_sub_f32_e32 v55, v53, v52
	v_pk_add_f32 v[60:61], v[52:53], v[54:55] neg_lo:[0,1] neg_hi:[0,1]
	v_mov_b32_e32 v57, v52
	v_pk_add_f32 v[52:53], v[60:61], v[56:57] neg_lo:[0,1] neg_hi:[0,1]
	v_cmp_neq_f32_e32 vcc, s57, v48
	v_add_f32_e32 v53, v65, v53
	v_add_f32_e32 v52, v52, v53
	v_add_f32_e32 v53, v55, v52
	v_mul_f32_e32 v65, v64, v53
	v_mul_f32_e32 v54, v63, v65
	v_fma_f32 v56, v65, v63, -v54
	v_fmac_f32_e32 v56, v65, v50
	v_sub_f32_e32 v50, v55, v53
	v_add_f32_e32 v50, v52, v50
	v_add_f32_e32 v52, v54, v56
	v_sub_f32_e32 v55, v53, v52
	v_pk_add_f32 v[60:61], v[52:53], v[54:55] neg_lo:[0,1] neg_hi:[0,1]
	v_mov_b32_e32 v57, v52
	v_pk_add_f32 v[52:53], v[60:61], v[56:57] neg_lo:[0,1] neg_hi:[0,1]
	s_nop 0
	v_add_f32_e32 v50, v50, v53
	v_add_f32_e32 v50, v52, v50
	v_add_f32_e32 v53, v66, v65
	v_add_f32_e32 v50, v55, v50
	v_sub_f32_e32 v52, v53, v66
	v_mul_f32_e32 v50, v64, v50
	v_sub_f32_e32 v52, v65, v52
	v_add_f32_e32 v50, v52, v50
	v_add_f32_e32 v54, v53, v50
	v_mul_f32_e32 v56, v54, v54
	v_fmamk_f32 v52, v56, 0x3e9b6dac, v235
	v_fmaak_f32 v227, v56, v52, 0x3f2aaada
	v_cvt_f32_i32_e32 v52, v62
	v_sub_f32_e32 v53, v54, v53
	v_sub_f32_e32 v50, v50, v53
	v_mul_f32_e32 v53, v54, v56
	v_pk_mul_f32 v[56:57], v[52:53], v[226:227]
	v_ldexp_f32 v55, v54, 1
	v_fma_f32 v54, v52, s56, -v56
	v_fmac_f32_e32 v54, 0xb102e308, v52
	v_pk_add_f32 v[52:53], v[56:57], v[54:55]
	v_ldexp_f32 v50, v50, 1
	v_sub_f32_e32 v55, v53, v55
	v_sub_f32_e32 v55, v57, v55
	v_add_f32_e32 v61, v50, v55
	v_mov_b32_e32 v60, v56
	v_pk_add_f32 v[56:57], v[52:53], v[56:57] neg_lo:[0,1] neg_hi:[0,1]
	v_pk_add_f32 v[62:63], v[52:53], v[60:61]
	v_mov_b32_e32 v55, v52
	v_mov_b32_e32 v57, v63
	v_pk_add_f32 v[64:65], v[54:55], v[56:57] neg_lo:[0,1] neg_hi:[0,1]
	v_pk_add_f32 v[54:55], v[54:55], v[56:57]
	v_mov_b32_e32 v60, v61
	v_pk_add_f32 v[56:57], v[54:55], v[52:53] op_sel:[1,0] op_sel_hi:[0,1] neg_lo:[0,1] neg_hi:[0,1]
	v_pk_add_f32 v[66:67], v[62:63], v[56:57] op_sel_hi:[1,0] neg_lo:[0,1] neg_hi:[0,1]
	v_mov_b32_e32 v62, v63
	v_mov_b32_e32 v63, v55
	v_pk_mov_b32 v[56:57], v[52:53], v[56:57] op_sel:[1,0]
	v_mov_b32_e32 v61, v52
	v_pk_add_f32 v[56:57], v[62:63], v[56:57] neg_lo:[0,1] neg_hi:[0,1]
	v_mov_b32_e32 v66, v64
	v_pk_add_f32 v[52:53], v[60:61], v[56:57] neg_lo:[0,1] neg_hi:[0,1]
	v_mov_b32_e32 v65, v55
	v_pk_add_f32 v[56:57], v[66:67], v[52:53]
	s_nop 0
	v_pk_add_f32 v[60:61], v[56:57], v[56:57] op_sel:[0,1] op_sel_hi:[1,0]
	s_nop 0
	v_pk_add_f32 v[54:55], v[54:55], v[60:61] op_sel:[1,0] op_sel_hi:[0,1]
	v_mov_b32_e32 v57, v54
	v_pk_add_f32 v[62:63], v[56:57], v[64:65] neg_lo:[0,1] neg_hi:[0,1]
	v_mov_b32_e32 v53, v60
	v_sub_f32_e32 v50, v56, v62
	v_pk_add_f32 v[52:53], v[52:53], v[62:63] neg_lo:[0,1] neg_hi:[0,1]
	v_sub_f32_e32 v50, v64, v50
	v_add_f32_e32 v50, v52, v50
	v_add_f32_e32 v50, v50, v53
	v_add_f32_e32 v50, v54, v50
	v_cndmask_b32_e32 v50, v236, v50, vcc
	v_cmp_ngt_f32_e32 vcc, -1.0, v48
	s_nop 1
	v_cndmask_b32_e32 v50, v237, v50, vcc
	v_cmp_neq_f32_e32 vcc, -1.0, v48
	s_nop 1
	v_cndmask_b32_e32 v50, v238, v50, vcc
	v_cmp_lt_f32_e64 vcc, |v48|, s58
	s_nop 1
	v_cndmask_b32_e32 v48, v50, v48, vcc
;     __device__ __forceinline__ void operator()(f32x4 (&acc)[2][2][4][2], const Unit& u, int row0t, int wr, int wc, int fr, int fq) const {
;     ...
;                                 for (int e = 0; e < 4; ++e) { const int h = 4 * n + e; const float xx = v[e] + dt_bias[h]; const float sp = xx > 20.f ? xx : log1pf(__expf(xx)); o[e] = -__expf(A_log[h]) * sp; } }
.LBB0_246:
	s_or_b64 exec, exec, s[36:37]
	v_mov_b32_e32 v50, v157
	v_mov_b32_e32 v52, v164
	v_add_f32_e32 v49, v49, v50
	v_cmp_nlt_f32_e32 vcc, s53, v49
	s_and_saveexec_b64 s[36:37], vcc
	s_cbranch_execz .LBB0_248
	v_mul_f32_e32 v49, 0x3fb8aa3b, v49
	v_exp_f32_e32 v49, v49
	s_nop 0
	v_add_f32_e32 v50, 1.0, v49
	v_frexp_mant_f32_e32 v56, v50
	v_cvt_f64_f32_e32 v[54:55], v50
	v_add_f32_e32 v53, -1.0, v50
	v_frexp_exp_i32_f64_e32 v54, v[54:55]
	v_cmp_gt_f32_e32 vcc, s55, v56
	v_sub_f32_e32 v57, v53, v50
	v_sub_f32_e32 v53, v49, v53
	v_subbrev_co_u32_e32 v64, vcc, 0, v54, vcc
	v_add_f32_e32 v57, 1.0, v57
	v_sub_u32_e32 v54, 0, v64
	v_add_f32_e32 v53, v53, v57
	v_ldexp_f32 v50, v50, v54
	v_ldexp_f32 v53, v53, v54
	v_add_f32_e32 v54, -1.0, v50
	v_add_f32_e32 v55, 1.0, v54
	v_sub_f32_e32 v55, v50, v55
	v_add_f32_e32 v56, v53, v55
	v_add_f32_e32 v55, 1.0, v50
	v_add_f32_e32 v57, -1.0, v55
	v_sub_f32_e32 v50, v50, v57
	v_add_f32_e32 v50, v53, v50
	v_add_f32_e32 v53, v55, v50
	v_rcp_f32_e32 v65, v53
	v_sub_f32_e32 v55, v53, v55
	v_sub_f32_e32 v50, v50, v55
	v_add_f32_e32 v55, v54, v56
	v_sub_f32_e32 v54, v55, v54
	v_mul_f32_e32 v67, v55, v65
	v_sub_f32_e32 v66, v56, v54
	v_mul_f32_e32 v56, v53, v67
	v_fma_f32 v60, v67, v53, -v56
	v_fmac_f32_e32 v60, v67, v50
	v_add_f32_e32 v54, v56, v60
	v_sub_f32_e32 v57, v55, v54
	v_pk_add_f32 v[62:63], v[54:55], v[56:57] neg_lo:[0,1] neg_hi:[0,1]
	v_mov_b32_e32 v61, v54
	v_pk_add_f32 v[54:55], v[62:63], v[60:61] neg_lo:[0,1] neg_hi:[0,1]
	v_cmp_neq_f32_e32 vcc, s57, v49
	v_add_f32_e32 v55, v66, v55
	v_add_f32_e32 v54, v54, v55
	v_add_f32_e32 v55, v57, v54
	v_mul_f32_e32 v66, v65, v55
	v_mul_f32_e32 v56, v53, v66
	v_fma_f32 v60, v66, v53, -v56
	v_fmac_f32_e32 v60, v66, v50
	v_sub_f32_e32 v50, v57, v55
	v_add_f32_e32 v50, v54, v50
	v_add_f32_e32 v54, v56, v60
	v_sub_f32_e32 v57, v55, v54
	v_pk_add_f32 v[62:63], v[54:55], v[56:57] neg_lo:[0,1] neg_hi:[0,1]
	v_mov_b32_e32 v61, v54
	v_pk_add_f32 v[54:55], v[62:63], v[60:61] neg_lo:[0,1] neg_hi:[0,1]
	v_add_f32_e32 v53, v67, v66
	v_add_f32_e32 v50, v50, v55
	v_add_f32_e32 v50, v54, v50
	v_add_f32_e32 v50, v57, v50
	v_sub_f32_e32 v54, v53, v67
	v_mul_f32_e32 v50, v65, v50
	v_sub_f32_e32 v54, v66, v54
	v_add_f32_e32 v50, v54, v50
	v_add_f32_e32 v55, v53, v50
	v_mul_f32_e32 v56, v55, v55
	v_fmamk_f32 v54, v56, 0x3e9b6dac, v235
	v_fmaak_f32 v227, v56, v54, 0x3f2aaada
	v_cvt_f32_i32_e32 v54, v64
	v_sub_f32_e32 v53, v55, v53
	v_ldexp_f32 v57, v55, 1
	v_mul_f32_e32 v55, v55, v56
	v_pk_mul_f32 v[60:61], v[54:55], v[226:227]
	v_sub_f32_e32 v50, v50, v53
	v_fma_f32 v56, v54, s56, -v60
	v_fmac_f32_e32 v56, 0xb102e308, v54
	v_pk_add_f32 v[54:55], v[60:61], v[56:57]
	v_ldexp_f32 v50, v50, 1
	v_sub_f32_e32 v53, v55, v57
	v_sub_f32_e32 v53, v61, v53
	v_add_f32_e32 v63, v50, v53
	v_mov_b32_e32 v62, v60
	v_pk_add_f32 v[60:61], v[54:55], v[60:61] neg_lo:[0,1] neg_hi:[0,1]
	v_pk_add_f32 v[64:65], v[54:55], v[62:63]
	v_mov_b32_e32 v57, v54
	v_mov_b32_e32 v61, v65
	v_pk_add_f32 v[66:67], v[56:57], v[60:61] neg_lo:[0,1] neg_hi:[0,1]
	v_pk_add_f32 v[56:57], v[56:57], v[60:61]
	v_mov_b32_e32 v62, v63
	v_pk_add_f32 v[60:61], v[56:57], v[54:55] op_sel:[1,0] op_sel_hi:[0,1] neg_lo:[0,1] neg_hi:[0,1]
	v_pk_add_f32 v[68:69], v[64:65], v[60:61] op_sel_hi:[1,0] neg_lo:[0,1] neg_hi:[0,1]
	v_mov_b32_e32 v64, v65
	v_mov_b32_e32 v65, v57
	v_pk_mov_b32 v[60:61], v[54:55], v[60:61] op_sel:[1,0]
	v_mov_b32_e32 v63, v54
	v_pk_add_f32 v[60:61], v[64:65], v[60:61] neg_lo:[0,1] neg_hi:[0,1]
	v_mov_b32_e32 v68, v66
	v_pk_add_f32 v[54:55], v[62:63], v[60:61] neg_lo:[0,1] neg_hi:[0,1]
	v_mov_b32_e32 v67, v57
	v_pk_add_f32 v[60:61], v[68:69], v[54:55]
	s_nop 0
	v_pk_add_f32 v[62:63], v[60:61], v[60:61] op_sel:[0,1] op_sel_hi:[1,0]
	s_nop 0
	v_pk_add_f32 v[56:57], v[56:57], v[62:63] op_sel:[1,0] op_sel_hi:[0,1]
	v_mov_b32_e32 v61, v56
	v_pk_add_f32 v[64:65], v[60:61], v[66:67] neg_lo:[0,1] neg_hi:[0,1]
	v_mov_b32_e32 v55, v62
	v_sub_f32_e32 v50, v60, v64
	v_pk_add_f32 v[54:55], v[54:55], v[64:65] neg_lo:[0,1] neg_hi:[0,1]
	v_sub_f32_e32 v50, v66, v50
	v_add_f32_e32 v50, v54, v50
	v_add_f32_e32 v50, v50, v55
	v_add_f32_e32 v50, v56, v50
	v_cndmask_b32_e32 v50, v236, v50, vcc
	v_cmp_ngt_f32_e32 vcc, -1.0, v49
	s_nop 1
	v_cndmask_b32_e32 v50, v237, v50, vcc
	v_cmp_neq_f32_e32 vcc, -1.0, v49
	s_nop 1
	v_cndmask_b32_e32 v50, v238, v50, vcc
	v_cmp_lt_f32_e64 vcc, |v49|, s58
	s_nop 1
	v_cndmask_b32_e32 v49, v50, v49, vcc
.LBB0_248:
	s_or_b64 exec, exec, s[36:37]
	v_mul_f32_e32 v46, 0x3fb8aa3b, v46
	v_exp_f32_e32 v46, v46
	s_nop 0
	v_mul_f32_e64 v50, v3, -v46
	v_mul_f32_e32 v3, 0x3fb8aa3b, v51
	v_exp_f32_e32 v3, v3
	s_nop 0
	v_mul_f32_e64 v51, v47, -v3
	v_mul_f32_e32 v3, 0x3fb8aa3b, v52
	v_exp_f32_e32 v3, v3
	s_nop 0
	v_mul_f32_e64 v52, v48, -v3
	v_mov_b32_e32 v3, v165
	v_mul_f32_e32 v3, 0x3fb8aa3b, v3
	v_exp_f32_e32 v3, v3
	s_nop 0
	v_mul_f32_e64 v53, v49, -v3

;     __device__ __forceinline__ void operator()(f32x4 (&acc)[2][2][4][2], const Unit& u, int row0t, int wr, int wc, int fr, int fq) const {
;     ...
;                                 for (int e = 0; e < 4; ++e) { const int h = 4 * n + e; const float xx = v[e] + dt_bias[h]; const float sp = xx > 20.f ? xx : log1pf(__expf(xx)); o[e] = -__expf(A_log[h]) * sp; } }
;                             *(f32x4*)(bg + (size_t)r * 16 + 8 * fq + 4 * n) = o; } }
.LBB0_251:
	s_or_b64 exec, exec, s[24:25]
	global_store_dwordx4 v[58:59], v[50:53], off offset:16
	s_and_saveexec_b64 s[2:3], s[4:5]
	s_xor_b64 s[24:25], exec, s[2:3]
	s_cbranch_execz .LBB0_261
	v_mov_b32_e32 v3, v150
	v_add_f32_e32 v3, v42, v3
	v_cmp_nlt_f32_e32 vcc, s53, v3
	s_and_saveexec_b64 s[36:37], vcc
	s_cbranch_execz .LBB0_254
	v_mul_f32_e32 v3, 0x3fb8aa3b, v3
	v_exp_f32_e32 v3, v3
	s_nop 0
	v_add_f32_e32 v42, 1.0, v3
	v_frexp_mant_f32_e32 v49, v42
	v_cvt_f64_f32_e32 v[46:47], v42
	v_add_f32_e32 v48, -1.0, v42
	v_frexp_exp_i32_f64_e32 v46, v[46:47]
	v_cmp_gt_f32_e32 vcc, s55, v49
	v_sub_f32_e32 v50, v48, v42
	v_sub_f32_e32 v48, v3, v48
	v_subbrev_co_u32_e32 v54, vcc, 0, v46, vcc
	v_add_f32_e32 v50, 1.0, v50
	v_sub_u32_e32 v46, 0, v54
	v_add_f32_e32 v48, v48, v50
	v_ldexp_f32 v42, v42, v46
	v_ldexp_f32 v46, v48, v46
	v_add_f32_e32 v48, -1.0, v42
	v_add_f32_e32 v47, 1.0, v48
	v_sub_f32_e32 v47, v42, v47
	v_add_f32_e32 v49, v46, v47
	v_add_f32_e32 v47, 1.0, v42
	v_add_f32_e32 v50, -1.0, v47
	v_sub_f32_e32 v42, v42, v50
	v_add_f32_e32 v42, v46, v42
	v_add_f32_e32 v55, v47, v42
	v_rcp_f32_e32 v56, v55
	v_sub_f32_e32 v46, v55, v47
	v_add_f32_e32 v47, v48, v49
	v_sub_f32_e32 v42, v42, v46
	v_mul_f32_e32 v58, v47, v56
	v_sub_f32_e32 v46, v47, v48
	v_mul_f32_e32 v48, v55, v58
	v_fma_f32 v50, v58, v55, -v48
	v_fmac_f32_e32 v50, v58, v42
	v_sub_f32_e32 v57, v49, v46
	v_add_f32_e32 v46, v48, v50
	v_sub_f32_e32 v49, v47, v46
	v_pk_add_f32 v[52:53], v[46:47], v[48:49] neg_lo:[0,1] neg_hi:[0,1]
	v_mov_b32_e32 v51, v46
	v_pk_add_f32 v[46:47], v[52:53], v[50:51] neg_lo:[0,1] neg_hi:[0,1]
	v_cmp_neq_f32_e32 vcc, s57, v3
	v_add_f32_e32 v47, v57, v47
	v_add_f32_e32 v46, v46, v47
	v_add_f32_e32 v47, v49, v46
	v_mul_f32_e32 v57, v56, v47
	v_mul_f32_e32 v48, v55, v57
	v_fma_f32 v50, v57, v55, -v48
	v_fmac_f32_e32 v50, v57, v42
	v_sub_f32_e32 v42, v49, v47
	v_add_f32_e32 v42, v46, v42
	v_add_f32_e32 v46, v48, v50
	v_sub_f32_e32 v49, v47, v46
	v_pk_add_f32 v[52:53], v[46:47], v[48:49] neg_lo:[0,1] neg_hi:[0,1]
	v_mov_b32_e32 v51, v46
	v_pk_add_f32 v[46:47], v[52:53], v[50:51] neg_lo:[0,1] neg_hi:[0,1]
	s_nop 0
	v_add_f32_e32 v42, v42, v47
	v_add_f32_e32 v42, v46, v42
	v_add_f32_e32 v47, v58, v57
	v_add_f32_e32 v42, v49, v42
	v_sub_f32_e32 v46, v47, v58
	v_mul_f32_e32 v42, v56, v42
	v_sub_f32_e32 v46, v57, v46
	v_add_f32_e32 v42, v46, v42
	v_add_f32_e32 v48, v47, v42
	v_mul_f32_e32 v50, v48, v48
	v_fmamk_f32 v46, v50, 0x3e9b6dac, v235
	v_fmaak_f32 v227, v50, v46, 0x3f2aaada
	v_cvt_f32_i32_e32 v46, v54
	v_sub_f32_e32 v47, v48, v47
	v_sub_f32_e32 v42, v42, v47
	v_mul_f32_e32 v47, v48, v50
	v_pk_mul_f32 v[50:51], v[46:47], v[226:227]
	v_ldexp_f32 v49, v48, 1
	v_fma_f32 v48, v46, s56, -v50
	v_fmac_f32_e32 v48, 0xb102e308, v46
	v_pk_add_f32 v[46:47], v[50:51], v[48:49]
	v_ldexp_f32 v42, v42, 1
	v_sub_f32_e32 v49, v47, v49
	v_sub_f32_e32 v49, v51, v49
	v_add_f32_e32 v53, v42, v49
	v_mov_b32_e32 v52, v50
	v_pk_add_f32 v[50:51], v[46:47], v[50:51] neg_lo:[0,1] neg_hi:[0,1]
	v_pk_add_f32 v[54:55], v[46:47], v[52:53]
	v_mov_b32_e32 v49, v46
	v_mov_b32_e32 v51, v55
	v_pk_add_f32 v[56:57], v[48:49], v[50:51] neg_lo:[0,1] neg_hi:[0,1]
	v_pk_add_f32 v[48:49], v[48:49], v[50:51]
	v_mov_b32_e32 v52, v53
	v_pk_add_f32 v[50:51], v[48:49], v[46:47] op_sel:[1,0] op_sel_hi:[0,1] neg_lo:[0,1] neg_hi:[0,1]
	v_pk_add_f32 v[58:59], v[54:55], v[50:51] op_sel_hi:[1,0] neg_lo:[0,1] neg_hi:[0,1]
	v_mov_b32_e32 v54, v55
	v_mov_b32_e32 v55, v49
	v_pk_mov_b32 v[50:51], v[46:47], v[50:51] op_sel:[1,0]
	v_mov_b32_e32 v53, v46
	v_pk_add_f32 v[50:51], v[54:55], v[50:51] neg_lo:[0,1] neg_hi:[0,1]
	v_mov_b32_e32 v58, v56
	v_pk_add_f32 v[46:47], v[52:53], v[50:51] neg_lo:[0,1] neg_hi:[0,1]
	v_mov_b32_e32 v57, v49
	v_pk_add_f32 v[50:51], v[58:59], v[46:47]
	s_nop 0
	v_pk_add_f32 v[52:53], v[50:51], v[50:51] op_sel:[0,1] op_sel_hi:[1,0]
	s_nop 0
	v_pk_add_f32 v[48:49], v[48:49], v[52:53] op_sel:[1,0] op_sel_hi:[0,1]
	v_mov_b32_e32 v51, v48
	v_pk_add_f32 v[54:55], v[50:51], v[56:57] neg_lo:[0,1] neg_hi:[0,1]
	v_mov_b32_e32 v47, v52
	v_sub_f32_e32 v42, v50, v54
	v_pk_add_f32 v[46:47], v[46:47], v[54:55] neg_lo:[0,1] neg_hi:[0,1]
	v_sub_f32_e32 v42, v56, v42
	v_add_f32_e32 v42, v46, v42
	v_add_f32_e32 v42, v42, v47
	v_add_f32_e32 v42, v48, v42
	v_cndmask_b32_e32 v42, v236, v42, vcc
	v_cmp_ngt_f32_e32 vcc, -1.0, v3
	s_nop 1
	v_cndmask_b32_e32 v42, v237, v42, vcc
	v_cmp_neq_f32_e32 vcc, -1.0, v3
	s_nop 1
	v_cndmask_b32_e32 v42, v238, v42, vcc
	v_cmp_lt_f32_e64 vcc, |v3|, s58
	s_nop 1
	v_cndmask_b32_e32 v3, v42, v3, vcc
;     __device__ __forceinline__ void operator()(f32x4 (&acc)[2][2][4][2], const Unit& u, int row0t, int wr, int wc, int fr, int fq) const {
;     ...
;                                 for (int e = 0; e < 4; ++e) { const int h = 4 * n + e; const float xx = v[e] + dt_bias[h]; const float sp = xx > 20.f ? xx : log1pf(__expf(xx)); o[e] = -__expf(A_log[h]) * sp; } }
.LBB0_254:
	s_or_b64 exec, exec, s[36:37]
	v_mov_b32_e32 v46, v151
	v_mov_b32_e32 v42, v158
	v_add_f32_e32 v43, v43, v46
	v_cmp_nlt_f32_e32 vcc, s53, v43
	s_and_saveexec_b64 s[36:37], vcc
	s_cbranch_execz .LBB0_256
	v_mul_f32_e32 v43, 0x3fb8aa3b, v43
	v_exp_f32_e32 v43, v43
	s_nop 0
	v_add_f32_e32 v48, 1.0, v43
	v_frexp_mant_f32_e32 v50, v48
	v_cvt_f64_f32_e32 v[46:47], v48
	v_frexp_exp_i32_f64_e32 v46, v[46:47]
	v_cmp_gt_f32_e32 vcc, s55, v50
	v_add_f32_e32 v49, -1.0, v48
	v_sub_f32_e32 v51, v49, v48
	v_subbrev_co_u32_e32 v54, vcc, 0, v46, vcc
	v_sub_u32_e32 v46, 0, v54
	v_sub_f32_e32 v49, v43, v49
	v_add_f32_e32 v51, 1.0, v51
	v_ldexp_f32 v47, v48, v46
	v_add_f32_e32 v49, v49, v51
	v_add_f32_e32 v48, -1.0, v47
	v_add_f32_e32 v50, 1.0, v47
	v_ldexp_f32 v46, v49, v46
	v_add_f32_e32 v49, 1.0, v48
	v_add_f32_e32 v51, -1.0, v50
	v_sub_f32_e32 v49, v47, v49
	v_sub_f32_e32 v47, v47, v51
	v_add_f32_e32 v49, v46, v49
	v_add_f32_e32 v46, v46, v47
	v_add_f32_e32 v55, v50, v46
	v_rcp_f32_e32 v57, v55
	v_sub_f32_e32 v47, v55, v50
	v_sub_f32_e32 v56, v46, v47
	v_add_f32_e32 v47, v48, v49
	v_mul_f32_e32 v59, v47, v57
	v_sub_f32_e32 v46, v47, v48
	v_mul_f32_e32 v48, v55, v59
	v_fma_f32 v50, v59, v55, -v48
	v_fmac_f32_e32 v50, v59, v56
	v_sub_f32_e32 v58, v49, v46
	v_add_f32_e32 v46, v48, v50
	v_sub_f32_e32 v49, v47, v46
	v_pk_add_f32 v[52:53], v[46:47], v[48:49] neg_lo:[0,1] neg_hi:[0,1]
	v_mov_b32_e32 v51, v46
	v_pk_add_f32 v[46:47], v[52:53], v[50:51] neg_lo:[0,1] neg_hi:[0,1]
	v_cmp_neq_f32_e32 vcc, s57, v43
	v_add_f32_e32 v47, v58, v47
	v_add_f32_e32 v46, v46, v47
	v_add_f32_e32 v47, v49, v46
	v_mul_f32_e32 v58, v57, v47
	v_mul_f32_e32 v48, v55, v58
	v_fma_f32 v50, v58, v55, -v48
	v_fmac_f32_e32 v50, v58, v56
	v_sub_f32_e32 v49, v49, v47
	v_add_f32_e32 v55, v46, v49
	v_add_f32_e32 v46, v48, v50
	v_sub_f32_e32 v49, v47, v46
	v_pk_add_f32 v[52:53], v[46:47], v[48:49] neg_lo:[0,1] neg_hi:[0,1]
	v_mov_b32_e32 v51, v46
	v_pk_add_f32 v[46:47], v[52:53], v[50:51] neg_lo:[0,1] neg_hi:[0,1]
	s_nop 0
	v_add_f32_e32 v47, v55, v47
	v_add_f32_e32 v46, v46, v47
	v_add_f32_e32 v47, v59, v58
	v_add_f32_e32 v46, v49, v46
	v_sub_f32_e32 v48, v47, v59
	v_mul_f32_e32 v46, v57, v46
	v_sub_f32_e32 v48, v58, v48
	v_add_f32_e32 v48, v48, v46
	v_add_f32_e32 v50, v47, v48
	v_mul_f32_e32 v51, v50, v50
	v_fmamk_f32 v46, v51, 0x3e9b6dac, v235
	v_fmaak_f32 v227, v51, v46, 0x3f2aaada
	v_cvt_f32_i32_e32 v46, v54
	v_sub_f32_e32 v47, v50, v47
	v_sub_f32_e32 v47, v48, v47
	v_ldexp_f32 v52, v47, 1
	v_mul_f32_e32 v47, v50, v51
	v_ldexp_f32 v49, v50, 1
	v_pk_mul_f32 v[50:51], v[46:47], v[226:227]
	s_nop 0
	v_fma_f32 v48, v46, s56, -v50
	v_fmac_f32_e32 v48, 0xb102e308, v46
	v_pk_add_f32 v[46:47], v[50:51], v[48:49]
	s_nop 0
	v_sub_f32_e32 v49, v47, v49
	v_sub_f32_e32 v49, v51, v49
	v_add_f32_e32 v53, v52, v49
	v_mov_b32_e32 v52, v50
	v_pk_add_f32 v[50:51], v[46:47], v[50:51] neg_lo:[0,1] neg_hi:[0,1]
	v_pk_add_f32 v[54:55], v[46:47], v[52:53]
	v_mov_b32_e32 v49, v46
	v_mov_b32_e32 v51, v55
	v_pk_add_f32 v[56:57], v[48:49], v[50:51] neg_lo:[0,1] neg_hi:[0,1]
	v_pk_add_f32 v[48:49], v[48:49], v[50:51]
	v_mov_b32_e32 v52, v53
	v_pk_add_f32 v[50:51], v[48:49], v[46:47] op_sel:[1,0] op_sel_hi:[0,1] neg_lo:[0,1] neg_hi:[0,1]
	v_pk_add_f32 v[58:59], v[54:55], v[50:51] op_sel_hi:[1,0] neg_lo:[0,1] neg_hi:[0,1]
	v_mov_b32_e32 v54, v55
	v_mov_b32_e32 v55, v49
	v_pk_mov_b32 v[50:51], v[46:47], v[50:51] op_sel:[1,0]
	v_mov_b32_e32 v53, v46
	v_pk_add_f32 v[50:51], v[54:55], v[50:51] neg_lo:[0,1] neg_hi:[0,1]
	v_mov_b32_e32 v58, v56
	v_pk_add_f32 v[46:47], v[52:53], v[50:51] neg_lo:[0,1] neg_hi:[0,1]
	v_mov_b32_e32 v57, v49
	v_pk_add_f32 v[50:51], v[58:59], v[46:47]
	s_nop 0
	v_pk_add_f32 v[52:53], v[50:51], v[50:51] op_sel:[0,1] op_sel_hi:[1,0]
	s_nop 0
	v_pk_add_f32 v[48:49], v[48:49], v[52:53] op_sel:[1,0] op_sel_hi:[0,1]
	v_mov_b32_e32 v51, v48
	v_pk_add_f32 v[54:55], v[50:51], v[56:57] neg_lo:[0,1] neg_hi:[0,1]
	v_mov_b32_e32 v47, v52
	v_sub_f32_e32 v49, v50, v54
	v_pk_add_f32 v[46:47], v[46:47], v[54:55] neg_lo:[0,1] neg_hi:[0,1]
	v_sub_f32_e32 v49, v56, v49
	v_add_f32_e32 v46, v46, v49
	v_add_f32_e32 v46, v46, v47
	v_add_f32_e32 v46, v48, v46
	v_cndmask_b32_e32 v46, v236, v46, vcc
	v_cmp_ngt_f32_e32 vcc, -1.0, v43
	s_nop 1
	v_cndmask_b32_e32 v46, v237, v46, vcc
	v_cmp_neq_f32_e32 vcc, -1.0, v43
	s_nop 1
	v_cndmask_b32_e32 v46, v238, v46, vcc
	v_cmp_lt_f32_e64 vcc, |v43|, s58
	s_nop 1
	v_cndmask_b32_e32 v43, v46, v43, vcc
;     __device__ __forceinline__ void operator()(f32x4 (&acc)[2][2][4][2], const Unit& u, int row0t, int wr, int wc, int fr, int fq) const {
;     ...
;                                 for (int e = 0; e < 4; ++e) { const int h = 4 * n + e; const float xx = v[e] + dt_bias[h]; const float sp = xx > 20.f ? xx : log1pf(__expf(xx)); o[e] = -__expf(A_log[h]) * sp; } }
.LBB0_256:
	s_or_b64 exec, exec, s[36:37]
	v_mov_b32_e32 v46, v152
	v_mov_b32_e32 v47, v159
	v_add_f32_e32 v44, v44, v46
	v_cmp_nlt_f32_e32 vcc, s53, v44
	s_and_saveexec_b64 s[36:37], vcc
	s_cbranch_execz .LBB0_258
	v_mul_f32_e32 v44, 0x3fb8aa3b, v44
	v_exp_f32_e32 v44, v44
	s_nop 0
	v_add_f32_e32 v46, 1.0, v44
	v_frexp_mant_f32_e32 v51, v46
	v_cvt_f64_f32_e32 v[48:49], v46
	v_add_f32_e32 v50, -1.0, v46
	v_frexp_exp_i32_f64_e32 v48, v[48:49]
	v_cmp_gt_f32_e32 vcc, s55, v51
	v_sub_f32_e32 v52, v50, v46
	v_sub_f32_e32 v50, v44, v50
	v_subbrev_co_u32_e32 v56, vcc, 0, v48, vcc
	v_add_f32_e32 v52, 1.0, v52
	v_sub_u32_e32 v48, 0, v56
	v_add_f32_e32 v50, v50, v52
	v_ldexp_f32 v46, v46, v48
	v_ldexp_f32 v48, v50, v48
	v_add_f32_e32 v50, -1.0, v46
	v_add_f32_e32 v49, 1.0, v50
	v_sub_f32_e32 v49, v46, v49
	v_add_f32_e32 v51, v48, v49
	v_add_f32_e32 v49, 1.0, v46
	v_add_f32_e32 v52, -1.0, v49
	v_sub_f32_e32 v46, v46, v52
	v_add_f32_e32 v46, v48, v46
	v_add_f32_e32 v57, v49, v46
	v_rcp_f32_e32 v58, v57
	v_sub_f32_e32 v48, v57, v49
	v_add_f32_e32 v49, v50, v51
	v_sub_f32_e32 v46, v46, v48
	v_mul_f32_e32 v60, v49, v58
	v_sub_f32_e32 v48, v49, v50
	v_mul_f32_e32 v50, v57, v60
	v_fma_f32 v52, v60, v57, -v50
	v_fmac_f32_e32 v52, v60, v46
	v_sub_f32_e32 v59, v51, v48
	v_add_f32_e32 v48, v50, v52
	v_sub_f32_e32 v51, v49, v48
	v_pk_add_f32 v[54:55], v[48:49], v[50:51] neg_lo:[0,1] neg_hi:[0,1]
	v_mov_b32_e32 v53, v48
	v_pk_add_f32 v[48:49], v[54:55], v[52:53] neg_lo:[0,1] neg_hi:[0,1]
	v_cmp_neq_f32_e32 vcc, s57, v44
	v_add_f32_e32 v49, v59, v49
	v_add_f32_e32 v48, v48, v49
	v_add_f32_e32 v49, v51, v48
	v_mul_f32_e32 v59, v58, v49
	v_mul_f32_e32 v50, v57, v59
	v_fma_f32 v52, v59, v57, -v50
	v_fmac_f32_e32 v52, v59, v46
	v_sub_f32_e32 v46, v51, v49
	v_add_f32_e32 v46, v48, v46
	v_add_f32_e32 v48, v50, v52
	v_sub_f32_e32 v51, v49, v48
	v_pk_add_f32 v[54:55], v[48:49], v[50:51] neg_lo:[0,1] neg_hi:[0,1]
	v_mov_b32_e32 v53, v48
	v_pk_add_f32 v[48:49], v[54:55], v[52:53] neg_lo:[0,1] neg_hi:[0,1]
	s_nop 0
	v_add_f32_e32 v46, v46, v49
	v_add_f32_e32 v46, v48, v46
	v_add_f32_e32 v49, v60, v59
	v_add_f32_e32 v46, v51, v46
	v_sub_f32_e32 v48, v49, v60
	v_mul_f32_e32 v46, v58, v46
	v_sub_f32_e32 v48, v59, v48
	v_add_f32_e32 v46, v48, v46
	v_add_f32_e32 v50, v49, v46
	v_mul_f32_e32 v52, v50, v50
	v_fmamk_f32 v48, v52, 0x3e9b6dac, v235
	v_fmaak_f32 v227, v52, v48, 0x3f2aaada
	v_cvt_f32_i32_e32 v48, v56
	v_sub_f32_e32 v49, v50, v49
	v_sub_f32_e32 v46, v46, v49
	v_mul_f32_e32 v49, v50, v52
	v_pk_mul_f32 v[52:53], v[48:49], v[226:227]
	v_ldexp_f32 v51, v50, 1
	v_fma_f32 v50, v48, s56, -v52
	v_fmac_f32_e32 v50, 0xb102e308, v48
	v_pk_add_f32 v[48:49], v[52:53], v[50:51]
	v_ldexp_f32 v46, v46, 1
	v_sub_f32_e32 v51, v49, v51
	v_sub_f32_e32 v51, v53, v51
	v_add_f32_e32 v55, v46, v51
	v_mov_b32_e32 v54, v52
	v_pk_add_f32 v[52:53], v[48:49], v[52:53] neg_lo:[0,1] neg_hi:[0,1]
	v_pk_add_f32 v[56:57], v[48:49], v[54:55]
	v_mov_b32_e32 v51, v48
	v_mov_b32_e32 v53, v57
	v_pk_add_f32 v[58:59], v[50:51], v[52:53] neg_lo:[0,1] neg_hi:[0,1]
	v_pk_add_f32 v[50:51], v[50:51], v[52:53]
	v_mov_b32_e32 v54, v55
	v_pk_add_f32 v[52:53], v[50:51], v[48:49] op_sel:[1,0] op_sel_hi:[0,1] neg_lo:[0,1] neg_hi:[0,1]
	v_pk_add_f32 v[60:61], v[56:57], v[52:53] op_sel_hi:[1,0] neg_lo:[0,1] neg_hi:[0,1]
	v_mov_b32_e32 v56, v57
	v_mov_b32_e32 v57, v51
	v_pk_mov_b32 v[52:53], v[48:49], v[52:53] op_sel:[1,0]
	v_mov_b32_e32 v55, v48
	v_pk_add_f32 v[52:53], v[56:57], v[52:53] neg_lo:[0,1] neg_hi:[0,1]
	v_mov_b32_e32 v60, v58
	v_pk_add_f32 v[48:49], v[54:55], v[52:53] neg_lo:[0,1] neg_hi:[0,1]
	v_mov_b32_e32 v59, v51
	v_pk_add_f32 v[52:53], v[60:61], v[48:49]
	s_nop 0
	v_pk_add_f32 v[54:55], v[52:53], v[52:53] op_sel:[0,1] op_sel_hi:[1,0]
	s_nop 0
	v_pk_add_f32 v[50:51], v[50:51], v[54:55] op_sel:[1,0] op_sel_hi:[0,1]
	v_mov_b32_e32 v53, v50
	v_pk_add_f32 v[56:57], v[52:53], v[58:59] neg_lo:[0,1] neg_hi:[0,1]
	v_mov_b32_e32 v49, v54
	v_sub_f32_e32 v46, v52, v56
	v_pk_add_f32 v[48:49], v[48:49], v[56:57] neg_lo:[0,1] neg_hi:[0,1]
	v_sub_f32_e32 v46, v58, v46
	v_add_f32_e32 v46, v48, v46
	v_add_f32_e32 v46, v46, v49
	v_add_f32_e32 v46, v50, v46
	v_cndmask_b32_e32 v46, v236, v46, vcc
	v_cmp_ngt_f32_e32 vcc, -1.0, v44
	s_nop 1
	v_cndmask_b32_e32 v46, v237, v46, vcc
	v_cmp_neq_f32_e32 vcc, -1.0, v44
	s_nop 1
	v_cndmask_b32_e32 v46, v238, v46, vcc
	v_cmp_lt_f32_e64 vcc, |v44|, s58
	s_nop 1
	v_cndmask_b32_e32 v44, v46, v44, vcc
;     __device__ __forceinline__ void operator()(f32x4 (&acc)[2][2][4][2], const Unit& u, int row0t, int wr, int wc, int fr, int fq) const {
;     ...
;                                 for (int e = 0; e < 4; ++e) { const int h = 4 * n + e; const float xx = v[e] + dt_bias[h]; const float sp = xx > 20.f ? xx : log1pf(__expf(xx)); o[e] = -__expf(A_log[h]) * sp; } }
.LBB0_258:
	s_or_b64 exec, exec, s[36:37]
	v_mov_b32_e32 v46, v153
	v_mov_b32_e32 v48, v160
	v_add_f32_e32 v45, v45, v46
	v_cmp_nlt_f32_e32 vcc, s53, v45
	s_and_saveexec_b64 s[36:37], vcc
	s_cbranch_execz .LBB0_260
	v_mul_f32_e32 v45, 0x3fb8aa3b, v45
	v_exp_f32_e32 v45, v45
	s_nop 0
	v_add_f32_e32 v46, 1.0, v45
	v_frexp_mant_f32_e32 v52, v46
	v_cvt_f64_f32_e32 v[50:51], v46
	v_add_f32_e32 v49, -1.0, v46
	v_frexp_exp_i32_f64_e32 v50, v[50:51]
	v_cmp_gt_f32_e32 vcc, s55, v52
	v_sub_f32_e32 v53, v49, v46
	v_sub_f32_e32 v49, v45, v49
	v_subbrev_co_u32_e32 v58, vcc, 0, v50, vcc
	v_add_f32_e32 v53, 1.0, v53
	v_sub_u32_e32 v50, 0, v58
	v_add_f32_e32 v49, v49, v53
	v_ldexp_f32 v46, v46, v50
	v_ldexp_f32 v49, v49, v50
	v_add_f32_e32 v50, -1.0, v46
	v_add_f32_e32 v51, 1.0, v50
	v_sub_f32_e32 v51, v46, v51
	v_add_f32_e32 v52, v49, v51
	v_add_f32_e32 v51, 1.0, v46
	v_add_f32_e32 v53, -1.0, v51
	v_sub_f32_e32 v46, v46, v53
	v_add_f32_e32 v46, v49, v46
	v_add_f32_e32 v49, v51, v46
	v_rcp_f32_e32 v59, v49
	v_sub_f32_e32 v51, v49, v51
	v_sub_f32_e32 v46, v46, v51
	v_add_f32_e32 v51, v50, v52
	v_sub_f32_e32 v50, v51, v50
	v_mul_f32_e32 v61, v51, v59
	v_sub_f32_e32 v60, v52, v50
	v_mul_f32_e32 v52, v49, v61
	v_fma_f32 v54, v61, v49, -v52
	v_fmac_f32_e32 v54, v61, v46
	v_add_f32_e32 v50, v52, v54
	v_sub_f32_e32 v53, v51, v50
	v_pk_add_f32 v[56:57], v[50:51], v[52:53] neg_lo:[0,1] neg_hi:[0,1]
	v_mov_b32_e32 v55, v50
	v_pk_add_f32 v[50:51], v[56:57], v[54:55] neg_lo:[0,1] neg_hi:[0,1]
	v_cmp_neq_f32_e32 vcc, s57, v45
	v_add_f32_e32 v51, v60, v51
	v_add_f32_e32 v50, v50, v51
	v_add_f32_e32 v51, v53, v50
	v_mul_f32_e32 v60, v59, v51
	v_mul_f32_e32 v52, v49, v60
	v_fma_f32 v54, v60, v49, -v52
	v_fmac_f32_e32 v54, v60, v46
	v_sub_f32_e32 v46, v53, v51
	v_add_f32_e32 v46, v50, v46
	v_add_f32_e32 v50, v52, v54
	v_sub_f32_e32 v53, v51, v50
	v_pk_add_f32 v[56:57], v[50:51], v[52:53] neg_lo:[0,1] neg_hi:[0,1]
	v_mov_b32_e32 v55, v50
	v_pk_add_f32 v[50:51], v[56:57], v[54:55] neg_lo:[0,1] neg_hi:[0,1]
	v_add_f32_e32 v49, v61, v60
	v_add_f32_e32 v46, v46, v51
	v_add_f32_e32 v46, v50, v46
	v_add_f32_e32 v46, v53, v46
	v_sub_f32_e32 v50, v49, v61
	v_mul_f32_e32 v46, v59, v46
	v_sub_f32_e32 v50, v60, v50
	v_add_f32_e32 v46, v50, v46
	v_add_f32_e32 v51, v49, v46
	v_mul_f32_e32 v52, v51, v51
	v_fmamk_f32 v50, v52, 0x3e9b6dac, v235
	v_fmaak_f32 v227, v52, v50, 0x3f2aaada
	v_cvt_f32_i32_e32 v50, v58
	v_sub_f32_e32 v49, v51, v49
	v_ldexp_f32 v53, v51, 1
	v_mul_f32_e32 v51, v51, v52
	v_pk_mul_f32 v[54:55], v[50:51], v[226:227]
	v_sub_f32_e32 v46, v46, v49
	v_fma_f32 v52, v50, s56, -v54
	v_fmac_f32_e32 v52, 0xb102e308, v50
	v_pk_add_f32 v[50:51], v[54:55], v[52:53]
	v_ldexp_f32 v46, v46, 1
	v_sub_f32_e32 v49, v51, v53
	v_sub_f32_e32 v49, v55, v49
	v_add_f32_e32 v57, v46, v49
	v_mov_b32_e32 v56, v54
	v_pk_add_f32 v[54:55], v[50:51], v[54:55] neg_lo:[0,1] neg_hi:[0,1]
	v_pk_add_f32 v[58:59], v[50:51], v[56:57]
	v_mov_b32_e32 v53, v50
	v_mov_b32_e32 v55, v59
	v_pk_add_f32 v[60:61], v[52:53], v[54:55] neg_lo:[0,1] neg_hi:[0,1]
	v_pk_add_f32 v[52:53], v[52:53], v[54:55]
	v_mov_b32_e32 v56, v57
	v_pk_add_f32 v[54:55], v[52:53], v[50:51] op_sel:[1,0] op_sel_hi:[0,1] neg_lo:[0,1] neg_hi:[0,1]
	v_pk_add_f32 v[62:63], v[58:59], v[54:55] op_sel_hi:[1,0] neg_lo:[0,1] neg_hi:[0,1]
	v_mov_b32_e32 v58, v59
	v_mov_b32_e32 v59, v53
	v_pk_mov_b32 v[54:55], v[50:51], v[54:55] op_sel:[1,0]
	v_mov_b32_e32 v57, v50
	v_pk_add_f32 v[54:55], v[58:59], v[54:55] neg_lo:[0,1] neg_hi:[0,1]
	v_mov_b32_e32 v62, v60
	v_pk_add_f32 v[50:51], v[56:57], v[54:55] neg_lo:[0,1] neg_hi:[0,1]
	v_mov_b32_e32 v61, v53
	v_pk_add_f32 v[54:55], v[62:63], v[50:51]
	s_nop 0
	v_pk_add_f32 v[56:57], v[54:55], v[54:55] op_sel:[0,1] op_sel_hi:[1,0]
	s_nop 0
	v_pk_add_f32 v[52:53], v[52:53], v[56:57] op_sel:[1,0] op_sel_hi:[0,1]
	v_mov_b32_e32 v55, v52
	v_pk_add_f32 v[58:59], v[54:55], v[60:61] neg_lo:[0,1] neg_hi:[0,1]
	v_mov_b32_e32 v51, v56
	v_sub_f32_e32 v46, v54, v58
	v_pk_add_f32 v[50:51], v[50:51], v[58:59] neg_lo:[0,1] neg_hi:[0,1]
	v_sub_f32_e32 v46, v60, v46
	v_add_f32_e32 v46, v50, v46
	v_add_f32_e32 v46, v46, v51
	v_add_f32_e32 v46, v52, v46
	v_cndmask_b32_e32 v46, v236, v46, vcc
	v_cmp_ngt_f32_e32 vcc, -1.0, v45
	s_nop 1
	v_cndmask_b32_e32 v46, v237, v46, vcc
	v_cmp_neq_f32_e32 vcc, -1.0, v45
	s_nop 1
	v_cndmask_b32_e32 v46, v238, v46, vcc
	v_cmp_lt_f32_e64 vcc, |v45|, s58
	s_nop 1
	v_cndmask_b32_e32 v45, v46, v45, vcc
.LBB0_260:
	s_or_b64 exec, exec, s[36:37]
	v_mul_f32_e32 v42, 0x3fb8aa3b, v42
	v_exp_f32_e32 v42, v42
	s_nop 0
	v_mul_f32_e64 v46, v3, -v42
	v_mul_f32_e32 v3, 0x3fb8aa3b, v47
	v_exp_f32_e32 v3, v3
	s_nop 0
	v_mul_f32_e64 v47, v43, -v3
	v_mul_f32_e32 v3, 0x3fb8aa3b, v48
	v_exp_f32_e32 v3, v3
	s_nop 0
	v_mul_f32_e64 v48, v44, -v3
	v_mov_b32_e32 v3, v161
	v_mul_f32_e32 v3, 0x3fb8aa3b, v3
	v_exp_f32_e32 v3, v3
	s_nop 0
	v_mul_f32_e64 v49, v45, -v3

;     __device__ __forceinline__ void operator()(f32x4 (&acc)[2][2][4][2], const Unit& u, int row0t, int wr, int wc, int fr, int fq) const {
;     ...
;                                 for (int e = 0; e < 4; ++e) { const int h = 4 * n + e; const float xx = v[e] + dt_bias[h]; const float sp = xx > 20.f ? xx : log1pf(__expf(xx)); o[e] = -__expf(A_log[h]) * sp; } }
;                             *(f32x4*)(bg + (size_t)r * 16 + 8 * fq + 4 * n) = o; } }
.LBB0_263:
	s_or_b64 exec, exec, s[24:25]
	v_or_b32_e32 v42, 48, v4
	v_ashrrev_i32_e32 v43, 31, v42
	v_lshlrev_b64 v[42:43], 6, v[42:43]
	v_lshl_add_u64 v[50:51], v[214:215], 0, v[42:43]
	global_store_dwordx4 v[50:51], v[46:49], off
	s_and_saveexec_b64 s[2:3], s[4:5]
	s_xor_b64 s[24:25], exec, s[2:3]
	s_cbranch_execz .LBB0_273
	v_mov_b32_e32 v3, v154
	v_add_f32_e32 v3, v38, v3
	v_cmp_nlt_f32_e32 vcc, s53, v3
	s_and_saveexec_b64 s[36:37], vcc
	s_cbranch_execz .LBB0_266
	v_mul_f32_e32 v3, 0x3fb8aa3b, v3
	v_exp_f32_e32 v3, v3
	s_nop 0
	v_add_f32_e32 v38, 1.0, v3
	v_frexp_mant_f32_e32 v45, v38
	v_cvt_f64_f32_e32 v[42:43], v38
	v_add_f32_e32 v44, -1.0, v38
	v_frexp_exp_i32_f64_e32 v42, v[42:43]
	v_cmp_gt_f32_e32 vcc, s55, v45
	v_sub_f32_e32 v46, v44, v38
	v_sub_f32_e32 v44, v3, v44
	v_subbrev_co_u32_e32 v52, vcc, 0, v42, vcc
	v_add_f32_e32 v46, 1.0, v46
	v_sub_u32_e32 v42, 0, v52
	v_add_f32_e32 v44, v44, v46
	v_ldexp_f32 v38, v38, v42
	v_ldexp_f32 v42, v44, v42
	v_add_f32_e32 v44, -1.0, v38
	v_add_f32_e32 v43, 1.0, v44
	v_sub_f32_e32 v43, v38, v43
	v_add_f32_e32 v45, v42, v43
	v_add_f32_e32 v43, 1.0, v38
	v_add_f32_e32 v46, -1.0, v43
	v_sub_f32_e32 v38, v38, v46
	v_add_f32_e32 v38, v42, v38
	v_add_f32_e32 v53, v43, v38
	v_rcp_f32_e32 v54, v53
	v_sub_f32_e32 v42, v53, v43
	v_add_f32_e32 v43, v44, v45
	v_sub_f32_e32 v38, v38, v42
	v_mul_f32_e32 v56, v43, v54
	v_sub_f32_e32 v42, v43, v44
	v_mul_f32_e32 v44, v53, v56
	v_fma_f32 v46, v56, v53, -v44
	v_fmac_f32_e32 v46, v56, v38
	v_sub_f32_e32 v55, v45, v42
	v_add_f32_e32 v42, v44, v46
	v_sub_f32_e32 v45, v43, v42
	v_pk_add_f32 v[48:49], v[42:43], v[44:45] neg_lo:[0,1] neg_hi:[0,1]
	v_mov_b32_e32 v47, v42
	v_pk_add_f32 v[42:43], v[48:49], v[46:47] neg_lo:[0,1] neg_hi:[0,1]
	v_cmp_neq_f32_e32 vcc, s57, v3
	v_add_f32_e32 v43, v55, v43
	v_add_f32_e32 v42, v42, v43
	v_add_f32_e32 v43, v45, v42
	v_mul_f32_e32 v55, v54, v43
	v_mul_f32_e32 v44, v53, v55
	v_fma_f32 v46, v55, v53, -v44
	v_fmac_f32_e32 v46, v55, v38
	v_sub_f32_e32 v38, v45, v43
	v_add_f32_e32 v38, v42, v38
	v_add_f32_e32 v42, v44, v46
	v_sub_f32_e32 v45, v43, v42
	v_pk_add_f32 v[48:49], v[42:43], v[44:45] neg_lo:[0,1] neg_hi:[0,1]
	v_mov_b32_e32 v47, v42
	v_pk_add_f32 v[42:43], v[48:49], v[46:47] neg_lo:[0,1] neg_hi:[0,1]
	s_nop 0
	v_add_f32_e32 v38, v38, v43
	v_add_f32_e32 v38, v42, v38
	v_add_f32_e32 v43, v56, v55
	v_add_f32_e32 v38, v45, v38
	v_sub_f32_e32 v42, v43, v56
	v_mul_f32_e32 v38, v54, v38
	v_sub_f32_e32 v42, v55, v42
	v_add_f32_e32 v38, v42, v38
	v_add_f32_e32 v44, v43, v38
	v_mul_f32_e32 v46, v44, v44
	v_fmamk_f32 v42, v46, 0x3e9b6dac, v235
	v_fmaak_f32 v227, v46, v42, 0x3f2aaada
	v_cvt_f32_i32_e32 v42, v52
	v_sub_f32_e32 v43, v44, v43
	v_sub_f32_e32 v38, v38, v43
	v_mul_f32_e32 v43, v44, v46
	v_pk_mul_f32 v[46:47], v[42:43], v[226:227]
	v_ldexp_f32 v45, v44, 1
	v_fma_f32 v44, v42, s56, -v46
	v_fmac_f32_e32 v44, 0xb102e308, v42
	v_pk_add_f32 v[42:43], v[46:47], v[44:45]
	v_ldexp_f32 v38, v38, 1
	v_sub_f32_e32 v45, v43, v45
	v_sub_f32_e32 v45, v47, v45
	v_add_f32_e32 v49, v38, v45
	v_mov_b32_e32 v48, v46
	v_pk_add_f32 v[46:47], v[42:43], v[46:47] neg_lo:[0,1] neg_hi:[0,1]
	v_pk_add_f32 v[52:53], v[42:43], v[48:49]
	v_mov_b32_e32 v45, v42
	v_mov_b32_e32 v47, v53
	v_pk_add_f32 v[54:55], v[44:45], v[46:47] neg_lo:[0,1] neg_hi:[0,1]
	v_pk_add_f32 v[44:45], v[44:45], v[46:47]
	v_mov_b32_e32 v48, v49
	v_pk_add_f32 v[46:47], v[44:45], v[42:43] op_sel:[1,0] op_sel_hi:[0,1] neg_lo:[0,1] neg_hi:[0,1]
	v_pk_add_f32 v[56:57], v[52:53], v[46:47] op_sel_hi:[1,0] neg_lo:[0,1] neg_hi:[0,1]
	v_mov_b32_e32 v52, v53
	v_mov_b32_e32 v53, v45
	v_pk_mov_b32 v[46:47], v[42:43], v[46:47] op_sel:[1,0]
	v_mov_b32_e32 v49, v42
	v_pk_add_f32 v[46:47], v[52:53], v[46:47] neg_lo:[0,1] neg_hi:[0,1]
	v_mov_b32_e32 v56, v54
	v_pk_add_f32 v[42:43], v[48:49], v[46:47] neg_lo:[0,1] neg_hi:[0,1]
	v_mov_b32_e32 v55, v45
	v_pk_add_f32 v[46:47], v[56:57], v[42:43]
	s_nop 0
	v_pk_add_f32 v[48:49], v[46:47], v[46:47] op_sel:[0,1] op_sel_hi:[1,0]
	s_nop 0
	v_pk_add_f32 v[44:45], v[44:45], v[48:49] op_sel:[1,0] op_sel_hi:[0,1]
	v_mov_b32_e32 v47, v44
	v_pk_add_f32 v[52:53], v[46:47], v[54:55] neg_lo:[0,1] neg_hi:[0,1]
	v_mov_b32_e32 v43, v48
	v_sub_f32_e32 v38, v46, v52
	v_pk_add_f32 v[42:43], v[42:43], v[52:53] neg_lo:[0,1] neg_hi:[0,1]
	v_sub_f32_e32 v38, v54, v38
	v_add_f32_e32 v38, v42, v38
	v_add_f32_e32 v38, v38, v43
	v_add_f32_e32 v38, v44, v38
	v_cndmask_b32_e32 v38, v236, v38, vcc
	v_cmp_ngt_f32_e32 vcc, -1.0, v3
	s_nop 1
	v_cndmask_b32_e32 v38, v237, v38, vcc
	v_cmp_neq_f32_e32 vcc, -1.0, v3
	s_nop 1
	v_cndmask_b32_e32 v38, v238, v38, vcc
	v_cmp_lt_f32_e64 vcc, |v3|, s58
	s_nop 1
	v_cndmask_b32_e32 v3, v38, v3, vcc
;     __device__ __forceinline__ void operator()(f32x4 (&acc)[2][2][4][2], const Unit& u, int row0t, int wr, int wc, int fr, int fq) const {
;     ...
;                                 for (int e = 0; e < 4; ++e) { const int h = 4 * n + e; const float xx = v[e] + dt_bias[h]; const float sp = xx > 20.f ? xx : log1pf(__expf(xx)); o[e] = -__expf(A_log[h]) * sp; } }
.LBB0_266:
	s_or_b64 exec, exec, s[36:37]
	v_mov_b32_e32 v42, v155
	v_mov_b32_e32 v38, v162
	v_add_f32_e32 v39, v39, v42
	v_cmp_nlt_f32_e32 vcc, s53, v39
	s_and_saveexec_b64 s[36:37], vcc
	s_cbranch_execz .LBB0_268
	v_mul_f32_e32 v39, 0x3fb8aa3b, v39
	v_exp_f32_e32 v39, v39
	s_nop 0
	v_add_f32_e32 v44, 1.0, v39
	v_frexp_mant_f32_e32 v46, v44
	v_cvt_f64_f32_e32 v[42:43], v44
	v_frexp_exp_i32_f64_e32 v42, v[42:43]
	v_cmp_gt_f32_e32 vcc, s55, v46
	v_add_f32_e32 v45, -1.0, v44
	v_sub_f32_e32 v47, v45, v44
	v_subbrev_co_u32_e32 v52, vcc, 0, v42, vcc
	v_sub_u32_e32 v42, 0, v52
	v_sub_f32_e32 v45, v39, v45
	v_add_f32_e32 v47, 1.0, v47
	v_ldexp_f32 v43, v44, v42
	v_add_f32_e32 v45, v45, v47
	v_add_f32_e32 v44, -1.0, v43
	v_add_f32_e32 v46, 1.0, v43
	v_ldexp_f32 v42, v45, v42
	v_add_f32_e32 v45, 1.0, v44
	v_add_f32_e32 v47, -1.0, v46
	v_sub_f32_e32 v45, v43, v45
	v_sub_f32_e32 v43, v43, v47
	v_add_f32_e32 v45, v42, v45
	v_add_f32_e32 v42, v42, v43
	v_add_f32_e32 v53, v46, v42
	v_rcp_f32_e32 v55, v53
	v_sub_f32_e32 v43, v53, v46
	v_sub_f32_e32 v54, v42, v43
	v_add_f32_e32 v43, v44, v45
	v_mul_f32_e32 v57, v43, v55
	v_sub_f32_e32 v42, v43, v44
	v_mul_f32_e32 v44, v53, v57
	v_fma_f32 v46, v57, v53, -v44
	v_fmac_f32_e32 v46, v57, v54
	v_sub_f32_e32 v56, v45, v42
	v_add_f32_e32 v42, v44, v46
	v_sub_f32_e32 v45, v43, v42
	v_pk_add_f32 v[48:49], v[42:43], v[44:45] neg_lo:[0,1] neg_hi:[0,1]
	v_mov_b32_e32 v47, v42
	v_pk_add_f32 v[42:43], v[48:49], v[46:47] neg_lo:[0,1] neg_hi:[0,1]
	v_cmp_neq_f32_e32 vcc, s57, v39
	v_add_f32_e32 v43, v56, v43
	v_add_f32_e32 v42, v42, v43
	v_add_f32_e32 v43, v45, v42
	v_mul_f32_e32 v56, v55, v43
	v_mul_f32_e32 v44, v53, v56
	v_fma_f32 v46, v56, v53, -v44
	v_fmac_f32_e32 v46, v56, v54
	v_sub_f32_e32 v45, v45, v43
	v_add_f32_e32 v53, v42, v45
	v_add_f32_e32 v42, v44, v46
	v_sub_f32_e32 v45, v43, v42
	v_pk_add_f32 v[48:49], v[42:43], v[44:45] neg_lo:[0,1] neg_hi:[0,1]
	v_mov_b32_e32 v47, v42
	v_pk_add_f32 v[42:43], v[48:49], v[46:47] neg_lo:[0,1] neg_hi:[0,1]
	s_nop 0
	v_add_f32_e32 v43, v53, v43
	v_add_f32_e32 v42, v42, v43
	v_add_f32_e32 v43, v57, v56
	v_add_f32_e32 v42, v45, v42
	v_sub_f32_e32 v44, v43, v57
	v_mul_f32_e32 v42, v55, v42
	v_sub_f32_e32 v44, v56, v44
	v_add_f32_e32 v44, v44, v42
	v_add_f32_e32 v46, v43, v44
	v_mul_f32_e32 v47, v46, v46
	v_fmamk_f32 v42, v47, 0x3e9b6dac, v235
	v_fmaak_f32 v227, v47, v42, 0x3f2aaada
	v_cvt_f32_i32_e32 v42, v52
	v_sub_f32_e32 v43, v46, v43
	v_sub_f32_e32 v43, v44, v43
	v_ldexp_f32 v48, v43, 1
	v_mul_f32_e32 v43, v46, v47
	v_ldexp_f32 v45, v46, 1
	v_pk_mul_f32 v[46:47], v[42:43], v[226:227]
	s_nop 0
	v_fma_f32 v44, v42, s56, -v46
	v_fmac_f32_e32 v44, 0xb102e308, v42
	v_pk_add_f32 v[42:43], v[46:47], v[44:45]
	s_nop 0
	v_sub_f32_e32 v45, v43, v45
	v_sub_f32_e32 v45, v47, v45
	v_add_f32_e32 v49, v48, v45
	v_mov_b32_e32 v48, v46
	v_pk_add_f32 v[46:47], v[42:43], v[46:47] neg_lo:[0,1] neg_hi:[0,1]
	v_pk_add_f32 v[52:53], v[42:43], v[48:49]
	v_mov_b32_e32 v45, v42
	v_mov_b32_e32 v47, v53
	v_pk_add_f32 v[54:55], v[44:45], v[46:47] neg_lo:[0,1] neg_hi:[0,1]
	v_pk_add_f32 v[44:45], v[44:45], v[46:47]
	v_mov_b32_e32 v48, v49
	v_pk_add_f32 v[46:47], v[44:45], v[42:43] op_sel:[1,0] op_sel_hi:[0,1] neg_lo:[0,1] neg_hi:[0,1]
	v_pk_add_f32 v[56:57], v[52:53], v[46:47] op_sel_hi:[1,0] neg_lo:[0,1] neg_hi:[0,1]
	v_mov_b32_e32 v52, v53
	v_mov_b32_e32 v53, v45
	v_pk_mov_b32 v[46:47], v[42:43], v[46:47] op_sel:[1,0]
	v_mov_b32_e32 v49, v42
	v_pk_add_f32 v[46:47], v[52:53], v[46:47] neg_lo:[0,1] neg_hi:[0,1]
	v_mov_b32_e32 v56, v54
	v_pk_add_f32 v[42:43], v[48:49], v[46:47] neg_lo:[0,1] neg_hi:[0,1]
	v_mov_b32_e32 v55, v45
	v_pk_add_f32 v[46:47], v[56:57], v[42:43]
	s_nop 0
	v_pk_add_f32 v[48:49], v[46:47], v[46:47] op_sel:[0,1] op_sel_hi:[1,0]
	s_nop 0
	v_pk_add_f32 v[44:45], v[44:45], v[48:49] op_sel:[1,0] op_sel_hi:[0,1]
	v_mov_b32_e32 v47, v44
	v_pk_add_f32 v[52:53], v[46:47], v[54:55] neg_lo:[0,1] neg_hi:[0,1]
	v_mov_b32_e32 v43, v48
	v_sub_f32_e32 v45, v46, v52
	v_pk_add_f32 v[42:43], v[42:43], v[52:53] neg_lo:[0,1] neg_hi:[0,1]
	v_sub_f32_e32 v45, v54, v45
	v_add_f32_e32 v42, v42, v45
	v_add_f32_e32 v42, v42, v43
	v_add_f32_e32 v42, v44, v42
	v_cndmask_b32_e32 v42, v236, v42, vcc
	v_cmp_ngt_f32_e32 vcc, -1.0, v39
	s_nop 1
	v_cndmask_b32_e32 v42, v237, v42, vcc
	v_cmp_neq_f32_e32 vcc, -1.0, v39
	s_nop 1
	v_cndmask_b32_e32 v42, v238, v42, vcc
	v_cmp_lt_f32_e64 vcc, |v39|, s58
	s_nop 1
	v_cndmask_b32_e32 v39, v42, v39, vcc
;     __device__ __forceinline__ void operator()(f32x4 (&acc)[2][2][4][2], const Unit& u, int row0t, int wr, int wc, int fr, int fq) const {
;     ...
;                                 for (int e = 0; e < 4; ++e) { const int h = 4 * n + e; const float xx = v[e] + dt_bias[h]; const float sp = xx > 20.f ? xx : log1pf(__expf(xx)); o[e] = -__expf(A_log[h]) * sp; } }
.LBB0_268:
	s_or_b64 exec, exec, s[36:37]
	v_mov_b32_e32 v42, v156
	v_mov_b32_e32 v43, v163
	v_add_f32_e32 v40, v40, v42
	v_cmp_nlt_f32_e32 vcc, s53, v40
	s_and_saveexec_b64 s[36:37], vcc
	s_cbranch_execz .LBB0_270
	v_mul_f32_e32 v40, 0x3fb8aa3b, v40
	v_exp_f32_e32 v40, v40
	s_nop 0
	v_add_f32_e32 v42, 1.0, v40
	v_frexp_mant_f32_e32 v47, v42
	v_cvt_f64_f32_e32 v[44:45], v42
	v_add_f32_e32 v46, -1.0, v42
	v_frexp_exp_i32_f64_e32 v44, v[44:45]
	v_cmp_gt_f32_e32 vcc, s55, v47
	v_sub_f32_e32 v48, v46, v42
	v_sub_f32_e32 v46, v40, v46
	v_subbrev_co_u32_e32 v54, vcc, 0, v44, vcc
	v_add_f32_e32 v48, 1.0, v48
	v_sub_u32_e32 v44, 0, v54
	v_add_f32_e32 v46, v46, v48
	v_ldexp_f32 v42, v42, v44
	v_ldexp_f32 v44, v46, v44
	v_add_f32_e32 v46, -1.0, v42
	v_add_f32_e32 v45, 1.0, v46
	v_sub_f32_e32 v45, v42, v45
	v_add_f32_e32 v47, v44, v45
	v_add_f32_e32 v45, 1.0, v42
	v_add_f32_e32 v48, -1.0, v45
	v_sub_f32_e32 v42, v42, v48
	v_add_f32_e32 v42, v44, v42
	v_add_f32_e32 v55, v45, v42
	v_rcp_f32_e32 v56, v55
	v_sub_f32_e32 v44, v55, v45
	v_add_f32_e32 v45, v46, v47
	v_sub_f32_e32 v42, v42, v44
	v_mul_f32_e32 v58, v45, v56
	v_sub_f32_e32 v44, v45, v46
	v_mul_f32_e32 v46, v55, v58
	v_fma_f32 v48, v58, v55, -v46
	v_fmac_f32_e32 v48, v58, v42
	v_sub_f32_e32 v57, v47, v44
	v_add_f32_e32 v44, v46, v48
	v_sub_f32_e32 v47, v45, v44
	v_pk_add_f32 v[52:53], v[44:45], v[46:47] neg_lo:[0,1] neg_hi:[0,1]
	v_mov_b32_e32 v49, v44
	v_pk_add_f32 v[44:45], v[52:53], v[48:49] neg_lo:[0,1] neg_hi:[0,1]
	v_cmp_neq_f32_e32 vcc, s57, v40
	v_add_f32_e32 v45, v57, v45
	v_add_f32_e32 v44, v44, v45
	v_add_f32_e32 v45, v47, v44
	v_mul_f32_e32 v57, v56, v45
	v_mul_f32_e32 v46, v55, v57
	v_fma_f32 v48, v57, v55, -v46
	v_fmac_f32_e32 v48, v57, v42
	v_sub_f32_e32 v42, v47, v45
	v_add_f32_e32 v42, v44, v42
	v_add_f32_e32 v44, v46, v48
	v_sub_f32_e32 v47, v45, v44
	v_pk_add_f32 v[52:53], v[44:45], v[46:47] neg_lo:[0,1] neg_hi:[0,1]
	v_mov_b32_e32 v49, v44
	v_pk_add_f32 v[44:45], v[52:53], v[48:49] neg_lo:[0,1] neg_hi:[0,1]
	s_nop 0
	v_add_f32_e32 v42, v42, v45
	v_add_f32_e32 v42, v44, v42
	v_add_f32_e32 v45, v58, v57
	v_add_f32_e32 v42, v47, v42
	v_sub_f32_e32 v44, v45, v58
	v_mul_f32_e32 v42, v56, v42
	v_sub_f32_e32 v44, v57, v44
	v_add_f32_e32 v42, v44, v42
	v_add_f32_e32 v46, v45, v42
	v_mul_f32_e32 v48, v46, v46
	v_fmamk_f32 v44, v48, 0x3e9b6dac, v235
	v_fmaak_f32 v227, v48, v44, 0x3f2aaada
	v_cvt_f32_i32_e32 v44, v54
	v_sub_f32_e32 v45, v46, v45
	v_sub_f32_e32 v42, v42, v45
	v_mul_f32_e32 v45, v46, v48
	v_pk_mul_f32 v[48:49], v[44:45], v[226:227]
	v_ldexp_f32 v47, v46, 1
	v_fma_f32 v46, v44, s56, -v48
	v_fmac_f32_e32 v46, 0xb102e308, v44
	v_pk_add_f32 v[44:45], v[48:49], v[46:47]
	v_ldexp_f32 v42, v42, 1
	v_sub_f32_e32 v47, v45, v47
	v_sub_f32_e32 v47, v49, v47
	v_add_f32_e32 v53, v42, v47
	v_mov_b32_e32 v52, v48
	v_pk_add_f32 v[48:49], v[44:45], v[48:49] neg_lo:[0,1] neg_hi:[0,1]
	v_pk_add_f32 v[54:55], v[44:45], v[52:53]
	v_mov_b32_e32 v47, v44
	v_mov_b32_e32 v49, v55
	v_pk_add_f32 v[56:57], v[46:47], v[48:49] neg_lo:[0,1] neg_hi:[0,1]
	v_pk_add_f32 v[46:47], v[46:47], v[48:49]
	v_mov_b32_e32 v52, v53
	v_pk_add_f32 v[48:49], v[46:47], v[44:45] op_sel:[1,0] op_sel_hi:[0,1] neg_lo:[0,1] neg_hi:[0,1]
	v_pk_add_f32 v[58:59], v[54:55], v[48:49] op_sel_hi:[1,0] neg_lo:[0,1] neg_hi:[0,1]
	v_mov_b32_e32 v54, v55
	v_mov_b32_e32 v55, v47
	v_pk_mov_b32 v[48:49], v[44:45], v[48:49] op_sel:[1,0]
	v_mov_b32_e32 v53, v44
	v_pk_add_f32 v[48:49], v[54:55], v[48:49] neg_lo:[0,1] neg_hi:[0,1]
	v_mov_b32_e32 v58, v56
	v_pk_add_f32 v[44:45], v[52:53], v[48:49] neg_lo:[0,1] neg_hi:[0,1]
	v_mov_b32_e32 v57, v47
	v_pk_add_f32 v[48:49], v[58:59], v[44:45]
	s_nop 0
	v_pk_add_f32 v[52:53], v[48:49], v[48:49] op_sel:[0,1] op_sel_hi:[1,0]
	s_nop 0
	v_pk_add_f32 v[46:47], v[46:47], v[52:53] op_sel:[1,0] op_sel_hi:[0,1]
	v_mov_b32_e32 v49, v46
	v_pk_add_f32 v[54:55], v[48:49], v[56:57] neg_lo:[0,1] neg_hi:[0,1]
	v_mov_b32_e32 v45, v52
	v_sub_f32_e32 v42, v48, v54
	v_pk_add_f32 v[44:45], v[44:45], v[54:55] neg_lo:[0,1] neg_hi:[0,1]
	v_sub_f32_e32 v42, v56, v42
	v_add_f32_e32 v42, v44, v42
	v_add_f32_e32 v42, v42, v45
	v_add_f32_e32 v42, v46, v42
	v_cndmask_b32_e32 v42, v236, v42, vcc
	v_cmp_ngt_f32_e32 vcc, -1.0, v40
	s_nop 1
	v_cndmask_b32_e32 v42, v237, v42, vcc
	v_cmp_neq_f32_e32 vcc, -1.0, v40
	s_nop 1
	v_cndmask_b32_e32 v42, v238, v42, vcc
	v_cmp_lt_f32_e64 vcc, |v40|, s58
	s_nop 1
	v_cndmask_b32_e32 v40, v42, v40, vcc
;     __device__ __forceinline__ void operator()(f32x4 (&acc)[2][2][4][2], const Unit& u, int row0t, int wr, int wc, int fr, int fq) const {
;     ...
;                                 for (int e = 0; e < 4; ++e) { const int h = 4 * n + e; const float xx = v[e] + dt_bias[h]; const float sp = xx > 20.f ? xx : log1pf(__expf(xx)); o[e] = -__expf(A_log[h]) * sp; } }
.LBB0_270:
	s_or_b64 exec, exec, s[36:37]
	v_mov_b32_e32 v42, v157
	v_mov_b32_e32 v44, v164
	v_add_f32_e32 v41, v41, v42
	v_cmp_nlt_f32_e32 vcc, s53, v41
	s_and_saveexec_b64 s[36:37], vcc
	s_cbranch_execz .LBB0_272
	v_mul_f32_e32 v41, 0x3fb8aa3b, v41
	v_exp_f32_e32 v41, v41
	s_nop 0
	v_add_f32_e32 v42, 1.0, v41
	v_frexp_mant_f32_e32 v48, v42
	v_cvt_f64_f32_e32 v[46:47], v42
	v_add_f32_e32 v45, -1.0, v42
	v_frexp_exp_i32_f64_e32 v46, v[46:47]
	v_cmp_gt_f32_e32 vcc, s55, v48
	v_sub_f32_e32 v49, v45, v42
	v_sub_f32_e32 v45, v41, v45
	v_subbrev_co_u32_e32 v56, vcc, 0, v46, vcc
	v_add_f32_e32 v49, 1.0, v49
	v_sub_u32_e32 v46, 0, v56
	v_add_f32_e32 v45, v45, v49
	v_ldexp_f32 v42, v42, v46
	v_ldexp_f32 v45, v45, v46
	v_add_f32_e32 v46, -1.0, v42
	v_add_f32_e32 v47, 1.0, v46
	v_sub_f32_e32 v47, v42, v47
	v_add_f32_e32 v48, v45, v47
	v_add_f32_e32 v47, 1.0, v42
	v_add_f32_e32 v49, -1.0, v47
	v_sub_f32_e32 v42, v42, v49
	v_add_f32_e32 v42, v45, v42
	v_add_f32_e32 v45, v47, v42
	v_rcp_f32_e32 v57, v45
	v_sub_f32_e32 v47, v45, v47
	v_sub_f32_e32 v42, v42, v47
	v_add_f32_e32 v47, v46, v48
	v_sub_f32_e32 v46, v47, v46
	v_mul_f32_e32 v59, v47, v57
	v_sub_f32_e32 v58, v48, v46
	v_mul_f32_e32 v48, v45, v59
	v_fma_f32 v52, v59, v45, -v48
	v_fmac_f32_e32 v52, v59, v42
	v_add_f32_e32 v46, v48, v52
	v_sub_f32_e32 v49, v47, v46
	v_pk_add_f32 v[54:55], v[46:47], v[48:49] neg_lo:[0,1] neg_hi:[0,1]
	v_mov_b32_e32 v53, v46
	v_pk_add_f32 v[46:47], v[54:55], v[52:53] neg_lo:[0,1] neg_hi:[0,1]
	v_cmp_neq_f32_e32 vcc, s57, v41
	v_add_f32_e32 v47, v58, v47
	v_add_f32_e32 v46, v46, v47
	v_add_f32_e32 v47, v49, v46
	v_mul_f32_e32 v58, v57, v47
	v_mul_f32_e32 v48, v45, v58
	v_fma_f32 v52, v58, v45, -v48
	v_fmac_f32_e32 v52, v58, v42
	v_sub_f32_e32 v42, v49, v47
	v_add_f32_e32 v42, v46, v42
	v_add_f32_e32 v46, v48, v52
	v_sub_f32_e32 v49, v47, v46
	v_pk_add_f32 v[54:55], v[46:47], v[48:49] neg_lo:[0,1] neg_hi:[0,1]
	v_mov_b32_e32 v53, v46
	v_pk_add_f32 v[46:47], v[54:55], v[52:53] neg_lo:[0,1] neg_hi:[0,1]
	v_add_f32_e32 v45, v59, v58
	v_add_f32_e32 v42, v42, v47
	v_add_f32_e32 v42, v46, v42
	v_add_f32_e32 v42, v49, v42
	v_sub_f32_e32 v46, v45, v59
	v_mul_f32_e32 v42, v57, v42
	v_sub_f32_e32 v46, v58, v46
	v_add_f32_e32 v42, v46, v42
	v_add_f32_e32 v47, v45, v42
	v_mul_f32_e32 v48, v47, v47
	v_fmamk_f32 v46, v48, 0x3e9b6dac, v235
	v_fmaak_f32 v227, v48, v46, 0x3f2aaada
	v_cvt_f32_i32_e32 v46, v56
	v_sub_f32_e32 v45, v47, v45
	v_ldexp_f32 v49, v47, 1
	v_mul_f32_e32 v47, v47, v48
	v_pk_mul_f32 v[52:53], v[46:47], v[226:227]
	v_sub_f32_e32 v42, v42, v45
	v_fma_f32 v48, v46, s56, -v52
	v_fmac_f32_e32 v48, 0xb102e308, v46
	v_pk_add_f32 v[46:47], v[52:53], v[48:49]
	v_ldexp_f32 v42, v42, 1
	v_sub_f32_e32 v45, v47, v49
	v_sub_f32_e32 v45, v53, v45
	v_add_f32_e32 v55, v42, v45
	v_mov_b32_e32 v54, v52
	v_pk_add_f32 v[52:53], v[46:47], v[52:53] neg_lo:[0,1] neg_hi:[0,1]
	v_pk_add_f32 v[56:57], v[46:47], v[54:55]
	v_mov_b32_e32 v49, v46
	v_mov_b32_e32 v53, v57
	v_pk_add_f32 v[58:59], v[48:49], v[52:53] neg_lo:[0,1] neg_hi:[0,1]
	v_pk_add_f32 v[48:49], v[48:49], v[52:53]
	v_mov_b32_e32 v54, v55
	v_pk_add_f32 v[52:53], v[48:49], v[46:47] op_sel:[1,0] op_sel_hi:[0,1] neg_lo:[0,1] neg_hi:[0,1]
	v_pk_add_f32 v[60:61], v[56:57], v[52:53] op_sel_hi:[1,0] neg_lo:[0,1] neg_hi:[0,1]
	v_mov_b32_e32 v56, v57
	v_mov_b32_e32 v57, v49
	v_pk_mov_b32 v[52:53], v[46:47], v[52:53] op_sel:[1,0]
	v_mov_b32_e32 v55, v46
	v_pk_add_f32 v[52:53], v[56:57], v[52:53] neg_lo:[0,1] neg_hi:[0,1]
	v_mov_b32_e32 v60, v58
	v_pk_add_f32 v[46:47], v[54:55], v[52:53] neg_lo:[0,1] neg_hi:[0,1]
	v_mov_b32_e32 v59, v49
	v_pk_add_f32 v[52:53], v[60:61], v[46:47]
	s_nop 0
	v_pk_add_f32 v[54:55], v[52:53], v[52:53] op_sel:[0,1] op_sel_hi:[1,0]
	s_nop 0
	v_pk_add_f32 v[48:49], v[48:49], v[54:55] op_sel:[1,0] op_sel_hi:[0,1]
	v_mov_b32_e32 v53, v48
	v_pk_add_f32 v[56:57], v[52:53], v[58:59] neg_lo:[0,1] neg_hi:[0,1]
	v_mov_b32_e32 v47, v54
	v_sub_f32_e32 v42, v52, v56
	v_pk_add_f32 v[46:47], v[46:47], v[56:57] neg_lo:[0,1] neg_hi:[0,1]
	v_sub_f32_e32 v42, v58, v42
	v_add_f32_e32 v42, v46, v42
	v_add_f32_e32 v42, v42, v47
	v_add_f32_e32 v42, v48, v42
	v_cndmask_b32_e32 v42, v236, v42, vcc
	v_cmp_ngt_f32_e32 vcc, -1.0, v41
	s_nop 1
	v_cndmask_b32_e32 v42, v237, v42, vcc
	v_cmp_neq_f32_e32 vcc, -1.0, v41
	s_nop 1
	v_cndmask_b32_e32 v42, v238, v42, vcc
	v_cmp_lt_f32_e64 vcc, |v41|, s58
	s_nop 1
	v_cndmask_b32_e32 v41, v42, v41, vcc
.LBB0_272:
	s_or_b64 exec, exec, s[36:37]
	v_mul_f32_e32 v38, 0x3fb8aa3b, v38
	v_exp_f32_e32 v38, v38
	s_nop 0
	v_mul_f32_e64 v42, v3, -v38
	v_mul_f32_e32 v3, 0x3fb8aa3b, v43
	v_exp_f32_e32 v3, v3
	s_nop 0
	v_mul_f32_e64 v43, v39, -v3
	v_mul_f32_e32 v3, 0x3fb8aa3b, v44
	v_exp_f32_e32 v3, v3
	s_nop 0
	v_mul_f32_e64 v44, v40, -v3
	v_mov_b32_e32 v3, v165
	v_mul_f32_e32 v3, 0x3fb8aa3b, v3
	v_exp_f32_e32 v3, v3
	s_nop 0
	v_mul_f32_e64 v45, v41, -v3

;     __device__ __forceinline__ void operator()(f32x4 (&acc)[2][2][4][2], const Unit& u, int row0t, int wr, int wc, int fr, int fq) const {
;     ...
;                                 for (int e = 0; e < 4; ++e) { const int h = 4 * n + e; const float xx = v[e] + dt_bias[h]; const float sp = xx > 20.f ? xx : log1pf(__expf(xx)); o[e] = -__expf(A_log[h]) * sp; } }
;                             *(f32x4*)(bg + (size_t)r * 16 + 8 * fq + 4 * n) = o; } }
.LBB0_275:
	s_or_b64 exec, exec, s[24:25]
	global_store_dwordx4 v[50:51], v[42:45], off offset:16
	s_and_saveexec_b64 s[2:3], s[4:5]
	s_xor_b64 s[24:25], exec, s[2:3]
	s_cbranch_execz .LBB0_285
	v_mov_b32_e32 v3, v150
	v_add_f32_e32 v3, v34, v3
	v_cmp_nlt_f32_e32 vcc, s53, v3
	s_and_saveexec_b64 s[36:37], vcc
	s_cbranch_execz .LBB0_278
	v_mul_f32_e32 v3, 0x3fb8aa3b, v3
	v_exp_f32_e32 v3, v3
	s_nop 0
	v_add_f32_e32 v34, 1.0, v3
	v_frexp_mant_f32_e32 v41, v34
	v_cvt_f64_f32_e32 v[38:39], v34
	v_add_f32_e32 v40, -1.0, v34
	v_frexp_exp_i32_f64_e32 v38, v[38:39]
	v_cmp_gt_f32_e32 vcc, s55, v41
	v_sub_f32_e32 v42, v40, v34
	v_sub_f32_e32 v40, v3, v40
	v_subbrev_co_u32_e32 v46, vcc, 0, v38, vcc
	v_add_f32_e32 v42, 1.0, v42
	v_sub_u32_e32 v38, 0, v46
	v_add_f32_e32 v40, v40, v42
	v_ldexp_f32 v34, v34, v38
	v_ldexp_f32 v38, v40, v38
	v_add_f32_e32 v40, -1.0, v34
	v_add_f32_e32 v39, 1.0, v40
	v_sub_f32_e32 v39, v34, v39
	v_add_f32_e32 v41, v38, v39
	v_add_f32_e32 v39, 1.0, v34
	v_add_f32_e32 v42, -1.0, v39
	v_sub_f32_e32 v34, v34, v42
	v_add_f32_e32 v34, v38, v34
	v_add_f32_e32 v47, v39, v34
	v_rcp_f32_e32 v48, v47
	v_sub_f32_e32 v38, v47, v39
	v_add_f32_e32 v39, v40, v41
	v_sub_f32_e32 v34, v34, v38
	v_mul_f32_e32 v50, v39, v48
	v_sub_f32_e32 v38, v39, v40
	v_mul_f32_e32 v40, v47, v50
	v_fma_f32 v42, v50, v47, -v40
	v_fmac_f32_e32 v42, v50, v34
	v_sub_f32_e32 v49, v41, v38
	v_add_f32_e32 v38, v40, v42
	v_sub_f32_e32 v41, v39, v38
	v_pk_add_f32 v[44:45], v[38:39], v[40:41] neg_lo:[0,1] neg_hi:[0,1]
	v_mov_b32_e32 v43, v38
	v_pk_add_f32 v[38:39], v[44:45], v[42:43] neg_lo:[0,1] neg_hi:[0,1]
	v_cmp_neq_f32_e32 vcc, s57, v3
	v_add_f32_e32 v39, v49, v39
	v_add_f32_e32 v38, v38, v39
	v_add_f32_e32 v39, v41, v38
	v_mul_f32_e32 v49, v48, v39
	v_mul_f32_e32 v40, v47, v49
	v_fma_f32 v42, v49, v47, -v40
	v_fmac_f32_e32 v42, v49, v34
	v_sub_f32_e32 v34, v41, v39
	v_add_f32_e32 v34, v38, v34
	v_add_f32_e32 v38, v40, v42
	v_sub_f32_e32 v41, v39, v38
	v_pk_add_f32 v[44:45], v[38:39], v[40:41] neg_lo:[0,1] neg_hi:[0,1]
	v_mov_b32_e32 v43, v38
	v_pk_add_f32 v[38:39], v[44:45], v[42:43] neg_lo:[0,1] neg_hi:[0,1]
	s_nop 0
	v_add_f32_e32 v34, v34, v39
	v_add_f32_e32 v34, v38, v34
	v_add_f32_e32 v39, v50, v49
	v_add_f32_e32 v34, v41, v34
	v_sub_f32_e32 v38, v39, v50
	v_mul_f32_e32 v34, v48, v34
	v_sub_f32_e32 v38, v49, v38
	v_add_f32_e32 v34, v38, v34
	v_add_f32_e32 v40, v39, v34
	v_mul_f32_e32 v42, v40, v40
	v_fmamk_f32 v38, v42, 0x3e9b6dac, v235
	v_fmaak_f32 v227, v42, v38, 0x3f2aaada
	v_cvt_f32_i32_e32 v38, v46
	v_sub_f32_e32 v39, v40, v39
	v_sub_f32_e32 v34, v34, v39
	v_mul_f32_e32 v39, v40, v42
	v_pk_mul_f32 v[42:43], v[38:39], v[226:227]
	v_ldexp_f32 v41, v40, 1
	v_fma_f32 v40, v38, s56, -v42
	v_fmac_f32_e32 v40, 0xb102e308, v38
	v_pk_add_f32 v[38:39], v[42:43], v[40:41]
	v_ldexp_f32 v34, v34, 1
	v_sub_f32_e32 v41, v39, v41
	v_sub_f32_e32 v41, v43, v41
	v_add_f32_e32 v45, v34, v41
	v_mov_b32_e32 v44, v42
	v_pk_add_f32 v[42:43], v[38:39], v[42:43] neg_lo:[0,1] neg_hi:[0,1]
	v_pk_add_f32 v[46:47], v[38:39], v[44:45]
	v_mov_b32_e32 v41, v38
	v_mov_b32_e32 v43, v47
	v_pk_add_f32 v[48:49], v[40:41], v[42:43] neg_lo:[0,1] neg_hi:[0,1]
	v_pk_add_f32 v[40:41], v[40:41], v[42:43]
	v_mov_b32_e32 v44, v45
	v_pk_add_f32 v[42:43], v[40:41], v[38:39] op_sel:[1,0] op_sel_hi:[0,1] neg_lo:[0,1] neg_hi:[0,1]
	v_pk_add_f32 v[50:51], v[46:47], v[42:43] op_sel_hi:[1,0] neg_lo:[0,1] neg_hi:[0,1]
	v_mov_b32_e32 v46, v47
	v_mov_b32_e32 v47, v41
	v_pk_mov_b32 v[42:43], v[38:39], v[42:43] op_sel:[1,0]
	v_mov_b32_e32 v45, v38
	v_pk_add_f32 v[42:43], v[46:47], v[42:43] neg_lo:[0,1] neg_hi:[0,1]
	v_mov_b32_e32 v50, v48
	v_pk_add_f32 v[38:39], v[44:45], v[42:43] neg_lo:[0,1] neg_hi:[0,1]
	v_mov_b32_e32 v49, v41
	v_pk_add_f32 v[42:43], v[50:51], v[38:39]
	s_nop 0
	v_pk_add_f32 v[44:45], v[42:43], v[42:43] op_sel:[0,1] op_sel_hi:[1,0]
	s_nop 0
	v_pk_add_f32 v[40:41], v[40:41], v[44:45] op_sel:[1,0] op_sel_hi:[0,1]
	v_mov_b32_e32 v43, v40
	v_pk_add_f32 v[46:47], v[42:43], v[48:49] neg_lo:[0,1] neg_hi:[0,1]
	v_mov_b32_e32 v39, v44
	v_sub_f32_e32 v34, v42, v46
	v_pk_add_f32 v[38:39], v[38:39], v[46:47] neg_lo:[0,1] neg_hi:[0,1]
	v_sub_f32_e32 v34, v48, v34
	v_add_f32_e32 v34, v38, v34
	v_add_f32_e32 v34, v34, v39
	v_add_f32_e32 v34, v40, v34
	v_cndmask_b32_e32 v34, v236, v34, vcc
	v_cmp_ngt_f32_e32 vcc, -1.0, v3
	s_nop 1
	v_cndmask_b32_e32 v34, v237, v34, vcc
	v_cmp_neq_f32_e32 vcc, -1.0, v3
	s_nop 1
	v_cndmask_b32_e32 v34, v238, v34, vcc
	v_cmp_lt_f32_e64 vcc, |v3|, s58
	s_nop 1
	v_cndmask_b32_e32 v3, v34, v3, vcc
;     __device__ __forceinline__ void operator()(f32x4 (&acc)[2][2][4][2], const Unit& u, int row0t, int wr, int wc, int fr, int fq) const {
;     ...
;                                 for (int e = 0; e < 4; ++e) { const int h = 4 * n + e; const float xx = v[e] + dt_bias[h]; const float sp = xx > 20.f ? xx : log1pf(__expf(xx)); o[e] = -__expf(A_log[h]) * sp; } }
.LBB0_278:
	s_or_b64 exec, exec, s[36:37]
	v_mov_b32_e32 v38, v151
	v_mov_b32_e32 v34, v158
	v_add_f32_e32 v35, v35, v38
	v_cmp_nlt_f32_e32 vcc, s53, v35
	s_and_saveexec_b64 s[36:37], vcc
	s_cbranch_execz .LBB0_280
	v_mul_f32_e32 v35, 0x3fb8aa3b, v35
	v_exp_f32_e32 v35, v35
	s_nop 0
	v_add_f32_e32 v40, 1.0, v35
	v_frexp_mant_f32_e32 v42, v40
	v_cvt_f64_f32_e32 v[38:39], v40
	v_frexp_exp_i32_f64_e32 v38, v[38:39]
	v_cmp_gt_f32_e32 vcc, s55, v42
	v_add_f32_e32 v41, -1.0, v40
	v_sub_f32_e32 v43, v41, v40
	v_subbrev_co_u32_e32 v46, vcc, 0, v38, vcc
	v_sub_u32_e32 v38, 0, v46
	v_sub_f32_e32 v41, v35, v41
	v_add_f32_e32 v43, 1.0, v43
	v_ldexp_f32 v39, v40, v38
	v_add_f32_e32 v41, v41, v43
	v_add_f32_e32 v40, -1.0, v39
	v_add_f32_e32 v42, 1.0, v39
	v_ldexp_f32 v38, v41, v38
	v_add_f32_e32 v41, 1.0, v40
	v_add_f32_e32 v43, -1.0, v42
	v_sub_f32_e32 v41, v39, v41
	v_sub_f32_e32 v39, v39, v43
	v_add_f32_e32 v41, v38, v41
	v_add_f32_e32 v38, v38, v39
	v_add_f32_e32 v47, v42, v38
	v_rcp_f32_e32 v49, v47
	v_sub_f32_e32 v39, v47, v42
	v_sub_f32_e32 v48, v38, v39
	v_add_f32_e32 v39, v40, v41
	v_mul_f32_e32 v51, v39, v49
	v_sub_f32_e32 v38, v39, v40
	v_mul_f32_e32 v40, v47, v51
	v_fma_f32 v42, v51, v47, -v40
	v_fmac_f32_e32 v42, v51, v48
	v_sub_f32_e32 v50, v41, v38
	v_add_f32_e32 v38, v40, v42
	v_sub_f32_e32 v41, v39, v38
	v_pk_add_f32 v[44:45], v[38:39], v[40:41] neg_lo:[0,1] neg_hi:[0,1]
	v_mov_b32_e32 v43, v38
	v_pk_add_f32 v[38:39], v[44:45], v[42:43] neg_lo:[0,1] neg_hi:[0,1]
	v_cmp_neq_f32_e32 vcc, s57, v35
	v_add_f32_e32 v39, v50, v39
	v_add_f32_e32 v38, v38, v39
	v_add_f32_e32 v39, v41, v38
	v_mul_f32_e32 v50, v49, v39
	v_mul_f32_e32 v40, v47, v50
	v_fma_f32 v42, v50, v47, -v40
	v_fmac_f32_e32 v42, v50, v48
	v_sub_f32_e32 v41, v41, v39
	v_add_f32_e32 v47, v38, v41
	v_add_f32_e32 v38, v40, v42
	v_sub_f32_e32 v41, v39, v38
	v_pk_add_f32 v[44:45], v[38:39], v[40:41] neg_lo:[0,1] neg_hi:[0,1]
	v_mov_b32_e32 v43, v38
	v_pk_add_f32 v[38:39], v[44:45], v[42:43] neg_lo:[0,1] neg_hi:[0,1]
	s_nop 0
	v_add_f32_e32 v39, v47, v39
	v_add_f32_e32 v38, v38, v39
	v_add_f32_e32 v39, v51, v50
	v_add_f32_e32 v38, v41, v38
	v_sub_f32_e32 v40, v39, v51
	v_mul_f32_e32 v38, v49, v38
	v_sub_f32_e32 v40, v50, v40
	v_add_f32_e32 v40, v40, v38
	v_add_f32_e32 v42, v39, v40
	v_mul_f32_e32 v43, v42, v42
	v_fmamk_f32 v38, v43, 0x3e9b6dac, v235
	v_fmaak_f32 v227, v43, v38, 0x3f2aaada
	v_cvt_f32_i32_e32 v38, v46
	v_sub_f32_e32 v39, v42, v39
	v_sub_f32_e32 v39, v40, v39
	v_ldexp_f32 v44, v39, 1
	v_mul_f32_e32 v39, v42, v43
	v_ldexp_f32 v41, v42, 1
	v_pk_mul_f32 v[42:43], v[38:39], v[226:227]
	s_nop 0
	v_fma_f32 v40, v38, s56, -v42
	v_fmac_f32_e32 v40, 0xb102e308, v38
	v_pk_add_f32 v[38:39], v[42:43], v[40:41]
	s_nop 0
	v_sub_f32_e32 v41, v39, v41
	v_sub_f32_e32 v41, v43, v41
	v_add_f32_e32 v45, v44, v41
	v_mov_b32_e32 v44, v42
	v_pk_add_f32 v[42:43], v[38:39], v[42:43] neg_lo:[0,1] neg_hi:[0,1]
	v_pk_add_f32 v[46:47], v[38:39], v[44:45]
	v_mov_b32_e32 v41, v38
	v_mov_b32_e32 v43, v47
	v_pk_add_f32 v[48:49], v[40:41], v[42:43] neg_lo:[0,1] neg_hi:[0,1]
	v_pk_add_f32 v[40:41], v[40:41], v[42:43]
	v_mov_b32_e32 v44, v45
	v_pk_add_f32 v[42:43], v[40:41], v[38:39] op_sel:[1,0] op_sel_hi:[0,1] neg_lo:[0,1] neg_hi:[0,1]
	v_pk_add_f32 v[50:51], v[46:47], v[42:43] op_sel_hi:[1,0] neg_lo:[0,1] neg_hi:[0,1]
	v_mov_b32_e32 v46, v47
	v_mov_b32_e32 v47, v41
	v_pk_mov_b32 v[42:43], v[38:39], v[42:43] op_sel:[1,0]
	v_mov_b32_e32 v45, v38
	v_pk_add_f32 v[42:43], v[46:47], v[42:43] neg_lo:[0,1] neg_hi:[0,1]
	v_mov_b32_e32 v50, v48
	v_pk_add_f32 v[38:39], v[44:45], v[42:43] neg_lo:[0,1] neg_hi:[0,1]
	v_mov_b32_e32 v49, v41
	v_pk_add_f32 v[42:43], v[50:51], v[38:39]
	s_nop 0
	v_pk_add_f32 v[44:45], v[42:43], v[42:43] op_sel:[0,1] op_sel_hi:[1,0]
	s_nop 0
	v_pk_add_f32 v[40:41], v[40:41], v[44:45] op_sel:[1,0] op_sel_hi:[0,1]
	v_mov_b32_e32 v43, v40
	v_pk_add_f32 v[46:47], v[42:43], v[48:49] neg_lo:[0,1] neg_hi:[0,1]
	v_mov_b32_e32 v39, v44
	v_sub_f32_e32 v41, v42, v46
	v_pk_add_f32 v[38:39], v[38:39], v[46:47] neg_lo:[0,1] neg_hi:[0,1]
	v_sub_f32_e32 v41, v48, v41
	v_add_f32_e32 v38, v38, v41
	v_add_f32_e32 v38, v38, v39
	v_add_f32_e32 v38, v40, v38
	v_cndmask_b32_e32 v38, v236, v38, vcc
	v_cmp_ngt_f32_e32 vcc, -1.0, v35
	s_nop 1
	v_cndmask_b32_e32 v38, v237, v38, vcc
	v_cmp_neq_f32_e32 vcc, -1.0, v35
	s_nop 1
	v_cndmask_b32_e32 v38, v238, v38, vcc
	v_cmp_lt_f32_e64 vcc, |v35|, s58
	s_nop 1
	v_cndmask_b32_e32 v35, v38, v35, vcc
;     __device__ __forceinline__ void operator()(f32x4 (&acc)[2][2][4][2], const Unit& u, int row0t, int wr, int wc, int fr, int fq) const {
;     ...
;                                 for (int e = 0; e < 4; ++e) { const int h = 4 * n + e; const float xx = v[e] + dt_bias[h]; const float sp = xx > 20.f ? xx : log1pf(__expf(xx)); o[e] = -__expf(A_log[h]) * sp; } }
.LBB0_280:
	s_or_b64 exec, exec, s[36:37]
	v_mov_b32_e32 v38, v152
	v_mov_b32_e32 v39, v159
	v_add_f32_e32 v36, v36, v38
	v_cmp_nlt_f32_e32 vcc, s53, v36
	s_and_saveexec_b64 s[36:37], vcc
	s_cbranch_execz .LBB0_282
	v_mul_f32_e32 v36, 0x3fb8aa3b, v36
	v_exp_f32_e32 v36, v36
	s_nop 0
	v_add_f32_e32 v38, 1.0, v36
	v_frexp_mant_f32_e32 v43, v38
	v_cvt_f64_f32_e32 v[40:41], v38
	v_add_f32_e32 v42, -1.0, v38
	v_frexp_exp_i32_f64_e32 v40, v[40:41]
	v_cmp_gt_f32_e32 vcc, s55, v43
	v_sub_f32_e32 v44, v42, v38
	v_sub_f32_e32 v42, v36, v42
	v_subbrev_co_u32_e32 v48, vcc, 0, v40, vcc
	v_add_f32_e32 v44, 1.0, v44
	v_sub_u32_e32 v40, 0, v48
	v_add_f32_e32 v42, v42, v44
	v_ldexp_f32 v38, v38, v40
	v_ldexp_f32 v40, v42, v40
	v_add_f32_e32 v42, -1.0, v38
	v_add_f32_e32 v41, 1.0, v42
	v_sub_f32_e32 v41, v38, v41
	v_add_f32_e32 v43, v40, v41
	v_add_f32_e32 v41, 1.0, v38
	v_add_f32_e32 v44, -1.0, v41
	v_sub_f32_e32 v38, v38, v44
	v_add_f32_e32 v38, v40, v38
	v_add_f32_e32 v49, v41, v38
	v_rcp_f32_e32 v50, v49
	v_sub_f32_e32 v40, v49, v41
	v_add_f32_e32 v41, v42, v43
	v_sub_f32_e32 v38, v38, v40
	v_mul_f32_e32 v52, v41, v50
	v_sub_f32_e32 v40, v41, v42
	v_mul_f32_e32 v42, v49, v52
	v_fma_f32 v44, v52, v49, -v42
	v_fmac_f32_e32 v44, v52, v38
	v_sub_f32_e32 v51, v43, v40
	v_add_f32_e32 v40, v42, v44
	v_sub_f32_e32 v43, v41, v40
	v_pk_add_f32 v[46:47], v[40:41], v[42:43] neg_lo:[0,1] neg_hi:[0,1]
	v_mov_b32_e32 v45, v40
	v_pk_add_f32 v[40:41], v[46:47], v[44:45] neg_lo:[0,1] neg_hi:[0,1]
	v_cmp_neq_f32_e32 vcc, s57, v36
	v_add_f32_e32 v41, v51, v41
	v_add_f32_e32 v40, v40, v41
	v_add_f32_e32 v41, v43, v40
	v_mul_f32_e32 v51, v50, v41
	v_mul_f32_e32 v42, v49, v51
	v_fma_f32 v44, v51, v49, -v42
	v_fmac_f32_e32 v44, v51, v38
	v_sub_f32_e32 v38, v43, v41
	v_add_f32_e32 v38, v40, v38
	v_add_f32_e32 v40, v42, v44
	v_sub_f32_e32 v43, v41, v40
	v_pk_add_f32 v[46:47], v[40:41], v[42:43] neg_lo:[0,1] neg_hi:[0,1]
	v_mov_b32_e32 v45, v40
	v_pk_add_f32 v[40:41], v[46:47], v[44:45] neg_lo:[0,1] neg_hi:[0,1]
	s_nop 0
	v_add_f32_e32 v38, v38, v41
	v_add_f32_e32 v38, v40, v38
	v_add_f32_e32 v41, v52, v51
	v_add_f32_e32 v38, v43, v38
	v_sub_f32_e32 v40, v41, v52
	v_mul_f32_e32 v38, v50, v38
	v_sub_f32_e32 v40, v51, v40
	v_add_f32_e32 v38, v40, v38
	v_add_f32_e32 v42, v41, v38
	v_mul_f32_e32 v44, v42, v42
	v_fmamk_f32 v40, v44, 0x3e9b6dac, v235
	v_fmaak_f32 v227, v44, v40, 0x3f2aaada
	v_cvt_f32_i32_e32 v40, v48
	v_sub_f32_e32 v41, v42, v41
	v_sub_f32_e32 v38, v38, v41
	v_mul_f32_e32 v41, v42, v44
	v_pk_mul_f32 v[44:45], v[40:41], v[226:227]
	v_ldexp_f32 v43, v42, 1
	v_fma_f32 v42, v40, s56, -v44
	v_fmac_f32_e32 v42, 0xb102e308, v40
	v_pk_add_f32 v[40:41], v[44:45], v[42:43]
	v_ldexp_f32 v38, v38, 1
	v_sub_f32_e32 v43, v41, v43
	v_sub_f32_e32 v43, v45, v43
	v_add_f32_e32 v47, v38, v43
	v_mov_b32_e32 v46, v44
	v_pk_add_f32 v[44:45], v[40:41], v[44:45] neg_lo:[0,1] neg_hi:[0,1]
	v_pk_add_f32 v[48:49], v[40:41], v[46:47]
	v_mov_b32_e32 v43, v40
	v_mov_b32_e32 v45, v49
	v_pk_add_f32 v[50:51], v[42:43], v[44:45] neg_lo:[0,1] neg_hi:[0,1]
	v_pk_add_f32 v[42:43], v[42:43], v[44:45]
	v_mov_b32_e32 v46, v47
	v_pk_add_f32 v[44:45], v[42:43], v[40:41] op_sel:[1,0] op_sel_hi:[0,1] neg_lo:[0,1] neg_hi:[0,1]
	v_pk_add_f32 v[52:53], v[48:49], v[44:45] op_sel_hi:[1,0] neg_lo:[0,1] neg_hi:[0,1]
	v_mov_b32_e32 v48, v49
	v_mov_b32_e32 v49, v43
	v_pk_mov_b32 v[44:45], v[40:41], v[44:45] op_sel:[1,0]
	v_mov_b32_e32 v47, v40
	v_pk_add_f32 v[44:45], v[48:49], v[44:45] neg_lo:[0,1] neg_hi:[0,1]
	v_mov_b32_e32 v52, v50
	v_pk_add_f32 v[40:41], v[46:47], v[44:45] neg_lo:[0,1] neg_hi:[0,1]
	v_mov_b32_e32 v51, v43
	v_pk_add_f32 v[44:45], v[52:53], v[40:41]
	s_nop 0
	v_pk_add_f32 v[46:47], v[44:45], v[44:45] op_sel:[0,1] op_sel_hi:[1,0]
	s_nop 0
	v_pk_add_f32 v[42:43], v[42:43], v[46:47] op_sel:[1,0] op_sel_hi:[0,1]
	v_mov_b32_e32 v45, v42
	v_pk_add_f32 v[48:49], v[44:45], v[50:51] neg_lo:[0,1] neg_hi:[0,1]
	v_mov_b32_e32 v41, v46
	v_sub_f32_e32 v38, v44, v48
	v_pk_add_f32 v[40:41], v[40:41], v[48:49] neg_lo:[0,1] neg_hi:[0,1]
	v_sub_f32_e32 v38, v50, v38
	v_add_f32_e32 v38, v40, v38
	v_add_f32_e32 v38, v38, v41
	v_add_f32_e32 v38, v42, v38
	v_cndmask_b32_e32 v38, v236, v38, vcc
	v_cmp_ngt_f32_e32 vcc, -1.0, v36
	s_nop 1
	v_cndmask_b32_e32 v38, v237, v38, vcc
	v_cmp_neq_f32_e32 vcc, -1.0, v36
	s_nop 1
	v_cndmask_b32_e32 v38, v238, v38, vcc
	v_cmp_lt_f32_e64 vcc, |v36|, s58
	s_nop 1
	v_cndmask_b32_e32 v36, v38, v36, vcc
;     __device__ __forceinline__ void operator()(f32x4 (&acc)[2][2][4][2], const Unit& u, int row0t, int wr, int wc, int fr, int fq) const {
;     ...
;                                 for (int e = 0; e < 4; ++e) { const int h = 4 * n + e; const float xx = v[e] + dt_bias[h]; const float sp = xx > 20.f ? xx : log1pf(__expf(xx)); o[e] = -__expf(A_log[h]) * sp; } }
.LBB0_282:
	s_or_b64 exec, exec, s[36:37]
	v_mov_b32_e32 v38, v153
	v_mov_b32_e32 v40, v160
	v_add_f32_e32 v37, v37, v38
	v_cmp_nlt_f32_e32 vcc, s53, v37
	s_and_saveexec_b64 s[36:37], vcc
	s_cbranch_execz .LBB0_284
	v_mul_f32_e32 v37, 0x3fb8aa3b, v37
	v_exp_f32_e32 v37, v37
	s_nop 0
	v_add_f32_e32 v38, 1.0, v37
	v_frexp_mant_f32_e32 v44, v38
	v_cvt_f64_f32_e32 v[42:43], v38
	v_add_f32_e32 v41, -1.0, v38
	v_frexp_exp_i32_f64_e32 v42, v[42:43]
	v_cmp_gt_f32_e32 vcc, s55, v44
	v_sub_f32_e32 v45, v41, v38
	v_sub_f32_e32 v41, v37, v41
	v_subbrev_co_u32_e32 v50, vcc, 0, v42, vcc
	v_add_f32_e32 v45, 1.0, v45
	v_sub_u32_e32 v42, 0, v50
	v_add_f32_e32 v41, v41, v45
	v_ldexp_f32 v38, v38, v42
	v_ldexp_f32 v41, v41, v42
	v_add_f32_e32 v42, -1.0, v38
	v_add_f32_e32 v43, 1.0, v42
	v_sub_f32_e32 v43, v38, v43
	v_add_f32_e32 v44, v41, v43
	v_add_f32_e32 v43, 1.0, v38
	v_add_f32_e32 v45, -1.0, v43
	v_sub_f32_e32 v38, v38, v45
	v_add_f32_e32 v38, v41, v38
	v_add_f32_e32 v41, v43, v38
	v_rcp_f32_e32 v51, v41
	v_sub_f32_e32 v43, v41, v43
	v_sub_f32_e32 v38, v38, v43
	v_add_f32_e32 v43, v42, v44
	v_sub_f32_e32 v42, v43, v42
	v_mul_f32_e32 v53, v43, v51
	v_sub_f32_e32 v52, v44, v42
	v_mul_f32_e32 v44, v41, v53
	v_fma_f32 v46, v53, v41, -v44
	v_fmac_f32_e32 v46, v53, v38
	v_add_f32_e32 v42, v44, v46
	v_sub_f32_e32 v45, v43, v42
	v_pk_add_f32 v[48:49], v[42:43], v[44:45] neg_lo:[0,1] neg_hi:[0,1]
	v_mov_b32_e32 v47, v42
	v_pk_add_f32 v[42:43], v[48:49], v[46:47] neg_lo:[0,1] neg_hi:[0,1]
	v_cmp_neq_f32_e32 vcc, s57, v37
	v_add_f32_e32 v43, v52, v43
	v_add_f32_e32 v42, v42, v43
	v_add_f32_e32 v43, v45, v42
	v_mul_f32_e32 v52, v51, v43
	v_mul_f32_e32 v44, v41, v52
	v_fma_f32 v46, v52, v41, -v44
	v_fmac_f32_e32 v46, v52, v38
	v_sub_f32_e32 v38, v45, v43
	v_add_f32_e32 v38, v42, v38
	v_add_f32_e32 v42, v44, v46
	v_sub_f32_e32 v45, v43, v42
	v_pk_add_f32 v[48:49], v[42:43], v[44:45] neg_lo:[0,1] neg_hi:[0,1]
	v_mov_b32_e32 v47, v42
	v_pk_add_f32 v[42:43], v[48:49], v[46:47] neg_lo:[0,1] neg_hi:[0,1]
	v_add_f32_e32 v41, v53, v52
	v_add_f32_e32 v38, v38, v43
	v_add_f32_e32 v38, v42, v38
	v_add_f32_e32 v38, v45, v38
	v_sub_f32_e32 v42, v41, v53
	v_mul_f32_e32 v38, v51, v38
	v_sub_f32_e32 v42, v52, v42
	v_add_f32_e32 v38, v42, v38
	v_add_f32_e32 v43, v41, v38
	v_mul_f32_e32 v44, v43, v43
	v_fmamk_f32 v42, v44, 0x3e9b6dac, v235
	v_fmaak_f32 v227, v44, v42, 0x3f2aaada
	v_cvt_f32_i32_e32 v42, v50
	v_sub_f32_e32 v41, v43, v41
	v_ldexp_f32 v45, v43, 1
	v_mul_f32_e32 v43, v43, v44
	v_pk_mul_f32 v[46:47], v[42:43], v[226:227]
	v_sub_f32_e32 v38, v38, v41
	v_fma_f32 v44, v42, s56, -v46
	v_fmac_f32_e32 v44, 0xb102e308, v42
	v_pk_add_f32 v[42:43], v[46:47], v[44:45]
	v_ldexp_f32 v38, v38, 1
	v_sub_f32_e32 v41, v43, v45
	v_sub_f32_e32 v41, v47, v41
	v_add_f32_e32 v49, v38, v41
	v_mov_b32_e32 v48, v46
	v_pk_add_f32 v[46:47], v[42:43], v[46:47] neg_lo:[0,1] neg_hi:[0,1]
	v_pk_add_f32 v[50:51], v[42:43], v[48:49]
	v_mov_b32_e32 v45, v42
	v_mov_b32_e32 v47, v51
	v_pk_add_f32 v[52:53], v[44:45], v[46:47] neg_lo:[0,1] neg_hi:[0,1]
	v_pk_add_f32 v[44:45], v[44:45], v[46:47]
	v_mov_b32_e32 v48, v49
	v_pk_add_f32 v[46:47], v[44:45], v[42:43] op_sel:[1,0] op_sel_hi:[0,1] neg_lo:[0,1] neg_hi:[0,1]
	v_pk_add_f32 v[54:55], v[50:51], v[46:47] op_sel_hi:[1,0] neg_lo:[0,1] neg_hi:[0,1]
	v_mov_b32_e32 v50, v51
	v_mov_b32_e32 v51, v45
	v_pk_mov_b32 v[46:47], v[42:43], v[46:47] op_sel:[1,0]
	v_mov_b32_e32 v49, v42
	v_pk_add_f32 v[46:47], v[50:51], v[46:47] neg_lo:[0,1] neg_hi:[0,1]
	v_mov_b32_e32 v54, v52
	v_pk_add_f32 v[42:43], v[48:49], v[46:47] neg_lo:[0,1] neg_hi:[0,1]
	v_mov_b32_e32 v53, v45
	v_pk_add_f32 v[46:47], v[54:55], v[42:43]
	s_nop 0
	v_pk_add_f32 v[48:49], v[46:47], v[46:47] op_sel:[0,1] op_sel_hi:[1,0]
	s_nop 0
	v_pk_add_f32 v[44:45], v[44:45], v[48:49] op_sel:[1,0] op_sel_hi:[0,1]
	v_mov_b32_e32 v47, v44
	v_pk_add_f32 v[50:51], v[46:47], v[52:53] neg_lo:[0,1] neg_hi:[0,1]
	v_mov_b32_e32 v43, v48
	v_sub_f32_e32 v38, v46, v50
	v_pk_add_f32 v[42:43], v[42:43], v[50:51] neg_lo:[0,1] neg_hi:[0,1]
	v_sub_f32_e32 v38, v52, v38
	v_add_f32_e32 v38, v42, v38
	v_add_f32_e32 v38, v38, v43
	v_add_f32_e32 v38, v44, v38
	v_cndmask_b32_e32 v38, v236, v38, vcc
	v_cmp_ngt_f32_e32 vcc, -1.0, v37
	s_nop 1
	v_cndmask_b32_e32 v38, v237, v38, vcc
	v_cmp_neq_f32_e32 vcc, -1.0, v37
	s_nop 1
	v_cndmask_b32_e32 v38, v238, v38, vcc
	v_cmp_lt_f32_e64 vcc, |v37|, s58
	s_nop 1
	v_cndmask_b32_e32 v37, v38, v37, vcc
.LBB0_284:
	s_or_b64 exec, exec, s[36:37]
	v_mul_f32_e32 v34, 0x3fb8aa3b, v34
	v_exp_f32_e32 v34, v34
	s_nop 0
	v_mul_f32_e64 v38, v3, -v34
	v_mul_f32_e32 v3, 0x3fb8aa3b, v39
	v_exp_f32_e32 v3, v3
	s_nop 0
	v_mul_f32_e64 v39, v35, -v3
	v_mul_f32_e32 v3, 0x3fb8aa3b, v40
	v_exp_f32_e32 v3, v3
	s_nop 0
	v_mul_f32_e64 v40, v36, -v3
	v_mov_b32_e32 v3, v161
	v_mul_f32_e32 v3, 0x3fb8aa3b, v3
	v_exp_f32_e32 v3, v3
	s_nop 0
	v_mul_f32_e64 v41, v37, -v3

;     __device__ __forceinline__ void operator()(f32x4 (&acc)[2][2][4][2], const Unit& u, int row0t, int wr, int wc, int fr, int fq) const {
;     ...
;                                 for (int e = 0; e < 4; ++e) { const int h = 4 * n + e; const float xx = v[e] + dt_bias[h]; const float sp = xx > 20.f ? xx : log1pf(__expf(xx)); o[e] = -__expf(A_log[h]) * sp; } }
;                             *(f32x4*)(bg + (size_t)r * 16 + 8 * fq + 4 * n) = o; } }
.LBB0_287:
	s_or_b64 exec, exec, s[24:25]
	v_lshlrev_b64 v[34:35], 6, v[4:5]
	v_lshl_add_u64 v[42:43], v[214:215], 0, v[34:35]
	v_add_co_u32_e32 v34, vcc, 0x2000, v42
	s_nop 1
	v_addc_co_u32_e32 v35, vcc, 0, v43, vcc
	global_store_dwordx4 v[34:35], v[38:41], off
	s_and_saveexec_b64 s[2:3], s[4:5]
	s_xor_b64 s[24:25], exec, s[2:3]
	s_cbranch_execz .LBB0_297
	v_mov_b32_e32 v3, v154
	v_add_f32_e32 v3, v30, v3
	v_cmp_nlt_f32_e32 vcc, s53, v3
	s_and_saveexec_b64 s[36:37], vcc
	s_cbranch_execz .LBB0_290
	v_mul_f32_e32 v3, 0x3fb8aa3b, v3
	v_exp_f32_e32 v3, v3
	s_nop 0
	v_add_f32_e32 v30, 1.0, v3
	v_frexp_mant_f32_e32 v37, v30
	v_cvt_f64_f32_e32 v[34:35], v30
	v_add_f32_e32 v36, -1.0, v30
	v_frexp_exp_i32_f64_e32 v34, v[34:35]
	v_cmp_gt_f32_e32 vcc, s55, v37
	v_sub_f32_e32 v38, v36, v30
	v_sub_f32_e32 v36, v3, v36
	v_subbrev_co_u32_e32 v44, vcc, 0, v34, vcc
	v_add_f32_e32 v38, 1.0, v38
	v_sub_u32_e32 v34, 0, v44
	v_add_f32_e32 v36, v36, v38
	v_ldexp_f32 v30, v30, v34
	v_ldexp_f32 v34, v36, v34
	v_add_f32_e32 v36, -1.0, v30
	v_add_f32_e32 v35, 1.0, v36
	v_sub_f32_e32 v35, v30, v35
	v_add_f32_e32 v37, v34, v35
	v_add_f32_e32 v35, 1.0, v30
	v_add_f32_e32 v38, -1.0, v35
	v_sub_f32_e32 v30, v30, v38
	v_add_f32_e32 v30, v34, v30
	v_add_f32_e32 v45, v35, v30
	v_rcp_f32_e32 v46, v45
	v_sub_f32_e32 v34, v45, v35
	v_add_f32_e32 v35, v36, v37
	v_sub_f32_e32 v30, v30, v34
	v_mul_f32_e32 v48, v35, v46
	v_sub_f32_e32 v34, v35, v36
	v_mul_f32_e32 v36, v45, v48
	v_fma_f32 v38, v48, v45, -v36
	v_fmac_f32_e32 v38, v48, v30
	v_sub_f32_e32 v47, v37, v34
	v_add_f32_e32 v34, v36, v38
	v_sub_f32_e32 v37, v35, v34
	v_pk_add_f32 v[40:41], v[34:35], v[36:37] neg_lo:[0,1] neg_hi:[0,1]
	v_mov_b32_e32 v39, v34
	v_pk_add_f32 v[34:35], v[40:41], v[38:39] neg_lo:[0,1] neg_hi:[0,1]
	v_cmp_neq_f32_e32 vcc, s57, v3
	v_add_f32_e32 v35, v47, v35
	v_add_f32_e32 v34, v34, v35
	v_add_f32_e32 v35, v37, v34
	v_mul_f32_e32 v47, v46, v35
	v_mul_f32_e32 v36, v45, v47
	v_fma_f32 v38, v47, v45, -v36
	v_fmac_f32_e32 v38, v47, v30
	v_sub_f32_e32 v30, v37, v35
	v_add_f32_e32 v30, v34, v30
	v_add_f32_e32 v34, v36, v38
	v_sub_f32_e32 v37, v35, v34
	v_pk_add_f32 v[40:41], v[34:35], v[36:37] neg_lo:[0,1] neg_hi:[0,1]
	v_mov_b32_e32 v39, v34
	v_pk_add_f32 v[34:35], v[40:41], v[38:39] neg_lo:[0,1] neg_hi:[0,1]
	s_nop 0
	v_add_f32_e32 v30, v30, v35
	v_add_f32_e32 v30, v34, v30
	v_add_f32_e32 v35, v48, v47
	v_add_f32_e32 v30, v37, v30
	v_sub_f32_e32 v34, v35, v48
	v_mul_f32_e32 v30, v46, v30
	v_sub_f32_e32 v34, v47, v34
	v_add_f32_e32 v30, v34, v30
	v_add_f32_e32 v36, v35, v30
	v_mul_f32_e32 v38, v36, v36
	v_fmamk_f32 v34, v38, 0x3e9b6dac, v235
	v_fmaak_f32 v227, v38, v34, 0x3f2aaada
	v_cvt_f32_i32_e32 v34, v44
	v_sub_f32_e32 v35, v36, v35
	v_sub_f32_e32 v30, v30, v35
	v_mul_f32_e32 v35, v36, v38
	v_pk_mul_f32 v[38:39], v[34:35], v[226:227]
	v_ldexp_f32 v37, v36, 1
	v_fma_f32 v36, v34, s56, -v38
	v_fmac_f32_e32 v36, 0xb102e308, v34
	v_pk_add_f32 v[34:35], v[38:39], v[36:37]
	v_ldexp_f32 v30, v30, 1
	v_sub_f32_e32 v37, v35, v37
	v_sub_f32_e32 v37, v39, v37
	v_add_f32_e32 v41, v30, v37
	v_mov_b32_e32 v40, v38
	v_pk_add_f32 v[38:39], v[34:35], v[38:39] neg_lo:[0,1] neg_hi:[0,1]
	v_pk_add_f32 v[44:45], v[34:35], v[40:41]
	v_mov_b32_e32 v37, v34
	v_mov_b32_e32 v39, v45
	v_pk_add_f32 v[46:47], v[36:37], v[38:39] neg_lo:[0,1] neg_hi:[0,1]
	v_pk_add_f32 v[36:37], v[36:37], v[38:39]
	v_mov_b32_e32 v40, v41
	v_pk_add_f32 v[38:39], v[36:37], v[34:35] op_sel:[1,0] op_sel_hi:[0,1] neg_lo:[0,1] neg_hi:[0,1]
	v_pk_add_f32 v[48:49], v[44:45], v[38:39] op_sel_hi:[1,0] neg_lo:[0,1] neg_hi:[0,1]
	v_mov_b32_e32 v44, v45
	v_mov_b32_e32 v45, v37
	v_pk_mov_b32 v[38:39], v[34:35], v[38:39] op_sel:[1,0]
	v_mov_b32_e32 v41, v34
	v_pk_add_f32 v[38:39], v[44:45], v[38:39] neg_lo:[0,1] neg_hi:[0,1]
	v_mov_b32_e32 v48, v46
	v_pk_add_f32 v[34:35], v[40:41], v[38:39] neg_lo:[0,1] neg_hi:[0,1]
	v_mov_b32_e32 v47, v37
	v_pk_add_f32 v[38:39], v[48:49], v[34:35]
	s_nop 0
	v_pk_add_f32 v[40:41], v[38:39], v[38:39] op_sel:[0,1] op_sel_hi:[1,0]
	s_nop 0
	v_pk_add_f32 v[36:37], v[36:37], v[40:41] op_sel:[1,0] op_sel_hi:[0,1]
	v_mov_b32_e32 v39, v36
	v_pk_add_f32 v[44:45], v[38:39], v[46:47] neg_lo:[0,1] neg_hi:[0,1]
	v_mov_b32_e32 v35, v40
	v_sub_f32_e32 v30, v38, v44
	v_pk_add_f32 v[34:35], v[34:35], v[44:45] neg_lo:[0,1] neg_hi:[0,1]
	v_sub_f32_e32 v30, v46, v30
	v_add_f32_e32 v30, v34, v30
	v_add_f32_e32 v30, v30, v35
	v_add_f32_e32 v30, v36, v30
	v_cndmask_b32_e32 v30, v236, v30, vcc
	v_cmp_ngt_f32_e32 vcc, -1.0, v3
	s_nop 1
	v_cndmask_b32_e32 v30, v237, v30, vcc
	v_cmp_neq_f32_e32 vcc, -1.0, v3
	s_nop 1
	v_cndmask_b32_e32 v30, v238, v30, vcc
	v_cmp_lt_f32_e64 vcc, |v3|, s58
	s_nop 1
	v_cndmask_b32_e32 v3, v30, v3, vcc
;     __device__ __forceinline__ void operator()(f32x4 (&acc)[2][2][4][2], const Unit& u, int row0t, int wr, int wc, int fr, int fq) const {
;     ...
;                                 for (int e = 0; e < 4; ++e) { const int h = 4 * n + e; const float xx = v[e] + dt_bias[h]; const float sp = xx > 20.f ? xx : log1pf(__expf(xx)); o[e] = -__expf(A_log[h]) * sp; } }
.LBB0_290:
	s_or_b64 exec, exec, s[36:37]
	v_mov_b32_e32 v34, v155
	v_mov_b32_e32 v30, v162
	v_add_f32_e32 v31, v31, v34
	v_cmp_nlt_f32_e32 vcc, s53, v31
	s_and_saveexec_b64 s[36:37], vcc
	s_cbranch_execz .LBB0_292
	v_mul_f32_e32 v31, 0x3fb8aa3b, v31
	v_exp_f32_e32 v31, v31
	s_nop 0
	v_add_f32_e32 v36, 1.0, v31
	v_frexp_mant_f32_e32 v38, v36
	v_cvt_f64_f32_e32 v[34:35], v36
	v_frexp_exp_i32_f64_e32 v34, v[34:35]
	v_cmp_gt_f32_e32 vcc, s55, v38
	v_add_f32_e32 v37, -1.0, v36
	v_sub_f32_e32 v39, v37, v36
	v_subbrev_co_u32_e32 v44, vcc, 0, v34, vcc
	v_sub_u32_e32 v34, 0, v44
	v_sub_f32_e32 v37, v31, v37
	v_add_f32_e32 v39, 1.0, v39
	v_ldexp_f32 v35, v36, v34
	v_add_f32_e32 v37, v37, v39
	v_add_f32_e32 v36, -1.0, v35
	v_add_f32_e32 v38, 1.0, v35
	v_ldexp_f32 v34, v37, v34
	v_add_f32_e32 v37, 1.0, v36
	v_add_f32_e32 v39, -1.0, v38
	v_sub_f32_e32 v37, v35, v37
	v_sub_f32_e32 v35, v35, v39
	v_add_f32_e32 v37, v34, v37
	v_add_f32_e32 v34, v34, v35
	v_add_f32_e32 v45, v38, v34
	v_rcp_f32_e32 v47, v45
	v_sub_f32_e32 v35, v45, v38
	v_sub_f32_e32 v46, v34, v35
	v_add_f32_e32 v35, v36, v37
	v_mul_f32_e32 v49, v35, v47
	v_sub_f32_e32 v34, v35, v36
	v_mul_f32_e32 v36, v45, v49
	v_fma_f32 v38, v49, v45, -v36
	v_fmac_f32_e32 v38, v49, v46
	v_sub_f32_e32 v48, v37, v34
	v_add_f32_e32 v34, v36, v38
	v_sub_f32_e32 v37, v35, v34
	v_pk_add_f32 v[40:41], v[34:35], v[36:37] neg_lo:[0,1] neg_hi:[0,1]
	v_mov_b32_e32 v39, v34
	v_pk_add_f32 v[34:35], v[40:41], v[38:39] neg_lo:[0,1] neg_hi:[0,1]
	v_cmp_neq_f32_e32 vcc, s57, v31
	v_add_f32_e32 v35, v48, v35
	v_add_f32_e32 v34, v34, v35
	v_add_f32_e32 v35, v37, v34
	v_mul_f32_e32 v48, v47, v35
	v_mul_f32_e32 v36, v45, v48
	v_fma_f32 v38, v48, v45, -v36
	v_fmac_f32_e32 v38, v48, v46
	v_sub_f32_e32 v37, v37, v35
	v_add_f32_e32 v45, v34, v37
	v_add_f32_e32 v34, v36, v38
	v_sub_f32_e32 v37, v35, v34
	v_pk_add_f32 v[40:41], v[34:35], v[36:37] neg_lo:[0,1] neg_hi:[0,1]
	v_mov_b32_e32 v39, v34
	v_pk_add_f32 v[34:35], v[40:41], v[38:39] neg_lo:[0,1] neg_hi:[0,1]
	s_nop 0
	v_add_f32_e32 v35, v45, v35
	v_add_f32_e32 v34, v34, v35
	v_add_f32_e32 v35, v49, v48
	v_add_f32_e32 v34, v37, v34
	v_sub_f32_e32 v36, v35, v49
	v_mul_f32_e32 v34, v47, v34
	v_sub_f32_e32 v36, v48, v36
	v_add_f32_e32 v36, v36, v34
	v_add_f32_e32 v38, v35, v36
	v_mul_f32_e32 v39, v38, v38
	v_fmamk_f32 v34, v39, 0x3e9b6dac, v235
	v_fmaak_f32 v227, v39, v34, 0x3f2aaada
	v_cvt_f32_i32_e32 v34, v44
	v_sub_f32_e32 v35, v38, v35
	v_sub_f32_e32 v35, v36, v35
	v_ldexp_f32 v40, v35, 1
	v_mul_f32_e32 v35, v38, v39
	v_ldexp_f32 v37, v38, 1
	v_pk_mul_f32 v[38:39], v[34:35], v[226:227]
	s_nop 0
	v_fma_f32 v36, v34, s56, -v38
	v_fmac_f32_e32 v36, 0xb102e308, v34
	v_pk_add_f32 v[34:35], v[38:39], v[36:37]
	s_nop 0
	v_sub_f32_e32 v37, v35, v37
	v_sub_f32_e32 v37, v39, v37
	v_add_f32_e32 v41, v40, v37
	v_mov_b32_e32 v40, v38
	v_pk_add_f32 v[38:39], v[34:35], v[38:39] neg_lo:[0,1] neg_hi:[0,1]
	v_pk_add_f32 v[44:45], v[34:35], v[40:41]
	v_mov_b32_e32 v37, v34
	v_mov_b32_e32 v39, v45
	v_pk_add_f32 v[46:47], v[36:37], v[38:39] neg_lo:[0,1] neg_hi:[0,1]
	v_pk_add_f32 v[36:37], v[36:37], v[38:39]
	v_mov_b32_e32 v40, v41
	v_pk_add_f32 v[38:39], v[36:37], v[34:35] op_sel:[1,0] op_sel_hi:[0,1] neg_lo:[0,1] neg_hi:[0,1]
	v_pk_add_f32 v[48:49], v[44:45], v[38:39] op_sel_hi:[1,0] neg_lo:[0,1] neg_hi:[0,1]
	v_mov_b32_e32 v44, v45
	v_mov_b32_e32 v45, v37
	v_pk_mov_b32 v[38:39], v[34:35], v[38:39] op_sel:[1,0]
	v_mov_b32_e32 v41, v34
	v_pk_add_f32 v[38:39], v[44:45], v[38:39] neg_lo:[0,1] neg_hi:[0,1]
	v_mov_b32_e32 v48, v46
	v_pk_add_f32 v[34:35], v[40:41], v[38:39] neg_lo:[0,1] neg_hi:[0,1]
	v_mov_b32_e32 v47, v37
	v_pk_add_f32 v[38:39], v[48:49], v[34:35]
	s_nop 0
	v_pk_add_f32 v[40:41], v[38:39], v[38:39] op_sel:[0,1] op_sel_hi:[1,0]
	s_nop 0
	v_pk_add_f32 v[36:37], v[36:37], v[40:41] op_sel:[1,0] op_sel_hi:[0,1]
	v_mov_b32_e32 v39, v36
	v_pk_add_f32 v[44:45], v[38:39], v[46:47] neg_lo:[0,1] neg_hi:[0,1]
	v_mov_b32_e32 v35, v40
	v_sub_f32_e32 v37, v38, v44
	v_pk_add_f32 v[34:35], v[34:35], v[44:45] neg_lo:[0,1] neg_hi:[0,1]
	v_sub_f32_e32 v37, v46, v37
	v_add_f32_e32 v34, v34, v37
	v_add_f32_e32 v34, v34, v35
	v_add_f32_e32 v34, v36, v34
	v_cndmask_b32_e32 v34, v236, v34, vcc
	v_cmp_ngt_f32_e32 vcc, -1.0, v31
	s_nop 1
	v_cndmask_b32_e32 v34, v237, v34, vcc
	v_cmp_neq_f32_e32 vcc, -1.0, v31
	s_nop 1
	v_cndmask_b32_e32 v34, v238, v34, vcc
	v_cmp_lt_f32_e64 vcc, |v31|, s58
	s_nop 1
	v_cndmask_b32_e32 v31, v34, v31, vcc
;     __device__ __forceinline__ void operator()(f32x4 (&acc)[2][2][4][2], const Unit& u, int row0t, int wr, int wc, int fr, int fq) const {
;     ...
;                                 for (int e = 0; e < 4; ++e) { const int h = 4 * n + e; const float xx = v[e] + dt_bias[h]; const float sp = xx > 20.f ? xx : log1pf(__expf(xx)); o[e] = -__expf(A_log[h]) * sp; } }
.LBB0_292:
	s_or_b64 exec, exec, s[36:37]
	v_mov_b32_e32 v34, v156
	v_mov_b32_e32 v35, v163
	v_add_f32_e32 v32, v32, v34
	v_cmp_nlt_f32_e32 vcc, s53, v32
	s_and_saveexec_b64 s[36:37], vcc
	s_cbranch_execz .LBB0_294
	v_mul_f32_e32 v32, 0x3fb8aa3b, v32
	v_exp_f32_e32 v32, v32
	s_nop 0
	v_add_f32_e32 v34, 1.0, v32
	v_frexp_mant_f32_e32 v39, v34
	v_cvt_f64_f32_e32 v[36:37], v34
	v_add_f32_e32 v38, -1.0, v34
	v_frexp_exp_i32_f64_e32 v36, v[36:37]
	v_cmp_gt_f32_e32 vcc, s55, v39
	v_sub_f32_e32 v40, v38, v34
	v_sub_f32_e32 v38, v32, v38
	v_subbrev_co_u32_e32 v46, vcc, 0, v36, vcc
	v_add_f32_e32 v40, 1.0, v40
	v_sub_u32_e32 v36, 0, v46
	v_add_f32_e32 v38, v38, v40
	v_ldexp_f32 v34, v34, v36
	v_ldexp_f32 v36, v38, v36
	v_add_f32_e32 v38, -1.0, v34
	v_add_f32_e32 v37, 1.0, v38
	v_sub_f32_e32 v37, v34, v37
	v_add_f32_e32 v39, v36, v37
	v_add_f32_e32 v37, 1.0, v34
	v_add_f32_e32 v40, -1.0, v37
	v_sub_f32_e32 v34, v34, v40
	v_add_f32_e32 v34, v36, v34
	v_add_f32_e32 v47, v37, v34
	v_rcp_f32_e32 v48, v47
	v_sub_f32_e32 v36, v47, v37
	v_add_f32_e32 v37, v38, v39
	v_sub_f32_e32 v34, v34, v36
	v_mul_f32_e32 v50, v37, v48
	v_sub_f32_e32 v36, v37, v38
	v_mul_f32_e32 v38, v47, v50
	v_fma_f32 v40, v50, v47, -v38
	v_fmac_f32_e32 v40, v50, v34
	v_sub_f32_e32 v49, v39, v36
	v_add_f32_e32 v36, v38, v40
	v_sub_f32_e32 v39, v37, v36
	v_pk_add_f32 v[44:45], v[36:37], v[38:39] neg_lo:[0,1] neg_hi:[0,1]
	v_mov_b32_e32 v41, v36
	v_pk_add_f32 v[36:37], v[44:45], v[40:41] neg_lo:[0,1] neg_hi:[0,1]
	v_cmp_neq_f32_e32 vcc, s57, v32
	v_add_f32_e32 v37, v49, v37
	v_add_f32_e32 v36, v36, v37
	v_add_f32_e32 v37, v39, v36
	v_mul_f32_e32 v49, v48, v37
	v_mul_f32_e32 v38, v47, v49
	v_fma_f32 v40, v49, v47, -v38
	v_fmac_f32_e32 v40, v49, v34
	v_sub_f32_e32 v34, v39, v37
	v_add_f32_e32 v34, v36, v34
	v_add_f32_e32 v36, v38, v40
	v_sub_f32_e32 v39, v37, v36
	v_pk_add_f32 v[44:45], v[36:37], v[38:39] neg_lo:[0,1] neg_hi:[0,1]
	v_mov_b32_e32 v41, v36
	v_pk_add_f32 v[36:37], v[44:45], v[40:41] neg_lo:[0,1] neg_hi:[0,1]
	s_nop 0
	v_add_f32_e32 v34, v34, v37
	v_add_f32_e32 v34, v36, v34
	v_add_f32_e32 v37, v50, v49
	v_add_f32_e32 v34, v39, v34
	v_sub_f32_e32 v36, v37, v50
	v_mul_f32_e32 v34, v48, v34
	v_sub_f32_e32 v36, v49, v36
	v_add_f32_e32 v34, v36, v34
	v_add_f32_e32 v38, v37, v34
	v_mul_f32_e32 v40, v38, v38
	v_fmamk_f32 v36, v40, 0x3e9b6dac, v235
	v_fmaak_f32 v227, v40, v36, 0x3f2aaada
	v_cvt_f32_i32_e32 v36, v46
	v_sub_f32_e32 v37, v38, v37
	v_sub_f32_e32 v34, v34, v37
	v_mul_f32_e32 v37, v38, v40
	v_pk_mul_f32 v[40:41], v[36:37], v[226:227]
	v_ldexp_f32 v39, v38, 1
	v_fma_f32 v38, v36, s56, -v40
	v_fmac_f32_e32 v38, 0xb102e308, v36
	v_pk_add_f32 v[36:37], v[40:41], v[38:39]
	v_ldexp_f32 v34, v34, 1
	v_sub_f32_e32 v39, v37, v39
	v_sub_f32_e32 v39, v41, v39
	v_add_f32_e32 v45, v34, v39
	v_mov_b32_e32 v44, v40
	v_pk_add_f32 v[40:41], v[36:37], v[40:41] neg_lo:[0,1] neg_hi:[0,1]
	v_pk_add_f32 v[46:47], v[36:37], v[44:45]
	v_mov_b32_e32 v39, v36
	v_mov_b32_e32 v41, v47
	v_pk_add_f32 v[48:49], v[38:39], v[40:41] neg_lo:[0,1] neg_hi:[0,1]
	v_pk_add_f32 v[38:39], v[38:39], v[40:41]
	v_mov_b32_e32 v44, v45
	v_pk_add_f32 v[40:41], v[38:39], v[36:37] op_sel:[1,0] op_sel_hi:[0,1] neg_lo:[0,1] neg_hi:[0,1]
	v_pk_add_f32 v[50:51], v[46:47], v[40:41] op_sel_hi:[1,0] neg_lo:[0,1] neg_hi:[0,1]
	v_mov_b32_e32 v46, v47
	v_mov_b32_e32 v47, v39
	v_pk_mov_b32 v[40:41], v[36:37], v[40:41] op_sel:[1,0]
	v_mov_b32_e32 v45, v36
	v_pk_add_f32 v[40:41], v[46:47], v[40:41] neg_lo:[0,1] neg_hi:[0,1]
	v_mov_b32_e32 v50, v48
	v_pk_add_f32 v[36:37], v[44:45], v[40:41] neg_lo:[0,1] neg_hi:[0,1]
	v_mov_b32_e32 v49, v39
	v_pk_add_f32 v[40:41], v[50:51], v[36:37]
	s_nop 0
	v_pk_add_f32 v[44:45], v[40:41], v[40:41] op_sel:[0,1] op_sel_hi:[1,0]
	s_nop 0
	v_pk_add_f32 v[38:39], v[38:39], v[44:45] op_sel:[1,0] op_sel_hi:[0,1]
	v_mov_b32_e32 v41, v38
	v_pk_add_f32 v[46:47], v[40:41], v[48:49] neg_lo:[0,1] neg_hi:[0,1]
	v_mov_b32_e32 v37, v44
	v_sub_f32_e32 v34, v40, v46
	v_pk_add_f32 v[36:37], v[36:37], v[46:47] neg_lo:[0,1] neg_hi:[0,1]
	v_sub_f32_e32 v34, v48, v34
	v_add_f32_e32 v34, v36, v34
	v_add_f32_e32 v34, v34, v37
	v_add_f32_e32 v34, v38, v34
	v_cndmask_b32_e32 v34, v236, v34, vcc
	v_cmp_ngt_f32_e32 vcc, -1.0, v32
	s_nop 1
	v_cndmask_b32_e32 v34, v237, v34, vcc
	v_cmp_neq_f32_e32 vcc, -1.0, v32
	s_nop 1
	v_cndmask_b32_e32 v34, v238, v34, vcc
	v_cmp_lt_f32_e64 vcc, |v32|, s58
	s_nop 1
	v_cndmask_b32_e32 v32, v34, v32, vcc
;     __device__ __forceinline__ void operator()(f32x4 (&acc)[2][2][4][2], const Unit& u, int row0t, int wr, int wc, int fr, int fq) const {
;     ...
;                                 for (int e = 0; e < 4; ++e) { const int h = 4 * n + e; const float xx = v[e] + dt_bias[h]; const float sp = xx > 20.f ? xx : log1pf(__expf(xx)); o[e] = -__expf(A_log[h]) * sp; } }
.LBB0_294:
	s_or_b64 exec, exec, s[36:37]
	v_mov_b32_e32 v34, v157
	v_mov_b32_e32 v36, v164
	v_add_f32_e32 v33, v33, v34
	v_cmp_nlt_f32_e32 vcc, s53, v33
	s_and_saveexec_b64 s[36:37], vcc
	s_cbranch_execz .LBB0_296
	v_mul_f32_e32 v33, 0x3fb8aa3b, v33
	v_exp_f32_e32 v33, v33
	s_nop 0
	v_add_f32_e32 v34, 1.0, v33
	v_frexp_mant_f32_e32 v40, v34
	v_cvt_f64_f32_e32 v[38:39], v34
	v_add_f32_e32 v37, -1.0, v34
	v_frexp_exp_i32_f64_e32 v38, v[38:39]
	v_cmp_gt_f32_e32 vcc, s55, v40
	v_sub_f32_e32 v41, v37, v34
	v_sub_f32_e32 v37, v33, v37
	v_subbrev_co_u32_e32 v48, vcc, 0, v38, vcc
	v_add_f32_e32 v41, 1.0, v41
	v_sub_u32_e32 v38, 0, v48
	v_add_f32_e32 v37, v37, v41
	v_ldexp_f32 v34, v34, v38
	v_ldexp_f32 v37, v37, v38
	v_add_f32_e32 v38, -1.0, v34
	v_add_f32_e32 v39, 1.0, v38
	v_sub_f32_e32 v39, v34, v39
	v_add_f32_e32 v40, v37, v39
	v_add_f32_e32 v39, 1.0, v34
	v_add_f32_e32 v41, -1.0, v39
	v_sub_f32_e32 v34, v34, v41
	v_add_f32_e32 v34, v37, v34
	v_add_f32_e32 v37, v39, v34
	v_rcp_f32_e32 v49, v37
	v_sub_f32_e32 v39, v37, v39
	v_sub_f32_e32 v34, v34, v39
	v_add_f32_e32 v39, v38, v40
	v_sub_f32_e32 v38, v39, v38
	v_mul_f32_e32 v51, v39, v49
	v_sub_f32_e32 v50, v40, v38
	v_mul_f32_e32 v40, v37, v51
	v_fma_f32 v44, v51, v37, -v40
	v_fmac_f32_e32 v44, v51, v34
	v_add_f32_e32 v38, v40, v44
	v_sub_f32_e32 v41, v39, v38
	v_pk_add_f32 v[46:47], v[38:39], v[40:41] neg_lo:[0,1] neg_hi:[0,1]
	v_mov_b32_e32 v45, v38
	v_pk_add_f32 v[38:39], v[46:47], v[44:45] neg_lo:[0,1] neg_hi:[0,1]
	v_cmp_neq_f32_e32 vcc, s57, v33
	v_add_f32_e32 v39, v50, v39
	v_add_f32_e32 v38, v38, v39
	v_add_f32_e32 v39, v41, v38
	v_mul_f32_e32 v50, v49, v39
	v_mul_f32_e32 v40, v37, v50
	v_fma_f32 v44, v50, v37, -v40
	v_fmac_f32_e32 v44, v50, v34
	v_sub_f32_e32 v34, v41, v39
	v_add_f32_e32 v34, v38, v34
	v_add_f32_e32 v38, v40, v44
	v_sub_f32_e32 v41, v39, v38
	v_pk_add_f32 v[46:47], v[38:39], v[40:41] neg_lo:[0,1] neg_hi:[0,1]
	v_mov_b32_e32 v45, v38
	v_pk_add_f32 v[38:39], v[46:47], v[44:45] neg_lo:[0,1] neg_hi:[0,1]
	v_add_f32_e32 v37, v51, v50
	v_add_f32_e32 v34, v34, v39
	v_add_f32_e32 v34, v38, v34
	v_add_f32_e32 v34, v41, v34
	v_sub_f32_e32 v38, v37, v51
	v_mul_f32_e32 v34, v49, v34
	v_sub_f32_e32 v38, v50, v38
	v_add_f32_e32 v34, v38, v34
	v_add_f32_e32 v39, v37, v34
	v_mul_f32_e32 v40, v39, v39
	v_fmamk_f32 v38, v40, 0x3e9b6dac, v235
	v_fmaak_f32 v227, v40, v38, 0x3f2aaada
	v_cvt_f32_i32_e32 v38, v48
	v_sub_f32_e32 v37, v39, v37
	v_ldexp_f32 v41, v39, 1
	v_mul_f32_e32 v39, v39, v40
	v_pk_mul_f32 v[44:45], v[38:39], v[226:227]
	v_sub_f32_e32 v34, v34, v37
	v_fma_f32 v40, v38, s56, -v44
	v_fmac_f32_e32 v40, 0xb102e308, v38
	v_pk_add_f32 v[38:39], v[44:45], v[40:41]
	v_ldexp_f32 v34, v34, 1
	v_sub_f32_e32 v37, v39, v41
	v_sub_f32_e32 v37, v45, v37
	v_add_f32_e32 v47, v34, v37
	v_mov_b32_e32 v46, v44
	v_pk_add_f32 v[44:45], v[38:39], v[44:45] neg_lo:[0,1] neg_hi:[0,1]
	v_pk_add_f32 v[48:49], v[38:39], v[46:47]
	v_mov_b32_e32 v41, v38
	v_mov_b32_e32 v45, v49
	v_pk_add_f32 v[50:51], v[40:41], v[44:45] neg_lo:[0,1] neg_hi:[0,1]
	v_pk_add_f32 v[40:41], v[40:41], v[44:45]
	v_mov_b32_e32 v46, v47
	v_pk_add_f32 v[44:45], v[40:41], v[38:39] op_sel:[1,0] op_sel_hi:[0,1] neg_lo:[0,1] neg_hi:[0,1]
	v_pk_add_f32 v[52:53], v[48:49], v[44:45] op_sel_hi:[1,0] neg_lo:[0,1] neg_hi:[0,1]
	v_mov_b32_e32 v48, v49
	v_mov_b32_e32 v49, v41
	v_pk_mov_b32 v[44:45], v[38:39], v[44:45] op_sel:[1,0]
	v_mov_b32_e32 v47, v38
	v_pk_add_f32 v[44:45], v[48:49], v[44:45] neg_lo:[0,1] neg_hi:[0,1]
	v_mov_b32_e32 v52, v50
	v_pk_add_f32 v[38:39], v[46:47], v[44:45] neg_lo:[0,1] neg_hi:[0,1]
	v_mov_b32_e32 v51, v41
	v_pk_add_f32 v[44:45], v[52:53], v[38:39]
	s_nop 0
	v_pk_add_f32 v[46:47], v[44:45], v[44:45] op_sel:[0,1] op_sel_hi:[1,0]
	s_nop 0
	v_pk_add_f32 v[40:41], v[40:41], v[46:47] op_sel:[1,0] op_sel_hi:[0,1]
	v_mov_b32_e32 v45, v40
	v_pk_add_f32 v[48:49], v[44:45], v[50:51] neg_lo:[0,1] neg_hi:[0,1]
	v_mov_b32_e32 v39, v46
	v_sub_f32_e32 v34, v44, v48
	v_pk_add_f32 v[38:39], v[38:39], v[48:49] neg_lo:[0,1] neg_hi:[0,1]
	v_sub_f32_e32 v34, v50, v34
	v_add_f32_e32 v34, v38, v34
	v_add_f32_e32 v34, v34, v39
	v_add_f32_e32 v34, v40, v34
	v_cndmask_b32_e32 v34, v236, v34, vcc
	v_cmp_ngt_f32_e32 vcc, -1.0, v33
	s_nop 1
	v_cndmask_b32_e32 v34, v237, v34, vcc
	v_cmp_neq_f32_e32 vcc, -1.0, v33
	s_nop 1
	v_cndmask_b32_e32 v34, v238, v34, vcc
	v_cmp_lt_f32_e64 vcc, |v33|, s58
	s_nop 1
	v_cndmask_b32_e32 v33, v34, v33, vcc
.LBB0_296:
	s_or_b64 exec, exec, s[36:37]
	v_mul_f32_e32 v30, 0x3fb8aa3b, v30
	v_exp_f32_e32 v30, v30
	s_nop 0
	v_mul_f32_e64 v34, v3, -v30
	v_mul_f32_e32 v3, 0x3fb8aa3b, v35
	v_exp_f32_e32 v3, v3
	s_nop 0
	v_mul_f32_e64 v35, v31, -v3
	v_mul_f32_e32 v3, 0x3fb8aa3b, v36
	v_exp_f32_e32 v3, v3
	s_nop 0
	v_mul_f32_e64 v36, v32, -v3
	v_mov_b32_e32 v3, v165
	v_mul_f32_e32 v3, 0x3fb8aa3b, v3
	v_exp_f32_e32 v3, v3
	s_nop 0
	v_mul_f32_e64 v37, v33, -v3

;     __device__ __forceinline__ void operator()(f32x4 (&acc)[2][2][4][2], const Unit& u, int row0t, int wr, int wc, int fr, int fq) const {
;     ...
;                                 for (int e = 0; e < 4; ++e) { const int h = 4 * n + e; const float xx = v[e] + dt_bias[h]; const float sp = xx > 20.f ? xx : log1pf(__expf(xx)); o[e] = -__expf(A_log[h]) * sp; } }
;                             *(f32x4*)(bg + (size_t)r * 16 + 8 * fq + 4 * n) = o; } }
.LBB0_299:
	s_or_b64 exec, exec, s[24:25]
	s_mov_b64 s[2:3], 0x2000
	v_lshl_add_u64 v[30:31], v[42:43], 0, s[2:3]
	global_store_dwordx4 v[30:31], v[34:37], off offset:16
	s_and_saveexec_b64 s[2:3], s[4:5]
	s_xor_b64 s[24:25], exec, s[2:3]
	s_cbranch_execz .LBB0_309
	v_mov_b32_e32 v3, v150
	v_add_f32_e32 v3, v26, v3
	v_cmp_nlt_f32_e32 vcc, s53, v3
	s_and_saveexec_b64 s[36:37], vcc
	s_cbranch_execz .LBB0_302
	v_mul_f32_e32 v3, 0x3fb8aa3b, v3
	v_exp_f32_e32 v3, v3
	s_nop 0
	v_add_f32_e32 v26, 1.0, v3
	v_frexp_mant_f32_e32 v33, v26
	v_cvt_f64_f32_e32 v[30:31], v26
	v_add_f32_e32 v32, -1.0, v26
	v_frexp_exp_i32_f64_e32 v30, v[30:31]
	v_cmp_gt_f32_e32 vcc, s55, v33
	v_sub_f32_e32 v34, v32, v26
	v_sub_f32_e32 v32, v3, v32
	v_subbrev_co_u32_e32 v38, vcc, 0, v30, vcc
	v_add_f32_e32 v34, 1.0, v34
	v_sub_u32_e32 v30, 0, v38
	v_add_f32_e32 v32, v32, v34
	v_ldexp_f32 v26, v26, v30
	v_ldexp_f32 v30, v32, v30
	v_add_f32_e32 v32, -1.0, v26
	v_add_f32_e32 v31, 1.0, v32
	v_sub_f32_e32 v31, v26, v31
	v_add_f32_e32 v33, v30, v31
	v_add_f32_e32 v31, 1.0, v26
	v_add_f32_e32 v34, -1.0, v31
	v_sub_f32_e32 v26, v26, v34
	v_add_f32_e32 v26, v30, v26
	v_add_f32_e32 v39, v31, v26
	v_rcp_f32_e32 v40, v39
	v_sub_f32_e32 v30, v39, v31
	v_add_f32_e32 v31, v32, v33
	v_sub_f32_e32 v26, v26, v30
	v_mul_f32_e32 v42, v31, v40
	v_sub_f32_e32 v30, v31, v32
	v_mul_f32_e32 v32, v39, v42
	v_fma_f32 v34, v42, v39, -v32
	v_fmac_f32_e32 v34, v42, v26
	v_sub_f32_e32 v41, v33, v30
	v_add_f32_e32 v30, v32, v34
	v_sub_f32_e32 v33, v31, v30
	v_pk_add_f32 v[36:37], v[30:31], v[32:33] neg_lo:[0,1] neg_hi:[0,1]
	v_mov_b32_e32 v35, v30
	v_pk_add_f32 v[30:31], v[36:37], v[34:35] neg_lo:[0,1] neg_hi:[0,1]
	v_cmp_neq_f32_e32 vcc, s57, v3
	v_add_f32_e32 v31, v41, v31
	v_add_f32_e32 v30, v30, v31
	v_add_f32_e32 v31, v33, v30
	v_mul_f32_e32 v41, v40, v31
	v_mul_f32_e32 v32, v39, v41
	v_fma_f32 v34, v41, v39, -v32
	v_fmac_f32_e32 v34, v41, v26
	v_sub_f32_e32 v26, v33, v31
	v_add_f32_e32 v26, v30, v26
	v_add_f32_e32 v30, v32, v34
	v_sub_f32_e32 v33, v31, v30
	v_pk_add_f32 v[36:37], v[30:31], v[32:33] neg_lo:[0,1] neg_hi:[0,1]
	v_mov_b32_e32 v35, v30
	v_pk_add_f32 v[30:31], v[36:37], v[34:35] neg_lo:[0,1] neg_hi:[0,1]
	s_nop 0
	v_add_f32_e32 v26, v26, v31
	v_add_f32_e32 v26, v30, v26
	v_add_f32_e32 v31, v42, v41
	v_add_f32_e32 v26, v33, v26
	v_sub_f32_e32 v30, v31, v42
	v_mul_f32_e32 v26, v40, v26
	v_sub_f32_e32 v30, v41, v30
	v_add_f32_e32 v26, v30, v26
	v_add_f32_e32 v32, v31, v26
	v_mul_f32_e32 v34, v32, v32
	v_fmamk_f32 v30, v34, 0x3e9b6dac, v235
	v_fmaak_f32 v227, v34, v30, 0x3f2aaada
	v_cvt_f32_i32_e32 v30, v38
	v_sub_f32_e32 v31, v32, v31
	v_sub_f32_e32 v26, v26, v31
	v_mul_f32_e32 v31, v32, v34
	v_pk_mul_f32 v[34:35], v[30:31], v[226:227]
	v_ldexp_f32 v33, v32, 1
	v_fma_f32 v32, v30, s56, -v34
	v_fmac_f32_e32 v32, 0xb102e308, v30
	v_pk_add_f32 v[30:31], v[34:35], v[32:33]
	v_ldexp_f32 v26, v26, 1
	v_sub_f32_e32 v33, v31, v33
	v_sub_f32_e32 v33, v35, v33
	v_add_f32_e32 v37, v26, v33
	v_mov_b32_e32 v36, v34
	v_pk_add_f32 v[34:35], v[30:31], v[34:35] neg_lo:[0,1] neg_hi:[0,1]
	v_pk_add_f32 v[38:39], v[30:31], v[36:37]
	v_mov_b32_e32 v33, v30
	v_mov_b32_e32 v35, v39
	v_pk_add_f32 v[40:41], v[32:33], v[34:35] neg_lo:[0,1] neg_hi:[0,1]
	v_pk_add_f32 v[32:33], v[32:33], v[34:35]
	v_mov_b32_e32 v36, v37
	v_pk_add_f32 v[34:35], v[32:33], v[30:31] op_sel:[1,0] op_sel_hi:[0,1] neg_lo:[0,1] neg_hi:[0,1]
	v_pk_add_f32 v[42:43], v[38:39], v[34:35] op_sel_hi:[1,0] neg_lo:[0,1] neg_hi:[0,1]
	v_mov_b32_e32 v38, v39
	v_mov_b32_e32 v39, v33
	v_pk_mov_b32 v[34:35], v[30:31], v[34:35] op_sel:[1,0]
	v_mov_b32_e32 v37, v30
	v_pk_add_f32 v[34:35], v[38:39], v[34:35] neg_lo:[0,1] neg_hi:[0,1]
	v_mov_b32_e32 v42, v40
	v_pk_add_f32 v[30:31], v[36:37], v[34:35] neg_lo:[0,1] neg_hi:[0,1]
	v_mov_b32_e32 v41, v33
	v_pk_add_f32 v[34:35], v[42:43], v[30:31]
	s_nop 0
	v_pk_add_f32 v[36:37], v[34:35], v[34:35] op_sel:[0,1] op_sel_hi:[1,0]
	s_nop 0
	v_pk_add_f32 v[32:33], v[32:33], v[36:37] op_sel:[1,0] op_sel_hi:[0,1]
	v_mov_b32_e32 v35, v32
	v_pk_add_f32 v[38:39], v[34:35], v[40:41] neg_lo:[0,1] neg_hi:[0,1]
	v_mov_b32_e32 v31, v36
	v_sub_f32_e32 v26, v34, v38
	v_pk_add_f32 v[30:31], v[30:31], v[38:39] neg_lo:[0,1] neg_hi:[0,1]
	v_sub_f32_e32 v26, v40, v26
	v_add_f32_e32 v26, v30, v26
	v_add_f32_e32 v26, v26, v31
	v_add_f32_e32 v26, v32, v26
	v_cndmask_b32_e32 v26, v236, v26, vcc
	v_cmp_ngt_f32_e32 vcc, -1.0, v3
	s_nop 1
	v_cndmask_b32_e32 v26, v237, v26, vcc
	v_cmp_neq_f32_e32 vcc, -1.0, v3
	s_nop 1
	v_cndmask_b32_e32 v26, v238, v26, vcc
	v_cmp_lt_f32_e64 vcc, |v3|, s58
	s_nop 1
	v_cndmask_b32_e32 v3, v26, v3, vcc
;     __device__ __forceinline__ void operator()(f32x4 (&acc)[2][2][4][2], const Unit& u, int row0t, int wr, int wc, int fr, int fq) const {
;     ...
;                                 for (int e = 0; e < 4; ++e) { const int h = 4 * n + e; const float xx = v[e] + dt_bias[h]; const float sp = xx > 20.f ? xx : log1pf(__expf(xx)); o[e] = -__expf(A_log[h]) * sp; } }
.LBB0_302:
	s_or_b64 exec, exec, s[36:37]
	v_mov_b32_e32 v30, v151
	v_mov_b32_e32 v26, v158
	v_add_f32_e32 v27, v27, v30
	v_cmp_nlt_f32_e32 vcc, s53, v27
	s_and_saveexec_b64 s[36:37], vcc
	s_cbranch_execz .LBB0_304
	v_mul_f32_e32 v27, 0x3fb8aa3b, v27
	v_exp_f32_e32 v27, v27
	s_nop 0
	v_add_f32_e32 v32, 1.0, v27
	v_frexp_mant_f32_e32 v34, v32
	v_cvt_f64_f32_e32 v[30:31], v32
	v_frexp_exp_i32_f64_e32 v30, v[30:31]
	v_cmp_gt_f32_e32 vcc, s55, v34
	v_add_f32_e32 v33, -1.0, v32
	v_sub_f32_e32 v35, v33, v32
	v_subbrev_co_u32_e32 v38, vcc, 0, v30, vcc
	v_sub_u32_e32 v30, 0, v38
	v_sub_f32_e32 v33, v27, v33
	v_add_f32_e32 v35, 1.0, v35
	v_ldexp_f32 v31, v32, v30
	v_add_f32_e32 v33, v33, v35
	v_add_f32_e32 v32, -1.0, v31
	v_add_f32_e32 v34, 1.0, v31
	v_ldexp_f32 v30, v33, v30
	v_add_f32_e32 v33, 1.0, v32
	v_add_f32_e32 v35, -1.0, v34
	v_sub_f32_e32 v33, v31, v33
	v_sub_f32_e32 v31, v31, v35
	v_add_f32_e32 v33, v30, v33
	v_add_f32_e32 v30, v30, v31
	v_add_f32_e32 v39, v34, v30
	v_rcp_f32_e32 v41, v39
	v_sub_f32_e32 v31, v39, v34
	v_sub_f32_e32 v40, v30, v31
	v_add_f32_e32 v31, v32, v33
	v_mul_f32_e32 v43, v31, v41
	v_sub_f32_e32 v30, v31, v32
	v_mul_f32_e32 v32, v39, v43
	v_fma_f32 v34, v43, v39, -v32
	v_fmac_f32_e32 v34, v43, v40
	v_sub_f32_e32 v42, v33, v30
	v_add_f32_e32 v30, v32, v34
	v_sub_f32_e32 v33, v31, v30
	v_pk_add_f32 v[36:37], v[30:31], v[32:33] neg_lo:[0,1] neg_hi:[0,1]
	v_mov_b32_e32 v35, v30
	v_pk_add_f32 v[30:31], v[36:37], v[34:35] neg_lo:[0,1] neg_hi:[0,1]
	v_cmp_neq_f32_e32 vcc, s57, v27
	v_add_f32_e32 v31, v42, v31
	v_add_f32_e32 v30, v30, v31
	v_add_f32_e32 v31, v33, v30
	v_mul_f32_e32 v42, v41, v31
	v_mul_f32_e32 v32, v39, v42
	v_fma_f32 v34, v42, v39, -v32
	v_fmac_f32_e32 v34, v42, v40
	v_sub_f32_e32 v33, v33, v31
	v_add_f32_e32 v39, v30, v33
	v_add_f32_e32 v30, v32, v34
	v_sub_f32_e32 v33, v31, v30
	v_pk_add_f32 v[36:37], v[30:31], v[32:33] neg_lo:[0,1] neg_hi:[0,1]
	v_mov_b32_e32 v35, v30
	v_pk_add_f32 v[30:31], v[36:37], v[34:35] neg_lo:[0,1] neg_hi:[0,1]
	s_nop 0
	v_add_f32_e32 v31, v39, v31
	v_add_f32_e32 v30, v30, v31
	v_add_f32_e32 v31, v43, v42
	v_add_f32_e32 v30, v33, v30
	v_sub_f32_e32 v32, v31, v43
	v_mul_f32_e32 v30, v41, v30
	v_sub_f32_e32 v32, v42, v32
	v_add_f32_e32 v32, v32, v30
	v_add_f32_e32 v34, v31, v32
	v_mul_f32_e32 v35, v34, v34
	v_fmamk_f32 v30, v35, 0x3e9b6dac, v235
	v_fmaak_f32 v227, v35, v30, 0x3f2aaada
	v_cvt_f32_i32_e32 v30, v38
	v_sub_f32_e32 v31, v34, v31
	v_sub_f32_e32 v31, v32, v31
	v_ldexp_f32 v36, v31, 1
	v_mul_f32_e32 v31, v34, v35
	v_ldexp_f32 v33, v34, 1
	v_pk_mul_f32 v[34:35], v[30:31], v[226:227]
	s_nop 0
	v_fma_f32 v32, v30, s56, -v34
	v_fmac_f32_e32 v32, 0xb102e308, v30
	v_pk_add_f32 v[30:31], v[34:35], v[32:33]
	s_nop 0
	v_sub_f32_e32 v33, v31, v33
	v_sub_f32_e32 v33, v35, v33
	v_add_f32_e32 v37, v36, v33
	v_mov_b32_e32 v36, v34
	v_pk_add_f32 v[34:35], v[30:31], v[34:35] neg_lo:[0,1] neg_hi:[0,1]
	v_pk_add_f32 v[38:39], v[30:31], v[36:37]
	v_mov_b32_e32 v33, v30
	v_mov_b32_e32 v35, v39
	v_pk_add_f32 v[40:41], v[32:33], v[34:35] neg_lo:[0,1] neg_hi:[0,1]
	v_pk_add_f32 v[32:33], v[32:33], v[34:35]
	v_mov_b32_e32 v36, v37
	v_pk_add_f32 v[34:35], v[32:33], v[30:31] op_sel:[1,0] op_sel_hi:[0,1] neg_lo:[0,1] neg_hi:[0,1]
	v_pk_add_f32 v[42:43], v[38:39], v[34:35] op_sel_hi:[1,0] neg_lo:[0,1] neg_hi:[0,1]
	v_mov_b32_e32 v38, v39
	v_mov_b32_e32 v39, v33
	v_pk_mov_b32 v[34:35], v[30:31], v[34:35] op_sel:[1,0]
	v_mov_b32_e32 v37, v30
	v_pk_add_f32 v[34:35], v[38:39], v[34:35] neg_lo:[0,1] neg_hi:[0,1]
	v_mov_b32_e32 v42, v40
	v_pk_add_f32 v[30:31], v[36:37], v[34:35] neg_lo:[0,1] neg_hi:[0,1]
	v_mov_b32_e32 v41, v33
	v_pk_add_f32 v[34:35], v[42:43], v[30:31]
	s_nop 0
	v_pk_add_f32 v[36:37], v[34:35], v[34:35] op_sel:[0,1] op_sel_hi:[1,0]
	s_nop 0
	v_pk_add_f32 v[32:33], v[32:33], v[36:37] op_sel:[1,0] op_sel_hi:[0,1]
	v_mov_b32_e32 v35, v32
	v_pk_add_f32 v[38:39], v[34:35], v[40:41] neg_lo:[0,1] neg_hi:[0,1]
	v_mov_b32_e32 v31, v36
	v_sub_f32_e32 v33, v34, v38
	v_pk_add_f32 v[30:31], v[30:31], v[38:39] neg_lo:[0,1] neg_hi:[0,1]
	v_sub_f32_e32 v33, v40, v33
	v_add_f32_e32 v30, v30, v33
	v_add_f32_e32 v30, v30, v31
	v_add_f32_e32 v30, v32, v30
	v_cndmask_b32_e32 v30, v236, v30, vcc
	v_cmp_ngt_f32_e32 vcc, -1.0, v27
	s_nop 1
	v_cndmask_b32_e32 v30, v237, v30, vcc
	v_cmp_neq_f32_e32 vcc, -1.0, v27
	s_nop 1
	v_cndmask_b32_e32 v30, v238, v30, vcc
	v_cmp_lt_f32_e64 vcc, |v27|, s58
	s_nop 1
	v_cndmask_b32_e32 v27, v30, v27, vcc
;     __device__ __forceinline__ void operator()(f32x4 (&acc)[2][2][4][2], const Unit& u, int row0t, int wr, int wc, int fr, int fq) const {
;     ...
;                                 for (int e = 0; e < 4; ++e) { const int h = 4 * n + e; const float xx = v[e] + dt_bias[h]; const float sp = xx > 20.f ? xx : log1pf(__expf(xx)); o[e] = -__expf(A_log[h]) * sp; } }
.LBB0_304:
	s_or_b64 exec, exec, s[36:37]
	v_mov_b32_e32 v30, v152
	v_mov_b32_e32 v31, v159
	v_add_f32_e32 v28, v28, v30
	v_cmp_nlt_f32_e32 vcc, s53, v28
	s_and_saveexec_b64 s[36:37], vcc
	s_cbranch_execz .LBB0_306
	v_mul_f32_e32 v28, 0x3fb8aa3b, v28
	v_exp_f32_e32 v28, v28
	s_nop 0
	v_add_f32_e32 v30, 1.0, v28
	v_frexp_mant_f32_e32 v35, v30
	v_cvt_f64_f32_e32 v[32:33], v30
	v_add_f32_e32 v34, -1.0, v30
	v_frexp_exp_i32_f64_e32 v32, v[32:33]
	v_cmp_gt_f32_e32 vcc, s55, v35
	v_sub_f32_e32 v36, v34, v30
	v_sub_f32_e32 v34, v28, v34
	v_subbrev_co_u32_e32 v40, vcc, 0, v32, vcc
	v_add_f32_e32 v36, 1.0, v36
	v_sub_u32_e32 v32, 0, v40
	v_add_f32_e32 v34, v34, v36
	v_ldexp_f32 v30, v30, v32
	v_ldexp_f32 v32, v34, v32
	v_add_f32_e32 v34, -1.0, v30
	v_add_f32_e32 v33, 1.0, v34
	v_sub_f32_e32 v33, v30, v33
	v_add_f32_e32 v35, v32, v33
	v_add_f32_e32 v33, 1.0, v30
	v_add_f32_e32 v36, -1.0, v33
	v_sub_f32_e32 v30, v30, v36
	v_add_f32_e32 v30, v32, v30
	v_add_f32_e32 v41, v33, v30
	v_rcp_f32_e32 v42, v41
	v_sub_f32_e32 v32, v41, v33
	v_add_f32_e32 v33, v34, v35
	v_sub_f32_e32 v30, v30, v32
	v_mul_f32_e32 v44, v33, v42
	v_sub_f32_e32 v32, v33, v34
	v_mul_f32_e32 v34, v41, v44
	v_fma_f32 v36, v44, v41, -v34
	v_fmac_f32_e32 v36, v44, v30
	v_sub_f32_e32 v43, v35, v32
	v_add_f32_e32 v32, v34, v36
	v_sub_f32_e32 v35, v33, v32
	v_pk_add_f32 v[38:39], v[32:33], v[34:35] neg_lo:[0,1] neg_hi:[0,1]
	v_mov_b32_e32 v37, v32
	v_pk_add_f32 v[32:33], v[38:39], v[36:37] neg_lo:[0,1] neg_hi:[0,1]
	v_cmp_neq_f32_e32 vcc, s57, v28
	v_add_f32_e32 v33, v43, v33
	v_add_f32_e32 v32, v32, v33
	v_add_f32_e32 v33, v35, v32
	v_mul_f32_e32 v43, v42, v33
	v_mul_f32_e32 v34, v41, v43
	v_fma_f32 v36, v43, v41, -v34
	v_fmac_f32_e32 v36, v43, v30
	v_sub_f32_e32 v30, v35, v33
	v_add_f32_e32 v30, v32, v30
	v_add_f32_e32 v32, v34, v36
	v_sub_f32_e32 v35, v33, v32
	v_pk_add_f32 v[38:39], v[32:33], v[34:35] neg_lo:[0,1] neg_hi:[0,1]
	v_mov_b32_e32 v37, v32
	v_pk_add_f32 v[32:33], v[38:39], v[36:37] neg_lo:[0,1] neg_hi:[0,1]
	s_nop 0
	v_add_f32_e32 v30, v30, v33
	v_add_f32_e32 v30, v32, v30
	v_add_f32_e32 v33, v44, v43
	v_add_f32_e32 v30, v35, v30
	v_sub_f32_e32 v32, v33, v44
	v_mul_f32_e32 v30, v42, v30
	v_sub_f32_e32 v32, v43, v32
	v_add_f32_e32 v30, v32, v30
	v_add_f32_e32 v34, v33, v30
	v_mul_f32_e32 v36, v34, v34
	v_fmamk_f32 v32, v36, 0x3e9b6dac, v235
	v_fmaak_f32 v227, v36, v32, 0x3f2aaada
	v_cvt_f32_i32_e32 v32, v40
	v_sub_f32_e32 v33, v34, v33
	v_sub_f32_e32 v30, v30, v33
	v_mul_f32_e32 v33, v34, v36
	v_pk_mul_f32 v[36:37], v[32:33], v[226:227]
	v_ldexp_f32 v35, v34, 1
	v_fma_f32 v34, v32, s56, -v36
	v_fmac_f32_e32 v34, 0xb102e308, v32
	v_pk_add_f32 v[32:33], v[36:37], v[34:35]
	v_ldexp_f32 v30, v30, 1
	v_sub_f32_e32 v35, v33, v35
	v_sub_f32_e32 v35, v37, v35
	v_add_f32_e32 v39, v30, v35
	v_mov_b32_e32 v38, v36
	v_pk_add_f32 v[36:37], v[32:33], v[36:37] neg_lo:[0,1] neg_hi:[0,1]
	v_pk_add_f32 v[40:41], v[32:33], v[38:39]
	v_mov_b32_e32 v35, v32
	v_mov_b32_e32 v37, v41
	v_pk_add_f32 v[42:43], v[34:35], v[36:37] neg_lo:[0,1] neg_hi:[0,1]
	v_pk_add_f32 v[34:35], v[34:35], v[36:37]
	v_mov_b32_e32 v38, v39
	v_pk_add_f32 v[36:37], v[34:35], v[32:33] op_sel:[1,0] op_sel_hi:[0,1] neg_lo:[0,1] neg_hi:[0,1]
	v_pk_add_f32 v[44:45], v[40:41], v[36:37] op_sel_hi:[1,0] neg_lo:[0,1] neg_hi:[0,1]
	v_mov_b32_e32 v40, v41
	v_mov_b32_e32 v41, v35
	v_pk_mov_b32 v[36:37], v[32:33], v[36:37] op_sel:[1,0]
	v_mov_b32_e32 v39, v32
	v_pk_add_f32 v[36:37], v[40:41], v[36:37] neg_lo:[0,1] neg_hi:[0,1]
	v_mov_b32_e32 v44, v42
	v_pk_add_f32 v[32:33], v[38:39], v[36:37] neg_lo:[0,1] neg_hi:[0,1]
	v_mov_b32_e32 v43, v35
	v_pk_add_f32 v[36:37], v[44:45], v[32:33]
	s_nop 0
	v_pk_add_f32 v[38:39], v[36:37], v[36:37] op_sel:[0,1] op_sel_hi:[1,0]
	s_nop 0
	v_pk_add_f32 v[34:35], v[34:35], v[38:39] op_sel:[1,0] op_sel_hi:[0,1]
	v_mov_b32_e32 v37, v34
	v_pk_add_f32 v[40:41], v[36:37], v[42:43] neg_lo:[0,1] neg_hi:[0,1]
	v_mov_b32_e32 v33, v38
	v_sub_f32_e32 v30, v36, v40
	v_pk_add_f32 v[32:33], v[32:33], v[40:41] neg_lo:[0,1] neg_hi:[0,1]
	v_sub_f32_e32 v30, v42, v30
	v_add_f32_e32 v30, v32, v30
	v_add_f32_e32 v30, v30, v33
	v_add_f32_e32 v30, v34, v30
	v_cndmask_b32_e32 v30, v236, v30, vcc
	v_cmp_ngt_f32_e32 vcc, -1.0, v28
	s_nop 1
	v_cndmask_b32_e32 v30, v237, v30, vcc
	v_cmp_neq_f32_e32 vcc, -1.0, v28
	s_nop 1
	v_cndmask_b32_e32 v30, v238, v30, vcc
	v_cmp_lt_f32_e64 vcc, |v28|, s58
	s_nop 1
	v_cndmask_b32_e32 v28, v30, v28, vcc
;     __device__ __forceinline__ void operator()(f32x4 (&acc)[2][2][4][2], const Unit& u, int row0t, int wr, int wc, int fr, int fq) const {
;     ...
;                                 for (int e = 0; e < 4; ++e) { const int h = 4 * n + e; const float xx = v[e] + dt_bias[h]; const float sp = xx > 20.f ? xx : log1pf(__expf(xx)); o[e] = -__expf(A_log[h]) * sp; } }
.LBB0_306:
	s_or_b64 exec, exec, s[36:37]
	v_mov_b32_e32 v30, v153
	v_mov_b32_e32 v32, v160
	v_add_f32_e32 v29, v29, v30
	v_cmp_nlt_f32_e32 vcc, s53, v29
	s_and_saveexec_b64 s[36:37], vcc
	s_cbranch_execz .LBB0_308
	v_mul_f32_e32 v29, 0x3fb8aa3b, v29
	v_exp_f32_e32 v29, v29
	s_nop 0
	v_add_f32_e32 v30, 1.0, v29
	v_frexp_mant_f32_e32 v36, v30
	v_cvt_f64_f32_e32 v[34:35], v30
	v_add_f32_e32 v33, -1.0, v30
	v_frexp_exp_i32_f64_e32 v34, v[34:35]
	v_cmp_gt_f32_e32 vcc, s55, v36
	v_sub_f32_e32 v37, v33, v30
	v_sub_f32_e32 v33, v29, v33
	v_subbrev_co_u32_e32 v42, vcc, 0, v34, vcc
	v_add_f32_e32 v37, 1.0, v37
	v_sub_u32_e32 v34, 0, v42
	v_add_f32_e32 v33, v33, v37
	v_ldexp_f32 v30, v30, v34
	v_ldexp_f32 v33, v33, v34
	v_add_f32_e32 v34, -1.0, v30
	v_add_f32_e32 v35, 1.0, v34
	v_sub_f32_e32 v35, v30, v35
	v_add_f32_e32 v36, v33, v35
	v_add_f32_e32 v35, 1.0, v30
	v_add_f32_e32 v37, -1.0, v35
	v_sub_f32_e32 v30, v30, v37
	v_add_f32_e32 v30, v33, v30
	v_add_f32_e32 v33, v35, v30
	v_rcp_f32_e32 v43, v33
	v_sub_f32_e32 v35, v33, v35
	v_sub_f32_e32 v30, v30, v35
	v_add_f32_e32 v35, v34, v36
	v_sub_f32_e32 v34, v35, v34
	v_mul_f32_e32 v45, v35, v43
	v_sub_f32_e32 v44, v36, v34
	v_mul_f32_e32 v36, v33, v45
	v_fma_f32 v38, v45, v33, -v36
	v_fmac_f32_e32 v38, v45, v30
	v_add_f32_e32 v34, v36, v38
	v_sub_f32_e32 v37, v35, v34
	v_pk_add_f32 v[40:41], v[34:35], v[36:37] neg_lo:[0,1] neg_hi:[0,1]
	v_mov_b32_e32 v39, v34
	v_pk_add_f32 v[34:35], v[40:41], v[38:39] neg_lo:[0,1] neg_hi:[0,1]
	v_cmp_neq_f32_e32 vcc, s57, v29
	v_add_f32_e32 v35, v44, v35
	v_add_f32_e32 v34, v34, v35
	v_add_f32_e32 v35, v37, v34
	v_mul_f32_e32 v44, v43, v35
	v_mul_f32_e32 v36, v33, v44
	v_fma_f32 v38, v44, v33, -v36
	v_fmac_f32_e32 v38, v44, v30
	v_sub_f32_e32 v30, v37, v35
	v_add_f32_e32 v30, v34, v30
	v_add_f32_e32 v34, v36, v38
	v_sub_f32_e32 v37, v35, v34
	v_pk_add_f32 v[40:41], v[34:35], v[36:37] neg_lo:[0,1] neg_hi:[0,1]
	v_mov_b32_e32 v39, v34
	v_pk_add_f32 v[34:35], v[40:41], v[38:39] neg_lo:[0,1] neg_hi:[0,1]
	v_add_f32_e32 v33, v45, v44
	v_add_f32_e32 v30, v30, v35
	v_add_f32_e32 v30, v34, v30
	v_add_f32_e32 v30, v37, v30
	v_sub_f32_e32 v34, v33, v45
	v_mul_f32_e32 v30, v43, v30
	v_sub_f32_e32 v34, v44, v34
	v_add_f32_e32 v30, v34, v30
	v_add_f32_e32 v35, v33, v30
	v_mul_f32_e32 v36, v35, v35
	v_fmamk_f32 v34, v36, 0x3e9b6dac, v235
	v_fmaak_f32 v227, v36, v34, 0x3f2aaada
	v_cvt_f32_i32_e32 v34, v42
	v_sub_f32_e32 v33, v35, v33
	v_ldexp_f32 v37, v35, 1
	v_mul_f32_e32 v35, v35, v36
	v_pk_mul_f32 v[38:39], v[34:35], v[226:227]
	v_sub_f32_e32 v30, v30, v33
	v_fma_f32 v36, v34, s56, -v38
	v_fmac_f32_e32 v36, 0xb102e308, v34
	v_pk_add_f32 v[34:35], v[38:39], v[36:37]
	v_ldexp_f32 v30, v30, 1
	v_sub_f32_e32 v33, v35, v37
	v_sub_f32_e32 v33, v39, v33
	v_add_f32_e32 v41, v30, v33
	v_mov_b32_e32 v40, v38
	v_pk_add_f32 v[38:39], v[34:35], v[38:39] neg_lo:[0,1] neg_hi:[0,1]
	v_pk_add_f32 v[42:43], v[34:35], v[40:41]
	v_mov_b32_e32 v37, v34
	v_mov_b32_e32 v39, v43
	v_pk_add_f32 v[44:45], v[36:37], v[38:39] neg_lo:[0,1] neg_hi:[0,1]
	v_pk_add_f32 v[36:37], v[36:37], v[38:39]
	v_mov_b32_e32 v40, v41
	v_pk_add_f32 v[38:39], v[36:37], v[34:35] op_sel:[1,0] op_sel_hi:[0,1] neg_lo:[0,1] neg_hi:[0,1]
	v_pk_add_f32 v[46:47], v[42:43], v[38:39] op_sel_hi:[1,0] neg_lo:[0,1] neg_hi:[0,1]
	v_mov_b32_e32 v42, v43
	v_mov_b32_e32 v43, v37
	v_pk_mov_b32 v[38:39], v[34:35], v[38:39] op_sel:[1,0]
	v_mov_b32_e32 v41, v34
	v_pk_add_f32 v[38:39], v[42:43], v[38:39] neg_lo:[0,1] neg_hi:[0,1]
	v_mov_b32_e32 v46, v44
	v_pk_add_f32 v[34:35], v[40:41], v[38:39] neg_lo:[0,1] neg_hi:[0,1]
	v_mov_b32_e32 v45, v37
	v_pk_add_f32 v[38:39], v[46:47], v[34:35]
	s_nop 0
	v_pk_add_f32 v[40:41], v[38:39], v[38:39] op_sel:[0,1] op_sel_hi:[1,0]
	s_nop 0
	v_pk_add_f32 v[36:37], v[36:37], v[40:41] op_sel:[1,0] op_sel_hi:[0,1]
	v_mov_b32_e32 v39, v36
	v_pk_add_f32 v[42:43], v[38:39], v[44:45] neg_lo:[0,1] neg_hi:[0,1]
	v_mov_b32_e32 v35, v40
	v_sub_f32_e32 v30, v38, v42
	v_pk_add_f32 v[34:35], v[34:35], v[42:43] neg_lo:[0,1] neg_hi:[0,1]
	v_sub_f32_e32 v30, v44, v30
	v_add_f32_e32 v30, v34, v30
	v_add_f32_e32 v30, v30, v35
	v_add_f32_e32 v30, v36, v30
	v_cndmask_b32_e32 v30, v236, v30, vcc
	v_cmp_ngt_f32_e32 vcc, -1.0, v29
	s_nop 1
	v_cndmask_b32_e32 v30, v237, v30, vcc
	v_cmp_neq_f32_e32 vcc, -1.0, v29
	s_nop 1
	v_cndmask_b32_e32 v30, v238, v30, vcc
	v_cmp_lt_f32_e64 vcc, |v29|, s58
	s_nop 1
	v_cndmask_b32_e32 v29, v30, v29, vcc
.LBB0_308:
	s_or_b64 exec, exec, s[36:37]
	v_mul_f32_e32 v26, 0x3fb8aa3b, v26
	v_exp_f32_e32 v26, v26
	s_nop 0
	v_mul_f32_e64 v30, v3, -v26
	v_mul_f32_e32 v3, 0x3fb8aa3b, v31
	v_exp_f32_e32 v3, v3
	s_nop 0
	v_mul_f32_e64 v31, v27, -v3
	v_mul_f32_e32 v3, 0x3fb8aa3b, v32
	v_exp_f32_e32 v3, v3
	s_nop 0
	v_mul_f32_e64 v32, v28, -v3
	v_mov_b32_e32 v3, v161
	v_mul_f32_e32 v3, 0x3fb8aa3b, v3
	v_exp_f32_e32 v3, v3
	s_nop 0
	v_mul_f32_e64 v33, v29, -v3

;     __device__ __forceinline__ void operator()(f32x4 (&acc)[2][2][4][2], const Unit& u, int row0t, int wr, int wc, int fr, int fq) const {
;     ...
;                                 for (int e = 0; e < 4; ++e) { const int h = 4 * n + e; const float xx = v[e] + dt_bias[h]; const float sp = xx > 20.f ? xx : log1pf(__expf(xx)); o[e] = -__expf(A_log[h]) * sp; } }
;                             *(f32x4*)(bg + (size_t)r * 16 + 8 * fq + 4 * n) = o; } }
.LBB0_311:
	s_or_b64 exec, exec, s[24:25]
	v_lshlrev_b64 v[26:27], 6, v[4:5]
	v_lshl_add_u64 v[34:35], v[214:215], 0, v[26:27]
	v_add_co_u32_e32 v26, vcc, 0x2000, v34
	s_nop 1
	v_addc_co_u32_e32 v27, vcc, 0, v35, vcc
	global_store_dwordx4 v[26:27], v[30:33], off offset:1024
	s_and_saveexec_b64 s[2:3], s[4:5]
	s_xor_b64 s[24:25], exec, s[2:3]
	s_cbranch_execz .LBB0_321
	v_mov_b32_e32 v3, v154
	v_add_f32_e32 v3, v22, v3
	v_cmp_nlt_f32_e32 vcc, s53, v3
	s_and_saveexec_b64 s[36:37], vcc
	s_cbranch_execz .LBB0_314
	v_mul_f32_e32 v3, 0x3fb8aa3b, v3
	v_exp_f32_e32 v3, v3
	s_nop 0
	v_add_f32_e32 v22, 1.0, v3
	v_frexp_mant_f32_e32 v29, v22
	v_cvt_f64_f32_e32 v[26:27], v22
	v_add_f32_e32 v28, -1.0, v22
	v_frexp_exp_i32_f64_e32 v26, v[26:27]
	v_cmp_gt_f32_e32 vcc, s55, v29
	v_sub_f32_e32 v30, v28, v22
	v_sub_f32_e32 v28, v3, v28
	v_subbrev_co_u32_e32 v36, vcc, 0, v26, vcc
	v_add_f32_e32 v30, 1.0, v30
	v_sub_u32_e32 v26, 0, v36
	v_add_f32_e32 v28, v28, v30
	v_ldexp_f32 v22, v22, v26
	v_ldexp_f32 v26, v28, v26
	v_add_f32_e32 v28, -1.0, v22
	v_add_f32_e32 v27, 1.0, v28
	v_sub_f32_e32 v27, v22, v27
	v_add_f32_e32 v29, v26, v27
	v_add_f32_e32 v27, 1.0, v22
	v_add_f32_e32 v30, -1.0, v27
	v_sub_f32_e32 v22, v22, v30
	v_add_f32_e32 v22, v26, v22
	v_add_f32_e32 v37, v27, v22
	v_rcp_f32_e32 v38, v37
	v_sub_f32_e32 v26, v37, v27
	v_add_f32_e32 v27, v28, v29
	v_sub_f32_e32 v22, v22, v26
	v_mul_f32_e32 v40, v27, v38
	v_sub_f32_e32 v26, v27, v28
	v_mul_f32_e32 v28, v37, v40
	v_fma_f32 v30, v40, v37, -v28
	v_fmac_f32_e32 v30, v40, v22
	v_sub_f32_e32 v39, v29, v26
	v_add_f32_e32 v26, v28, v30
	v_sub_f32_e32 v29, v27, v26
	v_pk_add_f32 v[32:33], v[26:27], v[28:29] neg_lo:[0,1] neg_hi:[0,1]
	v_mov_b32_e32 v31, v26
	v_pk_add_f32 v[26:27], v[32:33], v[30:31] neg_lo:[0,1] neg_hi:[0,1]
	v_cmp_neq_f32_e32 vcc, s57, v3
	v_add_f32_e32 v27, v39, v27
	v_add_f32_e32 v26, v26, v27
	v_add_f32_e32 v27, v29, v26
	v_mul_f32_e32 v39, v38, v27
	v_mul_f32_e32 v28, v37, v39
	v_fma_f32 v30, v39, v37, -v28
	v_fmac_f32_e32 v30, v39, v22
	v_sub_f32_e32 v22, v29, v27
	v_add_f32_e32 v22, v26, v22
	v_add_f32_e32 v26, v28, v30
	v_sub_f32_e32 v29, v27, v26
	v_pk_add_f32 v[32:33], v[26:27], v[28:29] neg_lo:[0,1] neg_hi:[0,1]
	v_mov_b32_e32 v31, v26
	v_pk_add_f32 v[26:27], v[32:33], v[30:31] neg_lo:[0,1] neg_hi:[0,1]
	s_nop 0
	v_add_f32_e32 v22, v22, v27
	v_add_f32_e32 v22, v26, v22
	v_add_f32_e32 v27, v40, v39
	v_add_f32_e32 v22, v29, v22
	v_sub_f32_e32 v26, v27, v40
	v_mul_f32_e32 v22, v38, v22
	v_sub_f32_e32 v26, v39, v26
	v_add_f32_e32 v22, v26, v22
	v_add_f32_e32 v28, v27, v22
	v_mul_f32_e32 v30, v28, v28
	v_fmamk_f32 v26, v30, 0x3e9b6dac, v235
	v_fmaak_f32 v227, v30, v26, 0x3f2aaada
	v_cvt_f32_i32_e32 v26, v36
	v_sub_f32_e32 v27, v28, v27
	v_sub_f32_e32 v22, v22, v27
	v_mul_f32_e32 v27, v28, v30
	v_pk_mul_f32 v[30:31], v[26:27], v[226:227]
	v_ldexp_f32 v29, v28, 1
	v_fma_f32 v28, v26, s56, -v30
	v_fmac_f32_e32 v28, 0xb102e308, v26
	v_pk_add_f32 v[26:27], v[30:31], v[28:29]
	v_ldexp_f32 v22, v22, 1
	v_sub_f32_e32 v29, v27, v29
	v_sub_f32_e32 v29, v31, v29
	v_add_f32_e32 v33, v22, v29
	v_mov_b32_e32 v32, v30
	v_pk_add_f32 v[30:31], v[26:27], v[30:31] neg_lo:[0,1] neg_hi:[0,1]
	v_pk_add_f32 v[36:37], v[26:27], v[32:33]
	v_mov_b32_e32 v29, v26
	v_mov_b32_e32 v31, v37
	v_pk_add_f32 v[38:39], v[28:29], v[30:31] neg_lo:[0,1] neg_hi:[0,1]
	v_pk_add_f32 v[28:29], v[28:29], v[30:31]
	v_mov_b32_e32 v32, v33
	v_pk_add_f32 v[30:31], v[28:29], v[26:27] op_sel:[1,0] op_sel_hi:[0,1] neg_lo:[0,1] neg_hi:[0,1]
	v_pk_add_f32 v[40:41], v[36:37], v[30:31] op_sel_hi:[1,0] neg_lo:[0,1] neg_hi:[0,1]
	v_mov_b32_e32 v36, v37
	v_mov_b32_e32 v37, v29
	v_pk_mov_b32 v[30:31], v[26:27], v[30:31] op_sel:[1,0]
	v_mov_b32_e32 v33, v26
	v_pk_add_f32 v[30:31], v[36:37], v[30:31] neg_lo:[0,1] neg_hi:[0,1]
	v_mov_b32_e32 v40, v38
	v_pk_add_f32 v[26:27], v[32:33], v[30:31] neg_lo:[0,1] neg_hi:[0,1]
	v_mov_b32_e32 v39, v29
	v_pk_add_f32 v[30:31], v[40:41], v[26:27]
	s_nop 0
	v_pk_add_f32 v[32:33], v[30:31], v[30:31] op_sel:[0,1] op_sel_hi:[1,0]
	s_nop 0
	v_pk_add_f32 v[28:29], v[28:29], v[32:33] op_sel:[1,0] op_sel_hi:[0,1]
	v_mov_b32_e32 v31, v28
	v_pk_add_f32 v[36:37], v[30:31], v[38:39] neg_lo:[0,1] neg_hi:[0,1]
	v_mov_b32_e32 v27, v32
	v_sub_f32_e32 v22, v30, v36
	v_pk_add_f32 v[26:27], v[26:27], v[36:37] neg_lo:[0,1] neg_hi:[0,1]
	v_sub_f32_e32 v22, v38, v22
	v_add_f32_e32 v22, v26, v22
	v_add_f32_e32 v22, v22, v27
	v_add_f32_e32 v22, v28, v22
	v_cndmask_b32_e32 v22, v236, v22, vcc
	v_cmp_ngt_f32_e32 vcc, -1.0, v3
	s_nop 1
	v_cndmask_b32_e32 v22, v237, v22, vcc
	v_cmp_neq_f32_e32 vcc, -1.0, v3
	s_nop 1
	v_cndmask_b32_e32 v22, v238, v22, vcc
	v_cmp_lt_f32_e64 vcc, |v3|, s58
	s_nop 1
	v_cndmask_b32_e32 v3, v22, v3, vcc
;     __device__ __forceinline__ void operator()(f32x4 (&acc)[2][2][4][2], const Unit& u, int row0t, int wr, int wc, int fr, int fq) const {
;     ...
;                                 for (int e = 0; e < 4; ++e) { const int h = 4 * n + e; const float xx = v[e] + dt_bias[h]; const float sp = xx > 20.f ? xx : log1pf(__expf(xx)); o[e] = -__expf(A_log[h]) * sp; } }
.LBB0_314:
	s_or_b64 exec, exec, s[36:37]
	v_mov_b32_e32 v26, v155
	v_mov_b32_e32 v22, v162
	v_add_f32_e32 v23, v23, v26
	v_cmp_nlt_f32_e32 vcc, s53, v23
	s_and_saveexec_b64 s[36:37], vcc
	s_cbranch_execz .LBB0_316
	v_mul_f32_e32 v23, 0x3fb8aa3b, v23
	v_exp_f32_e32 v23, v23
	s_nop 0
	v_add_f32_e32 v28, 1.0, v23
	v_frexp_mant_f32_e32 v30, v28
	v_cvt_f64_f32_e32 v[26:27], v28
	v_frexp_exp_i32_f64_e32 v26, v[26:27]
	v_cmp_gt_f32_e32 vcc, s55, v30
	v_add_f32_e32 v29, -1.0, v28
	v_sub_f32_e32 v31, v29, v28
	v_subbrev_co_u32_e32 v36, vcc, 0, v26, vcc
	v_sub_u32_e32 v26, 0, v36
	v_sub_f32_e32 v29, v23, v29
	v_add_f32_e32 v31, 1.0, v31
	v_ldexp_f32 v27, v28, v26
	v_add_f32_e32 v29, v29, v31
	v_add_f32_e32 v28, -1.0, v27
	v_add_f32_e32 v30, 1.0, v27
	v_ldexp_f32 v26, v29, v26
	v_add_f32_e32 v29, 1.0, v28
	v_add_f32_e32 v31, -1.0, v30
	v_sub_f32_e32 v29, v27, v29
	v_sub_f32_e32 v27, v27, v31
	v_add_f32_e32 v29, v26, v29
	v_add_f32_e32 v26, v26, v27
	v_add_f32_e32 v37, v30, v26
	v_rcp_f32_e32 v39, v37
	v_sub_f32_e32 v27, v37, v30
	v_sub_f32_e32 v38, v26, v27
	v_add_f32_e32 v27, v28, v29
	v_mul_f32_e32 v41, v27, v39
	v_sub_f32_e32 v26, v27, v28
	v_mul_f32_e32 v28, v37, v41
	v_fma_f32 v30, v41, v37, -v28
	v_fmac_f32_e32 v30, v41, v38
	v_sub_f32_e32 v40, v29, v26
	v_add_f32_e32 v26, v28, v30
	v_sub_f32_e32 v29, v27, v26
	v_pk_add_f32 v[32:33], v[26:27], v[28:29] neg_lo:[0,1] neg_hi:[0,1]
	v_mov_b32_e32 v31, v26
	v_pk_add_f32 v[26:27], v[32:33], v[30:31] neg_lo:[0,1] neg_hi:[0,1]
	v_cmp_neq_f32_e32 vcc, s57, v23
	v_add_f32_e32 v27, v40, v27
	v_add_f32_e32 v26, v26, v27
	v_add_f32_e32 v27, v29, v26
	v_mul_f32_e32 v40, v39, v27
	v_mul_f32_e32 v28, v37, v40
	v_fma_f32 v30, v40, v37, -v28
	v_fmac_f32_e32 v30, v40, v38
	v_sub_f32_e32 v29, v29, v27
	v_add_f32_e32 v37, v26, v29
	v_add_f32_e32 v26, v28, v30
	v_sub_f32_e32 v29, v27, v26
	v_pk_add_f32 v[32:33], v[26:27], v[28:29] neg_lo:[0,1] neg_hi:[0,1]
	v_mov_b32_e32 v31, v26
	v_pk_add_f32 v[26:27], v[32:33], v[30:31] neg_lo:[0,1] neg_hi:[0,1]
	s_nop 0
	v_add_f32_e32 v27, v37, v27
	v_add_f32_e32 v26, v26, v27
	v_add_f32_e32 v27, v41, v40
	v_add_f32_e32 v26, v29, v26
	v_sub_f32_e32 v28, v27, v41
	v_mul_f32_e32 v26, v39, v26
	v_sub_f32_e32 v28, v40, v28
	v_add_f32_e32 v28, v28, v26
	v_add_f32_e32 v30, v27, v28
	v_mul_f32_e32 v31, v30, v30
	v_fmamk_f32 v26, v31, 0x3e9b6dac, v235
	v_fmaak_f32 v227, v31, v26, 0x3f2aaada
	v_cvt_f32_i32_e32 v26, v36
	v_sub_f32_e32 v27, v30, v27
	v_sub_f32_e32 v27, v28, v27
	v_ldexp_f32 v32, v27, 1
	v_mul_f32_e32 v27, v30, v31
	v_ldexp_f32 v29, v30, 1
	v_pk_mul_f32 v[30:31], v[26:27], v[226:227]
	s_nop 0
	v_fma_f32 v28, v26, s56, -v30
	v_fmac_f32_e32 v28, 0xb102e308, v26
	v_pk_add_f32 v[26:27], v[30:31], v[28:29]
	s_nop 0
	v_sub_f32_e32 v29, v27, v29
	v_sub_f32_e32 v29, v31, v29
	v_add_f32_e32 v33, v32, v29
	v_mov_b32_e32 v32, v30
	v_pk_add_f32 v[30:31], v[26:27], v[30:31] neg_lo:[0,1] neg_hi:[0,1]
	v_pk_add_f32 v[36:37], v[26:27], v[32:33]
	v_mov_b32_e32 v29, v26
	v_mov_b32_e32 v31, v37
	v_pk_add_f32 v[38:39], v[28:29], v[30:31] neg_lo:[0,1] neg_hi:[0,1]
	v_pk_add_f32 v[28:29], v[28:29], v[30:31]
	v_mov_b32_e32 v32, v33
	v_pk_add_f32 v[30:31], v[28:29], v[26:27] op_sel:[1,0] op_sel_hi:[0,1] neg_lo:[0,1] neg_hi:[0,1]
	v_pk_add_f32 v[40:41], v[36:37], v[30:31] op_sel_hi:[1,0] neg_lo:[0,1] neg_hi:[0,1]
	v_mov_b32_e32 v36, v37
	v_mov_b32_e32 v37, v29
	v_pk_mov_b32 v[30:31], v[26:27], v[30:31] op_sel:[1,0]
	v_mov_b32_e32 v33, v26
	v_pk_add_f32 v[30:31], v[36:37], v[30:31] neg_lo:[0,1] neg_hi:[0,1]
	v_mov_b32_e32 v40, v38
	v_pk_add_f32 v[26:27], v[32:33], v[30:31] neg_lo:[0,1] neg_hi:[0,1]
	v_mov_b32_e32 v39, v29
	v_pk_add_f32 v[30:31], v[40:41], v[26:27]
	s_nop 0
	v_pk_add_f32 v[32:33], v[30:31], v[30:31] op_sel:[0,1] op_sel_hi:[1,0]
	s_nop 0
	v_pk_add_f32 v[28:29], v[28:29], v[32:33] op_sel:[1,0] op_sel_hi:[0,1]
	v_mov_b32_e32 v31, v28
	v_pk_add_f32 v[36:37], v[30:31], v[38:39] neg_lo:[0,1] neg_hi:[0,1]
	v_mov_b32_e32 v27, v32
	v_sub_f32_e32 v29, v30, v36
	v_pk_add_f32 v[26:27], v[26:27], v[36:37] neg_lo:[0,1] neg_hi:[0,1]
	v_sub_f32_e32 v29, v38, v29
	v_add_f32_e32 v26, v26, v29
	v_add_f32_e32 v26, v26, v27
	v_add_f32_e32 v26, v28, v26
	v_cndmask_b32_e32 v26, v236, v26, vcc
	v_cmp_ngt_f32_e32 vcc, -1.0, v23
	s_nop 1
	v_cndmask_b32_e32 v26, v237, v26, vcc
	v_cmp_neq_f32_e32 vcc, -1.0, v23
	s_nop 1
	v_cndmask_b32_e32 v26, v238, v26, vcc
	v_cmp_lt_f32_e64 vcc, |v23|, s58
	s_nop 1
	v_cndmask_b32_e32 v23, v26, v23, vcc
;     __device__ __forceinline__ void operator()(f32x4 (&acc)[2][2][4][2], const Unit& u, int row0t, int wr, int wc, int fr, int fq) const {
;     ...
;                                 for (int e = 0; e < 4; ++e) { const int h = 4 * n + e; const float xx = v[e] + dt_bias[h]; const float sp = xx > 20.f ? xx : log1pf(__expf(xx)); o[e] = -__expf(A_log[h]) * sp; } }
.LBB0_316:
	s_or_b64 exec, exec, s[36:37]
	v_mov_b32_e32 v26, v156
	v_mov_b32_e32 v27, v163
	v_add_f32_e32 v24, v24, v26
	v_cmp_nlt_f32_e32 vcc, s53, v24
	s_and_saveexec_b64 s[36:37], vcc
	s_cbranch_execz .LBB0_318
	v_mul_f32_e32 v24, 0x3fb8aa3b, v24
	v_exp_f32_e32 v24, v24
	s_nop 0
	v_add_f32_e32 v26, 1.0, v24
	v_frexp_mant_f32_e32 v31, v26
	v_cvt_f64_f32_e32 v[28:29], v26
	v_add_f32_e32 v30, -1.0, v26
	v_frexp_exp_i32_f64_e32 v28, v[28:29]
	v_cmp_gt_f32_e32 vcc, s55, v31
	v_sub_f32_e32 v32, v30, v26
	v_sub_f32_e32 v30, v24, v30
	v_subbrev_co_u32_e32 v38, vcc, 0, v28, vcc
	v_add_f32_e32 v32, 1.0, v32
	v_sub_u32_e32 v28, 0, v38
	v_add_f32_e32 v30, v30, v32
	v_ldexp_f32 v26, v26, v28
	v_ldexp_f32 v28, v30, v28
	v_add_f32_e32 v30, -1.0, v26
	v_add_f32_e32 v29, 1.0, v30
	v_sub_f32_e32 v29, v26, v29
	v_add_f32_e32 v31, v28, v29
	v_add_f32_e32 v29, 1.0, v26
	v_add_f32_e32 v32, -1.0, v29
	v_sub_f32_e32 v26, v26, v32
	v_add_f32_e32 v26, v28, v26
	v_add_f32_e32 v39, v29, v26
	v_rcp_f32_e32 v40, v39
	v_sub_f32_e32 v28, v39, v29
	v_add_f32_e32 v29, v30, v31
	v_sub_f32_e32 v26, v26, v28
	v_mul_f32_e32 v42, v29, v40
	v_sub_f32_e32 v28, v29, v30
	v_mul_f32_e32 v30, v39, v42
	v_fma_f32 v32, v42, v39, -v30
	v_fmac_f32_e32 v32, v42, v26
	v_sub_f32_e32 v41, v31, v28
	v_add_f32_e32 v28, v30, v32
	v_sub_f32_e32 v31, v29, v28
	v_pk_add_f32 v[36:37], v[28:29], v[30:31] neg_lo:[0,1] neg_hi:[0,1]
	v_mov_b32_e32 v33, v28
	v_pk_add_f32 v[28:29], v[36:37], v[32:33] neg_lo:[0,1] neg_hi:[0,1]
	v_cmp_neq_f32_e32 vcc, s57, v24
	v_add_f32_e32 v29, v41, v29
	v_add_f32_e32 v28, v28, v29
	v_add_f32_e32 v29, v31, v28
	v_mul_f32_e32 v41, v40, v29
	v_mul_f32_e32 v30, v39, v41
	v_fma_f32 v32, v41, v39, -v30
	v_fmac_f32_e32 v32, v41, v26
	v_sub_f32_e32 v26, v31, v29
	v_add_f32_e32 v26, v28, v26
	v_add_f32_e32 v28, v30, v32
	v_sub_f32_e32 v31, v29, v28
	v_pk_add_f32 v[36:37], v[28:29], v[30:31] neg_lo:[0,1] neg_hi:[0,1]
	v_mov_b32_e32 v33, v28
	v_pk_add_f32 v[28:29], v[36:37], v[32:33] neg_lo:[0,1] neg_hi:[0,1]
	s_nop 0
	v_add_f32_e32 v26, v26, v29
	v_add_f32_e32 v26, v28, v26
	v_add_f32_e32 v29, v42, v41
	v_add_f32_e32 v26, v31, v26
	v_sub_f32_e32 v28, v29, v42
	v_mul_f32_e32 v26, v40, v26
	v_sub_f32_e32 v28, v41, v28
	v_add_f32_e32 v26, v28, v26
	v_add_f32_e32 v30, v29, v26
	v_mul_f32_e32 v32, v30, v30
	v_fmamk_f32 v28, v32, 0x3e9b6dac, v235
	v_fmaak_f32 v227, v32, v28, 0x3f2aaada
	v_cvt_f32_i32_e32 v28, v38
	v_sub_f32_e32 v29, v30, v29
	v_sub_f32_e32 v26, v26, v29
	v_mul_f32_e32 v29, v30, v32
	v_pk_mul_f32 v[32:33], v[28:29], v[226:227]
	v_ldexp_f32 v31, v30, 1
	v_fma_f32 v30, v28, s56, -v32
	v_fmac_f32_e32 v30, 0xb102e308, v28
	v_pk_add_f32 v[28:29], v[32:33], v[30:31]
	v_ldexp_f32 v26, v26, 1
	v_sub_f32_e32 v31, v29, v31
	v_sub_f32_e32 v31, v33, v31
	v_add_f32_e32 v37, v26, v31
	v_mov_b32_e32 v36, v32
	v_pk_add_f32 v[32:33], v[28:29], v[32:33] neg_lo:[0,1] neg_hi:[0,1]
	v_pk_add_f32 v[38:39], v[28:29], v[36:37]
	v_mov_b32_e32 v31, v28
	v_mov_b32_e32 v33, v39
	v_pk_add_f32 v[40:41], v[30:31], v[32:33] neg_lo:[0,1] neg_hi:[0,1]
	v_pk_add_f32 v[30:31], v[30:31], v[32:33]
	v_mov_b32_e32 v36, v37
	v_pk_add_f32 v[32:33], v[30:31], v[28:29] op_sel:[1,0] op_sel_hi:[0,1] neg_lo:[0,1] neg_hi:[0,1]
	v_pk_add_f32 v[42:43], v[38:39], v[32:33] op_sel_hi:[1,0] neg_lo:[0,1] neg_hi:[0,1]
	v_mov_b32_e32 v38, v39
	v_mov_b32_e32 v39, v31
	v_pk_mov_b32 v[32:33], v[28:29], v[32:33] op_sel:[1,0]
	v_mov_b32_e32 v37, v28
	v_pk_add_f32 v[32:33], v[38:39], v[32:33] neg_lo:[0,1] neg_hi:[0,1]
	v_mov_b32_e32 v42, v40
	v_pk_add_f32 v[28:29], v[36:37], v[32:33] neg_lo:[0,1] neg_hi:[0,1]
	v_mov_b32_e32 v41, v31
	v_pk_add_f32 v[32:33], v[42:43], v[28:29]
	s_nop 0
	v_pk_add_f32 v[36:37], v[32:33], v[32:33] op_sel:[0,1] op_sel_hi:[1,0]
	s_nop 0
	v_pk_add_f32 v[30:31], v[30:31], v[36:37] op_sel:[1,0] op_sel_hi:[0,1]
	v_mov_b32_e32 v33, v30
	v_pk_add_f32 v[38:39], v[32:33], v[40:41] neg_lo:[0,1] neg_hi:[0,1]
	v_mov_b32_e32 v29, v36
	v_sub_f32_e32 v26, v32, v38
	v_pk_add_f32 v[28:29], v[28:29], v[38:39] neg_lo:[0,1] neg_hi:[0,1]
	v_sub_f32_e32 v26, v40, v26
	v_add_f32_e32 v26, v28, v26
	v_add_f32_e32 v26, v26, v29
	v_add_f32_e32 v26, v30, v26
	v_cndmask_b32_e32 v26, v236, v26, vcc
	v_cmp_ngt_f32_e32 vcc, -1.0, v24
	s_nop 1
	v_cndmask_b32_e32 v26, v237, v26, vcc
	v_cmp_neq_f32_e32 vcc, -1.0, v24
	s_nop 1
	v_cndmask_b32_e32 v26, v238, v26, vcc
	v_cmp_lt_f32_e64 vcc, |v24|, s58
	s_nop 1
	v_cndmask_b32_e32 v24, v26, v24, vcc
;     __device__ __forceinline__ void operator()(f32x4 (&acc)[2][2][4][2], const Unit& u, int row0t, int wr, int wc, int fr, int fq) const {
;     ...
;                                 for (int e = 0; e < 4; ++e) { const int h = 4 * n + e; const float xx = v[e] + dt_bias[h]; const float sp = xx > 20.f ? xx : log1pf(__expf(xx)); o[e] = -__expf(A_log[h]) * sp; } }
.LBB0_318:
	s_or_b64 exec, exec, s[36:37]
	v_mov_b32_e32 v26, v157
	v_mov_b32_e32 v28, v164
	v_add_f32_e32 v25, v25, v26
	v_cmp_nlt_f32_e32 vcc, s53, v25
	s_and_saveexec_b64 s[36:37], vcc
	s_cbranch_execz .LBB0_320
	v_mul_f32_e32 v25, 0x3fb8aa3b, v25
	v_exp_f32_e32 v25, v25
	s_nop 0
	v_add_f32_e32 v26, 1.0, v25
	v_frexp_mant_f32_e32 v32, v26
	v_cvt_f64_f32_e32 v[30:31], v26
	v_add_f32_e32 v29, -1.0, v26
	v_frexp_exp_i32_f64_e32 v30, v[30:31]
	v_cmp_gt_f32_e32 vcc, s55, v32
	v_sub_f32_e32 v33, v29, v26
	v_sub_f32_e32 v29, v25, v29
	v_subbrev_co_u32_e32 v40, vcc, 0, v30, vcc
	v_add_f32_e32 v33, 1.0, v33
	v_sub_u32_e32 v30, 0, v40
	v_add_f32_e32 v29, v29, v33
	v_ldexp_f32 v26, v26, v30
	v_ldexp_f32 v29, v29, v30
	v_add_f32_e32 v30, -1.0, v26
	v_add_f32_e32 v31, 1.0, v30
	v_sub_f32_e32 v31, v26, v31
	v_add_f32_e32 v32, v29, v31
	v_add_f32_e32 v31, 1.0, v26
	v_add_f32_e32 v33, -1.0, v31
	v_sub_f32_e32 v26, v26, v33
	v_add_f32_e32 v26, v29, v26
	v_add_f32_e32 v29, v31, v26
	v_rcp_f32_e32 v41, v29
	v_sub_f32_e32 v31, v29, v31
	v_sub_f32_e32 v26, v26, v31
	v_add_f32_e32 v31, v30, v32
	v_sub_f32_e32 v30, v31, v30
	v_mul_f32_e32 v43, v31, v41
	v_sub_f32_e32 v42, v32, v30
	v_mul_f32_e32 v32, v29, v43
	v_fma_f32 v36, v43, v29, -v32
	v_fmac_f32_e32 v36, v43, v26
	v_add_f32_e32 v30, v32, v36
	v_sub_f32_e32 v33, v31, v30
	v_pk_add_f32 v[38:39], v[30:31], v[32:33] neg_lo:[0,1] neg_hi:[0,1]
	v_mov_b32_e32 v37, v30
	v_pk_add_f32 v[30:31], v[38:39], v[36:37] neg_lo:[0,1] neg_hi:[0,1]
	v_cmp_neq_f32_e32 vcc, s57, v25
	v_add_f32_e32 v31, v42, v31
	v_add_f32_e32 v30, v30, v31
	v_add_f32_e32 v31, v33, v30
	v_mul_f32_e32 v42, v41, v31
	v_mul_f32_e32 v32, v29, v42
	v_fma_f32 v36, v42, v29, -v32
	v_fmac_f32_e32 v36, v42, v26
	v_sub_f32_e32 v26, v33, v31
	v_add_f32_e32 v26, v30, v26
	v_add_f32_e32 v30, v32, v36
	v_sub_f32_e32 v33, v31, v30
	v_pk_add_f32 v[38:39], v[30:31], v[32:33] neg_lo:[0,1] neg_hi:[0,1]
	v_mov_b32_e32 v37, v30
	v_pk_add_f32 v[30:31], v[38:39], v[36:37] neg_lo:[0,1] neg_hi:[0,1]
	v_add_f32_e32 v29, v43, v42
	v_add_f32_e32 v26, v26, v31
	v_add_f32_e32 v26, v30, v26
	v_add_f32_e32 v26, v33, v26
	v_sub_f32_e32 v30, v29, v43
	v_mul_f32_e32 v26, v41, v26
	v_sub_f32_e32 v30, v42, v30
	v_add_f32_e32 v26, v30, v26
	v_add_f32_e32 v31, v29, v26
	v_mul_f32_e32 v32, v31, v31
	v_fmamk_f32 v30, v32, 0x3e9b6dac, v235
	v_fmaak_f32 v227, v32, v30, 0x3f2aaada
	v_cvt_f32_i32_e32 v30, v40
	v_sub_f32_e32 v29, v31, v29
	v_ldexp_f32 v33, v31, 1
	v_mul_f32_e32 v31, v31, v32
	v_pk_mul_f32 v[36:37], v[30:31], v[226:227]
	v_sub_f32_e32 v26, v26, v29
	v_fma_f32 v32, v30, s56, -v36
	v_fmac_f32_e32 v32, 0xb102e308, v30
	v_pk_add_f32 v[30:31], v[36:37], v[32:33]
	v_ldexp_f32 v26, v26, 1
	v_sub_f32_e32 v29, v31, v33
	v_sub_f32_e32 v29, v37, v29
	v_add_f32_e32 v39, v26, v29
	v_mov_b32_e32 v38, v36
	v_pk_add_f32 v[36:37], v[30:31], v[36:37] neg_lo:[0,1] neg_hi:[0,1]
	v_pk_add_f32 v[40:41], v[30:31], v[38:39]
	v_mov_b32_e32 v33, v30
	v_mov_b32_e32 v37, v41
	v_pk_add_f32 v[42:43], v[32:33], v[36:37] neg_lo:[0,1] neg_hi:[0,1]
	v_pk_add_f32 v[32:33], v[32:33], v[36:37]
	v_mov_b32_e32 v38, v39
	v_pk_add_f32 v[36:37], v[32:33], v[30:31] op_sel:[1,0] op_sel_hi:[0,1] neg_lo:[0,1] neg_hi:[0,1]
	v_pk_add_f32 v[44:45], v[40:41], v[36:37] op_sel_hi:[1,0] neg_lo:[0,1] neg_hi:[0,1]
	v_mov_b32_e32 v40, v41
	v_mov_b32_e32 v41, v33
	v_pk_mov_b32 v[36:37], v[30:31], v[36:37] op_sel:[1,0]
	v_mov_b32_e32 v39, v30
	v_pk_add_f32 v[36:37], v[40:41], v[36:37] neg_lo:[0,1] neg_hi:[0,1]
	v_mov_b32_e32 v44, v42
	v_pk_add_f32 v[30:31], v[38:39], v[36:37] neg_lo:[0,1] neg_hi:[0,1]
	v_mov_b32_e32 v43, v33
	v_pk_add_f32 v[36:37], v[44:45], v[30:31]
	s_nop 0
	v_pk_add_f32 v[38:39], v[36:37], v[36:37] op_sel:[0,1] op_sel_hi:[1,0]
	s_nop 0
	v_pk_add_f32 v[32:33], v[32:33], v[38:39] op_sel:[1,0] op_sel_hi:[0,1]
	v_mov_b32_e32 v37, v32
	v_pk_add_f32 v[40:41], v[36:37], v[42:43] neg_lo:[0,1] neg_hi:[0,1]
	v_mov_b32_e32 v31, v38
	v_sub_f32_e32 v26, v36, v40
	v_pk_add_f32 v[30:31], v[30:31], v[40:41] neg_lo:[0,1] neg_hi:[0,1]
	v_sub_f32_e32 v26, v42, v26
	v_add_f32_e32 v26, v30, v26
	v_add_f32_e32 v26, v26, v31
	v_add_f32_e32 v26, v32, v26
	v_cndmask_b32_e32 v26, v236, v26, vcc
	v_cmp_ngt_f32_e32 vcc, -1.0, v25
	s_nop 1
	v_cndmask_b32_e32 v26, v237, v26, vcc
	v_cmp_neq_f32_e32 vcc, -1.0, v25
	s_nop 1
	v_cndmask_b32_e32 v26, v238, v26, vcc
	v_cmp_lt_f32_e64 vcc, |v25|, s58
	s_nop 1
	v_cndmask_b32_e32 v25, v26, v25, vcc
.LBB0_320:
	s_or_b64 exec, exec, s[36:37]
	v_mul_f32_e32 v22, 0x3fb8aa3b, v22
	v_exp_f32_e32 v22, v22
	s_nop 0
	v_mul_f32_e64 v26, v3, -v22
	v_mul_f32_e32 v3, 0x3fb8aa3b, v27
	v_exp_f32_e32 v3, v3
	s_nop 0
	v_mul_f32_e64 v27, v23, -v3
	v_mul_f32_e32 v3, 0x3fb8aa3b, v28
	v_exp_f32_e32 v3, v3
	s_nop 0
	v_mul_f32_e64 v28, v24, -v3
	v_mov_b32_e32 v3, v165
	v_mul_f32_e32 v3, 0x3fb8aa3b, v3
	v_exp_f32_e32 v3, v3
	s_nop 0
	v_mul_f32_e64 v29, v25, -v3

;     __device__ __forceinline__ void operator()(f32x4 (&acc)[2][2][4][2], const Unit& u, int row0t, int wr, int wc, int fr, int fq) const {
;     ...
;                                 for (int e = 0; e < 4; ++e) { const int h = 4 * n + e; const float xx = v[e] + dt_bias[h]; const float sp = xx > 20.f ? xx : log1pf(__expf(xx)); o[e] = -__expf(A_log[h]) * sp; } }
;                             *(f32x4*)(bg + (size_t)r * 16 + 8 * fq + 4 * n) = o; } }
.LBB0_323:
	s_or_b64 exec, exec, s[24:25]
	s_mov_b64 s[2:3], 0x2400
	v_lshl_add_u64 v[22:23], v[34:35], 0, s[2:3]
	global_store_dwordx4 v[22:23], v[26:29], off offset:16
	s_and_saveexec_b64 s[2:3], s[4:5]
	s_xor_b64 s[24:25], exec, s[2:3]
	s_cbranch_execz .LBB0_333
	v_mov_b32_e32 v3, v150
	v_add_f32_e32 v3, v18, v3
	v_cmp_nlt_f32_e32 vcc, s53, v3
	s_and_saveexec_b64 s[36:37], vcc
	s_cbranch_execz .LBB0_326
	v_mul_f32_e32 v3, 0x3fb8aa3b, v3
	v_exp_f32_e32 v3, v3
	s_nop 0
	v_add_f32_e32 v18, 1.0, v3
	v_frexp_mant_f32_e32 v25, v18
	v_cvt_f64_f32_e32 v[22:23], v18
	v_add_f32_e32 v24, -1.0, v18
	v_frexp_exp_i32_f64_e32 v22, v[22:23]
	v_cmp_gt_f32_e32 vcc, s55, v25
	v_sub_f32_e32 v26, v24, v18
	v_sub_f32_e32 v24, v3, v24
	v_subbrev_co_u32_e32 v30, vcc, 0, v22, vcc
	v_add_f32_e32 v26, 1.0, v26
	v_sub_u32_e32 v22, 0, v30
	v_add_f32_e32 v24, v24, v26
	v_ldexp_f32 v18, v18, v22
	v_ldexp_f32 v22, v24, v22
	v_add_f32_e32 v24, -1.0, v18
	v_add_f32_e32 v23, 1.0, v24
	v_sub_f32_e32 v23, v18, v23
	v_add_f32_e32 v25, v22, v23
	v_add_f32_e32 v23, 1.0, v18
	v_add_f32_e32 v26, -1.0, v23
	v_sub_f32_e32 v18, v18, v26
	v_add_f32_e32 v18, v22, v18
	v_add_f32_e32 v31, v23, v18
	v_rcp_f32_e32 v32, v31
	v_sub_f32_e32 v22, v31, v23
	v_add_f32_e32 v23, v24, v25
	v_sub_f32_e32 v18, v18, v22
	v_mul_f32_e32 v34, v23, v32
	v_sub_f32_e32 v22, v23, v24
	v_mul_f32_e32 v24, v31, v34
	v_fma_f32 v26, v34, v31, -v24
	v_fmac_f32_e32 v26, v34, v18
	v_sub_f32_e32 v33, v25, v22
	v_add_f32_e32 v22, v24, v26
	v_sub_f32_e32 v25, v23, v22
	v_pk_add_f32 v[28:29], v[22:23], v[24:25] neg_lo:[0,1] neg_hi:[0,1]
	v_mov_b32_e32 v27, v22
	v_pk_add_f32 v[22:23], v[28:29], v[26:27] neg_lo:[0,1] neg_hi:[0,1]
	v_cmp_neq_f32_e32 vcc, s57, v3
	v_add_f32_e32 v23, v33, v23
	v_add_f32_e32 v22, v22, v23
	v_add_f32_e32 v23, v25, v22
	v_mul_f32_e32 v33, v32, v23
	v_mul_f32_e32 v24, v31, v33
	v_fma_f32 v26, v33, v31, -v24
	v_fmac_f32_e32 v26, v33, v18
	v_sub_f32_e32 v18, v25, v23
	v_add_f32_e32 v18, v22, v18
	v_add_f32_e32 v22, v24, v26
	v_sub_f32_e32 v25, v23, v22
	v_pk_add_f32 v[28:29], v[22:23], v[24:25] neg_lo:[0,1] neg_hi:[0,1]
	v_mov_b32_e32 v27, v22
	v_pk_add_f32 v[22:23], v[28:29], v[26:27] neg_lo:[0,1] neg_hi:[0,1]
	s_nop 0
	v_add_f32_e32 v18, v18, v23
	v_add_f32_e32 v18, v22, v18
	v_add_f32_e32 v23, v34, v33
	v_add_f32_e32 v18, v25, v18
	v_sub_f32_e32 v22, v23, v34
	v_mul_f32_e32 v18, v32, v18
	v_sub_f32_e32 v22, v33, v22
	v_add_f32_e32 v18, v22, v18
	v_add_f32_e32 v24, v23, v18
	v_mul_f32_e32 v26, v24, v24
	v_fmamk_f32 v22, v26, 0x3e9b6dac, v235
	v_fmaak_f32 v227, v26, v22, 0x3f2aaada
	v_cvt_f32_i32_e32 v22, v30
	v_sub_f32_e32 v23, v24, v23
	v_sub_f32_e32 v18, v18, v23
	v_mul_f32_e32 v23, v24, v26
	v_pk_mul_f32 v[26:27], v[22:23], v[226:227]
	v_ldexp_f32 v25, v24, 1
	v_fma_f32 v24, v22, s56, -v26
	v_fmac_f32_e32 v24, 0xb102e308, v22
	v_pk_add_f32 v[22:23], v[26:27], v[24:25]
	v_ldexp_f32 v18, v18, 1
	v_sub_f32_e32 v25, v23, v25
	v_sub_f32_e32 v25, v27, v25
	v_add_f32_e32 v29, v18, v25
	v_mov_b32_e32 v28, v26
	v_pk_add_f32 v[26:27], v[22:23], v[26:27] neg_lo:[0,1] neg_hi:[0,1]
	v_pk_add_f32 v[30:31], v[22:23], v[28:29]
	v_mov_b32_e32 v25, v22
	v_mov_b32_e32 v27, v31
	v_pk_add_f32 v[32:33], v[24:25], v[26:27] neg_lo:[0,1] neg_hi:[0,1]
	v_pk_add_f32 v[24:25], v[24:25], v[26:27]
	v_mov_b32_e32 v28, v29
	v_pk_add_f32 v[26:27], v[24:25], v[22:23] op_sel:[1,0] op_sel_hi:[0,1] neg_lo:[0,1] neg_hi:[0,1]
	v_pk_add_f32 v[34:35], v[30:31], v[26:27] op_sel_hi:[1,0] neg_lo:[0,1] neg_hi:[0,1]
	v_mov_b32_e32 v30, v31
	v_mov_b32_e32 v31, v25
	v_pk_mov_b32 v[26:27], v[22:23], v[26:27] op_sel:[1,0]
	v_mov_b32_e32 v29, v22
	v_pk_add_f32 v[26:27], v[30:31], v[26:27] neg_lo:[0,1] neg_hi:[0,1]
	v_mov_b32_e32 v34, v32
	v_pk_add_f32 v[22:23], v[28:29], v[26:27] neg_lo:[0,1] neg_hi:[0,1]
	v_mov_b32_e32 v33, v25
	v_pk_add_f32 v[26:27], v[34:35], v[22:23]
	s_nop 0
	v_pk_add_f32 v[28:29], v[26:27], v[26:27] op_sel:[0,1] op_sel_hi:[1,0]
	s_nop 0
	v_pk_add_f32 v[24:25], v[24:25], v[28:29] op_sel:[1,0] op_sel_hi:[0,1]
	v_mov_b32_e32 v27, v24
	v_pk_add_f32 v[30:31], v[26:27], v[32:33] neg_lo:[0,1] neg_hi:[0,1]
	v_mov_b32_e32 v23, v28
	v_sub_f32_e32 v18, v26, v30
	v_pk_add_f32 v[22:23], v[22:23], v[30:31] neg_lo:[0,1] neg_hi:[0,1]
	v_sub_f32_e32 v18, v32, v18
	v_add_f32_e32 v18, v22, v18
	v_add_f32_e32 v18, v18, v23
	v_add_f32_e32 v18, v24, v18
	v_cndmask_b32_e32 v18, v236, v18, vcc
	v_cmp_ngt_f32_e32 vcc, -1.0, v3
	s_nop 1
	v_cndmask_b32_e32 v18, v237, v18, vcc
	v_cmp_neq_f32_e32 vcc, -1.0, v3
	s_nop 1
	v_cndmask_b32_e32 v18, v238, v18, vcc
	v_cmp_lt_f32_e64 vcc, |v3|, s58
	s_nop 1
	v_cndmask_b32_e32 v3, v18, v3, vcc
;     __device__ __forceinline__ void operator()(f32x4 (&acc)[2][2][4][2], const Unit& u, int row0t, int wr, int wc, int fr, int fq) const {
;     ...
;                                 for (int e = 0; e < 4; ++e) { const int h = 4 * n + e; const float xx = v[e] + dt_bias[h]; const float sp = xx > 20.f ? xx : log1pf(__expf(xx)); o[e] = -__expf(A_log[h]) * sp; } }
.LBB0_326:
	s_or_b64 exec, exec, s[36:37]
	v_mov_b32_e32 v22, v151
	v_mov_b32_e32 v18, v158
	v_add_f32_e32 v19, v19, v22
	v_cmp_nlt_f32_e32 vcc, s53, v19
	s_and_saveexec_b64 s[36:37], vcc
	s_cbranch_execz .LBB0_328
	v_mul_f32_e32 v19, 0x3fb8aa3b, v19
	v_exp_f32_e32 v19, v19
	s_nop 0
	v_add_f32_e32 v24, 1.0, v19
	v_frexp_mant_f32_e32 v26, v24
	v_cvt_f64_f32_e32 v[22:23], v24
	v_frexp_exp_i32_f64_e32 v22, v[22:23]
	v_cmp_gt_f32_e32 vcc, s55, v26
	v_add_f32_e32 v25, -1.0, v24
	v_sub_f32_e32 v27, v25, v24
	v_subbrev_co_u32_e32 v30, vcc, 0, v22, vcc
	v_sub_u32_e32 v22, 0, v30
	v_sub_f32_e32 v25, v19, v25
	v_add_f32_e32 v27, 1.0, v27
	v_ldexp_f32 v23, v24, v22
	v_add_f32_e32 v25, v25, v27
	v_add_f32_e32 v24, -1.0, v23
	v_add_f32_e32 v26, 1.0, v23
	v_ldexp_f32 v22, v25, v22
	v_add_f32_e32 v25, 1.0, v24
	v_add_f32_e32 v27, -1.0, v26
	v_sub_f32_e32 v25, v23, v25
	v_sub_f32_e32 v23, v23, v27
	v_add_f32_e32 v25, v22, v25
	v_add_f32_e32 v22, v22, v23
	v_add_f32_e32 v31, v26, v22
	v_rcp_f32_e32 v33, v31
	v_sub_f32_e32 v23, v31, v26
	v_sub_f32_e32 v32, v22, v23
	v_add_f32_e32 v23, v24, v25
	v_mul_f32_e32 v35, v23, v33
	v_sub_f32_e32 v22, v23, v24
	v_mul_f32_e32 v24, v31, v35
	v_fma_f32 v26, v35, v31, -v24
	v_fmac_f32_e32 v26, v35, v32
	v_sub_f32_e32 v34, v25, v22
	v_add_f32_e32 v22, v24, v26
	v_sub_f32_e32 v25, v23, v22
	v_pk_add_f32 v[28:29], v[22:23], v[24:25] neg_lo:[0,1] neg_hi:[0,1]
	v_mov_b32_e32 v27, v22
	v_pk_add_f32 v[22:23], v[28:29], v[26:27] neg_lo:[0,1] neg_hi:[0,1]
	v_cmp_neq_f32_e32 vcc, s57, v19
	v_add_f32_e32 v23, v34, v23
	v_add_f32_e32 v22, v22, v23
	v_add_f32_e32 v23, v25, v22
	v_mul_f32_e32 v34, v33, v23
	v_mul_f32_e32 v24, v31, v34
	v_fma_f32 v26, v34, v31, -v24
	v_fmac_f32_e32 v26, v34, v32
	v_sub_f32_e32 v25, v25, v23
	v_add_f32_e32 v31, v22, v25
	v_add_f32_e32 v22, v24, v26
	v_sub_f32_e32 v25, v23, v22
	v_pk_add_f32 v[28:29], v[22:23], v[24:25] neg_lo:[0,1] neg_hi:[0,1]
	v_mov_b32_e32 v27, v22
	v_pk_add_f32 v[22:23], v[28:29], v[26:27] neg_lo:[0,1] neg_hi:[0,1]
	s_nop 0
	v_add_f32_e32 v23, v31, v23
	v_add_f32_e32 v22, v22, v23
	v_add_f32_e32 v23, v35, v34
	v_add_f32_e32 v22, v25, v22
	v_sub_f32_e32 v24, v23, v35
	v_mul_f32_e32 v22, v33, v22
	v_sub_f32_e32 v24, v34, v24
	v_add_f32_e32 v24, v24, v22
	v_add_f32_e32 v26, v23, v24
	v_mul_f32_e32 v27, v26, v26
	v_fmamk_f32 v22, v27, 0x3e9b6dac, v235
	v_fmaak_f32 v227, v27, v22, 0x3f2aaada
	v_cvt_f32_i32_e32 v22, v30
	v_sub_f32_e32 v23, v26, v23
	v_sub_f32_e32 v23, v24, v23
	v_ldexp_f32 v28, v23, 1
	v_mul_f32_e32 v23, v26, v27
	v_ldexp_f32 v25, v26, 1
	v_pk_mul_f32 v[26:27], v[22:23], v[226:227]
	s_nop 0
	v_fma_f32 v24, v22, s56, -v26
	v_fmac_f32_e32 v24, 0xb102e308, v22
	v_pk_add_f32 v[22:23], v[26:27], v[24:25]
	s_nop 0
	v_sub_f32_e32 v25, v23, v25
	v_sub_f32_e32 v25, v27, v25
	v_add_f32_e32 v29, v28, v25
	v_mov_b32_e32 v28, v26
	v_pk_add_f32 v[26:27], v[22:23], v[26:27] neg_lo:[0,1] neg_hi:[0,1]
	v_pk_add_f32 v[30:31], v[22:23], v[28:29]
	v_mov_b32_e32 v25, v22
	v_mov_b32_e32 v27, v31
	v_pk_add_f32 v[32:33], v[24:25], v[26:27] neg_lo:[0,1] neg_hi:[0,1]
	v_pk_add_f32 v[24:25], v[24:25], v[26:27]
	v_mov_b32_e32 v28, v29
	v_pk_add_f32 v[26:27], v[24:25], v[22:23] op_sel:[1,0] op_sel_hi:[0,1] neg_lo:[0,1] neg_hi:[0,1]
	v_pk_add_f32 v[34:35], v[30:31], v[26:27] op_sel_hi:[1,0] neg_lo:[0,1] neg_hi:[0,1]
	v_mov_b32_e32 v30, v31
	v_mov_b32_e32 v31, v25
	v_pk_mov_b32 v[26:27], v[22:23], v[26:27] op_sel:[1,0]
	v_mov_b32_e32 v29, v22
	v_pk_add_f32 v[26:27], v[30:31], v[26:27] neg_lo:[0,1] neg_hi:[0,1]
	v_mov_b32_e32 v34, v32
	v_pk_add_f32 v[22:23], v[28:29], v[26:27] neg_lo:[0,1] neg_hi:[0,1]
	v_mov_b32_e32 v33, v25
	v_pk_add_f32 v[26:27], v[34:35], v[22:23]
	s_nop 0
	v_pk_add_f32 v[28:29], v[26:27], v[26:27] op_sel:[0,1] op_sel_hi:[1,0]
	s_nop 0
	v_pk_add_f32 v[24:25], v[24:25], v[28:29] op_sel:[1,0] op_sel_hi:[0,1]
	v_mov_b32_e32 v27, v24
	v_pk_add_f32 v[30:31], v[26:27], v[32:33] neg_lo:[0,1] neg_hi:[0,1]
	v_mov_b32_e32 v23, v28
	v_sub_f32_e32 v25, v26, v30
	v_pk_add_f32 v[22:23], v[22:23], v[30:31] neg_lo:[0,1] neg_hi:[0,1]
	v_sub_f32_e32 v25, v32, v25
	v_add_f32_e32 v22, v22, v25
	v_add_f32_e32 v22, v22, v23
	v_add_f32_e32 v22, v24, v22
	v_cndmask_b32_e32 v22, v236, v22, vcc
	v_cmp_ngt_f32_e32 vcc, -1.0, v19
	s_nop 1
	v_cndmask_b32_e32 v22, v237, v22, vcc
	v_cmp_neq_f32_e32 vcc, -1.0, v19
	s_nop 1
	v_cndmask_b32_e32 v22, v238, v22, vcc
	v_cmp_lt_f32_e64 vcc, |v19|, s58
	s_nop 1
	v_cndmask_b32_e32 v19, v22, v19, vcc
;     __device__ __forceinline__ void operator()(f32x4 (&acc)[2][2][4][2], const Unit& u, int row0t, int wr, int wc, int fr, int fq) const {
;     ...
;                         for (int n = 0; n < 2; ++n) { const f32x4 v = acc[ai][0][m][n]; f32x4 o;
;                             if (fq == 0) {
; #pragma unroll
;                                 for (int e = 0; e < 4; ++e) o[e] = 1.0f / (1.0f + __expf(-v[e])); }
;                             else {
; #pragma unroll
;                                 for (int e = 0; e < 4; ++e) { const int h = 4 * n + e; const float xx = v[e] + dt_bias[h]; const float sp = xx > 20.f ? xx : log1pf(__expf(xx)); o[e] = -__expf(A_log[h]) * sp; } }
;                             *(f32x4*)(bg + (size_t)r * 16 + 8 * fq + 4 * n) = o; } }
.LBB0_328:
	s_or_b64 exec, exec, s[36:37]
	v_mov_b32_e32 v22, v152
	v_mov_b32_e32 v23, v159
	v_add_f32_e32 v20, v20, v22
	v_cmp_nlt_f32_e32 vcc, s53, v20
	s_and_saveexec_b64 s[36:37], vcc
	s_cbranch_execz .LBB0_330
	v_mul_f32_e32 v20, 0x3fb8aa3b, v20
	v_exp_f32_e32 v20, v20
	s_nop 0
	v_add_f32_e32 v22, 1.0, v20
	v_frexp_mant_f32_e32 v27, v22
	v_cvt_f64_f32_e32 v[24:25], v22
	v_add_f32_e32 v26, -1.0, v22
	v_frexp_exp_i32_f64_e32 v24, v[24:25]
	v_cmp_gt_f32_e32 vcc, s55, v27
	v_sub_f32_e32 v28, v26, v22
	v_sub_f32_e32 v26, v20, v26
	v_subbrev_co_u32_e32 v32, vcc, 0, v24, vcc
	v_add_f32_e32 v28, 1.0, v28
	v_sub_u32_e32 v24, 0, v32
	v_add_f32_e32 v26, v26, v28
	v_ldexp_f32 v22, v22, v24
	v_ldexp_f32 v24, v26, v24
	v_add_f32_e32 v26, -1.0, v22
	v_add_f32_e32 v25, 1.0, v26
	v_sub_f32_e32 v25, v22, v25
	v_add_f32_e32 v27, v24, v25
	v_add_f32_e32 v25, 1.0, v22
	v_add_f32_e32 v28, -1.0, v25
	v_sub_f32_e32 v22, v22, v28
	v_add_f32_e32 v22, v24, v22
	v_add_f32_e32 v33, v25, v22
	v_rcp_f32_e32 v34, v33
	v_sub_f32_e32 v24, v33, v25
	v_add_f32_e32 v25, v26, v27
	v_sub_f32_e32 v22, v22, v24
	v_mul_f32_e32 v36, v25, v34
	v_sub_f32_e32 v24, v25, v26
	v_mul_f32_e32 v26, v33, v36
	v_fma_f32 v28, v36, v33, -v26
	v_fmac_f32_e32 v28, v36, v22
	v_sub_f32_e32 v35, v27, v24
	v_add_f32_e32 v24, v26, v28
	v_sub_f32_e32 v27, v25, v24
	v_pk_add_f32 v[30:31], v[24:25], v[26:27] neg_lo:[0,1] neg_hi:[0,1]
	v_mov_b32_e32 v29, v24
	v_pk_add_f32 v[24:25], v[30:31], v[28:29] neg_lo:[0,1] neg_hi:[0,1]
	v_cmp_neq_f32_e32 vcc, s57, v20
	v_add_f32_e32 v25, v35, v25
	v_add_f32_e32 v24, v24, v25
	v_add_f32_e32 v25, v27, v24
	v_mul_f32_e32 v35, v34, v25
	v_mul_f32_e32 v26, v33, v35
	v_fma_f32 v28, v35, v33, -v26
	v_fmac_f32_e32 v28, v35, v22
	v_sub_f32_e32 v22, v27, v25
	v_add_f32_e32 v22, v24, v22
	v_add_f32_e32 v24, v26, v28
	v_sub_f32_e32 v27, v25, v24
	v_pk_add_f32 v[30:31], v[24:25], v[26:27] neg_lo:[0,1] neg_hi:[0,1]
	v_mov_b32_e32 v29, v24
	v_pk_add_f32 v[24:25], v[30:31], v[28:29] neg_lo:[0,1] neg_hi:[0,1]
	s_nop 0
	v_add_f32_e32 v22, v22, v25
	v_add_f32_e32 v22, v24, v22
	v_add_f32_e32 v25, v36, v35
	v_add_f32_e32 v22, v27, v22
	v_sub_f32_e32 v24, v25, v36
	v_mul_f32_e32 v22, v34, v22
	v_sub_f32_e32 v24, v35, v24
	v_add_f32_e32 v22, v24, v22
	v_add_f32_e32 v26, v25, v22
	v_mul_f32_e32 v28, v26, v26
	v_fmamk_f32 v24, v28, 0x3e9b6dac, v235
	v_fmaak_f32 v227, v28, v24, 0x3f2aaada
	v_cvt_f32_i32_e32 v24, v32
	v_sub_f32_e32 v25, v26, v25
	v_sub_f32_e32 v22, v22, v25
	v_mul_f32_e32 v25, v26, v28
	v_pk_mul_f32 v[28:29], v[24:25], v[226:227]
	v_ldexp_f32 v27, v26, 1
	v_fma_f32 v26, v24, s56, -v28
	v_fmac_f32_e32 v26, 0xb102e308, v24
	v_pk_add_f32 v[24:25], v[28:29], v[26:27]
	v_ldexp_f32 v22, v22, 1
	v_sub_f32_e32 v27, v25, v27
	v_sub_f32_e32 v27, v29, v27
	v_add_f32_e32 v31, v22, v27
	v_mov_b32_e32 v30, v28
	v_pk_add_f32 v[28:29], v[24:25], v[28:29] neg_lo:[0,1] neg_hi:[0,1]
	v_pk_add_f32 v[32:33], v[24:25], v[30:31]
	v_mov_b32_e32 v27, v24
	v_mov_b32_e32 v29, v33
	v_pk_add_f32 v[34:35], v[26:27], v[28:29] neg_lo:[0,1] neg_hi:[0,1]
	v_pk_add_f32 v[26:27], v[26:27], v[28:29]
	v_mov_b32_e32 v30, v31
	v_pk_add_f32 v[28:29], v[26:27], v[24:25] op_sel:[1,0] op_sel_hi:[0,1] neg_lo:[0,1] neg_hi:[0,1]
	v_pk_add_f32 v[36:37], v[32:33], v[28:29] op_sel_hi:[1,0] neg_lo:[0,1] neg_hi:[0,1]
	v_mov_b32_e32 v32, v33
	v_mov_b32_e32 v33, v27
	v_pk_mov_b32 v[28:29], v[24:25], v[28:29] op_sel:[1,0]
	v_mov_b32_e32 v31, v24
	v_pk_add_f32 v[28:29], v[32:33], v[28:29] neg_lo:[0,1] neg_hi:[0,1]
	v_mov_b32_e32 v36, v34
	v_pk_add_f32 v[24:25], v[30:31], v[28:29] neg_lo:[0,1] neg_hi:[0,1]
	v_mov_b32_e32 v35, v27
	v_pk_add_f32 v[28:29], v[36:37], v[24:25]
	s_nop 0
	v_pk_add_f32 v[30:31], v[28:29], v[28:29] op_sel:[0,1] op_sel_hi:[1,0]
	s_nop 0
	v_pk_add_f32 v[26:27], v[26:27], v[30:31] op_sel:[1,0] op_sel_hi:[0,1]
	v_mov_b32_e32 v29, v26
	v_pk_add_f32 v[32:33], v[28:29], v[34:35] neg_lo:[0,1] neg_hi:[0,1]
	v_mov_b32_e32 v25, v30
	v_sub_f32_e32 v22, v28, v32
	v_pk_add_f32 v[24:25], v[24:25], v[32:33] neg_lo:[0,1] neg_hi:[0,1]
	v_sub_f32_e32 v22, v34, v22
	v_add_f32_e32 v22, v24, v22
	v_add_f32_e32 v22, v22, v25
	v_add_f32_e32 v22, v26, v22
	v_cndmask_b32_e32 v22, v236, v22, vcc
	v_cmp_ngt_f32_e32 vcc, -1.0, v20
	s_nop 1
	v_cndmask_b32_e32 v22, v237, v22, vcc
	v_cmp_neq_f32_e32 vcc, -1.0, v20
	s_nop 1
	v_cndmask_b32_e32 v22, v238, v22, vcc
	v_cmp_lt_f32_e64 vcc, |v20|, s58
	s_nop 1
	v_cndmask_b32_e32 v20, v22, v20, vcc
;     __device__ __forceinline__ void operator()(f32x4 (&acc)[2][2][4][2], const Unit& u, int row0t, int wr, int wc, int fr, int fq) const {
;     ...
;                         for (int n = 0; n < 2; ++n) { const f32x4 v = acc[ai][0][m][n]; f32x4 o;
;                             if (fq == 0) {
; #pragma unroll
;                                 for (int e = 0; e < 4; ++e) o[e] = 1.0f / (1.0f + __expf(-v[e])); }
;                             else {
; #pragma unroll
;                                 for (int e = 0; e < 4; ++e) { const int h = 4 * n + e; const float xx = v[e] + dt_bias[h]; const float sp = xx > 20.f ? xx : log1pf(__expf(xx)); o[e] = -__expf(A_log[h]) * sp; } }
;                             *(f32x4*)(bg + (size_t)r * 16 + 8 * fq + 4 * n) = o; } }
.LBB0_330:
	s_or_b64 exec, exec, s[36:37]
	v_mov_b32_e32 v22, v153
	v_mov_b32_e32 v24, v160
	v_add_f32_e32 v21, v21, v22
	v_cmp_nlt_f32_e32 vcc, s53, v21
	s_and_saveexec_b64 s[36:37], vcc
	s_cbranch_execz .LBB0_332
	v_mul_f32_e32 v21, 0x3fb8aa3b, v21
	v_exp_f32_e32 v21, v21
	s_nop 0
	v_add_f32_e32 v22, 1.0, v21
	v_frexp_mant_f32_e32 v28, v22
	v_cvt_f64_f32_e32 v[26:27], v22
	v_add_f32_e32 v25, -1.0, v22
	v_frexp_exp_i32_f64_e32 v26, v[26:27]
	v_cmp_gt_f32_e32 vcc, s55, v28
	v_sub_f32_e32 v29, v25, v22
	v_sub_f32_e32 v25, v21, v25
	v_subbrev_co_u32_e32 v34, vcc, 0, v26, vcc
	v_add_f32_e32 v29, 1.0, v29
	v_sub_u32_e32 v26, 0, v34
	v_add_f32_e32 v25, v25, v29
	v_ldexp_f32 v22, v22, v26
	v_ldexp_f32 v25, v25, v26
	v_add_f32_e32 v26, -1.0, v22
	v_add_f32_e32 v27, 1.0, v26
	v_sub_f32_e32 v27, v22, v27
	v_add_f32_e32 v28, v25, v27
	v_add_f32_e32 v27, 1.0, v22
	v_add_f32_e32 v29, -1.0, v27
	v_sub_f32_e32 v22, v22, v29
	v_add_f32_e32 v22, v25, v22
	v_add_f32_e32 v25, v27, v22
	v_rcp_f32_e32 v35, v25
	v_sub_f32_e32 v27, v25, v27
	v_sub_f32_e32 v22, v22, v27
	v_add_f32_e32 v27, v26, v28
	v_sub_f32_e32 v26, v27, v26
	v_mul_f32_e32 v37, v27, v35
	v_sub_f32_e32 v36, v28, v26
	v_mul_f32_e32 v28, v25, v37
	v_fma_f32 v30, v37, v25, -v28
	v_fmac_f32_e32 v30, v37, v22
	v_add_f32_e32 v26, v28, v30
	v_sub_f32_e32 v29, v27, v26
	v_pk_add_f32 v[32:33], v[26:27], v[28:29] neg_lo:[0,1] neg_hi:[0,1]
	v_mov_b32_e32 v31, v26
	v_pk_add_f32 v[26:27], v[32:33], v[30:31] neg_lo:[0,1] neg_hi:[0,1]
	v_cmp_neq_f32_e32 vcc, s57, v21
	v_add_f32_e32 v27, v36, v27
	v_add_f32_e32 v26, v26, v27
	v_add_f32_e32 v27, v29, v26
	v_mul_f32_e32 v36, v35, v27
	v_mul_f32_e32 v28, v25, v36
	v_fma_f32 v30, v36, v25, -v28
	v_fmac_f32_e32 v30, v36, v22
	v_sub_f32_e32 v22, v29, v27
	v_add_f32_e32 v22, v26, v22
	v_add_f32_e32 v26, v28, v30
	v_sub_f32_e32 v29, v27, v26
	v_pk_add_f32 v[32:33], v[26:27], v[28:29] neg_lo:[0,1] neg_hi:[0,1]
	v_mov_b32_e32 v31, v26
	v_pk_add_f32 v[26:27], v[32:33], v[30:31] neg_lo:[0,1] neg_hi:[0,1]
	v_add_f32_e32 v25, v37, v36
	v_add_f32_e32 v22, v22, v27
	v_add_f32_e32 v22, v26, v22
	v_add_f32_e32 v22, v29, v22
	v_sub_f32_e32 v26, v25, v37
	v_mul_f32_e32 v22, v35, v22
	v_sub_f32_e32 v26, v36, v26
	v_add_f32_e32 v22, v26, v22
	v_add_f32_e32 v27, v25, v22
	v_mul_f32_e32 v28, v27, v27
	v_fmamk_f32 v26, v28, 0x3e9b6dac, v235
	v_fmaak_f32 v227, v28, v26, 0x3f2aaada
	v_cvt_f32_i32_e32 v26, v34
	v_sub_f32_e32 v25, v27, v25
	v_ldexp_f32 v29, v27, 1
	v_mul_f32_e32 v27, v27, v28
	v_pk_mul_f32 v[30:31], v[26:27], v[226:227]
	v_sub_f32_e32 v22, v22, v25
	v_fma_f32 v28, v26, s56, -v30
	v_fmac_f32_e32 v28, 0xb102e308, v26
	v_pk_add_f32 v[26:27], v[30:31], v[28:29]
	v_ldexp_f32 v22, v22, 1
	v_sub_f32_e32 v25, v27, v29
	v_sub_f32_e32 v25, v31, v25
	v_add_f32_e32 v33, v22, v25
	v_mov_b32_e32 v32, v30
	v_pk_add_f32 v[30:31], v[26:27], v[30:31] neg_lo:[0,1] neg_hi:[0,1]
	v_pk_add_f32 v[34:35], v[26:27], v[32:33]
	v_mov_b32_e32 v29, v26
	v_mov_b32_e32 v31, v35
	v_pk_add_f32 v[36:37], v[28:29], v[30:31] neg_lo:[0,1] neg_hi:[0,1]
	v_pk_add_f32 v[28:29], v[28:29], v[30:31]
	v_mov_b32_e32 v32, v33
	v_pk_add_f32 v[30:31], v[28:29], v[26:27] op_sel:[1,0] op_sel_hi:[0,1] neg_lo:[0,1] neg_hi:[0,1]
	v_pk_add_f32 v[38:39], v[34:35], v[30:31] op_sel_hi:[1,0] neg_lo:[0,1] neg_hi:[0,1]
	v_mov_b32_e32 v34, v35
	v_mov_b32_e32 v35, v29
	v_pk_mov_b32 v[30:31], v[26:27], v[30:31] op_sel:[1,0]
	v_mov_b32_e32 v33, v26
	v_pk_add_f32 v[30:31], v[34:35], v[30:31] neg_lo:[0,1] neg_hi:[0,1]
	v_mov_b32_e32 v38, v36
	v_pk_add_f32 v[26:27], v[32:33], v[30:31] neg_lo:[0,1] neg_hi:[0,1]
	v_mov_b32_e32 v37, v29
	v_pk_add_f32 v[30:31], v[38:39], v[26:27]
	s_nop 0
	v_pk_add_f32 v[32:33], v[30:31], v[30:31] op_sel:[0,1] op_sel_hi:[1,0]
	s_nop 0
	v_pk_add_f32 v[28:29], v[28:29], v[32:33] op_sel:[1,0] op_sel_hi:[0,1]
	v_mov_b32_e32 v31, v28
	v_pk_add_f32 v[34:35], v[30:31], v[36:37] neg_lo:[0,1] neg_hi:[0,1]
	v_mov_b32_e32 v27, v32
	v_sub_f32_e32 v22, v30, v34
	v_pk_add_f32 v[26:27], v[26:27], v[34:35] neg_lo:[0,1] neg_hi:[0,1]
	v_sub_f32_e32 v22, v36, v22
	v_add_f32_e32 v22, v26, v22
	v_add_f32_e32 v22, v22, v27
	v_add_f32_e32 v22, v28, v22
	v_cndmask_b32_e32 v22, v236, v22, vcc
	v_cmp_ngt_f32_e32 vcc, -1.0, v21
	s_nop 1
	v_cndmask_b32_e32 v22, v237, v22, vcc
	v_cmp_neq_f32_e32 vcc, -1.0, v21
	s_nop 1
	v_cndmask_b32_e32 v22, v238, v22, vcc
	v_cmp_lt_f32_e64 vcc, |v21|, s58
	s_nop 1
	v_cndmask_b32_e32 v21, v22, v21, vcc
.LBB0_332:
	s_or_b64 exec, exec, s[36:37]
	v_mul_f32_e32 v18, 0x3fb8aa3b, v18
	v_exp_f32_e32 v18, v18
	s_nop 0
	v_mul_f32_e64 v22, v3, -v18
	v_mul_f32_e32 v3, 0x3fb8aa3b, v23
	v_exp_f32_e32 v3, v3
	s_nop 0
	v_mul_f32_e64 v23, v19, -v3
	v_mul_f32_e32 v3, 0x3fb8aa3b, v24
	v_exp_f32_e32 v3, v3
	s_nop 0
	v_mul_f32_e64 v24, v20, -v3
	v_mov_b32_e32 v3, v161
	v_mul_f32_e32 v3, 0x3fb8aa3b, v3
	v_exp_f32_e32 v3, v3
	s_nop 0
	v_mul_f32_e64 v25, v21, -v3

;     __device__ __forceinline__ void operator()(f32x4 (&acc)[2][2][4][2], const Unit& u, int row0t, int wr, int wc, int fr, int fq) const {
;     ...
;                         for (int n = 0; n < 2; ++n) { const f32x4 v = acc[ai][0][m][n]; f32x4 o;
;                             if (fq == 0) {
; #pragma unroll
;                                 for (int e = 0; e < 4; ++e) o[e] = 1.0f / (1.0f + __expf(-v[e])); }
;                             else {
; #pragma unroll
;                                 for (int e = 0; e < 4; ++e) { const int h = 4 * n + e; const float xx = v[e] + dt_bias[h]; const float sp = xx > 20.f ? xx : log1pf(__expf(xx)); o[e] = -__expf(A_log[h]) * sp; } }
;                             *(f32x4*)(bg + (size_t)r * 16 + 8 * fq + 4 * n) = o; } }
.LBB0_335:
	s_or_b64 exec, exec, s[24:25]
	v_lshlrev_b64 v[18:19], 6, v[4:5]
	v_lshl_add_u64 v[26:27], v[214:215], 0, v[18:19]
	v_add_co_u32_e32 v18, vcc, 0x2000, v26
	s_nop 1
	v_addc_co_u32_e32 v19, vcc, 0, v27, vcc
	global_store_dwordx4 v[18:19], v[22:25], off offset:2048
	s_and_saveexec_b64 s[2:3], s[4:5]
	s_xor_b64 s[24:25], exec, s[2:3]
	s_cbranch_execz .LBB0_345
	v_mov_b32_e32 v3, v154
	v_add_f32_e32 v3, v14, v3
	v_cmp_nlt_f32_e32 vcc, s53, v3
	s_and_saveexec_b64 s[36:37], vcc
	s_cbranch_execz .LBB0_338
	v_mul_f32_e32 v3, 0x3fb8aa3b, v3
	v_exp_f32_e32 v3, v3
	s_nop 0
	v_add_f32_e32 v14, 1.0, v3
	v_frexp_mant_f32_e32 v21, v14
	v_cvt_f64_f32_e32 v[18:19], v14
	v_add_f32_e32 v20, -1.0, v14
	v_frexp_exp_i32_f64_e32 v18, v[18:19]
	v_cmp_gt_f32_e32 vcc, s55, v21
	v_sub_f32_e32 v22, v20, v14
	v_sub_f32_e32 v20, v3, v20
	v_subbrev_co_u32_e32 v28, vcc, 0, v18, vcc
	v_add_f32_e32 v22, 1.0, v22
	v_sub_u32_e32 v18, 0, v28
	v_add_f32_e32 v20, v20, v22
	v_ldexp_f32 v14, v14, v18
	v_ldexp_f32 v18, v20, v18
	v_add_f32_e32 v20, -1.0, v14
	v_add_f32_e32 v19, 1.0, v20
	v_sub_f32_e32 v19, v14, v19
	v_add_f32_e32 v21, v18, v19
	v_add_f32_e32 v19, 1.0, v14
	v_add_f32_e32 v22, -1.0, v19
	v_sub_f32_e32 v14, v14, v22
	v_add_f32_e32 v14, v18, v14
	v_add_f32_e32 v29, v19, v14
	v_rcp_f32_e32 v30, v29
	v_sub_f32_e32 v18, v29, v19
	v_add_f32_e32 v19, v20, v21
	v_sub_f32_e32 v14, v14, v18
	v_mul_f32_e32 v32, v19, v30
	v_sub_f32_e32 v18, v19, v20
	v_mul_f32_e32 v20, v29, v32
	v_fma_f32 v22, v32, v29, -v20
	v_fmac_f32_e32 v22, v32, v14
	v_sub_f32_e32 v31, v21, v18
	v_add_f32_e32 v18, v20, v22
	v_sub_f32_e32 v21, v19, v18
	v_pk_add_f32 v[24:25], v[18:19], v[20:21] neg_lo:[0,1] neg_hi:[0,1]
	v_mov_b32_e32 v23, v18
	v_pk_add_f32 v[18:19], v[24:25], v[22:23] neg_lo:[0,1] neg_hi:[0,1]
	v_cmp_neq_f32_e32 vcc, s57, v3
	v_add_f32_e32 v19, v31, v19
	v_add_f32_e32 v18, v18, v19
	v_add_f32_e32 v19, v21, v18
	v_mul_f32_e32 v31, v30, v19
	v_mul_f32_e32 v20, v29, v31
	v_fma_f32 v22, v31, v29, -v20
	v_fmac_f32_e32 v22, v31, v14
	v_sub_f32_e32 v14, v21, v19
	v_add_f32_e32 v14, v18, v14
	v_add_f32_e32 v18, v20, v22
	v_sub_f32_e32 v21, v19, v18
	v_pk_add_f32 v[24:25], v[18:19], v[20:21] neg_lo:[0,1] neg_hi:[0,1]
	v_mov_b32_e32 v23, v18
	v_pk_add_f32 v[18:19], v[24:25], v[22:23] neg_lo:[0,1] neg_hi:[0,1]
	s_nop 0
	v_add_f32_e32 v14, v14, v19
	v_add_f32_e32 v14, v18, v14
	v_add_f32_e32 v19, v32, v31
	v_add_f32_e32 v14, v21, v14
	v_sub_f32_e32 v18, v19, v32
	v_mul_f32_e32 v14, v30, v14
	v_sub_f32_e32 v18, v31, v18
	v_add_f32_e32 v14, v18, v14
	v_add_f32_e32 v20, v19, v14
	v_mul_f32_e32 v22, v20, v20
	v_fmamk_f32 v18, v22, 0x3e9b6dac, v235
	v_fmaak_f32 v227, v22, v18, 0x3f2aaada
	v_cvt_f32_i32_e32 v18, v28
	v_sub_f32_e32 v19, v20, v19
	v_sub_f32_e32 v14, v14, v19
	v_mul_f32_e32 v19, v20, v22
	v_pk_mul_f32 v[22:23], v[18:19], v[226:227]
	v_ldexp_f32 v21, v20, 1
	v_fma_f32 v20, v18, s56, -v22
	v_fmac_f32_e32 v20, 0xb102e308, v18
	v_pk_add_f32 v[18:19], v[22:23], v[20:21]
	v_ldexp_f32 v14, v14, 1
	v_sub_f32_e32 v21, v19, v21
	v_sub_f32_e32 v21, v23, v21
	v_add_f32_e32 v25, v14, v21
	v_mov_b32_e32 v24, v22
	v_pk_add_f32 v[22:23], v[18:19], v[22:23] neg_lo:[0,1] neg_hi:[0,1]
	v_pk_add_f32 v[28:29], v[18:19], v[24:25]
	v_mov_b32_e32 v21, v18
	v_mov_b32_e32 v23, v29
	v_pk_add_f32 v[30:31], v[20:21], v[22:23] neg_lo:[0,1] neg_hi:[0,1]
	v_pk_add_f32 v[20:21], v[20:21], v[22:23]
	v_mov_b32_e32 v24, v25
	v_pk_add_f32 v[22:23], v[20:21], v[18:19] op_sel:[1,0] op_sel_hi:[0,1] neg_lo:[0,1] neg_hi:[0,1]
	v_pk_add_f32 v[32:33], v[28:29], v[22:23] op_sel_hi:[1,0] neg_lo:[0,1] neg_hi:[0,1]
	v_mov_b32_e32 v28, v29
	v_mov_b32_e32 v29, v21
	v_pk_mov_b32 v[22:23], v[18:19], v[22:23] op_sel:[1,0]
	v_mov_b32_e32 v25, v18
	v_pk_add_f32 v[22:23], v[28:29], v[22:23] neg_lo:[0,1] neg_hi:[0,1]
	v_mov_b32_e32 v32, v30
	v_pk_add_f32 v[18:19], v[24:25], v[22:23] neg_lo:[0,1] neg_hi:[0,1]
	v_mov_b32_e32 v31, v21
	v_pk_add_f32 v[22:23], v[32:33], v[18:19]
	s_nop 0
	v_pk_add_f32 v[24:25], v[22:23], v[22:23] op_sel:[0,1] op_sel_hi:[1,0]
	s_nop 0
	v_pk_add_f32 v[20:21], v[20:21], v[24:25] op_sel:[1,0] op_sel_hi:[0,1]
	v_mov_b32_e32 v23, v20
	v_pk_add_f32 v[28:29], v[22:23], v[30:31] neg_lo:[0,1] neg_hi:[0,1]
	v_mov_b32_e32 v19, v24
	v_sub_f32_e32 v14, v22, v28
	v_pk_add_f32 v[18:19], v[18:19], v[28:29] neg_lo:[0,1] neg_hi:[0,1]
	v_sub_f32_e32 v14, v30, v14
	v_add_f32_e32 v14, v18, v14
	v_add_f32_e32 v14, v14, v19
	v_add_f32_e32 v14, v20, v14
	v_cndmask_b32_e32 v14, v236, v14, vcc
	v_cmp_ngt_f32_e32 vcc, -1.0, v3
	s_nop 1
	v_cndmask_b32_e32 v14, v237, v14, vcc
	v_cmp_neq_f32_e32 vcc, -1.0, v3
	s_nop 1
	v_cndmask_b32_e32 v14, v238, v14, vcc
	v_cmp_lt_f32_e64 vcc, |v3|, s58
	s_nop 1
	v_cndmask_b32_e32 v3, v14, v3, vcc
;     __device__ __forceinline__ void operator()(f32x4 (&acc)[2][2][4][2], const Unit& u, int row0t, int wr, int wc, int fr, int fq) const {
;     ...
;                         for (int n = 0; n < 2; ++n) { const f32x4 v = acc[ai][0][m][n]; f32x4 o;
;                             if (fq == 0) {
; #pragma unroll
;                                 for (int e = 0; e < 4; ++e) o[e] = 1.0f / (1.0f + __expf(-v[e])); }
;                             else {
; #pragma unroll
;                                 for (int e = 0; e < 4; ++e) { const int h = 4 * n + e; const float xx = v[e] + dt_bias[h]; const float sp = xx > 20.f ? xx : log1pf(__expf(xx)); o[e] = -__expf(A_log[h]) * sp; } }
;                             *(f32x4*)(bg + (size_t)r * 16 + 8 * fq + 4 * n) = o; } }
.LBB0_338:
	s_or_b64 exec, exec, s[36:37]
	v_mov_b32_e32 v18, v155
	v_mov_b32_e32 v14, v162
	v_add_f32_e32 v15, v15, v18
	v_cmp_nlt_f32_e32 vcc, s53, v15
	s_and_saveexec_b64 s[36:37], vcc
	s_cbranch_execz .LBB0_340
	v_mul_f32_e32 v15, 0x3fb8aa3b, v15
	v_exp_f32_e32 v15, v15
	s_nop 0
	v_add_f32_e32 v20, 1.0, v15
	v_frexp_mant_f32_e32 v22, v20
	v_cvt_f64_f32_e32 v[18:19], v20
	v_frexp_exp_i32_f64_e32 v18, v[18:19]
	v_cmp_gt_f32_e32 vcc, s55, v22
	v_add_f32_e32 v21, -1.0, v20
	v_sub_f32_e32 v23, v21, v20
	v_subbrev_co_u32_e32 v28, vcc, 0, v18, vcc
	v_sub_u32_e32 v18, 0, v28
	v_sub_f32_e32 v21, v15, v21
	v_add_f32_e32 v23, 1.0, v23
	v_ldexp_f32 v19, v20, v18
	v_add_f32_e32 v21, v21, v23
	v_add_f32_e32 v20, -1.0, v19
	v_add_f32_e32 v22, 1.0, v19
	v_ldexp_f32 v18, v21, v18
	v_add_f32_e32 v21, 1.0, v20
	v_add_f32_e32 v23, -1.0, v22
	v_sub_f32_e32 v21, v19, v21
	v_sub_f32_e32 v19, v19, v23
	v_add_f32_e32 v21, v18, v21
	v_add_f32_e32 v18, v18, v19
	v_add_f32_e32 v29, v22, v18
	v_rcp_f32_e32 v31, v29
	v_sub_f32_e32 v19, v29, v22
	v_sub_f32_e32 v30, v18, v19
	v_add_f32_e32 v19, v20, v21
	v_mul_f32_e32 v33, v19, v31
	v_sub_f32_e32 v18, v19, v20
	v_mul_f32_e32 v20, v29, v33
	v_fma_f32 v22, v33, v29, -v20
	v_fmac_f32_e32 v22, v33, v30
	v_sub_f32_e32 v32, v21, v18
	v_add_f32_e32 v18, v20, v22
	v_sub_f32_e32 v21, v19, v18
	v_pk_add_f32 v[24:25], v[18:19], v[20:21] neg_lo:[0,1] neg_hi:[0,1]
	v_mov_b32_e32 v23, v18
	v_pk_add_f32 v[18:19], v[24:25], v[22:23] neg_lo:[0,1] neg_hi:[0,1]
	v_cmp_neq_f32_e32 vcc, s57, v15
	v_add_f32_e32 v19, v32, v19
	v_add_f32_e32 v18, v18, v19
	v_add_f32_e32 v19, v21, v18
	v_mul_f32_e32 v32, v31, v19
	v_mul_f32_e32 v20, v29, v32
	v_fma_f32 v22, v32, v29, -v20
	v_fmac_f32_e32 v22, v32, v30
	v_sub_f32_e32 v21, v21, v19
	v_add_f32_e32 v29, v18, v21
	v_add_f32_e32 v18, v20, v22
	v_sub_f32_e32 v21, v19, v18
	v_pk_add_f32 v[24:25], v[18:19], v[20:21] neg_lo:[0,1] neg_hi:[0,1]
	v_mov_b32_e32 v23, v18
	v_pk_add_f32 v[18:19], v[24:25], v[22:23] neg_lo:[0,1] neg_hi:[0,1]
	s_nop 0
	v_add_f32_e32 v19, v29, v19
	v_add_f32_e32 v18, v18, v19
	v_add_f32_e32 v19, v33, v32
	v_add_f32_e32 v18, v21, v18
	v_sub_f32_e32 v20, v19, v33
	v_mul_f32_e32 v18, v31, v18
	v_sub_f32_e32 v20, v32, v20
	v_add_f32_e32 v20, v20, v18
	v_add_f32_e32 v22, v19, v20
	v_mul_f32_e32 v23, v22, v22
	v_fmamk_f32 v18, v23, 0x3e9b6dac, v235
	v_fmaak_f32 v227, v23, v18, 0x3f2aaada
	v_cvt_f32_i32_e32 v18, v28
	v_sub_f32_e32 v19, v22, v19
	v_sub_f32_e32 v19, v20, v19
	v_ldexp_f32 v24, v19, 1
	v_mul_f32_e32 v19, v22, v23
	v_ldexp_f32 v21, v22, 1
	v_pk_mul_f32 v[22:23], v[18:19], v[226:227]
	s_nop 0
	v_fma_f32 v20, v18, s56, -v22
	v_fmac_f32_e32 v20, 0xb102e308, v18
	v_pk_add_f32 v[18:19], v[22:23], v[20:21]
	s_nop 0
	v_sub_f32_e32 v21, v19, v21
	v_sub_f32_e32 v21, v23, v21
	v_add_f32_e32 v25, v24, v21
	v_mov_b32_e32 v24, v22
	v_pk_add_f32 v[22:23], v[18:19], v[22:23] neg_lo:[0,1] neg_hi:[0,1]
	v_pk_add_f32 v[28:29], v[18:19], v[24:25]
	v_mov_b32_e32 v21, v18
	v_mov_b32_e32 v23, v29
	v_pk_add_f32 v[30:31], v[20:21], v[22:23] neg_lo:[0,1] neg_hi:[0,1]
	v_pk_add_f32 v[20:21], v[20:21], v[22:23]
	v_mov_b32_e32 v24, v25
	v_pk_add_f32 v[22:23], v[20:21], v[18:19] op_sel:[1,0] op_sel_hi:[0,1] neg_lo:[0,1] neg_hi:[0,1]
	v_pk_add_f32 v[32:33], v[28:29], v[22:23] op_sel_hi:[1,0] neg_lo:[0,1] neg_hi:[0,1]
	v_mov_b32_e32 v28, v29
	v_mov_b32_e32 v29, v21
	v_pk_mov_b32 v[22:23], v[18:19], v[22:23] op_sel:[1,0]
	v_mov_b32_e32 v25, v18
	v_pk_add_f32 v[22:23], v[28:29], v[22:23] neg_lo:[0,1] neg_hi:[0,1]
	v_mov_b32_e32 v32, v30
	v_pk_add_f32 v[18:19], v[24:25], v[22:23] neg_lo:[0,1] neg_hi:[0,1]
	v_mov_b32_e32 v31, v21
	v_pk_add_f32 v[22:23], v[32:33], v[18:19]
	s_nop 0
	v_pk_add_f32 v[24:25], v[22:23], v[22:23] op_sel:[0,1] op_sel_hi:[1,0]
	s_nop 0
	v_pk_add_f32 v[20:21], v[20:21], v[24:25] op_sel:[1,0] op_sel_hi:[0,1]
	v_mov_b32_e32 v23, v20
	v_pk_add_f32 v[28:29], v[22:23], v[30:31] neg_lo:[0,1] neg_hi:[0,1]
	v_mov_b32_e32 v19, v24
	v_sub_f32_e32 v21, v22, v28
	v_pk_add_f32 v[18:19], v[18:19], v[28:29] neg_lo:[0,1] neg_hi:[0,1]
	v_sub_f32_e32 v21, v30, v21
	v_add_f32_e32 v18, v18, v21
	v_add_f32_e32 v18, v18, v19
	v_add_f32_e32 v18, v20, v18
	v_cndmask_b32_e32 v18, v236, v18, vcc
	v_cmp_ngt_f32_e32 vcc, -1.0, v15
	s_nop 1
	v_cndmask_b32_e32 v18, v237, v18, vcc
	v_cmp_neq_f32_e32 vcc, -1.0, v15
	s_nop 1
	v_cndmask_b32_e32 v18, v238, v18, vcc
	v_cmp_lt_f32_e64 vcc, |v15|, s58
	s_nop 1
	v_cndmask_b32_e32 v15, v18, v15, vcc
;     __device__ __forceinline__ void operator()(f32x4 (&acc)[2][2][4][2], const Unit& u, int row0t, int wr, int wc, int fr, int fq) const {
;     ...
;                         for (int n = 0; n < 2; ++n) { const f32x4 v = acc[ai][0][m][n]; f32x4 o;
;                             if (fq == 0) {
; #pragma unroll
;                                 for (int e = 0; e < 4; ++e) o[e] = 1.0f / (1.0f + __expf(-v[e])); }
;                             else {
; #pragma unroll
;                                 for (int e = 0; e < 4; ++e) { const int h = 4 * n + e; const float xx = v[e] + dt_bias[h]; const float sp = xx > 20.f ? xx : log1pf(__expf(xx)); o[e] = -__expf(A_log[h]) * sp; } }
;                             *(f32x4*)(bg + (size_t)r * 16 + 8 * fq + 4 * n) = o; } }
.LBB0_340:
	s_or_b64 exec, exec, s[36:37]
	v_mov_b32_e32 v18, v156
	v_mov_b32_e32 v19, v163
	v_add_f32_e32 v16, v16, v18
	v_cmp_nlt_f32_e32 vcc, s53, v16
	s_and_saveexec_b64 s[36:37], vcc
	s_cbranch_execz .LBB0_342
	v_mul_f32_e32 v16, 0x3fb8aa3b, v16
	v_exp_f32_e32 v16, v16
	s_nop 0
	v_add_f32_e32 v18, 1.0, v16
	v_frexp_mant_f32_e32 v23, v18
	v_cvt_f64_f32_e32 v[20:21], v18
	v_add_f32_e32 v22, -1.0, v18
	v_frexp_exp_i32_f64_e32 v20, v[20:21]
	v_cmp_gt_f32_e32 vcc, s55, v23
	v_sub_f32_e32 v24, v22, v18
	v_sub_f32_e32 v22, v16, v22
	v_subbrev_co_u32_e32 v30, vcc, 0, v20, vcc
	v_add_f32_e32 v24, 1.0, v24
	v_sub_u32_e32 v20, 0, v30
	v_add_f32_e32 v22, v22, v24
	v_ldexp_f32 v18, v18, v20
	v_ldexp_f32 v20, v22, v20
	v_add_f32_e32 v22, -1.0, v18
	v_add_f32_e32 v21, 1.0, v22
	v_sub_f32_e32 v21, v18, v21
	v_add_f32_e32 v23, v20, v21
	v_add_f32_e32 v21, 1.0, v18
	v_add_f32_e32 v24, -1.0, v21
	v_sub_f32_e32 v18, v18, v24
	v_add_f32_e32 v18, v20, v18
	v_add_f32_e32 v31, v21, v18
	v_rcp_f32_e32 v32, v31
	v_sub_f32_e32 v20, v31, v21
	v_add_f32_e32 v21, v22, v23
	v_sub_f32_e32 v18, v18, v20
	v_mul_f32_e32 v34, v21, v32
	v_sub_f32_e32 v20, v21, v22
	v_mul_f32_e32 v22, v31, v34
	v_fma_f32 v24, v34, v31, -v22
	v_fmac_f32_e32 v24, v34, v18
	v_sub_f32_e32 v33, v23, v20
	v_add_f32_e32 v20, v22, v24
	v_sub_f32_e32 v23, v21, v20
	v_pk_add_f32 v[28:29], v[20:21], v[22:23] neg_lo:[0,1] neg_hi:[0,1]
	v_mov_b32_e32 v25, v20
	v_pk_add_f32 v[20:21], v[28:29], v[24:25] neg_lo:[0,1] neg_hi:[0,1]
	v_cmp_neq_f32_e32 vcc, s57, v16
	v_add_f32_e32 v21, v33, v21
	v_add_f32_e32 v20, v20, v21
	v_add_f32_e32 v21, v23, v20
	v_mul_f32_e32 v33, v32, v21
	v_mul_f32_e32 v22, v31, v33
	v_fma_f32 v24, v33, v31, -v22
	v_fmac_f32_e32 v24, v33, v18
	v_sub_f32_e32 v18, v23, v21
	v_add_f32_e32 v18, v20, v18
	v_add_f32_e32 v20, v22, v24
	v_sub_f32_e32 v23, v21, v20
	v_pk_add_f32 v[28:29], v[20:21], v[22:23] neg_lo:[0,1] neg_hi:[0,1]
	v_mov_b32_e32 v25, v20
	v_pk_add_f32 v[20:21], v[28:29], v[24:25] neg_lo:[0,1] neg_hi:[0,1]
	s_nop 0
	v_add_f32_e32 v18, v18, v21
	v_add_f32_e32 v18, v20, v18
	v_add_f32_e32 v21, v34, v33
	v_add_f32_e32 v18, v23, v18
	v_sub_f32_e32 v20, v21, v34
	v_mul_f32_e32 v18, v32, v18
	v_sub_f32_e32 v20, v33, v20
	v_add_f32_e32 v18, v20, v18
	v_add_f32_e32 v22, v21, v18
	v_mul_f32_e32 v24, v22, v22
	v_fmamk_f32 v20, v24, 0x3e9b6dac, v235
	v_fmaak_f32 v227, v24, v20, 0x3f2aaada
	v_cvt_f32_i32_e32 v20, v30
	v_sub_f32_e32 v21, v22, v21
	v_sub_f32_e32 v18, v18, v21
	v_mul_f32_e32 v21, v22, v24
	v_pk_mul_f32 v[24:25], v[20:21], v[226:227]
	v_ldexp_f32 v23, v22, 1
	v_fma_f32 v22, v20, s56, -v24
	v_fmac_f32_e32 v22, 0xb102e308, v20
	v_pk_add_f32 v[20:21], v[24:25], v[22:23]
	v_ldexp_f32 v18, v18, 1
	v_sub_f32_e32 v23, v21, v23
	v_sub_f32_e32 v23, v25, v23
	v_add_f32_e32 v29, v18, v23
	v_mov_b32_e32 v28, v24
	v_pk_add_f32 v[24:25], v[20:21], v[24:25] neg_lo:[0,1] neg_hi:[0,1]
	v_pk_add_f32 v[30:31], v[20:21], v[28:29]
	v_mov_b32_e32 v23, v20
	v_mov_b32_e32 v25, v31
	v_pk_add_f32 v[32:33], v[22:23], v[24:25] neg_lo:[0,1] neg_hi:[0,1]
	v_pk_add_f32 v[22:23], v[22:23], v[24:25]
	v_mov_b32_e32 v28, v29
	v_pk_add_f32 v[24:25], v[22:23], v[20:21] op_sel:[1,0] op_sel_hi:[0,1] neg_lo:[0,1] neg_hi:[0,1]
	v_pk_add_f32 v[34:35], v[30:31], v[24:25] op_sel_hi:[1,0] neg_lo:[0,1] neg_hi:[0,1]
	v_mov_b32_e32 v30, v31
	v_mov_b32_e32 v31, v23
	v_pk_mov_b32 v[24:25], v[20:21], v[24:25] op_sel:[1,0]
	v_mov_b32_e32 v29, v20
	v_pk_add_f32 v[24:25], v[30:31], v[24:25] neg_lo:[0,1] neg_hi:[0,1]
	v_mov_b32_e32 v34, v32
	v_pk_add_f32 v[20:21], v[28:29], v[24:25] neg_lo:[0,1] neg_hi:[0,1]
	v_mov_b32_e32 v33, v23
	v_pk_add_f32 v[24:25], v[34:35], v[20:21]
	s_nop 0
	v_pk_add_f32 v[28:29], v[24:25], v[24:25] op_sel:[0,1] op_sel_hi:[1,0]
	s_nop 0
	v_pk_add_f32 v[22:23], v[22:23], v[28:29] op_sel:[1,0] op_sel_hi:[0,1]
	v_mov_b32_e32 v25, v22
	v_pk_add_f32 v[30:31], v[24:25], v[32:33] neg_lo:[0,1] neg_hi:[0,1]
	v_mov_b32_e32 v21, v28
	v_sub_f32_e32 v18, v24, v30
	v_pk_add_f32 v[20:21], v[20:21], v[30:31] neg_lo:[0,1] neg_hi:[0,1]
	v_sub_f32_e32 v18, v32, v18
	v_add_f32_e32 v18, v20, v18
	v_add_f32_e32 v18, v18, v21
	v_add_f32_e32 v18, v22, v18
	v_cndmask_b32_e32 v18, v236, v18, vcc
	v_cmp_ngt_f32_e32 vcc, -1.0, v16
	s_nop 1
	v_cndmask_b32_e32 v18, v237, v18, vcc
	v_cmp_neq_f32_e32 vcc, -1.0, v16
	s_nop 1
	v_cndmask_b32_e32 v18, v238, v18, vcc
	v_cmp_lt_f32_e64 vcc, |v16|, s58
	s_nop 1
	v_cndmask_b32_e32 v16, v18, v16, vcc
;     __device__ __forceinline__ void operator()(f32x4 (&acc)[2][2][4][2], const Unit& u, int row0t, int wr, int wc, int fr, int fq) const {
;     ...
;                         for (int n = 0; n < 2; ++n) { const f32x4 v = acc[ai][0][m][n]; f32x4 o;
;                             if (fq == 0) {
; #pragma unroll
;                                 for (int e = 0; e < 4; ++e) o[e] = 1.0f / (1.0f + __expf(-v[e])); }
;                             else {
; #pragma unroll
;                                 for (int e = 0; e < 4; ++e) { const int h = 4 * n + e; const float xx = v[e] + dt_bias[h]; const float sp = xx > 20.f ? xx : log1pf(__expf(xx)); o[e] = -__expf(A_log[h]) * sp; } }
;                             *(f32x4*)(bg + (size_t)r * 16 + 8 * fq + 4 * n) = o; } }
.LBB0_342:
	s_or_b64 exec, exec, s[36:37]
	v_mov_b32_e32 v18, v157
	v_mov_b32_e32 v20, v164
	v_add_f32_e32 v17, v17, v18
	v_cmp_nlt_f32_e32 vcc, s53, v17
	s_and_saveexec_b64 s[36:37], vcc
	s_cbranch_execz .LBB0_344
	v_mul_f32_e32 v17, 0x3fb8aa3b, v17
	v_exp_f32_e32 v17, v17
	s_nop 0
	v_add_f32_e32 v18, 1.0, v17
	v_frexp_mant_f32_e32 v24, v18
	v_cvt_f64_f32_e32 v[22:23], v18
	v_add_f32_e32 v21, -1.0, v18
	v_frexp_exp_i32_f64_e32 v22, v[22:23]
	v_cmp_gt_f32_e32 vcc, s55, v24
	v_sub_f32_e32 v25, v21, v18
	v_sub_f32_e32 v21, v17, v21
	v_subbrev_co_u32_e32 v32, vcc, 0, v22, vcc
	v_add_f32_e32 v25, 1.0, v25
	v_sub_u32_e32 v22, 0, v32
	v_add_f32_e32 v21, v21, v25
	v_ldexp_f32 v18, v18, v22
	v_ldexp_f32 v21, v21, v22
	v_add_f32_e32 v22, -1.0, v18
	v_add_f32_e32 v23, 1.0, v22
	v_sub_f32_e32 v23, v18, v23
	v_add_f32_e32 v24, v21, v23
	v_add_f32_e32 v23, 1.0, v18
	v_add_f32_e32 v25, -1.0, v23
	v_sub_f32_e32 v18, v18, v25
	v_add_f32_e32 v18, v21, v18
	v_add_f32_e32 v21, v23, v18
	v_rcp_f32_e32 v33, v21
	v_sub_f32_e32 v23, v21, v23
	v_sub_f32_e32 v18, v18, v23
	v_add_f32_e32 v23, v22, v24
	v_sub_f32_e32 v22, v23, v22
	v_mul_f32_e32 v35, v23, v33
	v_sub_f32_e32 v34, v24, v22
	v_mul_f32_e32 v24, v21, v35
	v_fma_f32 v28, v35, v21, -v24
	v_fmac_f32_e32 v28, v35, v18
	v_add_f32_e32 v22, v24, v28
	v_sub_f32_e32 v25, v23, v22
	v_pk_add_f32 v[30:31], v[22:23], v[24:25] neg_lo:[0,1] neg_hi:[0,1]
	v_mov_b32_e32 v29, v22
	v_pk_add_f32 v[22:23], v[30:31], v[28:29] neg_lo:[0,1] neg_hi:[0,1]
	v_cmp_neq_f32_e32 vcc, s57, v17
	v_add_f32_e32 v23, v34, v23
	v_add_f32_e32 v22, v22, v23
	v_add_f32_e32 v23, v25, v22
	v_mul_f32_e32 v34, v33, v23
	v_mul_f32_e32 v24, v21, v34
	v_fma_f32 v28, v34, v21, -v24
	v_fmac_f32_e32 v28, v34, v18
	v_sub_f32_e32 v18, v25, v23
	v_add_f32_e32 v18, v22, v18
	v_add_f32_e32 v22, v24, v28
	v_sub_f32_e32 v25, v23, v22
	v_pk_add_f32 v[30:31], v[22:23], v[24:25] neg_lo:[0,1] neg_hi:[0,1]
	v_mov_b32_e32 v29, v22
	v_pk_add_f32 v[22:23], v[30:31], v[28:29] neg_lo:[0,1] neg_hi:[0,1]
	v_add_f32_e32 v21, v35, v34
	v_add_f32_e32 v18, v18, v23
	v_add_f32_e32 v18, v22, v18
	v_add_f32_e32 v18, v25, v18
	v_sub_f32_e32 v22, v21, v35
	v_mul_f32_e32 v18, v33, v18
	v_sub_f32_e32 v22, v34, v22
	v_add_f32_e32 v18, v22, v18
	v_add_f32_e32 v23, v21, v18
	v_mul_f32_e32 v24, v23, v23
	v_fmamk_f32 v22, v24, 0x3e9b6dac, v235
	v_fmaak_f32 v227, v24, v22, 0x3f2aaada
	v_cvt_f32_i32_e32 v22, v32
	v_sub_f32_e32 v21, v23, v21
	v_ldexp_f32 v25, v23, 1
	v_mul_f32_e32 v23, v23, v24
	v_pk_mul_f32 v[28:29], v[22:23], v[226:227]
	v_sub_f32_e32 v18, v18, v21
	v_fma_f32 v24, v22, s56, -v28
	v_fmac_f32_e32 v24, 0xb102e308, v22
	v_pk_add_f32 v[22:23], v[28:29], v[24:25]
	v_ldexp_f32 v18, v18, 1
	v_sub_f32_e32 v21, v23, v25
	v_sub_f32_e32 v21, v29, v21
	v_add_f32_e32 v31, v18, v21
	v_mov_b32_e32 v30, v28
	v_pk_add_f32 v[28:29], v[22:23], v[28:29] neg_lo:[0,1] neg_hi:[0,1]
	v_pk_add_f32 v[32:33], v[22:23], v[30:31]
	v_mov_b32_e32 v25, v22
	v_mov_b32_e32 v29, v33
	v_pk_add_f32 v[34:35], v[24:25], v[28:29] neg_lo:[0,1] neg_hi:[0,1]
	v_pk_add_f32 v[24:25], v[24:25], v[28:29]
	v_mov_b32_e32 v30, v31
	v_pk_add_f32 v[28:29], v[24:25], v[22:23] op_sel:[1,0] op_sel_hi:[0,1] neg_lo:[0,1] neg_hi:[0,1]
	v_pk_add_f32 v[36:37], v[32:33], v[28:29] op_sel_hi:[1,0] neg_lo:[0,1] neg_hi:[0,1]
	v_mov_b32_e32 v32, v33
	v_mov_b32_e32 v33, v25
	v_pk_mov_b32 v[28:29], v[22:23], v[28:29] op_sel:[1,0]
	v_mov_b32_e32 v31, v22
	v_pk_add_f32 v[28:29], v[32:33], v[28:29] neg_lo:[0,1] neg_hi:[0,1]
	v_mov_b32_e32 v36, v34
	v_pk_add_f32 v[22:23], v[30:31], v[28:29] neg_lo:[0,1] neg_hi:[0,1]
	v_mov_b32_e32 v35, v25
	v_pk_add_f32 v[28:29], v[36:37], v[22:23]
	s_nop 0
	v_pk_add_f32 v[30:31], v[28:29], v[28:29] op_sel:[0,1] op_sel_hi:[1,0]
	s_nop 0
	v_pk_add_f32 v[24:25], v[24:25], v[30:31] op_sel:[1,0] op_sel_hi:[0,1]
	v_mov_b32_e32 v29, v24
	v_pk_add_f32 v[32:33], v[28:29], v[34:35] neg_lo:[0,1] neg_hi:[0,1]
	v_mov_b32_e32 v23, v30
	v_sub_f32_e32 v18, v28, v32
	v_pk_add_f32 v[22:23], v[22:23], v[32:33] neg_lo:[0,1] neg_hi:[0,1]
	v_sub_f32_e32 v18, v34, v18
	v_add_f32_e32 v18, v22, v18
	v_add_f32_e32 v18, v18, v23
	v_add_f32_e32 v18, v24, v18
	v_cndmask_b32_e32 v18, v236, v18, vcc
	v_cmp_ngt_f32_e32 vcc, -1.0, v17
	s_nop 1
	v_cndmask_b32_e32 v18, v237, v18, vcc
	v_cmp_neq_f32_e32 vcc, -1.0, v17
	s_nop 1
	v_cndmask_b32_e32 v18, v238, v18, vcc
	v_cmp_lt_f32_e64 vcc, |v17|, s58
	s_nop 1
	v_cndmask_b32_e32 v17, v18, v17, vcc
.LBB0_344:
	s_or_b64 exec, exec, s[36:37]
	v_mul_f32_e32 v14, 0x3fb8aa3b, v14
	v_exp_f32_e32 v14, v14
	s_nop 0
	v_mul_f32_e64 v18, v3, -v14
	v_mul_f32_e32 v3, 0x3fb8aa3b, v19
	v_exp_f32_e32 v3, v3
	s_nop 0
	v_mul_f32_e64 v19, v15, -v3
	v_mul_f32_e32 v3, 0x3fb8aa3b, v20
	v_exp_f32_e32 v3, v3
	s_nop 0
	v_mul_f32_e64 v20, v16, -v3
	v_mov_b32_e32 v3, v165
	v_mul_f32_e32 v3, 0x3fb8aa3b, v3
	v_exp_f32_e32 v3, v3
	s_nop 0
	v_mul_f32_e64 v21, v17, -v3

;     __device__ __forceinline__ void operator()(f32x4 (&acc)[2][2][4][2], const Unit& u, int row0t, int wr, int wc, int fr, int fq) const {
;     ...
;                     for (int m = 0; m < 4; ++m) { const int r = row0t + wr * 64 + fr + ai * HALF + m * 16;
; #pragma unroll
;                         for (int n = 0; n < 2; ++n) { const f32x4 v = acc[ai][0][m][n]; f32x4 o;
;                             if (fq == 0) {
; #pragma unroll
;                                 for (int e = 0; e < 4; ++e) o[e] = 1.0f / (1.0f + __expf(-v[e])); }
;                             else {
; #pragma unroll
;                                 for (int e = 0; e < 4; ++e) { const int h = 4 * n + e; const float xx = v[e] + dt_bias[h]; const float sp = xx > 20.f ? xx : log1pf(__expf(xx)); o[e] = -__expf(A_log[h]) * sp; } }
;                             *(f32x4*)(bg + (size_t)r * 16 + 8 * fq + 4 * n) = o; } }
.LBB0_347:
	s_or_b64 exec, exec, s[24:25]
	s_mov_b64 s[2:3], 0x2800
	v_lshl_add_u64 v[14:15], v[26:27], 0, s[2:3]
	global_store_dwordx4 v[14:15], v[18:21], off offset:16
	s_and_saveexec_b64 s[2:3], s[4:5]
	s_xor_b64 s[24:25], exec, s[2:3]
	s_cbranch_execz .LBB0_357
	v_mov_b32_e32 v3, v150
	v_add_f32_e32 v3, v10, v3
	v_cmp_nlt_f32_e32 vcc, s53, v3
	s_and_saveexec_b64 s[36:37], vcc
	s_cbranch_execz .LBB0_350
	v_mul_f32_e32 v3, 0x3fb8aa3b, v3
	v_exp_f32_e32 v3, v3
	s_nop 0
	v_add_f32_e32 v10, 1.0, v3
	v_frexp_mant_f32_e32 v17, v10
	v_cvt_f64_f32_e32 v[14:15], v10
	v_add_f32_e32 v16, -1.0, v10
	v_frexp_exp_i32_f64_e32 v14, v[14:15]
	v_cmp_gt_f32_e32 vcc, s55, v17
	v_sub_f32_e32 v18, v16, v10
	v_sub_f32_e32 v16, v3, v16
	v_subbrev_co_u32_e32 v22, vcc, 0, v14, vcc
	v_add_f32_e32 v18, 1.0, v18
	v_sub_u32_e32 v14, 0, v22
	v_add_f32_e32 v16, v16, v18
	v_ldexp_f32 v10, v10, v14
	v_ldexp_f32 v14, v16, v14
	v_add_f32_e32 v16, -1.0, v10
	v_add_f32_e32 v15, 1.0, v16
	v_sub_f32_e32 v15, v10, v15
	v_add_f32_e32 v17, v14, v15
	v_add_f32_e32 v15, 1.0, v10
	v_add_f32_e32 v18, -1.0, v15
	v_sub_f32_e32 v10, v10, v18
	v_add_f32_e32 v10, v14, v10
	v_add_f32_e32 v23, v15, v10
	v_rcp_f32_e32 v24, v23
	v_sub_f32_e32 v14, v23, v15
	v_add_f32_e32 v15, v16, v17
	v_sub_f32_e32 v10, v10, v14
	v_mul_f32_e32 v26, v15, v24
	v_sub_f32_e32 v14, v15, v16
	v_mul_f32_e32 v16, v23, v26
	v_fma_f32 v18, v26, v23, -v16
	v_fmac_f32_e32 v18, v26, v10
	v_sub_f32_e32 v25, v17, v14
	v_add_f32_e32 v14, v16, v18
	v_sub_f32_e32 v17, v15, v14
	v_pk_add_f32 v[20:21], v[14:15], v[16:17] neg_lo:[0,1] neg_hi:[0,1]
	v_mov_b32_e32 v19, v14
	v_pk_add_f32 v[14:15], v[20:21], v[18:19] neg_lo:[0,1] neg_hi:[0,1]
	v_cmp_neq_f32_e32 vcc, s57, v3
	v_add_f32_e32 v15, v25, v15
	v_add_f32_e32 v14, v14, v15
	v_add_f32_e32 v15, v17, v14
	v_mul_f32_e32 v25, v24, v15
	v_mul_f32_e32 v16, v23, v25
	v_fma_f32 v18, v25, v23, -v16
	v_fmac_f32_e32 v18, v25, v10
	v_sub_f32_e32 v10, v17, v15
	v_add_f32_e32 v10, v14, v10
	v_add_f32_e32 v14, v16, v18
	v_sub_f32_e32 v17, v15, v14
	v_pk_add_f32 v[20:21], v[14:15], v[16:17] neg_lo:[0,1] neg_hi:[0,1]
	v_mov_b32_e32 v19, v14
	v_pk_add_f32 v[14:15], v[20:21], v[18:19] neg_lo:[0,1] neg_hi:[0,1]
	s_nop 0
	v_add_f32_e32 v10, v10, v15
	v_add_f32_e32 v10, v14, v10
	v_add_f32_e32 v15, v26, v25
	v_add_f32_e32 v10, v17, v10
	v_sub_f32_e32 v14, v15, v26
	v_mul_f32_e32 v10, v24, v10
	v_sub_f32_e32 v14, v25, v14
	v_add_f32_e32 v10, v14, v10
	v_add_f32_e32 v16, v15, v10
	v_mul_f32_e32 v18, v16, v16
	v_fmamk_f32 v14, v18, 0x3e9b6dac, v235
	v_fmaak_f32 v227, v18, v14, 0x3f2aaada
	v_cvt_f32_i32_e32 v14, v22
	v_sub_f32_e32 v15, v16, v15
	v_sub_f32_e32 v10, v10, v15
	v_mul_f32_e32 v15, v16, v18
	v_pk_mul_f32 v[18:19], v[14:15], v[226:227]
	v_ldexp_f32 v17, v16, 1
	v_fma_f32 v16, v14, s56, -v18
	v_fmac_f32_e32 v16, 0xb102e308, v14
	v_pk_add_f32 v[14:15], v[18:19], v[16:17]
	v_ldexp_f32 v10, v10, 1
	v_sub_f32_e32 v17, v15, v17
	v_sub_f32_e32 v17, v19, v17
	v_add_f32_e32 v21, v10, v17
	v_mov_b32_e32 v20, v18
	v_pk_add_f32 v[18:19], v[14:15], v[18:19] neg_lo:[0,1] neg_hi:[0,1]
	v_pk_add_f32 v[22:23], v[14:15], v[20:21]
	v_mov_b32_e32 v17, v14
	v_mov_b32_e32 v19, v23
	v_pk_add_f32 v[24:25], v[16:17], v[18:19] neg_lo:[0,1] neg_hi:[0,1]
	v_pk_add_f32 v[16:17], v[16:17], v[18:19]
	v_mov_b32_e32 v20, v21
	v_pk_add_f32 v[18:19], v[16:17], v[14:15] op_sel:[1,0] op_sel_hi:[0,1] neg_lo:[0,1] neg_hi:[0,1]
	v_pk_add_f32 v[26:27], v[22:23], v[18:19] op_sel_hi:[1,0] neg_lo:[0,1] neg_hi:[0,1]
	v_mov_b32_e32 v22, v23
	v_mov_b32_e32 v23, v17
	v_pk_mov_b32 v[18:19], v[14:15], v[18:19] op_sel:[1,0]
	v_mov_b32_e32 v21, v14
	v_pk_add_f32 v[18:19], v[22:23], v[18:19] neg_lo:[0,1] neg_hi:[0,1]
	v_mov_b32_e32 v26, v24
	v_pk_add_f32 v[14:15], v[20:21], v[18:19] neg_lo:[0,1] neg_hi:[0,1]
	v_mov_b32_e32 v25, v17
	v_pk_add_f32 v[18:19], v[26:27], v[14:15]
	s_nop 0
	v_pk_add_f32 v[20:21], v[18:19], v[18:19] op_sel:[0,1] op_sel_hi:[1,0]
	s_nop 0
	v_pk_add_f32 v[16:17], v[16:17], v[20:21] op_sel:[1,0] op_sel_hi:[0,1]
	v_mov_b32_e32 v19, v16
	v_pk_add_f32 v[22:23], v[18:19], v[24:25] neg_lo:[0,1] neg_hi:[0,1]
	v_mov_b32_e32 v15, v20
	v_sub_f32_e32 v10, v18, v22
	v_pk_add_f32 v[14:15], v[14:15], v[22:23] neg_lo:[0,1] neg_hi:[0,1]
	v_sub_f32_e32 v10, v24, v10
	v_add_f32_e32 v10, v14, v10
	v_add_f32_e32 v10, v10, v15
	v_add_f32_e32 v10, v16, v10
	v_cndmask_b32_e32 v10, v236, v10, vcc
	v_cmp_ngt_f32_e32 vcc, -1.0, v3
	s_nop 1
	v_cndmask_b32_e32 v10, v237, v10, vcc
	v_cmp_neq_f32_e32 vcc, -1.0, v3
	s_nop 1
	v_cndmask_b32_e32 v10, v238, v10, vcc
	v_cmp_lt_f32_e64 vcc, |v3|, s58
	s_nop 1
	v_cndmask_b32_e32 v3, v10, v3, vcc
;     __device__ __forceinline__ void operator()(f32x4 (&acc)[2][2][4][2], const Unit& u, int row0t, int wr, int wc, int fr, int fq) const {
;     ...
;                         for (int n = 0; n < 2; ++n) { const f32x4 v = acc[ai][0][m][n]; f32x4 o;
;                             if (fq == 0) {
; #pragma unroll
;                                 for (int e = 0; e < 4; ++e) o[e] = 1.0f / (1.0f + __expf(-v[e])); }
;                             else {
; #pragma unroll
;                                 for (int e = 0; e < 4; ++e) { const int h = 4 * n + e; const float xx = v[e] + dt_bias[h]; const float sp = xx > 20.f ? xx : log1pf(__expf(xx)); o[e] = -__expf(A_log[h]) * sp; } }
;                             *(f32x4*)(bg + (size_t)r * 16 + 8 * fq + 4 * n) = o; } }
.LBB0_350:
	s_or_b64 exec, exec, s[36:37]
	v_mov_b32_e32 v14, v151
	v_mov_b32_e32 v10, v158
	v_add_f32_e32 v11, v11, v14
	v_cmp_nlt_f32_e32 vcc, s53, v11
	s_and_saveexec_b64 s[36:37], vcc
	s_cbranch_execz .LBB0_352
	v_mul_f32_e32 v11, 0x3fb8aa3b, v11
	v_exp_f32_e32 v11, v11
	s_nop 0
	v_add_f32_e32 v16, 1.0, v11
	v_frexp_mant_f32_e32 v18, v16
	v_cvt_f64_f32_e32 v[14:15], v16
	v_frexp_exp_i32_f64_e32 v14, v[14:15]
	v_cmp_gt_f32_e32 vcc, s55, v18
	v_add_f32_e32 v17, -1.0, v16
	v_sub_f32_e32 v19, v17, v16
	v_subbrev_co_u32_e32 v22, vcc, 0, v14, vcc
	v_sub_u32_e32 v14, 0, v22
	v_sub_f32_e32 v17, v11, v17
	v_add_f32_e32 v19, 1.0, v19
	v_ldexp_f32 v15, v16, v14
	v_add_f32_e32 v17, v17, v19
	v_add_f32_e32 v16, -1.0, v15
	v_add_f32_e32 v18, 1.0, v15
	v_ldexp_f32 v14, v17, v14
	v_add_f32_e32 v17, 1.0, v16
	v_add_f32_e32 v19, -1.0, v18
	v_sub_f32_e32 v17, v15, v17
	v_sub_f32_e32 v15, v15, v19
	v_add_f32_e32 v17, v14, v17
	v_add_f32_e32 v14, v14, v15
	v_add_f32_e32 v23, v18, v14
	v_rcp_f32_e32 v25, v23
	v_sub_f32_e32 v15, v23, v18
	v_sub_f32_e32 v24, v14, v15
	v_add_f32_e32 v15, v16, v17
	v_mul_f32_e32 v27, v15, v25
	v_sub_f32_e32 v14, v15, v16
	v_mul_f32_e32 v16, v23, v27
	v_fma_f32 v18, v27, v23, -v16
	v_fmac_f32_e32 v18, v27, v24
	v_sub_f32_e32 v26, v17, v14
	v_add_f32_e32 v14, v16, v18
	v_sub_f32_e32 v17, v15, v14
	v_pk_add_f32 v[20:21], v[14:15], v[16:17] neg_lo:[0,1] neg_hi:[0,1]
	v_mov_b32_e32 v19, v14
	v_pk_add_f32 v[14:15], v[20:21], v[18:19] neg_lo:[0,1] neg_hi:[0,1]
	v_cmp_neq_f32_e32 vcc, s57, v11
	v_add_f32_e32 v15, v26, v15
	v_add_f32_e32 v14, v14, v15
	v_add_f32_e32 v15, v17, v14
	v_mul_f32_e32 v26, v25, v15
	v_mul_f32_e32 v16, v23, v26
	v_fma_f32 v18, v26, v23, -v16
	v_fmac_f32_e32 v18, v26, v24
	v_sub_f32_e32 v17, v17, v15
	v_add_f32_e32 v23, v14, v17
	v_add_f32_e32 v14, v16, v18
	v_sub_f32_e32 v17, v15, v14
	v_pk_add_f32 v[20:21], v[14:15], v[16:17] neg_lo:[0,1] neg_hi:[0,1]
	v_mov_b32_e32 v19, v14
	v_pk_add_f32 v[14:15], v[20:21], v[18:19] neg_lo:[0,1] neg_hi:[0,1]
	s_nop 0
	v_add_f32_e32 v15, v23, v15
	v_add_f32_e32 v14, v14, v15
	v_add_f32_e32 v15, v27, v26
	v_add_f32_e32 v14, v17, v14
	v_sub_f32_e32 v16, v15, v27
	v_mul_f32_e32 v14, v25, v14
	v_sub_f32_e32 v16, v26, v16
	v_add_f32_e32 v16, v16, v14
	v_add_f32_e32 v18, v15, v16
	v_mul_f32_e32 v19, v18, v18
	v_fmamk_f32 v14, v19, 0x3e9b6dac, v235
	v_fmaak_f32 v227, v19, v14, 0x3f2aaada
	v_cvt_f32_i32_e32 v14, v22
	v_sub_f32_e32 v15, v18, v15
	v_sub_f32_e32 v15, v16, v15
	v_ldexp_f32 v20, v15, 1
	v_mul_f32_e32 v15, v18, v19
	v_ldexp_f32 v17, v18, 1
	v_pk_mul_f32 v[18:19], v[14:15], v[226:227]
	s_nop 0
	v_fma_f32 v16, v14, s56, -v18
	v_fmac_f32_e32 v16, 0xb102e308, v14
	v_pk_add_f32 v[14:15], v[18:19], v[16:17]
	s_nop 0
	v_sub_f32_e32 v17, v15, v17
	v_sub_f32_e32 v17, v19, v17
	v_add_f32_e32 v21, v20, v17
	v_mov_b32_e32 v20, v18
	v_pk_add_f32 v[18:19], v[14:15], v[18:19] neg_lo:[0,1] neg_hi:[0,1]
	v_pk_add_f32 v[22:23], v[14:15], v[20:21]
	v_mov_b32_e32 v17, v14
	v_mov_b32_e32 v19, v23
	v_pk_add_f32 v[24:25], v[16:17], v[18:19] neg_lo:[0,1] neg_hi:[0,1]
	v_pk_add_f32 v[16:17], v[16:17], v[18:19]
	v_mov_b32_e32 v20, v21
	v_pk_add_f32 v[18:19], v[16:17], v[14:15] op_sel:[1,0] op_sel_hi:[0,1] neg_lo:[0,1] neg_hi:[0,1]
	v_pk_add_f32 v[26:27], v[22:23], v[18:19] op_sel_hi:[1,0] neg_lo:[0,1] neg_hi:[0,1]
	v_mov_b32_e32 v22, v23
	v_mov_b32_e32 v23, v17
	v_pk_mov_b32 v[18:19], v[14:15], v[18:19] op_sel:[1,0]
	v_mov_b32_e32 v21, v14
	v_pk_add_f32 v[18:19], v[22:23], v[18:19] neg_lo:[0,1] neg_hi:[0,1]
	v_mov_b32_e32 v26, v24
	v_pk_add_f32 v[14:15], v[20:21], v[18:19] neg_lo:[0,1] neg_hi:[0,1]
	v_mov_b32_e32 v25, v17
	v_pk_add_f32 v[18:19], v[26:27], v[14:15]
	s_nop 0
	v_pk_add_f32 v[20:21], v[18:19], v[18:19] op_sel:[0,1] op_sel_hi:[1,0]
	s_nop 0
	v_pk_add_f32 v[16:17], v[16:17], v[20:21] op_sel:[1,0] op_sel_hi:[0,1]
	v_mov_b32_e32 v19, v16
	v_pk_add_f32 v[22:23], v[18:19], v[24:25] neg_lo:[0,1] neg_hi:[0,1]
	v_mov_b32_e32 v15, v20
	v_sub_f32_e32 v17, v18, v22
	v_pk_add_f32 v[14:15], v[14:15], v[22:23] neg_lo:[0,1] neg_hi:[0,1]
	v_sub_f32_e32 v17, v24, v17
	v_add_f32_e32 v14, v14, v17
	v_add_f32_e32 v14, v14, v15
	v_add_f32_e32 v14, v16, v14
	v_cndmask_b32_e32 v14, v236, v14, vcc
	v_cmp_ngt_f32_e32 vcc, -1.0, v11
	s_nop 1
	v_cndmask_b32_e32 v14, v237, v14, vcc
	v_cmp_neq_f32_e32 vcc, -1.0, v11
	s_nop 1
	v_cndmask_b32_e32 v14, v238, v14, vcc
	v_cmp_lt_f32_e64 vcc, |v11|, s58
	s_nop 1
	v_cndmask_b32_e32 v11, v14, v11, vcc
;     __device__ __forceinline__ void operator()(f32x4 (&acc)[2][2][4][2], const Unit& u, int row0t, int wr, int wc, int fr, int fq) const {
;     ...
;                         for (int n = 0; n < 2; ++n) { const f32x4 v = acc[ai][0][m][n]; f32x4 o;
;                             if (fq == 0) {
; #pragma unroll
;                                 for (int e = 0; e < 4; ++e) o[e] = 1.0f / (1.0f + __expf(-v[e])); }
;                             else {
; #pragma unroll
;                                 for (int e = 0; e < 4; ++e) { const int h = 4 * n + e; const float xx = v[e] + dt_bias[h]; const float sp = xx > 20.f ? xx : log1pf(__expf(xx)); o[e] = -__expf(A_log[h]) * sp; } }
;                             *(f32x4*)(bg + (size_t)r * 16 + 8 * fq + 4 * n) = o; } }
.LBB0_352:
	s_or_b64 exec, exec, s[36:37]
	v_mov_b32_e32 v14, v152
	v_mov_b32_e32 v15, v159
	v_add_f32_e32 v12, v12, v14
	v_cmp_nlt_f32_e32 vcc, s53, v12
	s_and_saveexec_b64 s[36:37], vcc
	s_cbranch_execz .LBB0_354
	v_mul_f32_e32 v12, 0x3fb8aa3b, v12
	v_exp_f32_e32 v12, v12
	s_nop 0
	v_add_f32_e32 v14, 1.0, v12
	v_frexp_mant_f32_e32 v19, v14
	v_cvt_f64_f32_e32 v[16:17], v14
	v_add_f32_e32 v18, -1.0, v14
	v_frexp_exp_i32_f64_e32 v16, v[16:17]
	v_cmp_gt_f32_e32 vcc, s55, v19
	v_sub_f32_e32 v20, v18, v14
	v_sub_f32_e32 v18, v12, v18
	v_subbrev_co_u32_e32 v24, vcc, 0, v16, vcc
	v_add_f32_e32 v20, 1.0, v20
	v_sub_u32_e32 v16, 0, v24
	v_add_f32_e32 v18, v18, v20
	v_ldexp_f32 v14, v14, v16
	v_ldexp_f32 v16, v18, v16
	v_add_f32_e32 v18, -1.0, v14
	v_add_f32_e32 v17, 1.0, v18
	v_sub_f32_e32 v17, v14, v17
	v_add_f32_e32 v19, v16, v17
	v_add_f32_e32 v17, 1.0, v14
	v_add_f32_e32 v20, -1.0, v17
	v_sub_f32_e32 v14, v14, v20
	v_add_f32_e32 v14, v16, v14
	v_add_f32_e32 v25, v17, v14
	v_rcp_f32_e32 v26, v25
	v_sub_f32_e32 v16, v25, v17
	v_add_f32_e32 v17, v18, v19
	v_sub_f32_e32 v14, v14, v16
	v_mul_f32_e32 v28, v17, v26
	v_sub_f32_e32 v16, v17, v18
	v_mul_f32_e32 v18, v25, v28
	v_fma_f32 v20, v28, v25, -v18
	v_fmac_f32_e32 v20, v28, v14
	v_sub_f32_e32 v27, v19, v16
	v_add_f32_e32 v16, v18, v20
	v_sub_f32_e32 v19, v17, v16
	v_pk_add_f32 v[22:23], v[16:17], v[18:19] neg_lo:[0,1] neg_hi:[0,1]
	v_mov_b32_e32 v21, v16
	v_pk_add_f32 v[16:17], v[22:23], v[20:21] neg_lo:[0,1] neg_hi:[0,1]
	v_cmp_neq_f32_e32 vcc, s57, v12
	v_add_f32_e32 v17, v27, v17
	v_add_f32_e32 v16, v16, v17
	v_add_f32_e32 v17, v19, v16
	v_mul_f32_e32 v27, v26, v17
	v_mul_f32_e32 v18, v25, v27
	v_fma_f32 v20, v27, v25, -v18
	v_fmac_f32_e32 v20, v27, v14
	v_sub_f32_e32 v14, v19, v17
	v_add_f32_e32 v14, v16, v14
	v_add_f32_e32 v16, v18, v20
	v_sub_f32_e32 v19, v17, v16
	v_pk_add_f32 v[22:23], v[16:17], v[18:19] neg_lo:[0,1] neg_hi:[0,1]
	v_mov_b32_e32 v21, v16
	v_pk_add_f32 v[16:17], v[22:23], v[20:21] neg_lo:[0,1] neg_hi:[0,1]
	s_nop 0
	v_add_f32_e32 v14, v14, v17
	v_add_f32_e32 v14, v16, v14
	v_add_f32_e32 v17, v28, v27
	v_add_f32_e32 v14, v19, v14
	v_sub_f32_e32 v16, v17, v28
	v_mul_f32_e32 v14, v26, v14
	v_sub_f32_e32 v16, v27, v16
	v_add_f32_e32 v14, v16, v14
	v_add_f32_e32 v18, v17, v14
	v_mul_f32_e32 v20, v18, v18
	v_fmamk_f32 v16, v20, 0x3e9b6dac, v235
	v_fmaak_f32 v227, v20, v16, 0x3f2aaada
	v_cvt_f32_i32_e32 v16, v24
	v_sub_f32_e32 v17, v18, v17
	v_sub_f32_e32 v14, v14, v17
	v_mul_f32_e32 v17, v18, v20
	v_pk_mul_f32 v[20:21], v[16:17], v[226:227]
	v_ldexp_f32 v19, v18, 1
	v_fma_f32 v18, v16, s56, -v20
	v_fmac_f32_e32 v18, 0xb102e308, v16
	v_pk_add_f32 v[16:17], v[20:21], v[18:19]
	v_ldexp_f32 v14, v14, 1
	v_sub_f32_e32 v19, v17, v19
	v_sub_f32_e32 v19, v21, v19
	v_add_f32_e32 v23, v14, v19
	v_mov_b32_e32 v22, v20
	v_pk_add_f32 v[20:21], v[16:17], v[20:21] neg_lo:[0,1] neg_hi:[0,1]
	v_pk_add_f32 v[24:25], v[16:17], v[22:23]
	v_mov_b32_e32 v19, v16
	v_mov_b32_e32 v21, v25
	v_pk_add_f32 v[26:27], v[18:19], v[20:21] neg_lo:[0,1] neg_hi:[0,1]
	v_pk_add_f32 v[18:19], v[18:19], v[20:21]
	v_mov_b32_e32 v22, v23
	v_pk_add_f32 v[20:21], v[18:19], v[16:17] op_sel:[1,0] op_sel_hi:[0,1] neg_lo:[0,1] neg_hi:[0,1]
	v_pk_add_f32 v[28:29], v[24:25], v[20:21] op_sel_hi:[1,0] neg_lo:[0,1] neg_hi:[0,1]
	v_mov_b32_e32 v24, v25
	v_mov_b32_e32 v25, v19
	v_pk_mov_b32 v[20:21], v[16:17], v[20:21] op_sel:[1,0]
	v_mov_b32_e32 v23, v16
	v_pk_add_f32 v[20:21], v[24:25], v[20:21] neg_lo:[0,1] neg_hi:[0,1]
	v_mov_b32_e32 v28, v26
	v_pk_add_f32 v[16:17], v[22:23], v[20:21] neg_lo:[0,1] neg_hi:[0,1]
	v_mov_b32_e32 v27, v19
	v_pk_add_f32 v[20:21], v[28:29], v[16:17]
	s_nop 0
	v_pk_add_f32 v[22:23], v[20:21], v[20:21] op_sel:[0,1] op_sel_hi:[1,0]
	s_nop 0
	v_pk_add_f32 v[18:19], v[18:19], v[22:23] op_sel:[1,0] op_sel_hi:[0,1]
	v_mov_b32_e32 v21, v18
	v_pk_add_f32 v[24:25], v[20:21], v[26:27] neg_lo:[0,1] neg_hi:[0,1]
	v_mov_b32_e32 v17, v22
	v_sub_f32_e32 v14, v20, v24
	v_pk_add_f32 v[16:17], v[16:17], v[24:25] neg_lo:[0,1] neg_hi:[0,1]
	v_sub_f32_e32 v14, v26, v14
	v_add_f32_e32 v14, v16, v14
	v_add_f32_e32 v14, v14, v17
	v_add_f32_e32 v14, v18, v14
	v_cndmask_b32_e32 v14, v236, v14, vcc
	v_cmp_ngt_f32_e32 vcc, -1.0, v12
	s_nop 1
	v_cndmask_b32_e32 v14, v237, v14, vcc
	v_cmp_neq_f32_e32 vcc, -1.0, v12
	s_nop 1
	v_cndmask_b32_e32 v14, v238, v14, vcc
	v_cmp_lt_f32_e64 vcc, |v12|, s58
	s_nop 1
	v_cndmask_b32_e32 v12, v14, v12, vcc
;     __device__ __forceinline__ void operator()(f32x4 (&acc)[2][2][4][2], const Unit& u, int row0t, int wr, int wc, int fr, int fq) const {
;     ...
;                         for (int n = 0; n < 2; ++n) { const f32x4 v = acc[ai][0][m][n]; f32x4 o;
;                             if (fq == 0) {
; #pragma unroll
;                                 for (int e = 0; e < 4; ++e) o[e] = 1.0f / (1.0f + __expf(-v[e])); }
;                             else {
; #pragma unroll
;                                 for (int e = 0; e < 4; ++e) { const int h = 4 * n + e; const float xx = v[e] + dt_bias[h]; const float sp = xx > 20.f ? xx : log1pf(__expf(xx)); o[e] = -__expf(A_log[h]) * sp; } }
;                             *(f32x4*)(bg + (size_t)r * 16 + 8 * fq + 4 * n) = o; } }
.LBB0_354:
	s_or_b64 exec, exec, s[36:37]
	v_mov_b32_e32 v14, v153
	v_mov_b32_e32 v16, v160
	v_add_f32_e32 v13, v13, v14
	v_cmp_nlt_f32_e32 vcc, s53, v13
	s_and_saveexec_b64 s[36:37], vcc
	s_cbranch_execz .LBB0_356
	v_mul_f32_e32 v13, 0x3fb8aa3b, v13
	v_exp_f32_e32 v13, v13
	s_nop 0
	v_add_f32_e32 v14, 1.0, v13
	v_frexp_mant_f32_e32 v20, v14
	v_cvt_f64_f32_e32 v[18:19], v14
	v_add_f32_e32 v17, -1.0, v14
	v_frexp_exp_i32_f64_e32 v18, v[18:19]
	v_cmp_gt_f32_e32 vcc, s55, v20
	v_sub_f32_e32 v21, v17, v14
	v_sub_f32_e32 v17, v13, v17
	v_subbrev_co_u32_e32 v26, vcc, 0, v18, vcc
	v_add_f32_e32 v21, 1.0, v21
	v_sub_u32_e32 v18, 0, v26
	v_add_f32_e32 v17, v17, v21
	v_ldexp_f32 v14, v14, v18
	v_ldexp_f32 v17, v17, v18
	v_add_f32_e32 v18, -1.0, v14
	v_add_f32_e32 v19, 1.0, v18
	v_sub_f32_e32 v19, v14, v19
	v_add_f32_e32 v20, v17, v19
	v_add_f32_e32 v19, 1.0, v14
	v_add_f32_e32 v21, -1.0, v19
	v_sub_f32_e32 v14, v14, v21
	v_add_f32_e32 v14, v17, v14
	v_add_f32_e32 v17, v19, v14
	v_rcp_f32_e32 v27, v17
	v_sub_f32_e32 v19, v17, v19
	v_sub_f32_e32 v14, v14, v19
	v_add_f32_e32 v19, v18, v20
	v_sub_f32_e32 v18, v19, v18
	v_mul_f32_e32 v29, v19, v27
	v_sub_f32_e32 v28, v20, v18
	v_mul_f32_e32 v20, v17, v29
	v_fma_f32 v22, v29, v17, -v20
	v_fmac_f32_e32 v22, v29, v14
	v_add_f32_e32 v18, v20, v22
	v_sub_f32_e32 v21, v19, v18
	v_pk_add_f32 v[24:25], v[18:19], v[20:21] neg_lo:[0,1] neg_hi:[0,1]
	v_mov_b32_e32 v23, v18
	v_pk_add_f32 v[18:19], v[24:25], v[22:23] neg_lo:[0,1] neg_hi:[0,1]
	v_cmp_neq_f32_e32 vcc, s57, v13
	v_add_f32_e32 v19, v28, v19
	v_add_f32_e32 v18, v18, v19
	v_add_f32_e32 v19, v21, v18
	v_mul_f32_e32 v28, v27, v19
	v_mul_f32_e32 v20, v17, v28
	v_fma_f32 v22, v28, v17, -v20
	v_fmac_f32_e32 v22, v28, v14
	v_sub_f32_e32 v14, v21, v19
	v_add_f32_e32 v14, v18, v14
	v_add_f32_e32 v18, v20, v22
	v_sub_f32_e32 v21, v19, v18
	v_pk_add_f32 v[24:25], v[18:19], v[20:21] neg_lo:[0,1] neg_hi:[0,1]
	v_mov_b32_e32 v23, v18
	v_pk_add_f32 v[18:19], v[24:25], v[22:23] neg_lo:[0,1] neg_hi:[0,1]
	v_add_f32_e32 v17, v29, v28
	v_add_f32_e32 v14, v14, v19
	v_add_f32_e32 v14, v18, v14
	v_add_f32_e32 v14, v21, v14
	v_sub_f32_e32 v18, v17, v29
	v_mul_f32_e32 v14, v27, v14
	v_sub_f32_e32 v18, v28, v18
	v_add_f32_e32 v14, v18, v14
	v_add_f32_e32 v19, v17, v14
	v_mul_f32_e32 v20, v19, v19
	v_fmamk_f32 v18, v20, 0x3e9b6dac, v235
	v_fmaak_f32 v227, v20, v18, 0x3f2aaada
	v_cvt_f32_i32_e32 v18, v26
	v_sub_f32_e32 v17, v19, v17
	v_ldexp_f32 v21, v19, 1
	v_mul_f32_e32 v19, v19, v20
	v_pk_mul_f32 v[22:23], v[18:19], v[226:227]
	v_sub_f32_e32 v14, v14, v17
	v_fma_f32 v20, v18, s56, -v22
	v_fmac_f32_e32 v20, 0xb102e308, v18
	v_pk_add_f32 v[18:19], v[22:23], v[20:21]
	v_ldexp_f32 v14, v14, 1
	v_sub_f32_e32 v17, v19, v21
	v_sub_f32_e32 v17, v23, v17
	v_add_f32_e32 v25, v14, v17
	v_mov_b32_e32 v24, v22
	v_pk_add_f32 v[22:23], v[18:19], v[22:23] neg_lo:[0,1] neg_hi:[0,1]
	v_pk_add_f32 v[26:27], v[18:19], v[24:25]
	v_mov_b32_e32 v21, v18
	v_mov_b32_e32 v23, v27
	v_pk_add_f32 v[28:29], v[20:21], v[22:23] neg_lo:[0,1] neg_hi:[0,1]
	v_pk_add_f32 v[20:21], v[20:21], v[22:23]
	v_mov_b32_e32 v24, v25
	v_pk_add_f32 v[22:23], v[20:21], v[18:19] op_sel:[1,0] op_sel_hi:[0,1] neg_lo:[0,1] neg_hi:[0,1]
	v_pk_add_f32 v[30:31], v[26:27], v[22:23] op_sel_hi:[1,0] neg_lo:[0,1] neg_hi:[0,1]
	v_mov_b32_e32 v26, v27
	v_mov_b32_e32 v27, v21
	v_pk_mov_b32 v[22:23], v[18:19], v[22:23] op_sel:[1,0]
	v_mov_b32_e32 v25, v18
	v_pk_add_f32 v[22:23], v[26:27], v[22:23] neg_lo:[0,1] neg_hi:[0,1]
	v_mov_b32_e32 v30, v28
	v_pk_add_f32 v[18:19], v[24:25], v[22:23] neg_lo:[0,1] neg_hi:[0,1]
	v_mov_b32_e32 v29, v21
	v_pk_add_f32 v[22:23], v[30:31], v[18:19]
	s_nop 0
	v_pk_add_f32 v[24:25], v[22:23], v[22:23] op_sel:[0,1] op_sel_hi:[1,0]
	s_nop 0
	v_pk_add_f32 v[20:21], v[20:21], v[24:25] op_sel:[1,0] op_sel_hi:[0,1]
	v_mov_b32_e32 v23, v20
	v_pk_add_f32 v[26:27], v[22:23], v[28:29] neg_lo:[0,1] neg_hi:[0,1]
	v_mov_b32_e32 v19, v24
	v_sub_f32_e32 v14, v22, v26
	v_pk_add_f32 v[18:19], v[18:19], v[26:27] neg_lo:[0,1] neg_hi:[0,1]
	v_sub_f32_e32 v14, v28, v14
	v_add_f32_e32 v14, v18, v14
	v_add_f32_e32 v14, v14, v19
	v_add_f32_e32 v14, v20, v14
	v_cndmask_b32_e32 v14, v236, v14, vcc
	v_cmp_ngt_f32_e32 vcc, -1.0, v13
	s_nop 1
	v_cndmask_b32_e32 v14, v237, v14, vcc
	v_cmp_neq_f32_e32 vcc, -1.0, v13
	s_nop 1
	v_cndmask_b32_e32 v14, v238, v14, vcc
	v_cmp_lt_f32_e64 vcc, |v13|, s58
	s_nop 1
	v_cndmask_b32_e32 v13, v14, v13, vcc
.LBB0_356:
	s_or_b64 exec, exec, s[36:37]
	v_mul_f32_e32 v10, 0x3fb8aa3b, v10
	v_exp_f32_e32 v10, v10
	s_nop 0
	v_mul_f32_e64 v14, v3, -v10
	v_mul_f32_e32 v3, 0x3fb8aa3b, v15
	v_exp_f32_e32 v3, v3
	s_nop 0
	v_mul_f32_e64 v15, v11, -v3
	v_mul_f32_e32 v3, 0x3fb8aa3b, v16
	v_exp_f32_e32 v3, v3
	s_nop 0
	v_mul_f32_e64 v16, v12, -v3
	v_mov_b32_e32 v3, v161
	v_mul_f32_e32 v3, 0x3fb8aa3b, v3
	v_exp_f32_e32 v3, v3
	s_nop 0
	v_mul_f32_e64 v17, v13, -v3

;     __device__ __forceinline__ void operator()(f32x4 (&acc)[2][2][4][2], const Unit& u, int row0t, int wr, int wc, int fr, int fq) const {
;     ...
;                         for (int n = 0; n < 2; ++n) { const f32x4 v = acc[ai][0][m][n]; f32x4 o;
;                             if (fq == 0) {
; #pragma unroll
;                                 for (int e = 0; e < 4; ++e) o[e] = 1.0f / (1.0f + __expf(-v[e])); }
;                             else {
; #pragma unroll
;                                 for (int e = 0; e < 4; ++e) { const int h = 4 * n + e; const float xx = v[e] + dt_bias[h]; const float sp = xx > 20.f ? xx : log1pf(__expf(xx)); o[e] = -__expf(A_log[h]) * sp; } }
;                             *(f32x4*)(bg + (size_t)r * 16 + 8 * fq + 4 * n) = o; } }
.LBB0_359:
	s_or_b64 exec, exec, s[24:25]
	v_lshlrev_b64 v[4:5], 6, v[4:5]
	v_lshl_add_u64 v[4:5], v[214:215], 0, v[4:5]
	v_add_co_u32_e32 v10, vcc, 0x2000, v4
	s_nop 1
	v_addc_co_u32_e32 v11, vcc, 0, v5, vcc
	global_store_dwordx4 v[10:11], v[14:17], off offset:3072
	s_and_saveexec_b64 s[2:3], s[4:5]
	s_xor_b64 s[24:25], exec, s[2:3]
	s_cbranch_execz .LBB0_369
	v_mov_b32_e32 v3, v154
	v_add_f32_e32 v3, v6, v3
	v_cmp_nlt_f32_e32 vcc, s53, v3
	s_and_saveexec_b64 s[36:37], vcc
	s_cbranch_execz .LBB0_362
	v_mul_f32_e32 v3, 0x3fb8aa3b, v3
	v_exp_f32_e32 v3, v3
	s_nop 0
	v_add_f32_e32 v6, 1.0, v3
	v_frexp_mant_f32_e32 v13, v6
	v_cvt_f64_f32_e32 v[10:11], v6
	v_add_f32_e32 v12, -1.0, v6
	v_frexp_exp_i32_f64_e32 v10, v[10:11]
	v_cmp_gt_f32_e32 vcc, s55, v13
	v_sub_f32_e32 v14, v12, v6
	v_sub_f32_e32 v12, v3, v12
	v_subbrev_co_u32_e32 v18, vcc, 0, v10, vcc
	v_add_f32_e32 v14, 1.0, v14
	v_sub_u32_e32 v10, 0, v18
	v_add_f32_e32 v12, v12, v14
	v_ldexp_f32 v6, v6, v10
	v_ldexp_f32 v10, v12, v10
	v_add_f32_e32 v12, -1.0, v6
	v_add_f32_e32 v11, 1.0, v12
	v_sub_f32_e32 v11, v6, v11
	v_add_f32_e32 v13, v10, v11
	v_add_f32_e32 v11, 1.0, v6
	v_add_f32_e32 v14, -1.0, v11
	v_sub_f32_e32 v6, v6, v14
	v_add_f32_e32 v6, v10, v6
	v_add_f32_e32 v19, v11, v6
	v_rcp_f32_e32 v20, v19
	v_sub_f32_e32 v10, v19, v11
	v_add_f32_e32 v11, v12, v13
	v_sub_f32_e32 v6, v6, v10
	v_mul_f32_e32 v22, v11, v20
	v_sub_f32_e32 v10, v11, v12
	v_mul_f32_e32 v12, v19, v22
	v_fma_f32 v14, v22, v19, -v12
	v_fmac_f32_e32 v14, v22, v6
	v_sub_f32_e32 v21, v13, v10
	v_add_f32_e32 v10, v12, v14
	v_sub_f32_e32 v13, v11, v10
	v_pk_add_f32 v[16:17], v[10:11], v[12:13] neg_lo:[0,1] neg_hi:[0,1]
	v_mov_b32_e32 v15, v10
	v_pk_add_f32 v[10:11], v[16:17], v[14:15] neg_lo:[0,1] neg_hi:[0,1]
	v_cmp_neq_f32_e32 vcc, s57, v3
	v_add_f32_e32 v11, v21, v11
	v_add_f32_e32 v10, v10, v11
	v_add_f32_e32 v11, v13, v10
	v_mul_f32_e32 v21, v20, v11
	v_mul_f32_e32 v12, v19, v21
	v_fma_f32 v14, v21, v19, -v12
	v_fmac_f32_e32 v14, v21, v6
	v_sub_f32_e32 v6, v13, v11
	v_add_f32_e32 v6, v10, v6
	v_add_f32_e32 v10, v12, v14
	v_sub_f32_e32 v13, v11, v10
	v_pk_add_f32 v[16:17], v[10:11], v[12:13] neg_lo:[0,1] neg_hi:[0,1]
	v_mov_b32_e32 v15, v10
	v_pk_add_f32 v[10:11], v[16:17], v[14:15] neg_lo:[0,1] neg_hi:[0,1]
	s_nop 0
	v_add_f32_e32 v6, v6, v11
	v_add_f32_e32 v6, v10, v6
	v_add_f32_e32 v11, v22, v21
	v_add_f32_e32 v6, v13, v6
	v_sub_f32_e32 v10, v11, v22
	v_mul_f32_e32 v6, v20, v6
	v_sub_f32_e32 v10, v21, v10
	v_add_f32_e32 v6, v10, v6
	v_add_f32_e32 v12, v11, v6
	v_mul_f32_e32 v14, v12, v12
	v_fmamk_f32 v10, v14, 0x3e9b6dac, v235
	v_fmaak_f32 v227, v14, v10, 0x3f2aaada
	v_cvt_f32_i32_e32 v10, v18
	v_sub_f32_e32 v11, v12, v11
	v_sub_f32_e32 v6, v6, v11
	v_mul_f32_e32 v11, v12, v14
	v_pk_mul_f32 v[14:15], v[10:11], v[226:227]
	v_ldexp_f32 v13, v12, 1
	v_fma_f32 v12, v10, s56, -v14
	v_fmac_f32_e32 v12, 0xb102e308, v10
	v_pk_add_f32 v[10:11], v[14:15], v[12:13]
	v_ldexp_f32 v6, v6, 1
	v_sub_f32_e32 v13, v11, v13
	v_sub_f32_e32 v13, v15, v13
	v_add_f32_e32 v17, v6, v13
	v_mov_b32_e32 v16, v14
	v_pk_add_f32 v[14:15], v[10:11], v[14:15] neg_lo:[0,1] neg_hi:[0,1]
	v_pk_add_f32 v[18:19], v[10:11], v[16:17]
	v_mov_b32_e32 v13, v10
	v_mov_b32_e32 v15, v19
	v_pk_add_f32 v[20:21], v[12:13], v[14:15] neg_lo:[0,1] neg_hi:[0,1]
	v_pk_add_f32 v[12:13], v[12:13], v[14:15]
	v_mov_b32_e32 v16, v17
	v_pk_add_f32 v[14:15], v[12:13], v[10:11] op_sel:[1,0] op_sel_hi:[0,1] neg_lo:[0,1] neg_hi:[0,1]
	v_pk_add_f32 v[22:23], v[18:19], v[14:15] op_sel_hi:[1,0] neg_lo:[0,1] neg_hi:[0,1]
	v_mov_b32_e32 v18, v19
	v_mov_b32_e32 v19, v13
	v_pk_mov_b32 v[14:15], v[10:11], v[14:15] op_sel:[1,0]
	v_mov_b32_e32 v17, v10
	v_pk_add_f32 v[14:15], v[18:19], v[14:15] neg_lo:[0,1] neg_hi:[0,1]
	v_mov_b32_e32 v22, v20
	v_pk_add_f32 v[10:11], v[16:17], v[14:15] neg_lo:[0,1] neg_hi:[0,1]
	v_mov_b32_e32 v21, v13
	v_pk_add_f32 v[14:15], v[22:23], v[10:11]
	s_nop 0
	v_pk_add_f32 v[16:17], v[14:15], v[14:15] op_sel:[0,1] op_sel_hi:[1,0]
	s_nop 0
	v_pk_add_f32 v[12:13], v[12:13], v[16:17] op_sel:[1,0] op_sel_hi:[0,1]
	v_mov_b32_e32 v15, v12
	v_pk_add_f32 v[18:19], v[14:15], v[20:21] neg_lo:[0,1] neg_hi:[0,1]
	v_mov_b32_e32 v11, v16
	v_sub_f32_e32 v6, v14, v18
	v_pk_add_f32 v[10:11], v[10:11], v[18:19] neg_lo:[0,1] neg_hi:[0,1]
	v_sub_f32_e32 v6, v20, v6
	v_add_f32_e32 v6, v10, v6
	v_add_f32_e32 v6, v6, v11
	v_add_f32_e32 v6, v12, v6
	v_cndmask_b32_e32 v6, v236, v6, vcc
	v_cmp_ngt_f32_e32 vcc, -1.0, v3
	s_nop 1
	v_cndmask_b32_e32 v6, v237, v6, vcc
	v_cmp_neq_f32_e32 vcc, -1.0, v3
	s_nop 1
	v_cndmask_b32_e32 v6, v238, v6, vcc
	v_cmp_lt_f32_e64 vcc, |v3|, s58
	s_nop 1
	v_cndmask_b32_e32 v3, v6, v3, vcc
;     __device__ __forceinline__ void operator()(f32x4 (&acc)[2][2][4][2], const Unit& u, int row0t, int wr, int wc, int fr, int fq) const {
;     ...
;                         for (int n = 0; n < 2; ++n) { const f32x4 v = acc[ai][0][m][n]; f32x4 o;
;                             if (fq == 0) {
; #pragma unroll
;                                 for (int e = 0; e < 4; ++e) o[e] = 1.0f / (1.0f + __expf(-v[e])); }
;                             else {
; #pragma unroll
;                                 for (int e = 0; e < 4; ++e) { const int h = 4 * n + e; const float xx = v[e] + dt_bias[h]; const float sp = xx > 20.f ? xx : log1pf(__expf(xx)); o[e] = -__expf(A_log[h]) * sp; } }
;                             *(f32x4*)(bg + (size_t)r * 16 + 8 * fq + 4 * n) = o; } }
.LBB0_362:
	s_or_b64 exec, exec, s[36:37]
	v_mov_b32_e32 v10, v155
	v_mov_b32_e32 v6, v162
	v_add_f32_e32 v7, v7, v10
	v_cmp_nlt_f32_e32 vcc, s53, v7
	s_and_saveexec_b64 s[36:37], vcc
	s_cbranch_execz .LBB0_364
	v_mul_f32_e32 v7, 0x3fb8aa3b, v7
	v_exp_f32_e32 v7, v7
	s_nop 0
	v_add_f32_e32 v12, 1.0, v7
	v_frexp_mant_f32_e32 v14, v12
	v_cvt_f64_f32_e32 v[10:11], v12
	v_frexp_exp_i32_f64_e32 v10, v[10:11]
	v_cmp_gt_f32_e32 vcc, s55, v14
	v_add_f32_e32 v13, -1.0, v12
	v_sub_f32_e32 v15, v13, v12
	v_subbrev_co_u32_e32 v18, vcc, 0, v10, vcc
	v_sub_u32_e32 v10, 0, v18
	v_sub_f32_e32 v13, v7, v13
	v_add_f32_e32 v15, 1.0, v15
	v_ldexp_f32 v11, v12, v10
	v_add_f32_e32 v13, v13, v15
	v_add_f32_e32 v12, -1.0, v11
	v_add_f32_e32 v14, 1.0, v11
	v_ldexp_f32 v10, v13, v10
	v_add_f32_e32 v13, 1.0, v12
	v_add_f32_e32 v15, -1.0, v14
	v_sub_f32_e32 v13, v11, v13
	v_sub_f32_e32 v11, v11, v15
	v_add_f32_e32 v13, v10, v13
	v_add_f32_e32 v10, v10, v11
	v_add_f32_e32 v19, v14, v10
	v_rcp_f32_e32 v21, v19
	v_sub_f32_e32 v11, v19, v14
	v_sub_f32_e32 v20, v10, v11
	v_add_f32_e32 v11, v12, v13
	v_mul_f32_e32 v23, v11, v21
	v_sub_f32_e32 v10, v11, v12
	v_mul_f32_e32 v12, v19, v23
	v_fma_f32 v14, v23, v19, -v12
	v_fmac_f32_e32 v14, v23, v20
	v_sub_f32_e32 v22, v13, v10
	v_add_f32_e32 v10, v12, v14
	v_sub_f32_e32 v13, v11, v10
	v_pk_add_f32 v[16:17], v[10:11], v[12:13] neg_lo:[0,1] neg_hi:[0,1]
	v_mov_b32_e32 v15, v10
	v_pk_add_f32 v[10:11], v[16:17], v[14:15] neg_lo:[0,1] neg_hi:[0,1]
	v_cmp_neq_f32_e32 vcc, s57, v7
	v_add_f32_e32 v11, v22, v11
	v_add_f32_e32 v10, v10, v11
	v_add_f32_e32 v11, v13, v10
	v_mul_f32_e32 v22, v21, v11
	v_mul_f32_e32 v12, v19, v22
	v_fma_f32 v14, v22, v19, -v12
	v_fmac_f32_e32 v14, v22, v20
	v_sub_f32_e32 v13, v13, v11
	v_add_f32_e32 v19, v10, v13
	v_add_f32_e32 v10, v12, v14
	v_sub_f32_e32 v13, v11, v10
	v_pk_add_f32 v[16:17], v[10:11], v[12:13] neg_lo:[0,1] neg_hi:[0,1]
	v_mov_b32_e32 v15, v10
	v_pk_add_f32 v[10:11], v[16:17], v[14:15] neg_lo:[0,1] neg_hi:[0,1]
	s_nop 0
	v_add_f32_e32 v11, v19, v11
	v_add_f32_e32 v10, v10, v11
	v_add_f32_e32 v11, v23, v22
	v_add_f32_e32 v10, v13, v10
	v_sub_f32_e32 v12, v11, v23
	v_mul_f32_e32 v10, v21, v10
	v_sub_f32_e32 v12, v22, v12
	v_add_f32_e32 v12, v12, v10
	v_add_f32_e32 v14, v11, v12
	v_mul_f32_e32 v15, v14, v14
	v_fmamk_f32 v10, v15, 0x3e9b6dac, v235
	v_fmaak_f32 v227, v15, v10, 0x3f2aaada
	v_cvt_f32_i32_e32 v10, v18
	v_sub_f32_e32 v11, v14, v11
	v_sub_f32_e32 v11, v12, v11
	v_ldexp_f32 v16, v11, 1
	v_mul_f32_e32 v11, v14, v15
	v_ldexp_f32 v13, v14, 1
	v_pk_mul_f32 v[14:15], v[10:11], v[226:227]
	s_nop 0
	v_fma_f32 v12, v10, s56, -v14
	v_fmac_f32_e32 v12, 0xb102e308, v10
	v_pk_add_f32 v[10:11], v[14:15], v[12:13]
	s_nop 0
	v_sub_f32_e32 v13, v11, v13
	v_sub_f32_e32 v13, v15, v13
	v_add_f32_e32 v17, v16, v13
	v_mov_b32_e32 v16, v14
	v_pk_add_f32 v[14:15], v[10:11], v[14:15] neg_lo:[0,1] neg_hi:[0,1]
	v_pk_add_f32 v[18:19], v[10:11], v[16:17]
	v_mov_b32_e32 v13, v10
	v_mov_b32_e32 v15, v19
	v_pk_add_f32 v[20:21], v[12:13], v[14:15] neg_lo:[0,1] neg_hi:[0,1]
	v_pk_add_f32 v[12:13], v[12:13], v[14:15]
	v_mov_b32_e32 v16, v17
	v_pk_add_f32 v[14:15], v[12:13], v[10:11] op_sel:[1,0] op_sel_hi:[0,1] neg_lo:[0,1] neg_hi:[0,1]
	v_pk_add_f32 v[22:23], v[18:19], v[14:15] op_sel_hi:[1,0] neg_lo:[0,1] neg_hi:[0,1]
	v_mov_b32_e32 v18, v19
	v_mov_b32_e32 v19, v13
	v_pk_mov_b32 v[14:15], v[10:11], v[14:15] op_sel:[1,0]
	v_mov_b32_e32 v17, v10
	v_pk_add_f32 v[14:15], v[18:19], v[14:15] neg_lo:[0,1] neg_hi:[0,1]
	v_mov_b32_e32 v22, v20
	v_pk_add_f32 v[10:11], v[16:17], v[14:15] neg_lo:[0,1] neg_hi:[0,1]
	v_mov_b32_e32 v21, v13
	v_pk_add_f32 v[14:15], v[22:23], v[10:11]
	s_nop 0
	v_pk_add_f32 v[16:17], v[14:15], v[14:15] op_sel:[0,1] op_sel_hi:[1,0]
	s_nop 0
	v_pk_add_f32 v[12:13], v[12:13], v[16:17] op_sel:[1,0] op_sel_hi:[0,1]
	v_mov_b32_e32 v15, v12
	v_pk_add_f32 v[18:19], v[14:15], v[20:21] neg_lo:[0,1] neg_hi:[0,1]
	v_mov_b32_e32 v11, v16
	v_sub_f32_e32 v13, v14, v18
	v_pk_add_f32 v[10:11], v[10:11], v[18:19] neg_lo:[0,1] neg_hi:[0,1]
	v_sub_f32_e32 v13, v20, v13
	v_add_f32_e32 v10, v10, v13
	v_add_f32_e32 v10, v10, v11
	v_add_f32_e32 v10, v12, v10
	v_cndmask_b32_e32 v10, v236, v10, vcc
	v_cmp_ngt_f32_e32 vcc, -1.0, v7
	s_nop 1
	v_cndmask_b32_e32 v10, v237, v10, vcc
	v_cmp_neq_f32_e32 vcc, -1.0, v7
	s_nop 1
	v_cndmask_b32_e32 v10, v238, v10, vcc
	v_cmp_lt_f32_e64 vcc, |v7|, s58
	s_nop 1
	v_cndmask_b32_e32 v7, v10, v7, vcc
;     __device__ __forceinline__ void operator()(f32x4 (&acc)[2][2][4][2], const Unit& u, int row0t, int wr, int wc, int fr, int fq) const {
;     ...
;                         for (int n = 0; n < 2; ++n) { const f32x4 v = acc[ai][0][m][n]; f32x4 o;
;                             if (fq == 0) {
; #pragma unroll
;                                 for (int e = 0; e < 4; ++e) o[e] = 1.0f / (1.0f + __expf(-v[e])); }
;                             else {
; #pragma unroll
;                                 for (int e = 0; e < 4; ++e) { const int h = 4 * n + e; const float xx = v[e] + dt_bias[h]; const float sp = xx > 20.f ? xx : log1pf(__expf(xx)); o[e] = -__expf(A_log[h]) * sp; } }
;                             *(f32x4*)(bg + (size_t)r * 16 + 8 * fq + 4 * n) = o; } }
.LBB0_364:
	s_or_b64 exec, exec, s[36:37]
	v_mov_b32_e32 v10, v156
	v_mov_b32_e32 v11, v163
	v_add_f32_e32 v8, v8, v10
	v_cmp_nlt_f32_e32 vcc, s53, v8
	s_and_saveexec_b64 s[36:37], vcc
	s_cbranch_execz .LBB0_366
	v_mul_f32_e32 v8, 0x3fb8aa3b, v8
	v_exp_f32_e32 v8, v8
	s_nop 0
	v_add_f32_e32 v10, 1.0, v8
	v_frexp_mant_f32_e32 v15, v10
	v_cvt_f64_f32_e32 v[12:13], v10
	v_add_f32_e32 v14, -1.0, v10
	v_frexp_exp_i32_f64_e32 v12, v[12:13]
	v_cmp_gt_f32_e32 vcc, s55, v15
	v_sub_f32_e32 v16, v14, v10
	v_sub_f32_e32 v14, v8, v14
	v_subbrev_co_u32_e32 v20, vcc, 0, v12, vcc
	v_add_f32_e32 v16, 1.0, v16
	v_sub_u32_e32 v12, 0, v20
	v_add_f32_e32 v14, v14, v16
	v_ldexp_f32 v10, v10, v12
	v_ldexp_f32 v12, v14, v12
	v_add_f32_e32 v14, -1.0, v10
	v_add_f32_e32 v13, 1.0, v14
	v_sub_f32_e32 v13, v10, v13
	v_add_f32_e32 v15, v12, v13
	v_add_f32_e32 v13, 1.0, v10
	v_add_f32_e32 v16, -1.0, v13
	v_sub_f32_e32 v10, v10, v16
	v_add_f32_e32 v10, v12, v10
	v_add_f32_e32 v21, v13, v10
	v_rcp_f32_e32 v22, v21
	v_sub_f32_e32 v12, v21, v13
	v_add_f32_e32 v13, v14, v15
	v_sub_f32_e32 v10, v10, v12
	v_mul_f32_e32 v24, v13, v22
	v_sub_f32_e32 v12, v13, v14
	v_mul_f32_e32 v14, v21, v24
	v_fma_f32 v16, v24, v21, -v14
	v_fmac_f32_e32 v16, v24, v10
	v_sub_f32_e32 v23, v15, v12
	v_add_f32_e32 v12, v14, v16
	v_sub_f32_e32 v15, v13, v12
	v_pk_add_f32 v[18:19], v[12:13], v[14:15] neg_lo:[0,1] neg_hi:[0,1]
	v_mov_b32_e32 v17, v12
	v_pk_add_f32 v[12:13], v[18:19], v[16:17] neg_lo:[0,1] neg_hi:[0,1]
	v_cmp_neq_f32_e32 vcc, s57, v8
	v_add_f32_e32 v13, v23, v13
	v_add_f32_e32 v12, v12, v13
	v_add_f32_e32 v13, v15, v12
	v_mul_f32_e32 v23, v22, v13
	v_mul_f32_e32 v14, v21, v23
	v_fma_f32 v16, v23, v21, -v14
	v_fmac_f32_e32 v16, v23, v10
	v_sub_f32_e32 v10, v15, v13
	v_add_f32_e32 v10, v12, v10
	v_add_f32_e32 v12, v14, v16
	v_sub_f32_e32 v15, v13, v12
	v_pk_add_f32 v[18:19], v[12:13], v[14:15] neg_lo:[0,1] neg_hi:[0,1]
	v_mov_b32_e32 v17, v12
	v_pk_add_f32 v[12:13], v[18:19], v[16:17] neg_lo:[0,1] neg_hi:[0,1]
	s_nop 0
	v_add_f32_e32 v10, v10, v13
	v_add_f32_e32 v10, v12, v10
	v_add_f32_e32 v13, v24, v23
	v_add_f32_e32 v10, v15, v10
	v_sub_f32_e32 v12, v13, v24
	v_mul_f32_e32 v10, v22, v10
	v_sub_f32_e32 v12, v23, v12
	v_add_f32_e32 v10, v12, v10
	v_add_f32_e32 v14, v13, v10
	v_mul_f32_e32 v16, v14, v14
	v_fmamk_f32 v12, v16, 0x3e9b6dac, v235
	v_fmaak_f32 v227, v16, v12, 0x3f2aaada
	v_cvt_f32_i32_e32 v12, v20
	v_sub_f32_e32 v13, v14, v13
	v_sub_f32_e32 v10, v10, v13
	v_mul_f32_e32 v13, v14, v16
	v_pk_mul_f32 v[16:17], v[12:13], v[226:227]
	v_ldexp_f32 v15, v14, 1
	v_fma_f32 v14, v12, s56, -v16
	v_fmac_f32_e32 v14, 0xb102e308, v12
	v_pk_add_f32 v[12:13], v[16:17], v[14:15]
	v_ldexp_f32 v10, v10, 1
	v_sub_f32_e32 v15, v13, v15
	v_sub_f32_e32 v15, v17, v15
	v_add_f32_e32 v19, v10, v15
	v_mov_b32_e32 v18, v16
	v_pk_add_f32 v[16:17], v[12:13], v[16:17] neg_lo:[0,1] neg_hi:[0,1]
	v_pk_add_f32 v[20:21], v[12:13], v[18:19]
	v_mov_b32_e32 v15, v12
	v_mov_b32_e32 v17, v21
	v_pk_add_f32 v[22:23], v[14:15], v[16:17] neg_lo:[0,1] neg_hi:[0,1]
	v_pk_add_f32 v[14:15], v[14:15], v[16:17]
	v_mov_b32_e32 v18, v19
	v_pk_add_f32 v[16:17], v[14:15], v[12:13] op_sel:[1,0] op_sel_hi:[0,1] neg_lo:[0,1] neg_hi:[0,1]
	v_pk_add_f32 v[24:25], v[20:21], v[16:17] op_sel_hi:[1,0] neg_lo:[0,1] neg_hi:[0,1]
	v_mov_b32_e32 v20, v21
	v_mov_b32_e32 v21, v15
	v_pk_mov_b32 v[16:17], v[12:13], v[16:17] op_sel:[1,0]
	v_mov_b32_e32 v19, v12
	v_pk_add_f32 v[16:17], v[20:21], v[16:17] neg_lo:[0,1] neg_hi:[0,1]
	v_mov_b32_e32 v24, v22
	v_pk_add_f32 v[12:13], v[18:19], v[16:17] neg_lo:[0,1] neg_hi:[0,1]
	v_mov_b32_e32 v23, v15
	v_pk_add_f32 v[16:17], v[24:25], v[12:13]
	s_nop 0
	v_pk_add_f32 v[18:19], v[16:17], v[16:17] op_sel:[0,1] op_sel_hi:[1,0]
	s_nop 0
	v_pk_add_f32 v[14:15], v[14:15], v[18:19] op_sel:[1,0] op_sel_hi:[0,1]
	v_mov_b32_e32 v17, v14
	v_pk_add_f32 v[20:21], v[16:17], v[22:23] neg_lo:[0,1] neg_hi:[0,1]
	v_mov_b32_e32 v13, v18
	v_sub_f32_e32 v10, v16, v20
	v_pk_add_f32 v[12:13], v[12:13], v[20:21] neg_lo:[0,1] neg_hi:[0,1]
	v_sub_f32_e32 v10, v22, v10
	v_add_f32_e32 v10, v12, v10
	v_add_f32_e32 v10, v10, v13
	v_add_f32_e32 v10, v14, v10
	v_cndmask_b32_e32 v10, v236, v10, vcc
	v_cmp_ngt_f32_e32 vcc, -1.0, v8
	s_nop 1
	v_cndmask_b32_e32 v10, v237, v10, vcc
	v_cmp_neq_f32_e32 vcc, -1.0, v8
	s_nop 1
	v_cndmask_b32_e32 v10, v238, v10, vcc
	v_cmp_lt_f32_e64 vcc, |v8|, s58
	s_nop 1
	v_cndmask_b32_e32 v8, v10, v8, vcc
;     __device__ __forceinline__ void operator()(f32x4 (&acc)[2][2][4][2], const Unit& u, int row0t, int wr, int wc, int fr, int fq) const {
;     ...
;                         for (int n = 0; n < 2; ++n) { const f32x4 v = acc[ai][0][m][n]; f32x4 o;
;                             if (fq == 0) {
; #pragma unroll
;                                 for (int e = 0; e < 4; ++e) o[e] = 1.0f / (1.0f + __expf(-v[e])); }
;                             else {
; #pragma unroll
;                                 for (int e = 0; e < 4; ++e) { const int h = 4 * n + e; const float xx = v[e] + dt_bias[h]; const float sp = xx > 20.f ? xx : log1pf(__expf(xx)); o[e] = -__expf(A_log[h]) * sp; } }
;                             *(f32x4*)(bg + (size_t)r * 16 + 8 * fq + 4 * n) = o; } }
.LBB0_366:
	s_or_b64 exec, exec, s[36:37]
	v_mov_b32_e32 v10, v157
	v_mov_b32_e32 v12, v164
	v_add_f32_e32 v9, v9, v10
	v_cmp_nlt_f32_e32 vcc, s53, v9
	s_and_saveexec_b64 s[36:37], vcc
	s_cbranch_execz .LBB0_368
	v_mul_f32_e32 v9, 0x3fb8aa3b, v9
	v_exp_f32_e32 v9, v9
	s_nop 0
	v_add_f32_e32 v10, 1.0, v9
	v_frexp_mant_f32_e32 v16, v10
	v_cvt_f64_f32_e32 v[14:15], v10
	v_add_f32_e32 v13, -1.0, v10
	v_frexp_exp_i32_f64_e32 v14, v[14:15]
	v_cmp_gt_f32_e32 vcc, s55, v16
	v_sub_f32_e32 v17, v13, v10
	v_sub_f32_e32 v13, v9, v13
	v_subbrev_co_u32_e32 v22, vcc, 0, v14, vcc
	v_add_f32_e32 v17, 1.0, v17
	v_sub_u32_e32 v14, 0, v22
	v_add_f32_e32 v13, v13, v17
	v_ldexp_f32 v10, v10, v14
	v_ldexp_f32 v13, v13, v14
	v_add_f32_e32 v14, -1.0, v10
	v_add_f32_e32 v15, 1.0, v14
	v_sub_f32_e32 v15, v10, v15
	v_add_f32_e32 v16, v13, v15
	v_add_f32_e32 v15, 1.0, v10
	v_add_f32_e32 v17, -1.0, v15
	v_sub_f32_e32 v10, v10, v17
	v_add_f32_e32 v10, v13, v10
	v_add_f32_e32 v13, v15, v10
	v_rcp_f32_e32 v23, v13
	v_sub_f32_e32 v15, v13, v15
	v_sub_f32_e32 v10, v10, v15
	v_add_f32_e32 v15, v14, v16
	v_sub_f32_e32 v14, v15, v14
	v_mul_f32_e32 v25, v15, v23
	v_sub_f32_e32 v24, v16, v14
	v_mul_f32_e32 v16, v13, v25
	v_fma_f32 v18, v25, v13, -v16
	v_fmac_f32_e32 v18, v25, v10
	v_add_f32_e32 v14, v16, v18
	v_sub_f32_e32 v17, v15, v14
	v_pk_add_f32 v[20:21], v[14:15], v[16:17] neg_lo:[0,1] neg_hi:[0,1]
	v_mov_b32_e32 v19, v14
	v_pk_add_f32 v[14:15], v[20:21], v[18:19] neg_lo:[0,1] neg_hi:[0,1]
	v_cmp_neq_f32_e32 vcc, s57, v9
	v_add_f32_e32 v15, v24, v15
	v_add_f32_e32 v14, v14, v15
	v_add_f32_e32 v15, v17, v14
	v_mul_f32_e32 v24, v23, v15
	v_mul_f32_e32 v16, v13, v24
	v_fma_f32 v18, v24, v13, -v16
	v_fmac_f32_e32 v18, v24, v10
	v_sub_f32_e32 v10, v17, v15
	v_add_f32_e32 v10, v14, v10
	v_add_f32_e32 v14, v16, v18
	v_sub_f32_e32 v17, v15, v14
	v_pk_add_f32 v[20:21], v[14:15], v[16:17] neg_lo:[0,1] neg_hi:[0,1]
	v_mov_b32_e32 v19, v14
	v_pk_add_f32 v[14:15], v[20:21], v[18:19] neg_lo:[0,1] neg_hi:[0,1]
	v_add_f32_e32 v13, v25, v24
	v_add_f32_e32 v10, v10, v15
	v_add_f32_e32 v10, v14, v10
	v_add_f32_e32 v10, v17, v10
	v_sub_f32_e32 v14, v13, v25
	v_mul_f32_e32 v10, v23, v10
	v_sub_f32_e32 v14, v24, v14
	v_add_f32_e32 v10, v14, v10
	v_add_f32_e32 v15, v13, v10
	v_mul_f32_e32 v16, v15, v15
	v_fmamk_f32 v14, v16, 0x3e9b6dac, v235
	v_fmaak_f32 v227, v16, v14, 0x3f2aaada
	v_cvt_f32_i32_e32 v14, v22
	v_sub_f32_e32 v13, v15, v13
	v_ldexp_f32 v17, v15, 1
	v_mul_f32_e32 v15, v15, v16
	v_pk_mul_f32 v[18:19], v[14:15], v[226:227]
	v_sub_f32_e32 v10, v10, v13
	v_fma_f32 v16, v14, s56, -v18
	v_fmac_f32_e32 v16, 0xb102e308, v14
	v_pk_add_f32 v[14:15], v[18:19], v[16:17]
	v_ldexp_f32 v10, v10, 1
	v_sub_f32_e32 v13, v15, v17
	v_sub_f32_e32 v13, v19, v13
	v_add_f32_e32 v21, v10, v13
	v_mov_b32_e32 v20, v18
	v_pk_add_f32 v[18:19], v[14:15], v[18:19] neg_lo:[0,1] neg_hi:[0,1]
	v_pk_add_f32 v[22:23], v[14:15], v[20:21]
	v_mov_b32_e32 v17, v14
	v_mov_b32_e32 v19, v23
	v_pk_add_f32 v[24:25], v[16:17], v[18:19] neg_lo:[0,1] neg_hi:[0,1]
	v_pk_add_f32 v[16:17], v[16:17], v[18:19]
	v_mov_b32_e32 v20, v21
	v_pk_add_f32 v[18:19], v[16:17], v[14:15] op_sel:[1,0] op_sel_hi:[0,1] neg_lo:[0,1] neg_hi:[0,1]
	v_pk_add_f32 v[26:27], v[22:23], v[18:19] op_sel_hi:[1,0] neg_lo:[0,1] neg_hi:[0,1]
	v_mov_b32_e32 v22, v23
	v_mov_b32_e32 v23, v17
	v_pk_mov_b32 v[18:19], v[14:15], v[18:19] op_sel:[1,0]
	v_mov_b32_e32 v21, v14
	v_pk_add_f32 v[18:19], v[22:23], v[18:19] neg_lo:[0,1] neg_hi:[0,1]
	v_mov_b32_e32 v26, v24
	v_pk_add_f32 v[14:15], v[20:21], v[18:19] neg_lo:[0,1] neg_hi:[0,1]
	v_mov_b32_e32 v25, v17
	v_pk_add_f32 v[18:19], v[26:27], v[14:15]
	s_nop 0
	v_pk_add_f32 v[20:21], v[18:19], v[18:19] op_sel:[0,1] op_sel_hi:[1,0]
	s_nop 0
	v_pk_add_f32 v[16:17], v[16:17], v[20:21] op_sel:[1,0] op_sel_hi:[0,1]
	v_mov_b32_e32 v19, v16
	v_pk_add_f32 v[22:23], v[18:19], v[24:25] neg_lo:[0,1] neg_hi:[0,1]
	v_mov_b32_e32 v15, v20
	v_sub_f32_e32 v10, v18, v22
	v_pk_add_f32 v[14:15], v[14:15], v[22:23] neg_lo:[0,1] neg_hi:[0,1]
	v_sub_f32_e32 v10, v24, v10
	v_add_f32_e32 v10, v14, v10
	v_add_f32_e32 v10, v10, v15
	v_add_f32_e32 v10, v16, v10
	v_cndmask_b32_e32 v10, v236, v10, vcc
	v_cmp_ngt_f32_e32 vcc, -1.0, v9
	s_nop 1
	v_cndmask_b32_e32 v10, v237, v10, vcc
	v_cmp_neq_f32_e32 vcc, -1.0, v9
	s_nop 1
	v_cndmask_b32_e32 v10, v238, v10, vcc
	v_cmp_lt_f32_e64 vcc, |v9|, s58
	s_nop 1
	v_cndmask_b32_e32 v9, v10, v9, vcc
.LBB0_368:
	s_or_b64 exec, exec, s[36:37]
	v_mul_f32_e32 v6, 0x3fb8aa3b, v6
	v_exp_f32_e32 v6, v6
	s_nop 0
	v_mul_f32_e64 v10, v3, -v6
	v_mul_f32_e32 v3, 0x3fb8aa3b, v11
	v_exp_f32_e32 v3, v3
	s_nop 0
	v_mul_f32_e64 v11, v7, -v3
	v_mul_f32_e32 v3, 0x3fb8aa3b, v12
	v_exp_f32_e32 v3, v3
	s_nop 0
	v_mul_f32_e64 v12, v8, -v3
	v_mov_b32_e32 v3, v165
	v_mul_f32_e32 v3, 0x3fb8aa3b, v3
	v_exp_f32_e32 v3, v3
	s_nop 0
	v_mul_f32_e64 v13, v9, -v3
